# v24 + instruction selection: 151 cross-lane row reductions in GEMM epilogues done with v_permlane16/32_swap in the VALU instead of ds_bpermute LDS round trips (bit-identical sums)
# speedup vs baseline: 1.0041x; 1.0041x over previous
; __device__ __forceinline__ float row_ssq(const float* part, int pitch, int n4, int row, int fq) {
;     f32x4 v = (f32x4){0.f, 0.f, 0.f, 0.f};
;     if (fq < n4) v = *(const f32x4*)(part + (size_t)row * pitch + 4 * fq);
;     float s = (v[0] + v[1]) + (v[2] + v[3]);
;     s += __shfl_xor(s, 16); s += __shfl_xor(s, 32);
;     return s;
;     __device__ __forceinline__ void operator()(const f32x4 (&acc)[2][2][4][2], const Unit& u, int wr, int wc, int fr, int fq) const {
;         const int row0 = u.pm * BM + wr * 64 + fr, col0 = u.pn * 128 + wc * 32 + 8 * fq;
; #pragma unroll
;         for (int ai = 0; ai < 2; ++ai)
; #pragma unroll
;             for (int m = 0; m < 4; ++m) {
;                 const int row = row0 + ai * HALF + m * 16;
;                 const float rs = rsqrtf(row_ssq(ssq, 16, 4, row, fq) * (1.f / 1024.f) + EPS);
.LBB0_168:
	v_and_b32_e32 v145, 64, v241
	v_xor_b32_e32 v143, 16, v241
	v_add_u32_e32 v145, 64, v145
	v_cmp_lt_i32_e32 vcc, v143, v145
	v_lshl_add_u32 v144, s44, 8, v146
	v_lshl_or_b32 v142, s4, 7, v148
	v_cndmask_b32_e32 v143, v241, v143, vcc
	v_lshlrev_b32_e32 v150, 2, v143
	v_xor_b32_e32 v143, 32, v241
	v_cmp_lt_i32_e32 vcc, v143, v145
	v_ashrrev_i32_e32 v145, 31, v144
	v_and_b32_e32 v166, 48, v241
	v_lshl_add_u32 v166, v146, 6, v166
	v_add_u32_e32 v166, 0x24000, v166
	ds_read_b128 v[168:171], v166
	ds_read_b128 v[172:175], v166 offset:1024
	ds_read_b128 v[176:179], v166 offset:2048
	ds_read_b128 v[180:183], v166 offset:3072
	v_cndmask_b32_e32 v143, v241, v143, vcc
	v_lshlrev_b32_e32 v151, 2, v143
	ds_read_b128 v[184:187], v166 offset:8192
	ds_read_b128 v[188:191], v166 offset:9216
	ds_read_b128 v[192:195], v166 offset:10240
	ds_read_b128 v[196:199], v166 offset:11264
	v_ashrrev_i32_e32 v143, 31, v142
	v_lshl_add_u64 v[142:143], v[142:143], 1, s[96:97]
	s_movk_i32 s4, 0x1600
	s_mov_b64 s[24:25], -1
	s_waitcnt lgkmcnt(7)
	v_add_f32_e32 v168, v169, v168
	v_add_f32_e32 v170, v170, v171
	v_add_f32_e32 v168, v168, v170
	v_mov_b32_e32 v169, v168
	s_nop 1
	v_permlane16_swap_b32_e32 v168, v169
	s_waitcnt lgkmcnt(6)
	v_add_f32_e32 v172, v173, v172
	v_add_f32_e32 v174, v174, v175
	v_add_f32_e32 v172, v172, v174
	v_mov_b32_e32 v173, v172
	s_nop 1
	v_permlane16_swap_b32_e32 v172, v173
	s_waitcnt lgkmcnt(5)
	v_add_f32_e32 v176, v177, v176
	v_add_f32_e32 v178, v178, v179
	v_add_f32_e32 v176, v176, v178
	v_mov_b32_e32 v177, v176
	s_nop 1
	v_permlane16_swap_b32_e32 v176, v177
	s_waitcnt lgkmcnt(4)
	v_add_f32_e32 v180, v181, v180
	v_add_f32_e32 v182, v182, v183
	v_add_f32_e32 v180, v180, v182
	v_mov_b32_e32 v181, v180
	s_nop 1
	v_permlane16_swap_b32_e32 v180, v181
	s_waitcnt lgkmcnt(3)
	v_add_f32_e32 v184, v185, v184
	v_add_f32_e32 v186, v186, v187
	v_add_f32_e32 v184, v184, v186
	v_mov_b32_e32 v185, v184
	s_nop 1
	v_permlane16_swap_b32_e32 v184, v185
	s_waitcnt lgkmcnt(2)
	v_add_f32_e32 v188, v189, v188
	v_add_f32_e32 v190, v190, v191
	v_add_f32_e32 v188, v188, v190
	v_mov_b32_e32 v189, v188
	s_nop 1
	v_permlane16_swap_b32_e32 v188, v189
	s_waitcnt lgkmcnt(1)
	v_add_f32_e32 v192, v193, v192
	v_add_f32_e32 v194, v194, v195
	v_add_f32_e32 v192, v192, v194
	v_mov_b32_e32 v193, v192
	s_nop 1
	v_permlane16_swap_b32_e32 v192, v193
	s_waitcnt lgkmcnt(0)
	v_add_f32_e32 v196, v197, v196
	v_add_f32_e32 v198, v198, v199
	v_add_f32_e32 v196, v196, v198
	v_mov_b32_e32 v197, v196
	s_nop 1
	v_permlane16_swap_b32_e32 v196, v197
	s_waitcnt lgkmcnt(7)
	v_add_f32_e32 v168, v168, v169
	v_mov_b32_e32 v169, v168
	s_nop 1
	v_permlane32_swap_b32_e32 v168, v169
	s_waitcnt lgkmcnt(7)
	v_add_f32_e32 v172, v172, v173
	v_mov_b32_e32 v173, v172
	s_nop 1
	v_permlane32_swap_b32_e32 v172, v173
	s_waitcnt lgkmcnt(7)
	v_add_f32_e32 v176, v176, v177
	v_mov_b32_e32 v177, v176
	s_nop 1
	v_permlane32_swap_b32_e32 v176, v177
	s_waitcnt lgkmcnt(7)
	v_add_f32_e32 v180, v180, v181
	v_mov_b32_e32 v181, v180
	s_nop 1
	v_permlane32_swap_b32_e32 v180, v181
	s_waitcnt lgkmcnt(7)
	v_add_f32_e32 v184, v184, v185
	v_mov_b32_e32 v185, v184
	s_nop 1
	v_permlane32_swap_b32_e32 v184, v185
	s_waitcnt lgkmcnt(7)
	v_add_f32_e32 v188, v188, v189
	v_mov_b32_e32 v189, v188
	s_nop 1
	v_permlane32_swap_b32_e32 v188, v189
	s_waitcnt lgkmcnt(7)
	v_add_f32_e32 v192, v192, v193
	v_mov_b32_e32 v193, v192
	s_nop 1
	v_permlane32_swap_b32_e32 v192, v193
	s_waitcnt lgkmcnt(7)
	v_add_f32_e32 v196, v196, v197
	v_mov_b32_e32 v197, v196
	s_nop 1
	v_permlane32_swap_b32_e32 v196, v197
	s_waitcnt lgkmcnt(7)
	v_add_f32_e32 v168, v168, v169
	v_fmamk_f32 v168, v168, 0x3a800000, v239
	s_waitcnt lgkmcnt(6)
	v_add_f32_e32 v172, v172, v173
	v_fmamk_f32 v172, v172, 0x3a800000, v239
	s_waitcnt lgkmcnt(5)
	v_add_f32_e32 v176, v176, v177
	v_fmamk_f32 v176, v176, 0x3a800000, v239
	s_waitcnt lgkmcnt(4)
	v_add_f32_e32 v180, v180, v181
	v_fmamk_f32 v180, v180, 0x3a800000, v239
	s_waitcnt lgkmcnt(3)
	v_add_f32_e32 v184, v184, v185
	v_fmamk_f32 v184, v184, 0x3a800000, v239
	s_waitcnt lgkmcnt(2)
	v_add_f32_e32 v188, v188, v189
	v_fmamk_f32 v188, v188, 0x3a800000, v239
	s_waitcnt lgkmcnt(1)
	v_add_f32_e32 v192, v192, v193
	v_fmamk_f32 v192, v192, 0x3a800000, v239
	s_waitcnt lgkmcnt(0)
; __device__ __forceinline__ unsigned pk2(float lo, float hi) { f32x2_t v = {lo, hi}; bf16x2_t b = __builtin_convertvector(v, bf16x2_t); return __builtin_bit_cast(unsigned, b); }
; __device__ __forceinline__ float fast_sigmoid(float x) { return __builtin_amdgcn_rcpf(1.f + __expf(-x)); }
;     __device__ __forceinline__ void operator()(const f32x4 (&acc)[2][2][4][2], const Unit& u, int wr, int wc, int fr, int fq) const {
;     ...
;                 const int row = row0 + ai * HALF + m * 16;
;                 const float rs = rsqrtf(row_ssq(ssq, 16, 4, row, fq) * (1.f / 1024.f) + EPS);
;                 float r[8];
; #pragma unroll
;                 for (int n = 0; n < 2; ++n)
; #pragma unroll
;                     for (int e = 0; e < 4; ++e) { const float gv = acc[ai][0][m][n][e] * rs, uv = acc[ai][1][m][n][e] * rs; r[n * 4 + e] = gv * fast_sigmoid(gv) * uv; }
;                 u32x4 w; w.x = pk2(r[0], r[1]); w.y = pk2(r[2], r[3]); w.z = pk2(r[4], r[5]); w.w = pk2(r[6], r[7]);
;                 *(u32x4*)(O + (size_t)row * DFF + col0) = w;
	v_add_f32_e32 v196, v196, v197
	v_fmamk_f32 v196, v196, 0x3a800000, v239
	v_cmp_gt_f32_e32 vcc, s55, v168
	v_mul_f32_e32 v169, 0x4b800000, v168
	s_nop 0
	v_cndmask_b32_e32 v168, v168, v169, vcc
	v_rsq_f32_e32 v168, v168
	s_nop 0
	v_mul_f32_e32 v169, 0x45800000, v168
	v_cndmask_b32_e32 v158, v168, v169, vcc
	v_cmp_gt_f32_e32 vcc, s55, v172
	v_mul_f32_e32 v173, 0x4b800000, v172
	s_nop 0
	v_cndmask_b32_e32 v172, v172, v173, vcc
	v_rsq_f32_e32 v172, v172
	s_nop 0
	v_mul_f32_e32 v173, 0x45800000, v172
	v_cndmask_b32_e32 v159, v172, v173, vcc
	v_cmp_gt_f32_e32 vcc, s55, v176
	v_mul_f32_e32 v177, 0x4b800000, v176
	s_nop 0
	v_cndmask_b32_e32 v176, v176, v177, vcc
	v_rsq_f32_e32 v176, v176
	s_nop 0
	v_mul_f32_e32 v177, 0x45800000, v176
	v_cndmask_b32_e32 v160, v176, v177, vcc
	v_cmp_gt_f32_e32 vcc, s55, v180
	v_mul_f32_e32 v181, 0x4b800000, v180
	s_nop 0
	v_cndmask_b32_e32 v180, v180, v181, vcc
	v_rsq_f32_e32 v180, v180
	s_nop 0
	v_mul_f32_e32 v181, 0x45800000, v180
	v_cndmask_b32_e32 v161, v180, v181, vcc
	v_cmp_gt_f32_e32 vcc, s55, v184
	v_mul_f32_e32 v185, 0x4b800000, v184
	s_nop 0
	v_cndmask_b32_e32 v184, v184, v185, vcc
	v_rsq_f32_e32 v184, v184
	s_nop 0
	v_mul_f32_e32 v185, 0x45800000, v184
	v_cndmask_b32_e32 v162, v184, v185, vcc
	v_cmp_gt_f32_e32 vcc, s55, v188
	v_mul_f32_e32 v189, 0x4b800000, v188
	s_nop 0
	v_cndmask_b32_e32 v188, v188, v189, vcc
	v_rsq_f32_e32 v188, v188
	s_nop 0
	v_mul_f32_e32 v189, 0x45800000, v188
	v_cndmask_b32_e32 v163, v188, v189, vcc
	v_cmp_gt_f32_e32 vcc, s55, v192
	v_mul_f32_e32 v193, 0x4b800000, v192
	s_nop 0
	v_cndmask_b32_e32 v192, v192, v193, vcc
	v_rsq_f32_e32 v192, v192
	s_nop 0
	v_mul_f32_e32 v193, 0x45800000, v192
	v_cndmask_b32_e32 v164, v192, v193, vcc
	v_cmp_gt_f32_e32 vcc, s55, v196
	v_mul_f32_e32 v197, 0x4b800000, v196
	s_nop 0
	v_cndmask_b32_e32 v196, v196, v197, vcc
	v_rsq_f32_e32 v196, v196
	s_nop 0
	v_mul_f32_e32 v197, 0x45800000, v196
	v_cndmask_b32_e32 v165, v196, v197, vcc
	v_mov_b32_e32 v152, v158
	v_pk_mul_f32 v[126:127], v[126:127], v[152:153] op_sel_hi:[1,0]
	v_pk_mul_f32 v[118:119], v[118:119], v[152:153] op_sel_hi:[1,0]
	v_mul_f32_e32 v145, 0xbfb8aa3b, v126
	v_exp_f32_e32 v145, v145
	v_pk_mul_f32 v[120:121], v[120:121], v[152:153] op_sel_hi:[1,0]
	v_pk_mul_f32 v[122:123], v[122:123], v[152:153] op_sel_hi:[1,0]
	v_pk_mul_f32 v[114:115], v[114:115], v[152:153] op_sel_hi:[1,0]
	v_add_f32_e32 v145, 1.0, v145
	v_rcp_f32_e32 v154, v145
	v_mul_f32_e32 v145, 0xbfb8aa3b, v127
	v_exp_f32_e32 v145, v145
	v_pk_mul_f32 v[116:117], v[116:117], v[152:153] op_sel_hi:[1,0]
	v_add_f32_e32 v145, 1.0, v145
	v_rcp_f32_e32 v155, v145
	s_nop 0
	v_pk_mul_f32 v[126:127], v[126:127], v[154:155]
	s_nop 0
	v_pk_mul_f32 v[118:119], v[118:119], v[126:127]
	v_pk_mul_f32 v[126:127], v[128:129], v[152:153] op_sel_hi:[1,0]
	s_nop 0
	v_mul_f32_e32 v128, 0xbfb8aa3b, v126
	v_mul_f32_e32 v129, 0xbfb8aa3b, v127
	v_exp_f32_e32 v128, v128
	v_exp_f32_e32 v129, v129
	v_add_f32_e32 v128, 1.0, v128
	v_add_f32_e32 v129, 1.0, v129
	v_rcp_f32_e32 v128, v128
	v_rcp_f32_e32 v129, v129
	s_nop 0
	v_pk_mul_f32 v[126:127], v[126:127], v[128:129]
	s_nop 0
	v_pk_mul_f32 v[120:121], v[120:121], v[126:127]
	v_mul_f32_e32 v126, 0xbfb8aa3b, v122
	v_mul_f32_e32 v127, 0xbfb8aa3b, v123
	v_exp_f32_e32 v126, v126
	v_exp_f32_e32 v127, v127
	v_add_f32_e32 v126, 1.0, v126
	v_add_f32_e32 v127, 1.0, v127
	v_rcp_f32_e32 v126, v126
	v_rcp_f32_e32 v127, v127
	s_nop 0
	v_pk_mul_f32 v[122:123], v[122:123], v[126:127]
	s_nop 0
	v_pk_mul_f32 v[122:123], v[114:115], v[122:123]
	v_pk_mul_f32 v[114:115], v[124:125], v[152:153] op_sel_hi:[1,0]
	s_nop 0
	v_mul_f32_e32 v124, 0xbfb8aa3b, v114
	v_mul_f32_e32 v125, 0xbfb8aa3b, v115
	v_exp_f32_e32 v124, v124
	v_exp_f32_e32 v125, v125
	v_add_f32_e32 v124, 1.0, v124
	v_add_f32_e32 v125, 1.0, v125
	v_rcp_f32_e32 v124, v124
	v_rcp_f32_e32 v125, v125
	s_nop 0
	v_pk_mul_f32 v[114:115], v[114:115], v[124:125]
	s_nop 0
	v_pk_mul_f32 v[124:125], v[116:117], v[114:115]
	v_cvt_pk_bf16_f32 v114, v118, v119
	v_cvt_pk_bf16_f32 v115, v120, v121
	v_cvt_pk_bf16_f32 v116, v122, v123
	v_cvt_pk_bf16_f32 v117, v124, v125
	v_mad_i64_i32 v[118:119], s[6:7], v144, s4, v[142:143]
	global_store_dwordx4 v[118:119], v[114:117], off
	s_nop 1
	v_or_b32_e32 v114, 16, v144
	v_mov_b32_e32 v116, v159
	v_pk_mul_f32 v[110:111], v[110:111], v[116:117] op_sel_hi:[1,0]
	v_pk_mul_f32 v[102:103], v[102:103], v[116:117] op_sel_hi:[1,0]
	v_mul_f32_e32 v115, 0xbfb8aa3b, v110
	v_exp_f32_e32 v115, v115
	v_pk_mul_f32 v[104:105], v[104:105], v[116:117] op_sel_hi:[1,0]
	v_pk_mul_f32 v[106:107], v[106:107], v[116:117] op_sel_hi:[1,0]
	v_pk_mul_f32 v[98:99], v[98:99], v[116:117] op_sel_hi:[1,0]
	v_add_f32_e32 v115, 1.0, v115
	v_rcp_f32_e32 v118, v115
	v_mul_f32_e32 v115, 0xbfb8aa3b, v111
	v_exp_f32_e32 v115, v115
	v_pk_mul_f32 v[100:101], v[100:101], v[116:117] op_sel_hi:[1,0]
	v_add_f32_e32 v115, 1.0, v115
	v_rcp_f32_e32 v119, v115
	s_nop 0
	v_pk_mul_f32 v[110:111], v[110:111], v[118:119]
	s_nop 0
	v_pk_mul_f32 v[102:103], v[102:103], v[110:111]
	v_pk_mul_f32 v[110:111], v[112:113], v[116:117] op_sel_hi:[1,0]
	s_nop 0
	v_mul_f32_e32 v112, 0xbfb8aa3b, v110
	v_mul_f32_e32 v113, 0xbfb8aa3b, v111
	v_exp_f32_e32 v112, v112
	v_exp_f32_e32 v113, v113
	v_add_f32_e32 v112, 1.0, v112
	v_add_f32_e32 v113, 1.0, v113
	v_rcp_f32_e32 v112, v112
	v_rcp_f32_e32 v113, v113
	s_nop 0
	v_pk_mul_f32 v[110:111], v[110:111], v[112:113]
	s_nop 0
	v_pk_mul_f32 v[104:105], v[104:105], v[110:111]
	v_mul_f32_e32 v110, 0xbfb8aa3b, v106
	v_mul_f32_e32 v111, 0xbfb8aa3b, v107
	v_exp_f32_e32 v110, v110
	v_exp_f32_e32 v111, v111
	v_add_f32_e32 v110, 1.0, v110
	v_add_f32_e32 v111, 1.0, v111
; __device__ __forceinline__ unsigned pk2(float lo, float hi) { f32x2_t v = {lo, hi}; bf16x2_t b = __builtin_convertvector(v, bf16x2_t); return __builtin_bit_cast(unsigned, b); }
; __device__ __forceinline__ float fast_sigmoid(float x) { return __builtin_amdgcn_rcpf(1.f + __expf(-x)); }
;     __device__ __forceinline__ void operator()(const f32x4 (&acc)[2][2][4][2], const Unit& u, int wr, int wc, int fr, int fq) const {
;     ...
;                 const int row = row0 + ai * HALF + m * 16;
;                 const float rs = rsqrtf(row_ssq(ssq, 16, 4, row, fq) * (1.f / 1024.f) + EPS);
;                 float r[8];
; #pragma unroll
;                 for (int n = 0; n < 2; ++n)
; #pragma unroll
;                     for (int e = 0; e < 4; ++e) { const float gv = acc[ai][0][m][n][e] * rs, uv = acc[ai][1][m][n][e] * rs; r[n * 4 + e] = gv * fast_sigmoid(gv) * uv; }
;                 u32x4 w; w.x = pk2(r[0], r[1]); w.y = pk2(r[2], r[3]); w.z = pk2(r[4], r[5]); w.w = pk2(r[6], r[7]);
;                 *(u32x4*)(O + (size_t)row * DFF + col0) = w;
	v_rcp_f32_e32 v110, v110
	v_rcp_f32_e32 v111, v111
	s_nop 0
	v_pk_mul_f32 v[106:107], v[106:107], v[110:111]
	s_nop 0
	v_pk_mul_f32 v[106:107], v[98:99], v[106:107]
	v_pk_mul_f32 v[98:99], v[108:109], v[116:117] op_sel_hi:[1,0]
	s_nop 0
	v_mul_f32_e32 v108, 0xbfb8aa3b, v98
	v_mul_f32_e32 v109, 0xbfb8aa3b, v99
	v_exp_f32_e32 v108, v108
	v_exp_f32_e32 v109, v109
	v_add_f32_e32 v108, 1.0, v108
	v_add_f32_e32 v109, 1.0, v109
	v_rcp_f32_e32 v108, v108
	v_rcp_f32_e32 v109, v109
	s_nop 0
	v_pk_mul_f32 v[98:99], v[98:99], v[108:109]
	s_nop 0
	v_pk_mul_f32 v[108:109], v[100:101], v[98:99]
	v_cvt_pk_bf16_f32 v98, v102, v103
	v_cvt_pk_bf16_f32 v99, v104, v105
	v_cvt_pk_bf16_f32 v100, v106, v107
	v_cvt_pk_bf16_f32 v101, v108, v109
	v_mad_i64_i32 v[102:103], s[6:7], v114, s4, v[142:143]
	global_store_dwordx4 v[102:103], v[98:101], off
	s_nop 1
	v_or_b32_e32 v98, 32, v144
	v_mov_b32_e32 v100, v160
	v_pk_mul_f32 v[94:95], v[94:95], v[100:101] op_sel_hi:[1,0]
	v_pk_mul_f32 v[86:87], v[86:87], v[100:101] op_sel_hi:[1,0]
	v_mul_f32_e32 v99, 0xbfb8aa3b, v94
	v_exp_f32_e32 v99, v99
	v_pk_mul_f32 v[88:89], v[88:89], v[100:101] op_sel_hi:[1,0]
	v_pk_mul_f32 v[90:91], v[90:91], v[100:101] op_sel_hi:[1,0]
	v_pk_mul_f32 v[82:83], v[82:83], v[100:101] op_sel_hi:[1,0]
	v_add_f32_e32 v99, 1.0, v99
	v_rcp_f32_e32 v102, v99
	v_mul_f32_e32 v99, 0xbfb8aa3b, v95
	v_exp_f32_e32 v99, v99
	v_pk_mul_f32 v[84:85], v[84:85], v[100:101] op_sel_hi:[1,0]
	v_add_f32_e32 v99, 1.0, v99
	v_rcp_f32_e32 v103, v99
	s_nop 0
	v_pk_mul_f32 v[94:95], v[94:95], v[102:103]
	s_nop 0
	v_pk_mul_f32 v[86:87], v[86:87], v[94:95]
	v_pk_mul_f32 v[94:95], v[96:97], v[100:101] op_sel_hi:[1,0]
	s_nop 0
	v_mul_f32_e32 v96, 0xbfb8aa3b, v94
	v_mul_f32_e32 v97, 0xbfb8aa3b, v95
	v_exp_f32_e32 v96, v96
	v_exp_f32_e32 v97, v97
	v_add_f32_e32 v96, 1.0, v96
	v_add_f32_e32 v97, 1.0, v97
	v_rcp_f32_e32 v96, v96
	v_rcp_f32_e32 v97, v97
	s_nop 0
	v_pk_mul_f32 v[94:95], v[94:95], v[96:97]
	s_nop 0
	v_pk_mul_f32 v[88:89], v[88:89], v[94:95]
	v_mul_f32_e32 v94, 0xbfb8aa3b, v90
	v_mul_f32_e32 v95, 0xbfb8aa3b, v91
	v_exp_f32_e32 v94, v94
	v_exp_f32_e32 v95, v95
	v_add_f32_e32 v94, 1.0, v94
	v_add_f32_e32 v95, 1.0, v95
	v_rcp_f32_e32 v94, v94
	v_rcp_f32_e32 v95, v95
	s_nop 0
	v_pk_mul_f32 v[90:91], v[90:91], v[94:95]
	s_nop 0
	v_pk_mul_f32 v[90:91], v[82:83], v[90:91]
	v_pk_mul_f32 v[82:83], v[92:93], v[100:101] op_sel_hi:[1,0]
	s_nop 0
	v_mul_f32_e32 v92, 0xbfb8aa3b, v82
	v_mul_f32_e32 v93, 0xbfb8aa3b, v83
	v_exp_f32_e32 v92, v92
	v_exp_f32_e32 v93, v93
	v_add_f32_e32 v92, 1.0, v92
	v_add_f32_e32 v93, 1.0, v93
	v_rcp_f32_e32 v92, v92
	v_rcp_f32_e32 v93, v93
	s_nop 0
	v_pk_mul_f32 v[82:83], v[82:83], v[92:93]
	s_nop 0
	v_pk_mul_f32 v[92:93], v[84:85], v[82:83]
	v_cvt_pk_bf16_f32 v82, v86, v87
	v_cvt_pk_bf16_f32 v83, v88, v89
	v_cvt_pk_bf16_f32 v84, v90, v91
	v_cvt_pk_bf16_f32 v85, v92, v93
	v_mad_i64_i32 v[86:87], s[6:7], v98, s4, v[142:143]
	global_store_dwordx4 v[86:87], v[82:85], off
	s_nop 1
	v_or_b32_e32 v82, 48, v144
	v_mov_b32_e32 v84, v161
	v_pk_mul_f32 v[78:79], v[78:79], v[84:85] op_sel_hi:[1,0]
	v_pk_mul_f32 v[70:71], v[70:71], v[84:85] op_sel_hi:[1,0]
	v_mul_f32_e32 v83, 0xbfb8aa3b, v78
	v_exp_f32_e32 v83, v83
	v_pk_mul_f32 v[72:73], v[72:73], v[84:85] op_sel_hi:[1,0]
	v_pk_mul_f32 v[74:75], v[74:75], v[84:85] op_sel_hi:[1,0]
	v_pk_mul_f32 v[66:67], v[66:67], v[84:85] op_sel_hi:[1,0]
	v_add_f32_e32 v83, 1.0, v83
	v_rcp_f32_e32 v86, v83
	v_mul_f32_e32 v83, 0xbfb8aa3b, v79
	v_exp_f32_e32 v83, v83
	v_pk_mul_f32 v[68:69], v[68:69], v[84:85] op_sel_hi:[1,0]
	v_add_f32_e32 v83, 1.0, v83
	v_rcp_f32_e32 v87, v83
	s_nop 0
	v_pk_mul_f32 v[78:79], v[78:79], v[86:87]
	s_nop 0
	v_pk_mul_f32 v[70:71], v[70:71], v[78:79]
	v_pk_mul_f32 v[78:79], v[80:81], v[84:85] op_sel_hi:[1,0]
	s_nop 0
	v_mul_f32_e32 v80, 0xbfb8aa3b, v78
	v_mul_f32_e32 v81, 0xbfb8aa3b, v79
	v_exp_f32_e32 v80, v80
	v_exp_f32_e32 v81, v81
	v_add_f32_e32 v80, 1.0, v80
	v_add_f32_e32 v81, 1.0, v81
	v_rcp_f32_e32 v80, v80
	v_rcp_f32_e32 v81, v81
	s_nop 0
	v_pk_mul_f32 v[78:79], v[78:79], v[80:81]
	s_nop 0
	v_pk_mul_f32 v[72:73], v[72:73], v[78:79]
	v_mul_f32_e32 v78, 0xbfb8aa3b, v74
	v_mul_f32_e32 v79, 0xbfb8aa3b, v75
	v_exp_f32_e32 v78, v78
	v_exp_f32_e32 v79, v79
	v_add_f32_e32 v78, 1.0, v78
	v_add_f32_e32 v79, 1.0, v79
	v_rcp_f32_e32 v78, v78
	v_rcp_f32_e32 v79, v79
	s_nop 0
	v_pk_mul_f32 v[74:75], v[74:75], v[78:79]
	s_nop 0
	v_pk_mul_f32 v[74:75], v[66:67], v[74:75]
	v_pk_mul_f32 v[66:67], v[76:77], v[84:85] op_sel_hi:[1,0]
	s_nop 0
	v_mul_f32_e32 v76, 0xbfb8aa3b, v66
	v_mul_f32_e32 v77, 0xbfb8aa3b, v67
	v_exp_f32_e32 v76, v76
	v_exp_f32_e32 v77, v77
	v_add_f32_e32 v76, 1.0, v76
	v_add_f32_e32 v77, 1.0, v77
	v_rcp_f32_e32 v76, v76
	v_rcp_f32_e32 v77, v77
	s_nop 0
	v_pk_mul_f32 v[66:67], v[66:67], v[76:77]
	s_nop 0
	v_pk_mul_f32 v[76:77], v[68:69], v[66:67]
	v_cvt_pk_bf16_f32 v66, v70, v71
	v_cvt_pk_bf16_f32 v67, v72, v73
	v_cvt_pk_bf16_f32 v68, v74, v75
	v_cvt_pk_bf16_f32 v69, v76, v77
	v_mad_i64_i32 v[70:71], s[6:7], v82, s4, v[142:143]
	global_store_dwordx4 v[70:71], v[66:69], off
	s_nop 1
	v_add_u32_e32 v66, 0x80, v144
	v_mov_b32_e32 v68, v162
	v_pk_mul_f32 v[62:63], v[62:63], v[68:69] op_sel_hi:[1,0]
	v_pk_mul_f32 v[54:55], v[54:55], v[68:69] op_sel_hi:[1,0]
	v_mul_f32_e32 v67, 0xbfb8aa3b, v62
	v_exp_f32_e32 v67, v67
	v_pk_mul_f32 v[56:57], v[56:57], v[68:69] op_sel_hi:[1,0]
	v_pk_mul_f32 v[58:59], v[58:59], v[68:69] op_sel_hi:[1,0]
	v_pk_mul_f32 v[50:51], v[50:51], v[68:69] op_sel_hi:[1,0]
	v_add_f32_e32 v67, 1.0, v67
	v_rcp_f32_e32 v70, v67
	v_mul_f32_e32 v67, 0xbfb8aa3b, v63
	v_exp_f32_e32 v67, v67
	v_pk_mul_f32 v[52:53], v[52:53], v[68:69] op_sel_hi:[1,0]
; __device__ __forceinline__ unsigned pk2(float lo, float hi) { f32x2_t v = {lo, hi}; bf16x2_t b = __builtin_convertvector(v, bf16x2_t); return __builtin_bit_cast(unsigned, b); }
; __device__ __forceinline__ float fast_sigmoid(float x) { return __builtin_amdgcn_rcpf(1.f + __expf(-x)); }
;     __device__ __forceinline__ void operator()(const f32x4 (&acc)[2][2][4][2], const Unit& u, int wr, int wc, int fr, int fq) const {
;     ...
;                 const int row = row0 + ai * HALF + m * 16;
;                 const float rs = rsqrtf(row_ssq(ssq, 16, 4, row, fq) * (1.f / 1024.f) + EPS);
;                 float r[8];
; #pragma unroll
;                 for (int n = 0; n < 2; ++n)
; #pragma unroll
;                     for (int e = 0; e < 4; ++e) { const float gv = acc[ai][0][m][n][e] * rs, uv = acc[ai][1][m][n][e] * rs; r[n * 4 + e] = gv * fast_sigmoid(gv) * uv; }
;                 u32x4 w; w.x = pk2(r[0], r[1]); w.y = pk2(r[2], r[3]); w.z = pk2(r[4], r[5]); w.w = pk2(r[6], r[7]);
;                 *(u32x4*)(O + (size_t)row * DFF + col0) = w;
	v_add_f32_e32 v67, 1.0, v67
	v_rcp_f32_e32 v71, v67
	s_nop 0
	v_pk_mul_f32 v[62:63], v[62:63], v[70:71]
	s_nop 0
	v_pk_mul_f32 v[54:55], v[54:55], v[62:63]
	v_pk_mul_f32 v[62:63], v[64:65], v[68:69] op_sel_hi:[1,0]
	s_nop 0
	v_mul_f32_e32 v64, 0xbfb8aa3b, v62
	v_mul_f32_e32 v65, 0xbfb8aa3b, v63
	v_exp_f32_e32 v64, v64
	v_exp_f32_e32 v65, v65
	v_add_f32_e32 v64, 1.0, v64
	v_add_f32_e32 v65, 1.0, v65
	v_rcp_f32_e32 v64, v64
	v_rcp_f32_e32 v65, v65
	s_nop 0
	v_pk_mul_f32 v[62:63], v[62:63], v[64:65]
	s_nop 0
	v_pk_mul_f32 v[56:57], v[56:57], v[62:63]
	v_mul_f32_e32 v62, 0xbfb8aa3b, v58
	v_mul_f32_e32 v63, 0xbfb8aa3b, v59
	v_exp_f32_e32 v62, v62
	v_exp_f32_e32 v63, v63
	v_add_f32_e32 v62, 1.0, v62
	v_add_f32_e32 v63, 1.0, v63
	v_rcp_f32_e32 v62, v62
	v_rcp_f32_e32 v63, v63
	s_nop 0
	v_pk_mul_f32 v[58:59], v[58:59], v[62:63]
	s_nop 0
	v_pk_mul_f32 v[58:59], v[50:51], v[58:59]
	v_pk_mul_f32 v[50:51], v[60:61], v[68:69] op_sel_hi:[1,0]
	s_nop 0
	v_mul_f32_e32 v60, 0xbfb8aa3b, v50
	v_mul_f32_e32 v61, 0xbfb8aa3b, v51
	v_exp_f32_e32 v60, v60
	v_exp_f32_e32 v61, v61
	v_add_f32_e32 v60, 1.0, v60
	v_add_f32_e32 v61, 1.0, v61
	v_rcp_f32_e32 v60, v60
	v_rcp_f32_e32 v61, v61
	s_nop 0
	v_pk_mul_f32 v[50:51], v[50:51], v[60:61]
	s_nop 0
	v_pk_mul_f32 v[60:61], v[52:53], v[50:51]
	v_cvt_pk_bf16_f32 v50, v54, v55
	v_cvt_pk_bf16_f32 v51, v56, v57
	v_cvt_pk_bf16_f32 v52, v58, v59
	v_cvt_pk_bf16_f32 v53, v60, v61
	v_mad_i64_i32 v[54:55], s[6:7], v66, s4, v[142:143]
	global_store_dwordx4 v[54:55], v[50:53], off
	s_nop 1
	v_add_u32_e32 v50, 0x90, v144
	v_mov_b32_e32 v52, v163
	v_pk_mul_f32 v[46:47], v[46:47], v[52:53] op_sel_hi:[1,0]
	v_pk_mul_f32 v[38:39], v[38:39], v[52:53] op_sel_hi:[1,0]
	v_mul_f32_e32 v51, 0xbfb8aa3b, v46
	v_exp_f32_e32 v51, v51
	v_pk_mul_f32 v[40:41], v[40:41], v[52:53] op_sel_hi:[1,0]
	v_pk_mul_f32 v[42:43], v[42:43], v[52:53] op_sel_hi:[1,0]
	v_pk_mul_f32 v[34:35], v[34:35], v[52:53] op_sel_hi:[1,0]
	v_add_f32_e32 v51, 1.0, v51
	v_rcp_f32_e32 v54, v51
	v_mul_f32_e32 v51, 0xbfb8aa3b, v47
	v_exp_f32_e32 v51, v51
	v_pk_mul_f32 v[36:37], v[36:37], v[52:53] op_sel_hi:[1,0]
	v_add_f32_e32 v51, 1.0, v51
	v_rcp_f32_e32 v55, v51
	s_nop 0
	v_pk_mul_f32 v[46:47], v[46:47], v[54:55]
	s_nop 0
	v_pk_mul_f32 v[38:39], v[38:39], v[46:47]
	v_pk_mul_f32 v[46:47], v[48:49], v[52:53] op_sel_hi:[1,0]
	s_nop 0
	v_mul_f32_e32 v48, 0xbfb8aa3b, v46
	v_mul_f32_e32 v49, 0xbfb8aa3b, v47
	v_exp_f32_e32 v48, v48
	v_exp_f32_e32 v49, v49
	v_add_f32_e32 v48, 1.0, v48
	v_add_f32_e32 v49, 1.0, v49
	v_rcp_f32_e32 v48, v48
	v_rcp_f32_e32 v49, v49
	s_nop 0
	v_pk_mul_f32 v[46:47], v[46:47], v[48:49]
	s_nop 0
	v_pk_mul_f32 v[40:41], v[40:41], v[46:47]
	v_mul_f32_e32 v46, 0xbfb8aa3b, v42
	v_mul_f32_e32 v47, 0xbfb8aa3b, v43
	v_exp_f32_e32 v46, v46
	v_exp_f32_e32 v47, v47
	v_add_f32_e32 v46, 1.0, v46
	v_add_f32_e32 v47, 1.0, v47
	v_rcp_f32_e32 v46, v46
	v_rcp_f32_e32 v47, v47
	s_nop 0
	v_pk_mul_f32 v[42:43], v[42:43], v[46:47]
	s_nop 0
	v_pk_mul_f32 v[42:43], v[34:35], v[42:43]
	v_pk_mul_f32 v[34:35], v[44:45], v[52:53] op_sel_hi:[1,0]
	s_nop 0
	v_mul_f32_e32 v44, 0xbfb8aa3b, v34
	v_mul_f32_e32 v45, 0xbfb8aa3b, v35
	v_exp_f32_e32 v44, v44
	v_exp_f32_e32 v45, v45
	v_add_f32_e32 v44, 1.0, v44
	v_add_f32_e32 v45, 1.0, v45
	v_rcp_f32_e32 v44, v44
	v_rcp_f32_e32 v45, v45
	s_nop 0
	v_pk_mul_f32 v[34:35], v[34:35], v[44:45]
	s_nop 0
	v_pk_mul_f32 v[44:45], v[36:37], v[34:35]
	v_cvt_pk_bf16_f32 v34, v38, v39
	v_cvt_pk_bf16_f32 v35, v40, v41
	v_cvt_pk_bf16_f32 v36, v42, v43
	v_cvt_pk_bf16_f32 v37, v44, v45
	v_mad_i64_i32 v[38:39], s[6:7], v50, s4, v[142:143]
	global_store_dwordx4 v[38:39], v[34:37], off
	s_nop 1
	v_add_u32_e32 v34, 0xa0, v144
	v_mov_b32_e32 v36, v164
	v_pk_mul_f32 v[30:31], v[30:31], v[36:37] op_sel_hi:[1,0]
	v_pk_mul_f32 v[22:23], v[22:23], v[36:37] op_sel_hi:[1,0]
	v_mul_f32_e32 v35, 0xbfb8aa3b, v30
	v_exp_f32_e32 v35, v35
	v_pk_mul_f32 v[24:25], v[24:25], v[36:37] op_sel_hi:[1,0]
	v_pk_mul_f32 v[26:27], v[26:27], v[36:37] op_sel_hi:[1,0]
; __device__ __forceinline__ unsigned pk2(float lo, float hi) { f32x2_t v = {lo, hi}; bf16x2_t b = __builtin_convertvector(v, bf16x2_t); return __builtin_bit_cast(unsigned, b); }
; __device__ __forceinline__ float fast_sigmoid(float x) { return __builtin_amdgcn_rcpf(1.f + __expf(-x)); }
; #define PG8_BAR __builtin_amdgcn_s_barrier()
; template <class Epi>
; __device__ __forceinline__ void gemm_phase(LAS unsigned char* lds, int wave_s, const Gemm g, const StaticOrder S, const Epi E) {
;     ...
;         if (!has_next) break;
; #pragma unroll
;         for (int a = 0; a < 2; ++a)
; #pragma unroll
;             for (int b = 0; b < 2; ++b)
; #pragma unroll
;                 for (int m = 0; m < 4; ++m)
; #pragma unroll
;                     for (int n = 0; n < 2; ++n) acc[a][b][m][n] = (f32x4){0.f, 0.f, 0.f, 0.f};
;         cur = nxt; cA = nA; cB = nB; ++ui;
;         if (wr == 1) PG8_BAR;
;     __device__ __forceinline__ void operator()(const f32x4 (&acc)[2][2][4][2], const Unit& u, int wr, int wc, int fr, int fq) const {
;     ...
;                 const int row = row0 + ai * HALF + m * 16;
;                 const float rs = rsqrtf(row_ssq(ssq, 16, 4, row, fq) * (1.f / 1024.f) + EPS);
;                 float r[8];
; #pragma unroll
;                 for (int n = 0; n < 2; ++n)
; #pragma unroll
;                     for (int e = 0; e < 4; ++e) { const float gv = acc[ai][0][m][n][e] * rs, uv = acc[ai][1][m][n][e] * rs; r[n * 4 + e] = gv * fast_sigmoid(gv) * uv; }
;                 u32x4 w; w.x = pk2(r[0], r[1]); w.y = pk2(r[2], r[3]); w.z = pk2(r[4], r[5]); w.w = pk2(r[6], r[7]);
;                 *(u32x4*)(O + (size_t)row * DFF + col0) = w;
	v_pk_mul_f32 v[18:19], v[18:19], v[36:37] op_sel_hi:[1,0]
	v_add_f32_e32 v35, 1.0, v35
	v_rcp_f32_e32 v38, v35
	v_mul_f32_e32 v35, 0xbfb8aa3b, v31
	v_exp_f32_e32 v35, v35
	v_pk_mul_f32 v[20:21], v[20:21], v[36:37] op_sel_hi:[1,0]
	v_add_f32_e32 v35, 1.0, v35
	v_rcp_f32_e32 v39, v35
	s_nop 0
	v_pk_mul_f32 v[30:31], v[30:31], v[38:39]
	s_nop 0
	v_pk_mul_f32 v[22:23], v[22:23], v[30:31]
	v_pk_mul_f32 v[30:31], v[32:33], v[36:37] op_sel_hi:[1,0]
	s_nop 0
	v_mul_f32_e32 v32, 0xbfb8aa3b, v30
	v_mul_f32_e32 v33, 0xbfb8aa3b, v31
	v_exp_f32_e32 v32, v32
	v_exp_f32_e32 v33, v33
	v_add_f32_e32 v32, 1.0, v32
	v_add_f32_e32 v33, 1.0, v33
	v_rcp_f32_e32 v32, v32
	v_rcp_f32_e32 v33, v33
	s_nop 0
	v_pk_mul_f32 v[30:31], v[30:31], v[32:33]
	s_nop 0
	v_pk_mul_f32 v[24:25], v[24:25], v[30:31]
	v_mul_f32_e32 v30, 0xbfb8aa3b, v26
	v_mul_f32_e32 v31, 0xbfb8aa3b, v27
	v_exp_f32_e32 v30, v30
	v_exp_f32_e32 v31, v31
	v_add_f32_e32 v30, 1.0, v30
	v_add_f32_e32 v31, 1.0, v31
	v_rcp_f32_e32 v30, v30
	v_rcp_f32_e32 v31, v31
	s_nop 0
	v_pk_mul_f32 v[26:27], v[26:27], v[30:31]
	s_nop 0
	v_pk_mul_f32 v[26:27], v[18:19], v[26:27]
	v_pk_mul_f32 v[18:19], v[28:29], v[36:37] op_sel_hi:[1,0]
	s_nop 0
	v_mul_f32_e32 v28, 0xbfb8aa3b, v18
	v_mul_f32_e32 v29, 0xbfb8aa3b, v19
	v_exp_f32_e32 v28, v28
	v_exp_f32_e32 v29, v29
	v_add_f32_e32 v28, 1.0, v28
	v_add_f32_e32 v29, 1.0, v29
	v_rcp_f32_e32 v28, v28
	v_rcp_f32_e32 v29, v29
	s_nop 0
	v_pk_mul_f32 v[18:19], v[18:19], v[28:29]
	s_nop 0
	v_pk_mul_f32 v[28:29], v[20:21], v[18:19]
	v_cvt_pk_bf16_f32 v18, v22, v23
	v_cvt_pk_bf16_f32 v19, v24, v25
	v_cvt_pk_bf16_f32 v20, v26, v27
	v_cvt_pk_bf16_f32 v21, v28, v29
	v_mad_i64_i32 v[22:23], s[6:7], v34, s4, v[142:143]
	global_store_dwordx4 v[22:23], v[18:21], off
	s_nop 1
	v_add_u32_e32 v18, 0xb0, v144
	v_mov_b32_e32 v20, v165
	v_pk_mul_f32 v[14:15], v[14:15], v[20:21] op_sel_hi:[1,0]
	v_pk_mul_f32 v[6:7], v[6:7], v[20:21] op_sel_hi:[1,0]
	v_mul_f32_e32 v19, 0xbfb8aa3b, v14
	v_exp_f32_e32 v19, v19
	v_pk_mul_f32 v[8:9], v[8:9], v[20:21] op_sel_hi:[1,0]
	v_pk_mul_f32 v[10:11], v[10:11], v[20:21] op_sel_hi:[1,0]
	v_pk_mul_f32 v[2:3], v[2:3], v[20:21] op_sel_hi:[1,0]
	v_add_f32_e32 v19, 1.0, v19
	v_rcp_f32_e32 v22, v19
	v_mul_f32_e32 v19, 0xbfb8aa3b, v15
	v_exp_f32_e32 v19, v19
	v_pk_mul_f32 v[4:5], v[4:5], v[20:21] op_sel_hi:[1,0]
	s_andn2_b64 vcc, exec, s[0:1]
	v_add_f32_e32 v19, 1.0, v19
	v_rcp_f32_e32 v23, v19
	s_nop 0
	v_pk_mul_f32 v[14:15], v[14:15], v[22:23]
	s_nop 0
	v_pk_mul_f32 v[6:7], v[6:7], v[14:15]
	v_pk_mul_f32 v[14:15], v[16:17], v[20:21] op_sel_hi:[1,0]
	s_nop 0
	v_mul_f32_e32 v16, 0xbfb8aa3b, v14
	v_mul_f32_e32 v17, 0xbfb8aa3b, v15
	v_exp_f32_e32 v16, v16
	v_exp_f32_e32 v17, v17
	v_add_f32_e32 v16, 1.0, v16
	v_add_f32_e32 v17, 1.0, v17
	v_rcp_f32_e32 v16, v16
	v_rcp_f32_e32 v17, v17
	s_nop 0
	v_pk_mul_f32 v[14:15], v[14:15], v[16:17]
	s_nop 0
	v_pk_mul_f32 v[8:9], v[8:9], v[14:15]
	v_mul_f32_e32 v14, 0xbfb8aa3b, v10
	v_mul_f32_e32 v15, 0xbfb8aa3b, v11
	v_exp_f32_e32 v14, v14
	v_exp_f32_e32 v15, v15
	v_add_f32_e32 v14, 1.0, v14
	v_add_f32_e32 v15, 1.0, v15
	v_rcp_f32_e32 v14, v14
	v_rcp_f32_e32 v15, v15
	s_nop 0
	v_pk_mul_f32 v[10:11], v[10:11], v[14:15]
	s_nop 0
	v_pk_mul_f32 v[10:11], v[2:3], v[10:11]
	v_pk_mul_f32 v[2:3], v[12:13], v[20:21] op_sel_hi:[1,0]
	s_nop 0
	v_mul_f32_e32 v12, 0xbfb8aa3b, v2
	v_mul_f32_e32 v13, 0xbfb8aa3b, v3
	v_exp_f32_e32 v12, v12
	v_exp_f32_e32 v13, v13
	v_add_f32_e32 v12, 1.0, v12
	v_add_f32_e32 v13, 1.0, v13
	v_rcp_f32_e32 v12, v12
	v_rcp_f32_e32 v13, v13
	s_nop 0
	v_pk_mul_f32 v[2:3], v[2:3], v[12:13]
	s_nop 0
	v_pk_mul_f32 v[12:13], v[4:5], v[2:3]
	v_cvt_pk_bf16_f32 v2, v6, v7
	v_cvt_pk_bf16_f32 v3, v8, v9
	v_cvt_pk_bf16_f32 v4, v10, v11
	v_cvt_pk_bf16_f32 v5, v12, v13
	v_mad_i64_i32 v[6:7], s[6:7], v18, s4, v[142:143]
	global_store_dwordx4 v[6:7], v[2:5], off
	s_cbranch_vccnz .LBB0_161
	s_andn2_b64 vcc, exec, s[12:13]
	s_cbranch_vccnz .LBB0_160
	s_barrier
	s_branch .LBB0_160

; __device__ __forceinline__ float bflo(unsigned u) { return __uint_as_float(u << 16); }
;     __device__ __forceinline__ void operator()(const f32x4 (&acc)[2][2][4][2], const Unit& u, int wr, int wc, int fr, int fq) const {
;         const int row0 = u.pm * BM + wr * 64 + fr, col0 = u.pn * BM + wc * 32 + 8 * fq;
; #pragma unroll
;         for (int ai = 0; ai < 2; ++ai)
; #pragma unroll
;             for (int m = 0; m < 4; ++m) {
;                 const int row = row0 + ai * HALF + m * 16;
;                 float rs = 0.f; if (GATED) rs = rsqrtf(row_ssq(ssq_in, 16, 4, row, fq) * (1.f / 1024.f) + EPS);
;                 float sq = 0.f;
; #pragma unroll
;                 for (int bj = 0; bj < 2; ++bj) {
;                     const size_t off = (size_t)row * DM + col0 + bj * HALF;
;                     const u32x4 hh = *(const u32x4*)(HI + off), ll = *(const u32x4*)(LO + off);
;                     float hv[8] = {bflo(hh.x) + bflo(ll.x), bfhi(hh.x) + bfhi(ll.x), bflo(hh.y) + bflo(ll.y), bfhi(hh.y) + bfhi(ll.y),
;                                    bflo(hh.z) + bflo(ll.z), bfhi(hh.z) + bfhi(ll.z), bflo(hh.w) + bflo(ll.w), bfhi(hh.w) + bfhi(ll.w)};
;                     float av[8] = {acc[ai][bj][m][0][0], acc[ai][bj][m][0][1], acc[ai][bj][m][0][2], acc[ai][bj][m][0][3], acc[ai][bj][m][1][0], acc[ai][bj][m][1][1], acc[ai][bj][m][1][2], acc[ai][bj][m][1][3]};
;                     if (GATED) { const u32x4 pp = *(const u32x4*)(PP + off);
;                         const float pv[8] = {bflo(pp.x), bfhi(pp.x), bflo(pp.y), bfhi(pp.y), bflo(pp.z), bfhi(pp.z), bflo(pp.w), bfhi(pp.w)};
; #pragma unroll
;                         for (int e = 0; e < 8; ++e) av[e] = fast_sigmoid(av[e] * rs) * pv[e]; }
;                     else {
; #pragma unroll
;                         for (int e = 0; e < 8; ++e) av[e] *= alpha; }
;                     float lo[8];
; #pragma unroll
;                     for (int e = 0; e < 8; ++e) { hv[e] += av[e]; sq += hv[e] * hv[e]; }
;                     u32x4 wh; wh.x = pk2(hv[0], hv[1]); wh.y = pk2(hv[2], hv[3]); wh.z = pk2(hv[4], hv[5]); wh.w = pk2(hv[6], hv[7]);
;                     lo[0] = hv[0] - bflo(wh.x); lo[1] = hv[1] - bfhi(wh.x); lo[2] = hv[2] - bflo(wh.y); lo[3] = hv[3] - bfhi(wh.y);
;                     lo[4] = hv[4] - bflo(wh.z); lo[5] = hv[5] - bfhi(wh.z); lo[6] = hv[6] - bflo(wh.w); lo[7] = hv[7] - bfhi(wh.w);
.LBB0_244:
	v_and_b32_e32 v158, 64, v241
	v_xor_b32_e32 v214, 16, v241
	v_add_u32_e32 v158, 64, v158
	v_cmp_lt_i32_e32 vcc, v214, v158
	v_lshl_add_u32 v156, s31, 8, v160
	v_lshl_or_b32 v157, s4, 8, v162
	v_cndmask_b32_e32 v214, v241, v214, vcc
	v_lshlrev_b32_e32 v214, 2, v214
	v_xor_b32_e32 v215, 32, v241
	v_cmp_lt_i32_e32 vcc, v215, v158
	v_readlane_b32 s6, v250, 49
	v_readlane_b32 s7, v250, 50
	v_readlane_b32 s10, v253, 35
	v_readlane_b32 s11, v253, 36
	s_nop 1
	v_cndmask_b32_e32 v215, v241, v215, vcc
	v_lshlrev_b32_e32 v215, 2, v215
	v_lshl_add_u32 v213, v156, 10, v157
	v_lshlrev_b32_e32 v213, 1, v213
	s_lshl_b32 s40, s4, 4
	s_lshl_b32 s52, s25, 2
	s_add_i32 s40, s40, s52
	v_lshlrev_b32_e32 v216, 6, v156
	v_add_u32_e32 v216, s40, v216
	v_add_u32_e32 v217, 0x2000, v216
	s_nop 1
	v_mov_b32_e32 v210, v213
	global_load_dwordx4 v[140:143], v210, s[38:39]
	global_load_dwordx4 v[144:147], v210, s[6:7]
	global_load_dwordx4 v[148:151], v210, s[38:39] offset:256
	global_load_dwordx4 v[152:155], v210, s[6:7] offset:256
	v_add_u32_e32 v211, 0x8000, v213
	global_load_dwordx4 v[164:167], v211, s[38:39]
	global_load_dwordx4 v[168:171], v211, s[6:7]
	global_load_dwordx4 v[172:175], v211, s[38:39] offset:256
	global_load_dwordx4 v[176:179], v211, s[6:7] offset:256
	v_add_u32_e32 v212, 0x10000, v213
	global_load_dwordx4 v[180:183], v212, s[38:39]
	global_load_dwordx4 v[184:187], v212, s[6:7]
	global_load_dwordx4 v[188:191], v212, s[38:39] offset:256
	global_load_dwordx4 v[192:195], v212, s[6:7] offset:256
	s_waitcnt vmcnt(10)
	v_lshlrev_b32_e32 v156, 16, v140
	v_and_b32_e32 v157, 0xffff0000, v140
	v_lshlrev_b32_e32 v158, 16, v144
	v_and_b32_e32 v159, 0xffff0000, v144
	v_pk_add_f32 v[156:157], v[156:157], v[158:159]
	v_pk_fma_f32 v[156:157], v[126:127], 0.5, v[156:157] op_sel_hi:[1,0,1]
	v_cvt_pk_bf16_f32 v140, v156, v157
	v_pk_mul_f32 v[198:199], v[156:157], v[156:157]
	v_lshlrev_b32_e32 v158, 16, v140
	v_and_b32_e32 v159, 0xffff0000, v140
	v_pk_add_f32 v[196:197], v[156:157], v[158:159] neg_lo:[0,1] neg_hi:[0,1]
	v_cvt_pk_bf16_f32 v144, v196, v197
	v_lshlrev_b32_e32 v156, 16, v141
	v_and_b32_e32 v157, 0xffff0000, v141
	v_lshlrev_b32_e32 v158, 16, v145
	v_and_b32_e32 v159, 0xffff0000, v145
	v_pk_add_f32 v[156:157], v[156:157], v[158:159]
	v_pk_fma_f32 v[156:157], v[128:129], 0.5, v[156:157] op_sel_hi:[1,0,1]
	v_cvt_pk_bf16_f32 v141, v156, v157
	v_pk_fma_f32 v[198:199], v[156:157], v[156:157], v[198:199]
	v_lshlrev_b32_e32 v158, 16, v141
	v_and_b32_e32 v159, 0xffff0000, v141
	v_pk_add_f32 v[196:197], v[156:157], v[158:159] neg_lo:[0,1] neg_hi:[0,1]
	v_cvt_pk_bf16_f32 v145, v196, v197
	v_lshlrev_b32_e32 v156, 16, v142
	v_and_b32_e32 v157, 0xffff0000, v142
	v_lshlrev_b32_e32 v158, 16, v146
	v_and_b32_e32 v159, 0xffff0000, v146
	v_pk_add_f32 v[156:157], v[156:157], v[158:159]
	v_pk_fma_f32 v[156:157], v[122:123], 0.5, v[156:157] op_sel_hi:[1,0,1]
	v_cvt_pk_bf16_f32 v142, v156, v157
	v_pk_fma_f32 v[198:199], v[156:157], v[156:157], v[198:199]
	v_lshlrev_b32_e32 v158, 16, v142
	v_and_b32_e32 v159, 0xffff0000, v142
	v_pk_add_f32 v[196:197], v[156:157], v[158:159] neg_lo:[0,1] neg_hi:[0,1]
	v_cvt_pk_bf16_f32 v146, v196, v197
	v_lshlrev_b32_e32 v156, 16, v143
	v_and_b32_e32 v157, 0xffff0000, v143
	v_lshlrev_b32_e32 v158, 16, v147
	v_and_b32_e32 v159, 0xffff0000, v147
	v_pk_add_f32 v[156:157], v[156:157], v[158:159]
	v_pk_fma_f32 v[156:157], v[124:125], 0.5, v[156:157] op_sel_hi:[1,0,1]
	v_cvt_pk_bf16_f32 v143, v156, v157
	v_pk_fma_f32 v[198:199], v[156:157], v[156:157], v[198:199]
	v_lshlrev_b32_e32 v158, 16, v143
	v_and_b32_e32 v159, 0xffff0000, v143
	v_pk_add_f32 v[196:197], v[156:157], v[158:159] neg_lo:[0,1] neg_hi:[0,1]
	v_cvt_pk_bf16_f32 v147, v196, v197
	global_store_dwordx4 v210, v[140:143], s[10:11]
	global_store_dwordx4 v210, v[144:147], s[6:7]
	s_waitcnt vmcnt(10)
	v_lshlrev_b32_e32 v156, 16, v148
	v_and_b32_e32 v157, 0xffff0000, v148
	v_lshlrev_b32_e32 v158, 16, v152
	v_and_b32_e32 v159, 0xffff0000, v152
	v_pk_add_f32 v[156:157], v[156:157], v[158:159]
	v_pk_fma_f32 v[156:157], v[118:119], 0.5, v[156:157] op_sel_hi:[1,0,1]
	v_cvt_pk_bf16_f32 v148, v156, v157
	v_pk_fma_f32 v[198:199], v[156:157], v[156:157], v[198:199]
	v_lshlrev_b32_e32 v158, 16, v148
	v_and_b32_e32 v159, 0xffff0000, v148
	v_pk_add_f32 v[196:197], v[156:157], v[158:159] neg_lo:[0,1] neg_hi:[0,1]
	v_cvt_pk_bf16_f32 v152, v196, v197
	v_lshlrev_b32_e32 v156, 16, v149
	v_and_b32_e32 v157, 0xffff0000, v149
	v_lshlrev_b32_e32 v158, 16, v153
	v_and_b32_e32 v159, 0xffff0000, v153
	v_pk_add_f32 v[156:157], v[156:157], v[158:159]
	v_pk_fma_f32 v[156:157], v[120:121], 0.5, v[156:157] op_sel_hi:[1,0,1]
	v_cvt_pk_bf16_f32 v149, v156, v157
	v_pk_fma_f32 v[198:199], v[156:157], v[156:157], v[198:199]
	v_lshlrev_b32_e32 v158, 16, v149
	v_and_b32_e32 v159, 0xffff0000, v149
	v_pk_add_f32 v[196:197], v[156:157], v[158:159] neg_lo:[0,1] neg_hi:[0,1]
	v_cvt_pk_bf16_f32 v153, v196, v197
	v_lshlrev_b32_e32 v156, 16, v150
	v_and_b32_e32 v157, 0xffff0000, v150
	v_lshlrev_b32_e32 v158, 16, v154
	v_and_b32_e32 v159, 0xffff0000, v154
	v_pk_add_f32 v[156:157], v[156:157], v[158:159]
	v_pk_fma_f32 v[156:157], v[114:115], 0.5, v[156:157] op_sel_hi:[1,0,1]
	v_cvt_pk_bf16_f32 v150, v156, v157
	v_pk_fma_f32 v[198:199], v[156:157], v[156:157], v[198:199]
	v_lshlrev_b32_e32 v158, 16, v150
	v_and_b32_e32 v159, 0xffff0000, v150
	v_pk_add_f32 v[196:197], v[156:157], v[158:159] neg_lo:[0,1] neg_hi:[0,1]
	v_cvt_pk_bf16_f32 v154, v196, v197
	v_lshlrev_b32_e32 v156, 16, v151
	v_and_b32_e32 v157, 0xffff0000, v151
	v_lshlrev_b32_e32 v158, 16, v155
	v_and_b32_e32 v159, 0xffff0000, v155
	v_pk_add_f32 v[156:157], v[156:157], v[158:159]
	v_pk_fma_f32 v[156:157], v[116:117], 0.5, v[156:157] op_sel_hi:[1,0,1]
	v_cvt_pk_bf16_f32 v151, v156, v157
	v_pk_fma_f32 v[198:199], v[156:157], v[156:157], v[198:199]
	v_lshlrev_b32_e32 v158, 16, v151
	v_and_b32_e32 v159, 0xffff0000, v151
	v_pk_add_f32 v[196:197], v[156:157], v[158:159] neg_lo:[0,1] neg_hi:[0,1]
	v_cvt_pk_bf16_f32 v155, v196, v197
	global_store_dwordx4 v210, v[148:151], s[10:11] offset:256
	global_store_dwordx4 v210, v[152:155], s[6:7] offset:256
	v_add_f32_e32 v200, v198, v199
	s_nop 0
	v_add_u32_e32 v210, 0x18000, v213
	global_load_dwordx4 v[140:143], v210, s[38:39]
	global_load_dwordx4 v[144:147], v210, s[6:7]
	global_load_dwordx4 v[148:151], v210, s[38:39] offset:256
	global_load_dwordx4 v[152:155], v210, s[6:7] offset:256
	s_waitcnt vmcnt(14)
; __device__ __forceinline__ unsigned pk2(float lo, float hi) { f32x2_t v = {lo, hi}; bf16x2_t b = __builtin_convertvector(v, bf16x2_t); return __builtin_bit_cast(unsigned, b); }
; __device__ __forceinline__ float bflo(unsigned u) { return __uint_as_float(u << 16); }
;     __device__ __forceinline__ void operator()(const f32x4 (&acc)[2][2][4][2], const Unit& u, int wr, int wc, int fr, int fq) const {
;     ...
;                 for (int bj = 0; bj < 2; ++bj) {
;                     const size_t off = (size_t)row * DM + col0 + bj * HALF;
;                     const u32x4 hh = *(const u32x4*)(HI + off), ll = *(const u32x4*)(LO + off);
;                     float hv[8] = {bflo(hh.x) + bflo(ll.x), bfhi(hh.x) + bfhi(ll.x), bflo(hh.y) + bflo(ll.y), bfhi(hh.y) + bfhi(ll.y),
;                                    bflo(hh.z) + bflo(ll.z), bfhi(hh.z) + bfhi(ll.z), bflo(hh.w) + bflo(ll.w), bfhi(hh.w) + bfhi(ll.w)};
;                     float av[8] = {acc[ai][bj][m][0][0], acc[ai][bj][m][0][1], acc[ai][bj][m][0][2], acc[ai][bj][m][0][3], acc[ai][bj][m][1][0], acc[ai][bj][m][1][1], acc[ai][bj][m][1][2], acc[ai][bj][m][1][3]};
;                     if (GATED) { const u32x4 pp = *(const u32x4*)(PP + off);
;                         const float pv[8] = {bflo(pp.x), bfhi(pp.x), bflo(pp.y), bfhi(pp.y), bflo(pp.z), bfhi(pp.z), bflo(pp.w), bfhi(pp.w)};
; #pragma unroll
;                         for (int e = 0; e < 8; ++e) av[e] = fast_sigmoid(av[e] * rs) * pv[e]; }
;                     else {
; #pragma unroll
;                         for (int e = 0; e < 8; ++e) av[e] *= alpha; }
;                     float lo[8];
; #pragma unroll
;                     for (int e = 0; e < 8; ++e) { hv[e] += av[e]; sq += hv[e] * hv[e]; }
;                     u32x4 wh; wh.x = pk2(hv[0], hv[1]); wh.y = pk2(hv[2], hv[3]); wh.z = pk2(hv[4], hv[5]); wh.w = pk2(hv[6], hv[7]);
;                     lo[0] = hv[0] - bflo(wh.x); lo[1] = hv[1] - bfhi(wh.x); lo[2] = hv[2] - bflo(wh.y); lo[3] = hv[3] - bfhi(wh.y);
;                     lo[4] = hv[4] - bflo(wh.z); lo[5] = hv[5] - bfhi(wh.z); lo[6] = hv[6] - bflo(wh.w); lo[7] = hv[7] - bfhi(wh.w);
;                     u32x4 wl; wl.x = pk2(lo[0], lo[1]); wl.y = pk2(lo[2], lo[3]); wl.z = pk2(lo[4], lo[5]); wl.w = pk2(lo[6], lo[7]);
;                     *(u32x4*)(HO + off) = wh; *(u32x4*)(LO + off) = wl;
	v_lshlrev_b32_e32 v156, 16, v164
	v_and_b32_e32 v157, 0xffff0000, v164
	v_lshlrev_b32_e32 v158, 16, v168
	v_and_b32_e32 v159, 0xffff0000, v168
	v_pk_add_f32 v[156:157], v[156:157], v[158:159]
	v_pk_fma_f32 v[156:157], v[110:111], 0.5, v[156:157] op_sel_hi:[1,0,1]
	v_cvt_pk_bf16_f32 v164, v156, v157
	v_pk_mul_f32 v[198:199], v[156:157], v[156:157]
	v_lshlrev_b32_e32 v158, 16, v164
	v_and_b32_e32 v159, 0xffff0000, v164
	v_pk_add_f32 v[196:197], v[156:157], v[158:159] neg_lo:[0,1] neg_hi:[0,1]
	v_cvt_pk_bf16_f32 v168, v196, v197
	v_lshlrev_b32_e32 v156, 16, v165
	v_and_b32_e32 v157, 0xffff0000, v165
	v_lshlrev_b32_e32 v158, 16, v169
	v_and_b32_e32 v159, 0xffff0000, v169
	v_pk_add_f32 v[156:157], v[156:157], v[158:159]
	v_pk_fma_f32 v[156:157], v[112:113], 0.5, v[156:157] op_sel_hi:[1,0,1]
	v_cvt_pk_bf16_f32 v165, v156, v157
	v_pk_fma_f32 v[198:199], v[156:157], v[156:157], v[198:199]
	v_lshlrev_b32_e32 v158, 16, v165
	v_and_b32_e32 v159, 0xffff0000, v165
	v_pk_add_f32 v[196:197], v[156:157], v[158:159] neg_lo:[0,1] neg_hi:[0,1]
	v_cvt_pk_bf16_f32 v169, v196, v197
	v_lshlrev_b32_e32 v156, 16, v166
	v_and_b32_e32 v157, 0xffff0000, v166
	v_lshlrev_b32_e32 v158, 16, v170
	v_and_b32_e32 v159, 0xffff0000, v170
	v_pk_add_f32 v[156:157], v[156:157], v[158:159]
	v_pk_fma_f32 v[156:157], v[106:107], 0.5, v[156:157] op_sel_hi:[1,0,1]
	v_cvt_pk_bf16_f32 v166, v156, v157
	v_pk_fma_f32 v[198:199], v[156:157], v[156:157], v[198:199]
	v_lshlrev_b32_e32 v158, 16, v166
	v_and_b32_e32 v159, 0xffff0000, v166
	v_pk_add_f32 v[196:197], v[156:157], v[158:159] neg_lo:[0,1] neg_hi:[0,1]
	v_cvt_pk_bf16_f32 v170, v196, v197
	v_lshlrev_b32_e32 v156, 16, v167
	v_and_b32_e32 v157, 0xffff0000, v167
	v_lshlrev_b32_e32 v158, 16, v171
	v_and_b32_e32 v159, 0xffff0000, v171
	v_pk_add_f32 v[156:157], v[156:157], v[158:159]
	v_pk_fma_f32 v[156:157], v[108:109], 0.5, v[156:157] op_sel_hi:[1,0,1]
	v_cvt_pk_bf16_f32 v167, v156, v157
	v_pk_fma_f32 v[198:199], v[156:157], v[156:157], v[198:199]
	v_lshlrev_b32_e32 v158, 16, v167
	v_and_b32_e32 v159, 0xffff0000, v167
	v_pk_add_f32 v[196:197], v[156:157], v[158:159] neg_lo:[0,1] neg_hi:[0,1]
	v_cvt_pk_bf16_f32 v171, v196, v197
	global_store_dwordx4 v211, v[164:167], s[10:11]
	global_store_dwordx4 v211, v[168:171], s[6:7]
	s_waitcnt vmcnt(14)
	v_lshlrev_b32_e32 v156, 16, v172
	v_and_b32_e32 v157, 0xffff0000, v172
	v_lshlrev_b32_e32 v158, 16, v176
	v_and_b32_e32 v159, 0xffff0000, v176
	v_pk_add_f32 v[156:157], v[156:157], v[158:159]
	v_pk_fma_f32 v[156:157], v[102:103], 0.5, v[156:157] op_sel_hi:[1,0,1]
	v_cvt_pk_bf16_f32 v172, v156, v157
	v_pk_fma_f32 v[198:199], v[156:157], v[156:157], v[198:199]
	v_lshlrev_b32_e32 v158, 16, v172
	v_and_b32_e32 v159, 0xffff0000, v172
	v_pk_add_f32 v[196:197], v[156:157], v[158:159] neg_lo:[0,1] neg_hi:[0,1]
	v_cvt_pk_bf16_f32 v176, v196, v197
	v_lshlrev_b32_e32 v156, 16, v173
	v_and_b32_e32 v157, 0xffff0000, v173
	v_lshlrev_b32_e32 v158, 16, v177
	v_and_b32_e32 v159, 0xffff0000, v177
	v_pk_add_f32 v[156:157], v[156:157], v[158:159]
	v_pk_fma_f32 v[156:157], v[104:105], 0.5, v[156:157] op_sel_hi:[1,0,1]
	v_cvt_pk_bf16_f32 v173, v156, v157
	v_pk_fma_f32 v[198:199], v[156:157], v[156:157], v[198:199]
	v_lshlrev_b32_e32 v158, 16, v173
	v_and_b32_e32 v159, 0xffff0000, v173
	v_pk_add_f32 v[196:197], v[156:157], v[158:159] neg_lo:[0,1] neg_hi:[0,1]
	v_cvt_pk_bf16_f32 v177, v196, v197
	v_lshlrev_b32_e32 v156, 16, v174
	v_and_b32_e32 v157, 0xffff0000, v174
	v_lshlrev_b32_e32 v158, 16, v178
	v_and_b32_e32 v159, 0xffff0000, v178
	v_pk_add_f32 v[156:157], v[156:157], v[158:159]
	v_pk_fma_f32 v[156:157], v[98:99], 0.5, v[156:157] op_sel_hi:[1,0,1]
	v_cvt_pk_bf16_f32 v174, v156, v157
	v_pk_fma_f32 v[198:199], v[156:157], v[156:157], v[198:199]
	v_lshlrev_b32_e32 v158, 16, v174
	v_and_b32_e32 v159, 0xffff0000, v174
	v_pk_add_f32 v[196:197], v[156:157], v[158:159] neg_lo:[0,1] neg_hi:[0,1]
	v_cvt_pk_bf16_f32 v178, v196, v197
	v_lshlrev_b32_e32 v156, 16, v175
	v_and_b32_e32 v157, 0xffff0000, v175
	v_lshlrev_b32_e32 v158, 16, v179
	v_and_b32_e32 v159, 0xffff0000, v179
	v_pk_add_f32 v[156:157], v[156:157], v[158:159]
	v_pk_fma_f32 v[156:157], v[100:101], 0.5, v[156:157] op_sel_hi:[1,0,1]
	v_cvt_pk_bf16_f32 v175, v156, v157
	v_pk_fma_f32 v[198:199], v[156:157], v[156:157], v[198:199]
	v_lshlrev_b32_e32 v158, 16, v175
	v_and_b32_e32 v159, 0xffff0000, v175
	v_pk_add_f32 v[196:197], v[156:157], v[158:159] neg_lo:[0,1] neg_hi:[0,1]
	v_cvt_pk_bf16_f32 v179, v196, v197
	global_store_dwordx4 v211, v[172:175], s[10:11] offset:256
	global_store_dwordx4 v211, v[176:179], s[6:7] offset:256
	v_add_f32_e32 v201, v198, v199
	s_nop 0
	v_add_u32_e32 v211, 0x40000, v213
	global_load_dwordx4 v[164:167], v211, s[38:39]
	global_load_dwordx4 v[168:171], v211, s[6:7]
	global_load_dwordx4 v[172:175], v211, s[38:39] offset:256
	global_load_dwordx4 v[176:179], v211, s[6:7] offset:256
	s_waitcnt vmcnt(18)
; __device__ __forceinline__ unsigned pk2(float lo, float hi) { f32x2_t v = {lo, hi}; bf16x2_t b = __builtin_convertvector(v, bf16x2_t); return __builtin_bit_cast(unsigned, b); }
; __device__ __forceinline__ float bflo(unsigned u) { return __uint_as_float(u << 16); }
;     __device__ __forceinline__ void operator()(const f32x4 (&acc)[2][2][4][2], const Unit& u, int wr, int wc, int fr, int fq) const {
;     ...
;                 for (int bj = 0; bj < 2; ++bj) {
;                     const size_t off = (size_t)row * DM + col0 + bj * HALF;
;                     const u32x4 hh = *(const u32x4*)(HI + off), ll = *(const u32x4*)(LO + off);
;                     float hv[8] = {bflo(hh.x) + bflo(ll.x), bfhi(hh.x) + bfhi(ll.x), bflo(hh.y) + bflo(ll.y), bfhi(hh.y) + bfhi(ll.y),
;                                    bflo(hh.z) + bflo(ll.z), bfhi(hh.z) + bfhi(ll.z), bflo(hh.w) + bflo(ll.w), bfhi(hh.w) + bfhi(ll.w)};
;                     float av[8] = {acc[ai][bj][m][0][0], acc[ai][bj][m][0][1], acc[ai][bj][m][0][2], acc[ai][bj][m][0][3], acc[ai][bj][m][1][0], acc[ai][bj][m][1][1], acc[ai][bj][m][1][2], acc[ai][bj][m][1][3]};
;                     if (GATED) { const u32x4 pp = *(const u32x4*)(PP + off);
;                         const float pv[8] = {bflo(pp.x), bfhi(pp.x), bflo(pp.y), bfhi(pp.y), bflo(pp.z), bfhi(pp.z), bflo(pp.w), bfhi(pp.w)};
; #pragma unroll
;                         for (int e = 0; e < 8; ++e) av[e] = fast_sigmoid(av[e] * rs) * pv[e]; }
;                     else {
; #pragma unroll
;                         for (int e = 0; e < 8; ++e) av[e] *= alpha; }
;                     float lo[8];
; #pragma unroll
;                     for (int e = 0; e < 8; ++e) { hv[e] += av[e]; sq += hv[e] * hv[e]; }
;                     u32x4 wh; wh.x = pk2(hv[0], hv[1]); wh.y = pk2(hv[2], hv[3]); wh.z = pk2(hv[4], hv[5]); wh.w = pk2(hv[6], hv[7]);
;                     lo[0] = hv[0] - bflo(wh.x); lo[1] = hv[1] - bfhi(wh.x); lo[2] = hv[2] - bflo(wh.y); lo[3] = hv[3] - bfhi(wh.y);
;                     lo[4] = hv[4] - bflo(wh.z); lo[5] = hv[5] - bfhi(wh.z); lo[6] = hv[6] - bflo(wh.w); lo[7] = hv[7] - bfhi(wh.w);
;                     u32x4 wl; wl.x = pk2(lo[0], lo[1]); wl.y = pk2(lo[2], lo[3]); wl.z = pk2(lo[4], lo[5]); wl.w = pk2(lo[6], lo[7]);
;                     *(u32x4*)(HO + off) = wh; *(u32x4*)(LO + off) = wl;
	v_lshlrev_b32_e32 v156, 16, v180
	v_and_b32_e32 v157, 0xffff0000, v180
	v_lshlrev_b32_e32 v158, 16, v184
	v_and_b32_e32 v159, 0xffff0000, v184
	v_pk_add_f32 v[156:157], v[156:157], v[158:159]
	v_pk_fma_f32 v[156:157], v[94:95], 0.5, v[156:157] op_sel_hi:[1,0,1]
	v_cvt_pk_bf16_f32 v180, v156, v157
	v_pk_mul_f32 v[198:199], v[156:157], v[156:157]
	v_lshlrev_b32_e32 v158, 16, v180
	v_and_b32_e32 v159, 0xffff0000, v180
	v_pk_add_f32 v[196:197], v[156:157], v[158:159] neg_lo:[0,1] neg_hi:[0,1]
	v_cvt_pk_bf16_f32 v184, v196, v197
	v_lshlrev_b32_e32 v156, 16, v181
	v_and_b32_e32 v157, 0xffff0000, v181
	v_lshlrev_b32_e32 v158, 16, v185
	v_and_b32_e32 v159, 0xffff0000, v185
	v_pk_add_f32 v[156:157], v[156:157], v[158:159]
	v_pk_fma_f32 v[156:157], v[96:97], 0.5, v[156:157] op_sel_hi:[1,0,1]
	v_cvt_pk_bf16_f32 v181, v156, v157
	v_pk_fma_f32 v[198:199], v[156:157], v[156:157], v[198:199]
	v_lshlrev_b32_e32 v158, 16, v181
	v_and_b32_e32 v159, 0xffff0000, v181
	v_pk_add_f32 v[196:197], v[156:157], v[158:159] neg_lo:[0,1] neg_hi:[0,1]
	v_cvt_pk_bf16_f32 v185, v196, v197
	v_lshlrev_b32_e32 v156, 16, v182
	v_and_b32_e32 v157, 0xffff0000, v182
	v_lshlrev_b32_e32 v158, 16, v186
	v_and_b32_e32 v159, 0xffff0000, v186
	v_pk_add_f32 v[156:157], v[156:157], v[158:159]
	v_pk_fma_f32 v[156:157], v[90:91], 0.5, v[156:157] op_sel_hi:[1,0,1]
	v_cvt_pk_bf16_f32 v182, v156, v157
	v_pk_fma_f32 v[198:199], v[156:157], v[156:157], v[198:199]
	v_lshlrev_b32_e32 v158, 16, v182
	v_and_b32_e32 v159, 0xffff0000, v182
	v_pk_add_f32 v[196:197], v[156:157], v[158:159] neg_lo:[0,1] neg_hi:[0,1]
	v_cvt_pk_bf16_f32 v186, v196, v197
	v_lshlrev_b32_e32 v156, 16, v183
	v_and_b32_e32 v157, 0xffff0000, v183
	v_lshlrev_b32_e32 v158, 16, v187
	v_and_b32_e32 v159, 0xffff0000, v187
	v_pk_add_f32 v[156:157], v[156:157], v[158:159]
	v_pk_fma_f32 v[156:157], v[92:93], 0.5, v[156:157] op_sel_hi:[1,0,1]
	v_cvt_pk_bf16_f32 v183, v156, v157
	v_pk_fma_f32 v[198:199], v[156:157], v[156:157], v[198:199]
	v_lshlrev_b32_e32 v158, 16, v183
	v_and_b32_e32 v159, 0xffff0000, v183
	v_pk_add_f32 v[196:197], v[156:157], v[158:159] neg_lo:[0,1] neg_hi:[0,1]
	v_cvt_pk_bf16_f32 v187, v196, v197
	global_store_dwordx4 v212, v[180:183], s[10:11]
	global_store_dwordx4 v212, v[184:187], s[6:7]
	s_waitcnt vmcnt(18)
	v_lshlrev_b32_e32 v156, 16, v188
	v_and_b32_e32 v157, 0xffff0000, v188
	v_lshlrev_b32_e32 v158, 16, v192
	v_and_b32_e32 v159, 0xffff0000, v192
	v_pk_add_f32 v[156:157], v[156:157], v[158:159]
	v_pk_fma_f32 v[156:157], v[86:87], 0.5, v[156:157] op_sel_hi:[1,0,1]
	v_cvt_pk_bf16_f32 v188, v156, v157
	v_pk_fma_f32 v[198:199], v[156:157], v[156:157], v[198:199]
	v_lshlrev_b32_e32 v158, 16, v188
	v_and_b32_e32 v159, 0xffff0000, v188
	v_pk_add_f32 v[196:197], v[156:157], v[158:159] neg_lo:[0,1] neg_hi:[0,1]
	v_cvt_pk_bf16_f32 v192, v196, v197
	v_lshlrev_b32_e32 v156, 16, v189
	v_and_b32_e32 v157, 0xffff0000, v189
	v_lshlrev_b32_e32 v158, 16, v193
	v_and_b32_e32 v159, 0xffff0000, v193
	v_pk_add_f32 v[156:157], v[156:157], v[158:159]
	v_pk_fma_f32 v[156:157], v[88:89], 0.5, v[156:157] op_sel_hi:[1,0,1]
	v_cvt_pk_bf16_f32 v189, v156, v157
	v_pk_fma_f32 v[198:199], v[156:157], v[156:157], v[198:199]
	v_lshlrev_b32_e32 v158, 16, v189
	v_and_b32_e32 v159, 0xffff0000, v189
	v_pk_add_f32 v[196:197], v[156:157], v[158:159] neg_lo:[0,1] neg_hi:[0,1]
	v_cvt_pk_bf16_f32 v193, v196, v197
	v_lshlrev_b32_e32 v156, 16, v190
	v_and_b32_e32 v157, 0xffff0000, v190
	v_lshlrev_b32_e32 v158, 16, v194
	v_and_b32_e32 v159, 0xffff0000, v194
	v_pk_add_f32 v[156:157], v[156:157], v[158:159]
	v_pk_fma_f32 v[156:157], v[82:83], 0.5, v[156:157] op_sel_hi:[1,0,1]
	v_cvt_pk_bf16_f32 v190, v156, v157
	v_pk_fma_f32 v[198:199], v[156:157], v[156:157], v[198:199]
	v_lshlrev_b32_e32 v158, 16, v190
	v_and_b32_e32 v159, 0xffff0000, v190
	v_pk_add_f32 v[196:197], v[156:157], v[158:159] neg_lo:[0,1] neg_hi:[0,1]
	v_cvt_pk_bf16_f32 v194, v196, v197
	v_lshlrev_b32_e32 v156, 16, v191
	v_and_b32_e32 v157, 0xffff0000, v191
	v_lshlrev_b32_e32 v158, 16, v195
	v_and_b32_e32 v159, 0xffff0000, v195
	v_pk_add_f32 v[156:157], v[156:157], v[158:159]
	v_pk_fma_f32 v[156:157], v[84:85], 0.5, v[156:157] op_sel_hi:[1,0,1]
	v_cvt_pk_bf16_f32 v191, v156, v157
	v_pk_fma_f32 v[198:199], v[156:157], v[156:157], v[198:199]
	v_lshlrev_b32_e32 v158, 16, v191
	v_and_b32_e32 v159, 0xffff0000, v191
	v_pk_add_f32 v[196:197], v[156:157], v[158:159] neg_lo:[0,1] neg_hi:[0,1]
	v_cvt_pk_bf16_f32 v195, v196, v197
	global_store_dwordx4 v212, v[188:191], s[10:11] offset:256
	global_store_dwordx4 v212, v[192:195], s[6:7] offset:256
	v_add_f32_e32 v202, v198, v199
	s_nop 0
	v_add_u32_e32 v212, 0x48000, v213
	global_load_dwordx4 v[180:183], v212, s[38:39]
	global_load_dwordx4 v[184:187], v212, s[6:7]
	global_load_dwordx4 v[188:191], v212, s[38:39] offset:256
	global_load_dwordx4 v[192:195], v212, s[6:7] offset:256
	s_waitcnt vmcnt(18)
; __device__ __forceinline__ unsigned pk2(float lo, float hi) { f32x2_t v = {lo, hi}; bf16x2_t b = __builtin_convertvector(v, bf16x2_t); return __builtin_bit_cast(unsigned, b); }
; __device__ __forceinline__ float bflo(unsigned u) { return __uint_as_float(u << 16); }
;     __device__ __forceinline__ void operator()(const f32x4 (&acc)[2][2][4][2], const Unit& u, int wr, int wc, int fr, int fq) const {
;     ...
;                 for (int bj = 0; bj < 2; ++bj) {
;                     const size_t off = (size_t)row * DM + col0 + bj * HALF;
;                     const u32x4 hh = *(const u32x4*)(HI + off), ll = *(const u32x4*)(LO + off);
;                     float hv[8] = {bflo(hh.x) + bflo(ll.x), bfhi(hh.x) + bfhi(ll.x), bflo(hh.y) + bflo(ll.y), bfhi(hh.y) + bfhi(ll.y),
;                                    bflo(hh.z) + bflo(ll.z), bfhi(hh.z) + bfhi(ll.z), bflo(hh.w) + bflo(ll.w), bfhi(hh.w) + bfhi(ll.w)};
;                     float av[8] = {acc[ai][bj][m][0][0], acc[ai][bj][m][0][1], acc[ai][bj][m][0][2], acc[ai][bj][m][0][3], acc[ai][bj][m][1][0], acc[ai][bj][m][1][1], acc[ai][bj][m][1][2], acc[ai][bj][m][1][3]};
;                     if (GATED) { const u32x4 pp = *(const u32x4*)(PP + off);
;                         const float pv[8] = {bflo(pp.x), bfhi(pp.x), bflo(pp.y), bfhi(pp.y), bflo(pp.z), bfhi(pp.z), bflo(pp.w), bfhi(pp.w)};
; #pragma unroll
;                         for (int e = 0; e < 8; ++e) av[e] = fast_sigmoid(av[e] * rs) * pv[e]; }
;                     else {
; #pragma unroll
;                         for (int e = 0; e < 8; ++e) av[e] *= alpha; }
;                     float lo[8];
; #pragma unroll
;                     for (int e = 0; e < 8; ++e) { hv[e] += av[e]; sq += hv[e] * hv[e]; }
;                     u32x4 wh; wh.x = pk2(hv[0], hv[1]); wh.y = pk2(hv[2], hv[3]); wh.z = pk2(hv[4], hv[5]); wh.w = pk2(hv[6], hv[7]);
;                     lo[0] = hv[0] - bflo(wh.x); lo[1] = hv[1] - bfhi(wh.x); lo[2] = hv[2] - bflo(wh.y); lo[3] = hv[3] - bfhi(wh.y);
;                     lo[4] = hv[4] - bflo(wh.z); lo[5] = hv[5] - bfhi(wh.z); lo[6] = hv[6] - bflo(wh.w); lo[7] = hv[7] - bfhi(wh.w);
;                     u32x4 wl; wl.x = pk2(lo[0], lo[1]); wl.y = pk2(lo[2], lo[3]); wl.z = pk2(lo[4], lo[5]); wl.w = pk2(lo[6], lo[7]);
;                     *(u32x4*)(HO + off) = wh; *(u32x4*)(LO + off) = wl;
	v_lshlrev_b32_e32 v156, 16, v140
	v_and_b32_e32 v157, 0xffff0000, v140
	v_lshlrev_b32_e32 v158, 16, v144
	v_and_b32_e32 v159, 0xffff0000, v144
	v_pk_add_f32 v[156:157], v[156:157], v[158:159]
	v_pk_fma_f32 v[156:157], v[78:79], 0.5, v[156:157] op_sel_hi:[1,0,1]
	v_cvt_pk_bf16_f32 v140, v156, v157
	v_pk_mul_f32 v[198:199], v[156:157], v[156:157]
	v_lshlrev_b32_e32 v158, 16, v140
	v_and_b32_e32 v159, 0xffff0000, v140
	v_pk_add_f32 v[196:197], v[156:157], v[158:159] neg_lo:[0,1] neg_hi:[0,1]
	v_cvt_pk_bf16_f32 v144, v196, v197
	v_lshlrev_b32_e32 v156, 16, v141
	v_and_b32_e32 v157, 0xffff0000, v141
	v_lshlrev_b32_e32 v158, 16, v145
	v_and_b32_e32 v159, 0xffff0000, v145
	v_pk_add_f32 v[156:157], v[156:157], v[158:159]
	v_pk_fma_f32 v[156:157], v[80:81], 0.5, v[156:157] op_sel_hi:[1,0,1]
	v_cvt_pk_bf16_f32 v141, v156, v157
	v_pk_fma_f32 v[198:199], v[156:157], v[156:157], v[198:199]
	v_lshlrev_b32_e32 v158, 16, v141
	v_and_b32_e32 v159, 0xffff0000, v141
	v_pk_add_f32 v[196:197], v[156:157], v[158:159] neg_lo:[0,1] neg_hi:[0,1]
	v_cvt_pk_bf16_f32 v145, v196, v197
	v_lshlrev_b32_e32 v156, 16, v142
	v_and_b32_e32 v157, 0xffff0000, v142
	v_lshlrev_b32_e32 v158, 16, v146
	v_and_b32_e32 v159, 0xffff0000, v146
	v_pk_add_f32 v[156:157], v[156:157], v[158:159]
	v_pk_fma_f32 v[156:157], v[74:75], 0.5, v[156:157] op_sel_hi:[1,0,1]
	v_cvt_pk_bf16_f32 v142, v156, v157
	v_pk_fma_f32 v[198:199], v[156:157], v[156:157], v[198:199]
	v_lshlrev_b32_e32 v158, 16, v142
	v_and_b32_e32 v159, 0xffff0000, v142
	v_pk_add_f32 v[196:197], v[156:157], v[158:159] neg_lo:[0,1] neg_hi:[0,1]
	v_cvt_pk_bf16_f32 v146, v196, v197
	v_lshlrev_b32_e32 v156, 16, v143
	v_and_b32_e32 v157, 0xffff0000, v143
	v_lshlrev_b32_e32 v158, 16, v147
	v_and_b32_e32 v159, 0xffff0000, v147
	v_pk_add_f32 v[156:157], v[156:157], v[158:159]
	v_pk_fma_f32 v[156:157], v[76:77], 0.5, v[156:157] op_sel_hi:[1,0,1]
	v_cvt_pk_bf16_f32 v143, v156, v157
	v_pk_fma_f32 v[198:199], v[156:157], v[156:157], v[198:199]
	v_lshlrev_b32_e32 v158, 16, v143
	v_and_b32_e32 v159, 0xffff0000, v143
	v_pk_add_f32 v[196:197], v[156:157], v[158:159] neg_lo:[0,1] neg_hi:[0,1]
	v_cvt_pk_bf16_f32 v147, v196, v197
	global_store_dwordx4 v210, v[140:143], s[10:11]
	global_store_dwordx4 v210, v[144:147], s[6:7]
	s_waitcnt vmcnt(18)
	v_lshlrev_b32_e32 v156, 16, v148
	v_and_b32_e32 v157, 0xffff0000, v148
	v_lshlrev_b32_e32 v158, 16, v152
	v_and_b32_e32 v159, 0xffff0000, v152
	v_pk_add_f32 v[156:157], v[156:157], v[158:159]
	v_pk_fma_f32 v[156:157], v[70:71], 0.5, v[156:157] op_sel_hi:[1,0,1]
	v_cvt_pk_bf16_f32 v148, v156, v157
	v_pk_fma_f32 v[198:199], v[156:157], v[156:157], v[198:199]
	v_lshlrev_b32_e32 v158, 16, v148
	v_and_b32_e32 v159, 0xffff0000, v148
	v_pk_add_f32 v[196:197], v[156:157], v[158:159] neg_lo:[0,1] neg_hi:[0,1]
	v_cvt_pk_bf16_f32 v152, v196, v197
	v_lshlrev_b32_e32 v156, 16, v149
	v_and_b32_e32 v157, 0xffff0000, v149
	v_lshlrev_b32_e32 v158, 16, v153
	v_and_b32_e32 v159, 0xffff0000, v153
	v_pk_add_f32 v[156:157], v[156:157], v[158:159]
	v_pk_fma_f32 v[156:157], v[72:73], 0.5, v[156:157] op_sel_hi:[1,0,1]
	v_cvt_pk_bf16_f32 v149, v156, v157
	v_pk_fma_f32 v[198:199], v[156:157], v[156:157], v[198:199]
	v_lshlrev_b32_e32 v158, 16, v149
	v_and_b32_e32 v159, 0xffff0000, v149
	v_pk_add_f32 v[196:197], v[156:157], v[158:159] neg_lo:[0,1] neg_hi:[0,1]
	v_cvt_pk_bf16_f32 v153, v196, v197
	v_lshlrev_b32_e32 v156, 16, v150
	v_and_b32_e32 v157, 0xffff0000, v150
	v_lshlrev_b32_e32 v158, 16, v154
	v_and_b32_e32 v159, 0xffff0000, v154
	v_pk_add_f32 v[156:157], v[156:157], v[158:159]
	v_pk_fma_f32 v[156:157], v[66:67], 0.5, v[156:157] op_sel_hi:[1,0,1]
	v_cvt_pk_bf16_f32 v150, v156, v157
	v_pk_fma_f32 v[198:199], v[156:157], v[156:157], v[198:199]
	v_lshlrev_b32_e32 v158, 16, v150
	v_and_b32_e32 v159, 0xffff0000, v150
	v_pk_add_f32 v[196:197], v[156:157], v[158:159] neg_lo:[0,1] neg_hi:[0,1]
	v_cvt_pk_bf16_f32 v154, v196, v197
	v_lshlrev_b32_e32 v156, 16, v151
	v_and_b32_e32 v157, 0xffff0000, v151
	v_lshlrev_b32_e32 v158, 16, v155
	v_and_b32_e32 v159, 0xffff0000, v155
	v_pk_add_f32 v[156:157], v[156:157], v[158:159]
	v_pk_fma_f32 v[156:157], v[68:69], 0.5, v[156:157] op_sel_hi:[1,0,1]
	v_cvt_pk_bf16_f32 v151, v156, v157
	v_pk_fma_f32 v[198:199], v[156:157], v[156:157], v[198:199]
	v_lshlrev_b32_e32 v158, 16, v151
	v_and_b32_e32 v159, 0xffff0000, v151
	v_pk_add_f32 v[196:197], v[156:157], v[158:159] neg_lo:[0,1] neg_hi:[0,1]
	v_cvt_pk_bf16_f32 v155, v196, v197
	global_store_dwordx4 v210, v[148:151], s[10:11] offset:256
	global_store_dwordx4 v210, v[152:155], s[6:7] offset:256
	v_add_f32_e32 v203, v198, v199
	s_nop 0
	v_add_u32_e32 v210, 0x50000, v213
	global_load_dwordx4 v[140:143], v210, s[38:39]
	global_load_dwordx4 v[144:147], v210, s[6:7]
	global_load_dwordx4 v[148:151], v210, s[38:39] offset:256
	global_load_dwordx4 v[152:155], v210, s[6:7] offset:256
	s_waitcnt vmcnt(18)
; __device__ __forceinline__ unsigned pk2(float lo, float hi) { f32x2_t v = {lo, hi}; bf16x2_t b = __builtin_convertvector(v, bf16x2_t); return __builtin_bit_cast(unsigned, b); }
; __device__ __forceinline__ float bflo(unsigned u) { return __uint_as_float(u << 16); }
;     __device__ __forceinline__ void operator()(const f32x4 (&acc)[2][2][4][2], const Unit& u, int wr, int wc, int fr, int fq) const {
;     ...
;                 for (int bj = 0; bj < 2; ++bj) {
;                     const size_t off = (size_t)row * DM + col0 + bj * HALF;
;                     const u32x4 hh = *(const u32x4*)(HI + off), ll = *(const u32x4*)(LO + off);
;                     float hv[8] = {bflo(hh.x) + bflo(ll.x), bfhi(hh.x) + bfhi(ll.x), bflo(hh.y) + bflo(ll.y), bfhi(hh.y) + bfhi(ll.y),
;                                    bflo(hh.z) + bflo(ll.z), bfhi(hh.z) + bfhi(ll.z), bflo(hh.w) + bflo(ll.w), bfhi(hh.w) + bfhi(ll.w)};
;                     float av[8] = {acc[ai][bj][m][0][0], acc[ai][bj][m][0][1], acc[ai][bj][m][0][2], acc[ai][bj][m][0][3], acc[ai][bj][m][1][0], acc[ai][bj][m][1][1], acc[ai][bj][m][1][2], acc[ai][bj][m][1][3]};
;                     if (GATED) { const u32x4 pp = *(const u32x4*)(PP + off);
;                         const float pv[8] = {bflo(pp.x), bfhi(pp.x), bflo(pp.y), bfhi(pp.y), bflo(pp.z), bfhi(pp.z), bflo(pp.w), bfhi(pp.w)};
; #pragma unroll
;                         for (int e = 0; e < 8; ++e) av[e] = fast_sigmoid(av[e] * rs) * pv[e]; }
;                     else {
; #pragma unroll
;                         for (int e = 0; e < 8; ++e) av[e] *= alpha; }
;                     float lo[8];
; #pragma unroll
;                     for (int e = 0; e < 8; ++e) { hv[e] += av[e]; sq += hv[e] * hv[e]; }
;                     u32x4 wh; wh.x = pk2(hv[0], hv[1]); wh.y = pk2(hv[2], hv[3]); wh.z = pk2(hv[4], hv[5]); wh.w = pk2(hv[6], hv[7]);
;                     lo[0] = hv[0] - bflo(wh.x); lo[1] = hv[1] - bfhi(wh.x); lo[2] = hv[2] - bflo(wh.y); lo[3] = hv[3] - bfhi(wh.y);
;                     lo[4] = hv[4] - bflo(wh.z); lo[5] = hv[5] - bfhi(wh.z); lo[6] = hv[6] - bflo(wh.w); lo[7] = hv[7] - bfhi(wh.w);
;                     u32x4 wl; wl.x = pk2(lo[0], lo[1]); wl.y = pk2(lo[2], lo[3]); wl.z = pk2(lo[4], lo[5]); wl.w = pk2(lo[6], lo[7]);
;                     *(u32x4*)(HO + off) = wh; *(u32x4*)(LO + off) = wl;
	v_lshlrev_b32_e32 v156, 16, v164
	v_and_b32_e32 v157, 0xffff0000, v164
	v_lshlrev_b32_e32 v158, 16, v168
	v_and_b32_e32 v159, 0xffff0000, v168
	v_pk_add_f32 v[156:157], v[156:157], v[158:159]
	v_pk_fma_f32 v[156:157], v[62:63], 0.5, v[156:157] op_sel_hi:[1,0,1]
	v_cvt_pk_bf16_f32 v164, v156, v157
	v_pk_mul_f32 v[198:199], v[156:157], v[156:157]
	v_lshlrev_b32_e32 v158, 16, v164
	v_and_b32_e32 v159, 0xffff0000, v164
	v_pk_add_f32 v[196:197], v[156:157], v[158:159] neg_lo:[0,1] neg_hi:[0,1]
	v_cvt_pk_bf16_f32 v168, v196, v197
	v_lshlrev_b32_e32 v156, 16, v165
	v_and_b32_e32 v157, 0xffff0000, v165
	v_lshlrev_b32_e32 v158, 16, v169
	v_and_b32_e32 v159, 0xffff0000, v169
	v_pk_add_f32 v[156:157], v[156:157], v[158:159]
	v_pk_fma_f32 v[156:157], v[64:65], 0.5, v[156:157] op_sel_hi:[1,0,1]
	v_cvt_pk_bf16_f32 v165, v156, v157
	v_pk_fma_f32 v[198:199], v[156:157], v[156:157], v[198:199]
	v_lshlrev_b32_e32 v158, 16, v165
	v_and_b32_e32 v159, 0xffff0000, v165
	v_pk_add_f32 v[196:197], v[156:157], v[158:159] neg_lo:[0,1] neg_hi:[0,1]
	v_cvt_pk_bf16_f32 v169, v196, v197
	v_lshlrev_b32_e32 v156, 16, v166
	v_and_b32_e32 v157, 0xffff0000, v166
	v_lshlrev_b32_e32 v158, 16, v170
	v_and_b32_e32 v159, 0xffff0000, v170
	v_pk_add_f32 v[156:157], v[156:157], v[158:159]
	v_pk_fma_f32 v[156:157], v[58:59], 0.5, v[156:157] op_sel_hi:[1,0,1]
	v_cvt_pk_bf16_f32 v166, v156, v157
	v_pk_fma_f32 v[198:199], v[156:157], v[156:157], v[198:199]
	v_lshlrev_b32_e32 v158, 16, v166
	v_and_b32_e32 v159, 0xffff0000, v166
	v_pk_add_f32 v[196:197], v[156:157], v[158:159] neg_lo:[0,1] neg_hi:[0,1]
	v_cvt_pk_bf16_f32 v170, v196, v197
	v_lshlrev_b32_e32 v156, 16, v167
	v_and_b32_e32 v157, 0xffff0000, v167
	v_lshlrev_b32_e32 v158, 16, v171
	v_and_b32_e32 v159, 0xffff0000, v171
	v_pk_add_f32 v[156:157], v[156:157], v[158:159]
	v_pk_fma_f32 v[156:157], v[60:61], 0.5, v[156:157] op_sel_hi:[1,0,1]
	v_cvt_pk_bf16_f32 v167, v156, v157
	v_pk_fma_f32 v[198:199], v[156:157], v[156:157], v[198:199]
	v_lshlrev_b32_e32 v158, 16, v167
	v_and_b32_e32 v159, 0xffff0000, v167
	v_pk_add_f32 v[196:197], v[156:157], v[158:159] neg_lo:[0,1] neg_hi:[0,1]
	v_cvt_pk_bf16_f32 v171, v196, v197
	global_store_dwordx4 v211, v[164:167], s[10:11]
	global_store_dwordx4 v211, v[168:171], s[6:7]
	s_waitcnt vmcnt(18)
	v_lshlrev_b32_e32 v156, 16, v172
	v_and_b32_e32 v157, 0xffff0000, v172
	v_lshlrev_b32_e32 v158, 16, v176
	v_and_b32_e32 v159, 0xffff0000, v176
	v_pk_add_f32 v[156:157], v[156:157], v[158:159]
	v_pk_fma_f32 v[156:157], v[54:55], 0.5, v[156:157] op_sel_hi:[1,0,1]
	v_cvt_pk_bf16_f32 v172, v156, v157
	v_pk_fma_f32 v[198:199], v[156:157], v[156:157], v[198:199]
	v_lshlrev_b32_e32 v158, 16, v172
	v_and_b32_e32 v159, 0xffff0000, v172
	v_pk_add_f32 v[196:197], v[156:157], v[158:159] neg_lo:[0,1] neg_hi:[0,1]
	v_cvt_pk_bf16_f32 v176, v196, v197
	v_lshlrev_b32_e32 v156, 16, v173
	v_and_b32_e32 v157, 0xffff0000, v173
	v_lshlrev_b32_e32 v158, 16, v177
	v_and_b32_e32 v159, 0xffff0000, v177
	v_pk_add_f32 v[156:157], v[156:157], v[158:159]
	v_pk_fma_f32 v[156:157], v[56:57], 0.5, v[156:157] op_sel_hi:[1,0,1]
	v_cvt_pk_bf16_f32 v173, v156, v157
	v_pk_fma_f32 v[198:199], v[156:157], v[156:157], v[198:199]
	v_lshlrev_b32_e32 v158, 16, v173
	v_and_b32_e32 v159, 0xffff0000, v173
	v_pk_add_f32 v[196:197], v[156:157], v[158:159] neg_lo:[0,1] neg_hi:[0,1]
	v_cvt_pk_bf16_f32 v177, v196, v197
	v_lshlrev_b32_e32 v156, 16, v174
	v_and_b32_e32 v157, 0xffff0000, v174
	v_lshlrev_b32_e32 v158, 16, v178
	v_and_b32_e32 v159, 0xffff0000, v178
	v_pk_add_f32 v[156:157], v[156:157], v[158:159]
	v_pk_fma_f32 v[156:157], v[50:51], 0.5, v[156:157] op_sel_hi:[1,0,1]
	v_cvt_pk_bf16_f32 v174, v156, v157
	v_pk_fma_f32 v[198:199], v[156:157], v[156:157], v[198:199]
	v_lshlrev_b32_e32 v158, 16, v174
	v_and_b32_e32 v159, 0xffff0000, v174
	v_pk_add_f32 v[196:197], v[156:157], v[158:159] neg_lo:[0,1] neg_hi:[0,1]
	v_cvt_pk_bf16_f32 v178, v196, v197
	v_lshlrev_b32_e32 v156, 16, v175
	v_and_b32_e32 v157, 0xffff0000, v175
	v_lshlrev_b32_e32 v158, 16, v179
	v_and_b32_e32 v159, 0xffff0000, v179
	v_pk_add_f32 v[156:157], v[156:157], v[158:159]
	v_pk_fma_f32 v[156:157], v[52:53], 0.5, v[156:157] op_sel_hi:[1,0,1]
	v_cvt_pk_bf16_f32 v175, v156, v157
	v_pk_fma_f32 v[198:199], v[156:157], v[156:157], v[198:199]
	v_lshlrev_b32_e32 v158, 16, v175
	v_and_b32_e32 v159, 0xffff0000, v175
	v_pk_add_f32 v[196:197], v[156:157], v[158:159] neg_lo:[0,1] neg_hi:[0,1]
	v_cvt_pk_bf16_f32 v179, v196, v197
	global_store_dwordx4 v211, v[172:175], s[10:11] offset:256
	global_store_dwordx4 v211, v[176:179], s[6:7] offset:256
	v_add_f32_e32 v206, v198, v199
	s_nop 0
	v_add_u32_e32 v211, 0x58000, v213
	global_load_dwordx4 v[164:167], v211, s[38:39]
	global_load_dwordx4 v[168:171], v211, s[6:7]
	global_load_dwordx4 v[172:175], v211, s[38:39] offset:256
	global_load_dwordx4 v[176:179], v211, s[6:7] offset:256
	s_waitcnt vmcnt(18)
; __device__ __forceinline__ unsigned pk2(float lo, float hi) { f32x2_t v = {lo, hi}; bf16x2_t b = __builtin_convertvector(v, bf16x2_t); return __builtin_bit_cast(unsigned, b); }
; __device__ __forceinline__ float bflo(unsigned u) { return __uint_as_float(u << 16); }
;     __device__ __forceinline__ void operator()(const f32x4 (&acc)[2][2][4][2], const Unit& u, int wr, int wc, int fr, int fq) const {
;     ...
;                 for (int bj = 0; bj < 2; ++bj) {
;                     const size_t off = (size_t)row * DM + col0 + bj * HALF;
;                     const u32x4 hh = *(const u32x4*)(HI + off), ll = *(const u32x4*)(LO + off);
;                     float hv[8] = {bflo(hh.x) + bflo(ll.x), bfhi(hh.x) + bfhi(ll.x), bflo(hh.y) + bflo(ll.y), bfhi(hh.y) + bfhi(ll.y),
;                                    bflo(hh.z) + bflo(ll.z), bfhi(hh.z) + bfhi(ll.z), bflo(hh.w) + bflo(ll.w), bfhi(hh.w) + bfhi(ll.w)};
;                     float av[8] = {acc[ai][bj][m][0][0], acc[ai][bj][m][0][1], acc[ai][bj][m][0][2], acc[ai][bj][m][0][3], acc[ai][bj][m][1][0], acc[ai][bj][m][1][1], acc[ai][bj][m][1][2], acc[ai][bj][m][1][3]};
;                     if (GATED) { const u32x4 pp = *(const u32x4*)(PP + off);
;                         const float pv[8] = {bflo(pp.x), bfhi(pp.x), bflo(pp.y), bfhi(pp.y), bflo(pp.z), bfhi(pp.z), bflo(pp.w), bfhi(pp.w)};
; #pragma unroll
;                         for (int e = 0; e < 8; ++e) av[e] = fast_sigmoid(av[e] * rs) * pv[e]; }
;                     else {
; #pragma unroll
;                         for (int e = 0; e < 8; ++e) av[e] *= alpha; }
;                     float lo[8];
; #pragma unroll
;                     for (int e = 0; e < 8; ++e) { hv[e] += av[e]; sq += hv[e] * hv[e]; }
;                     u32x4 wh; wh.x = pk2(hv[0], hv[1]); wh.y = pk2(hv[2], hv[3]); wh.z = pk2(hv[4], hv[5]); wh.w = pk2(hv[6], hv[7]);
;                     lo[0] = hv[0] - bflo(wh.x); lo[1] = hv[1] - bfhi(wh.x); lo[2] = hv[2] - bflo(wh.y); lo[3] = hv[3] - bfhi(wh.y);
;                     lo[4] = hv[4] - bflo(wh.z); lo[5] = hv[5] - bfhi(wh.z); lo[6] = hv[6] - bflo(wh.w); lo[7] = hv[7] - bfhi(wh.w);
;                     u32x4 wl; wl.x = pk2(lo[0], lo[1]); wl.y = pk2(lo[2], lo[3]); wl.z = pk2(lo[4], lo[5]); wl.w = pk2(lo[6], lo[7]);
;                     *(u32x4*)(HO + off) = wh; *(u32x4*)(LO + off) = wl;
	v_lshlrev_b32_e32 v156, 16, v180
	v_and_b32_e32 v157, 0xffff0000, v180
	v_lshlrev_b32_e32 v158, 16, v184
	v_and_b32_e32 v159, 0xffff0000, v184
	v_pk_add_f32 v[156:157], v[156:157], v[158:159]
	v_pk_fma_f32 v[156:157], v[46:47], 0.5, v[156:157] op_sel_hi:[1,0,1]
	v_cvt_pk_bf16_f32 v180, v156, v157
	v_pk_mul_f32 v[198:199], v[156:157], v[156:157]
	v_lshlrev_b32_e32 v158, 16, v180
	v_and_b32_e32 v159, 0xffff0000, v180
	v_pk_add_f32 v[196:197], v[156:157], v[158:159] neg_lo:[0,1] neg_hi:[0,1]
	v_cvt_pk_bf16_f32 v184, v196, v197
	v_lshlrev_b32_e32 v156, 16, v181
	v_and_b32_e32 v157, 0xffff0000, v181
	v_lshlrev_b32_e32 v158, 16, v185
	v_and_b32_e32 v159, 0xffff0000, v185
	v_pk_add_f32 v[156:157], v[156:157], v[158:159]
	v_pk_fma_f32 v[156:157], v[48:49], 0.5, v[156:157] op_sel_hi:[1,0,1]
	v_cvt_pk_bf16_f32 v181, v156, v157
	v_pk_fma_f32 v[198:199], v[156:157], v[156:157], v[198:199]
	v_lshlrev_b32_e32 v158, 16, v181
	v_and_b32_e32 v159, 0xffff0000, v181
	v_pk_add_f32 v[196:197], v[156:157], v[158:159] neg_lo:[0,1] neg_hi:[0,1]
	v_cvt_pk_bf16_f32 v185, v196, v197
	v_lshlrev_b32_e32 v156, 16, v182
	v_and_b32_e32 v157, 0xffff0000, v182
	v_lshlrev_b32_e32 v158, 16, v186
	v_and_b32_e32 v159, 0xffff0000, v186
	v_pk_add_f32 v[156:157], v[156:157], v[158:159]
	v_pk_fma_f32 v[156:157], v[42:43], 0.5, v[156:157] op_sel_hi:[1,0,1]
	v_cvt_pk_bf16_f32 v182, v156, v157
	v_pk_fma_f32 v[198:199], v[156:157], v[156:157], v[198:199]
	v_lshlrev_b32_e32 v158, 16, v182
	v_and_b32_e32 v159, 0xffff0000, v182
	v_pk_add_f32 v[196:197], v[156:157], v[158:159] neg_lo:[0,1] neg_hi:[0,1]
	v_cvt_pk_bf16_f32 v186, v196, v197
	v_lshlrev_b32_e32 v156, 16, v183
	v_and_b32_e32 v157, 0xffff0000, v183
	v_lshlrev_b32_e32 v158, 16, v187
	v_and_b32_e32 v159, 0xffff0000, v187
	v_pk_add_f32 v[156:157], v[156:157], v[158:159]
	v_pk_fma_f32 v[156:157], v[44:45], 0.5, v[156:157] op_sel_hi:[1,0,1]
	v_cvt_pk_bf16_f32 v183, v156, v157
	v_pk_fma_f32 v[198:199], v[156:157], v[156:157], v[198:199]
	v_lshlrev_b32_e32 v158, 16, v183
	v_and_b32_e32 v159, 0xffff0000, v183
	v_pk_add_f32 v[196:197], v[156:157], v[158:159] neg_lo:[0,1] neg_hi:[0,1]
	v_cvt_pk_bf16_f32 v187, v196, v197
	global_store_dwordx4 v212, v[180:183], s[10:11]
	global_store_dwordx4 v212, v[184:187], s[6:7]
	s_waitcnt vmcnt(18)
	v_lshlrev_b32_e32 v156, 16, v188
	v_and_b32_e32 v157, 0xffff0000, v188
	v_lshlrev_b32_e32 v158, 16, v192
	v_and_b32_e32 v159, 0xffff0000, v192
	v_pk_add_f32 v[156:157], v[156:157], v[158:159]
	v_pk_fma_f32 v[156:157], v[38:39], 0.5, v[156:157] op_sel_hi:[1,0,1]
	v_cvt_pk_bf16_f32 v188, v156, v157
	v_pk_fma_f32 v[198:199], v[156:157], v[156:157], v[198:199]
	v_lshlrev_b32_e32 v158, 16, v188
	v_and_b32_e32 v159, 0xffff0000, v188
	v_pk_add_f32 v[196:197], v[156:157], v[158:159] neg_lo:[0,1] neg_hi:[0,1]
	v_cvt_pk_bf16_f32 v192, v196, v197
	v_lshlrev_b32_e32 v156, 16, v189
	v_and_b32_e32 v157, 0xffff0000, v189
	v_lshlrev_b32_e32 v158, 16, v193
	v_and_b32_e32 v159, 0xffff0000, v193
	v_pk_add_f32 v[156:157], v[156:157], v[158:159]
	v_pk_fma_f32 v[156:157], v[40:41], 0.5, v[156:157] op_sel_hi:[1,0,1]
	v_cvt_pk_bf16_f32 v189, v156, v157
	v_pk_fma_f32 v[198:199], v[156:157], v[156:157], v[198:199]
	v_lshlrev_b32_e32 v158, 16, v189
	v_and_b32_e32 v159, 0xffff0000, v189
	v_pk_add_f32 v[196:197], v[156:157], v[158:159] neg_lo:[0,1] neg_hi:[0,1]
	v_cvt_pk_bf16_f32 v193, v196, v197
	v_lshlrev_b32_e32 v156, 16, v190
	v_and_b32_e32 v157, 0xffff0000, v190
	v_lshlrev_b32_e32 v158, 16, v194
	v_and_b32_e32 v159, 0xffff0000, v194
	v_pk_add_f32 v[156:157], v[156:157], v[158:159]
	v_pk_fma_f32 v[156:157], v[34:35], 0.5, v[156:157] op_sel_hi:[1,0,1]
	v_cvt_pk_bf16_f32 v190, v156, v157
	v_pk_fma_f32 v[198:199], v[156:157], v[156:157], v[198:199]
	v_lshlrev_b32_e32 v158, 16, v190
	v_and_b32_e32 v159, 0xffff0000, v190
	v_pk_add_f32 v[196:197], v[156:157], v[158:159] neg_lo:[0,1] neg_hi:[0,1]
	v_cvt_pk_bf16_f32 v194, v196, v197
	v_lshlrev_b32_e32 v156, 16, v191
	v_and_b32_e32 v157, 0xffff0000, v191
	v_lshlrev_b32_e32 v158, 16, v195
	v_and_b32_e32 v159, 0xffff0000, v195
	v_pk_add_f32 v[156:157], v[156:157], v[158:159]
	v_pk_fma_f32 v[156:157], v[36:37], 0.5, v[156:157] op_sel_hi:[1,0,1]
	v_cvt_pk_bf16_f32 v191, v156, v157
	v_pk_fma_f32 v[198:199], v[156:157], v[156:157], v[198:199]
	v_lshlrev_b32_e32 v158, 16, v191
	v_and_b32_e32 v159, 0xffff0000, v191
	v_pk_add_f32 v[196:197], v[156:157], v[158:159] neg_lo:[0,1] neg_hi:[0,1]
	v_cvt_pk_bf16_f32 v195, v196, v197
	global_store_dwordx4 v212, v[188:191], s[10:11] offset:256
	global_store_dwordx4 v212, v[192:195], s[6:7] offset:256
	v_add_f32_e32 v207, v198, v199
	s_waitcnt vmcnt(14)
; __device__ __forceinline__ unsigned pk2(float lo, float hi) { f32x2_t v = {lo, hi}; bf16x2_t b = __builtin_convertvector(v, bf16x2_t); return __builtin_bit_cast(unsigned, b); }
; __device__ __forceinline__ float bflo(unsigned u) { return __uint_as_float(u << 16); }
;     __device__ __forceinline__ void operator()(const f32x4 (&acc)[2][2][4][2], const Unit& u, int wr, int wc, int fr, int fq) const {
;     ...
;                 for (int bj = 0; bj < 2; ++bj) {
;                     const size_t off = (size_t)row * DM + col0 + bj * HALF;
;                     const u32x4 hh = *(const u32x4*)(HI + off), ll = *(const u32x4*)(LO + off);
;                     float hv[8] = {bflo(hh.x) + bflo(ll.x), bfhi(hh.x) + bfhi(ll.x), bflo(hh.y) + bflo(ll.y), bfhi(hh.y) + bfhi(ll.y),
;                                    bflo(hh.z) + bflo(ll.z), bfhi(hh.z) + bfhi(ll.z), bflo(hh.w) + bflo(ll.w), bfhi(hh.w) + bfhi(ll.w)};
;                     float av[8] = {acc[ai][bj][m][0][0], acc[ai][bj][m][0][1], acc[ai][bj][m][0][2], acc[ai][bj][m][0][3], acc[ai][bj][m][1][0], acc[ai][bj][m][1][1], acc[ai][bj][m][1][2], acc[ai][bj][m][1][3]};
;                     if (GATED) { const u32x4 pp = *(const u32x4*)(PP + off);
;                         const float pv[8] = {bflo(pp.x), bfhi(pp.x), bflo(pp.y), bfhi(pp.y), bflo(pp.z), bfhi(pp.z), bflo(pp.w), bfhi(pp.w)};
; #pragma unroll
;                         for (int e = 0; e < 8; ++e) av[e] = fast_sigmoid(av[e] * rs) * pv[e]; }
;                     else {
; #pragma unroll
;                         for (int e = 0; e < 8; ++e) av[e] *= alpha; }
;                     float lo[8];
; #pragma unroll
;                     for (int e = 0; e < 8; ++e) { hv[e] += av[e]; sq += hv[e] * hv[e]; }
;                     u32x4 wh; wh.x = pk2(hv[0], hv[1]); wh.y = pk2(hv[2], hv[3]); wh.z = pk2(hv[4], hv[5]); wh.w = pk2(hv[6], hv[7]);
;                     lo[0] = hv[0] - bflo(wh.x); lo[1] = hv[1] - bfhi(wh.x); lo[2] = hv[2] - bflo(wh.y); lo[3] = hv[3] - bfhi(wh.y);
;                     lo[4] = hv[4] - bflo(wh.z); lo[5] = hv[5] - bfhi(wh.z); lo[6] = hv[6] - bflo(wh.w); lo[7] = hv[7] - bfhi(wh.w);
;                     u32x4 wl; wl.x = pk2(lo[0], lo[1]); wl.y = pk2(lo[2], lo[3]); wl.z = pk2(lo[4], lo[5]); wl.w = pk2(lo[6], lo[7]);
;                     *(u32x4*)(HO + off) = wh; *(u32x4*)(LO + off) = wl;
	v_lshlrev_b32_e32 v156, 16, v140
	v_and_b32_e32 v157, 0xffff0000, v140
	v_lshlrev_b32_e32 v158, 16, v144
	v_and_b32_e32 v159, 0xffff0000, v144
	v_pk_add_f32 v[156:157], v[156:157], v[158:159]
	v_pk_fma_f32 v[156:157], v[30:31], 0.5, v[156:157] op_sel_hi:[1,0,1]
	v_cvt_pk_bf16_f32 v140, v156, v157
	v_pk_mul_f32 v[198:199], v[156:157], v[156:157]
	v_lshlrev_b32_e32 v158, 16, v140
	v_and_b32_e32 v159, 0xffff0000, v140
	v_pk_add_f32 v[196:197], v[156:157], v[158:159] neg_lo:[0,1] neg_hi:[0,1]
	v_cvt_pk_bf16_f32 v144, v196, v197
	v_lshlrev_b32_e32 v156, 16, v141
	v_and_b32_e32 v157, 0xffff0000, v141
	v_lshlrev_b32_e32 v158, 16, v145
	v_and_b32_e32 v159, 0xffff0000, v145
	v_pk_add_f32 v[156:157], v[156:157], v[158:159]
	v_pk_fma_f32 v[156:157], v[32:33], 0.5, v[156:157] op_sel_hi:[1,0,1]
	v_cvt_pk_bf16_f32 v141, v156, v157
	v_pk_fma_f32 v[198:199], v[156:157], v[156:157], v[198:199]
	v_lshlrev_b32_e32 v158, 16, v141
	v_and_b32_e32 v159, 0xffff0000, v141
	v_pk_add_f32 v[196:197], v[156:157], v[158:159] neg_lo:[0,1] neg_hi:[0,1]
	v_cvt_pk_bf16_f32 v145, v196, v197
	v_lshlrev_b32_e32 v156, 16, v142
	v_and_b32_e32 v157, 0xffff0000, v142
	v_lshlrev_b32_e32 v158, 16, v146
	v_and_b32_e32 v159, 0xffff0000, v146
	v_pk_add_f32 v[156:157], v[156:157], v[158:159]
	v_pk_fma_f32 v[156:157], v[26:27], 0.5, v[156:157] op_sel_hi:[1,0,1]
	v_cvt_pk_bf16_f32 v142, v156, v157
	v_pk_fma_f32 v[198:199], v[156:157], v[156:157], v[198:199]
	v_lshlrev_b32_e32 v158, 16, v142
	v_and_b32_e32 v159, 0xffff0000, v142
	v_pk_add_f32 v[196:197], v[156:157], v[158:159] neg_lo:[0,1] neg_hi:[0,1]
	v_cvt_pk_bf16_f32 v146, v196, v197
	v_lshlrev_b32_e32 v156, 16, v143
	v_and_b32_e32 v157, 0xffff0000, v143
	v_lshlrev_b32_e32 v158, 16, v147
	v_and_b32_e32 v159, 0xffff0000, v147
	v_pk_add_f32 v[156:157], v[156:157], v[158:159]
	v_pk_fma_f32 v[156:157], v[28:29], 0.5, v[156:157] op_sel_hi:[1,0,1]
	v_cvt_pk_bf16_f32 v143, v156, v157
	v_pk_fma_f32 v[198:199], v[156:157], v[156:157], v[198:199]
	v_lshlrev_b32_e32 v158, 16, v143
	v_and_b32_e32 v159, 0xffff0000, v143
	v_pk_add_f32 v[196:197], v[156:157], v[158:159] neg_lo:[0,1] neg_hi:[0,1]
	v_cvt_pk_bf16_f32 v147, v196, v197
	global_store_dwordx4 v210, v[140:143], s[10:11]
	global_store_dwordx4 v210, v[144:147], s[6:7]
	s_waitcnt vmcnt(14)
	v_lshlrev_b32_e32 v156, 16, v148
	v_and_b32_e32 v157, 0xffff0000, v148
	v_lshlrev_b32_e32 v158, 16, v152
	v_and_b32_e32 v159, 0xffff0000, v152
	v_pk_add_f32 v[156:157], v[156:157], v[158:159]
	v_pk_fma_f32 v[156:157], v[22:23], 0.5, v[156:157] op_sel_hi:[1,0,1]
	v_cvt_pk_bf16_f32 v148, v156, v157
	v_pk_fma_f32 v[198:199], v[156:157], v[156:157], v[198:199]
	v_lshlrev_b32_e32 v158, 16, v148
	v_and_b32_e32 v159, 0xffff0000, v148
	v_pk_add_f32 v[196:197], v[156:157], v[158:159] neg_lo:[0,1] neg_hi:[0,1]
	v_cvt_pk_bf16_f32 v152, v196, v197
	v_lshlrev_b32_e32 v156, 16, v149
	v_and_b32_e32 v157, 0xffff0000, v149
	v_lshlrev_b32_e32 v158, 16, v153
	v_and_b32_e32 v159, 0xffff0000, v153
	v_pk_add_f32 v[156:157], v[156:157], v[158:159]
	v_pk_fma_f32 v[156:157], v[24:25], 0.5, v[156:157] op_sel_hi:[1,0,1]
	v_cvt_pk_bf16_f32 v149, v156, v157
	v_pk_fma_f32 v[198:199], v[156:157], v[156:157], v[198:199]
	v_lshlrev_b32_e32 v158, 16, v149
	v_and_b32_e32 v159, 0xffff0000, v149
	v_pk_add_f32 v[196:197], v[156:157], v[158:159] neg_lo:[0,1] neg_hi:[0,1]
	v_cvt_pk_bf16_f32 v153, v196, v197
	v_lshlrev_b32_e32 v156, 16, v150
	v_and_b32_e32 v157, 0xffff0000, v150
	v_lshlrev_b32_e32 v158, 16, v154
	v_and_b32_e32 v159, 0xffff0000, v154
	v_pk_add_f32 v[156:157], v[156:157], v[158:159]
	v_pk_fma_f32 v[156:157], v[18:19], 0.5, v[156:157] op_sel_hi:[1,0,1]
	v_cvt_pk_bf16_f32 v150, v156, v157
	v_pk_fma_f32 v[198:199], v[156:157], v[156:157], v[198:199]
	v_lshlrev_b32_e32 v158, 16, v150
	v_and_b32_e32 v159, 0xffff0000, v150
	v_pk_add_f32 v[196:197], v[156:157], v[158:159] neg_lo:[0,1] neg_hi:[0,1]
	v_cvt_pk_bf16_f32 v154, v196, v197
	v_lshlrev_b32_e32 v156, 16, v151
	v_and_b32_e32 v157, 0xffff0000, v151
	v_lshlrev_b32_e32 v158, 16, v155
	v_and_b32_e32 v159, 0xffff0000, v155
	v_pk_add_f32 v[156:157], v[156:157], v[158:159]
	v_pk_fma_f32 v[156:157], v[20:21], 0.5, v[156:157] op_sel_hi:[1,0,1]
	v_cvt_pk_bf16_f32 v151, v156, v157
	v_pk_fma_f32 v[198:199], v[156:157], v[156:157], v[198:199]
	v_lshlrev_b32_e32 v158, 16, v151
	v_and_b32_e32 v159, 0xffff0000, v151
	v_pk_add_f32 v[196:197], v[156:157], v[158:159] neg_lo:[0,1] neg_hi:[0,1]
	v_cvt_pk_bf16_f32 v155, v196, v197
	global_store_dwordx4 v210, v[148:151], s[10:11] offset:256
	global_store_dwordx4 v210, v[152:155], s[6:7] offset:256
	v_add_f32_e32 v208, v198, v199
	s_waitcnt vmcnt(10)
; __device__ __forceinline__ float bflo(unsigned u) { return __uint_as_float(u << 16); }
;     __device__ __forceinline__ void operator()(const f32x4 (&acc)[2][2][4][2], const Unit& u, int wr, int wc, int fr, int fq) const {
;     ...
;                 for (int bj = 0; bj < 2; ++bj) {
;                     const size_t off = (size_t)row * DM + col0 + bj * HALF;
;                     const u32x4 hh = *(const u32x4*)(HI + off), ll = *(const u32x4*)(LO + off);
;                     float hv[8] = {bflo(hh.x) + bflo(ll.x), bfhi(hh.x) + bfhi(ll.x), bflo(hh.y) + bflo(ll.y), bfhi(hh.y) + bfhi(ll.y),
;                                    bflo(hh.z) + bflo(ll.z), bfhi(hh.z) + bfhi(ll.z), bflo(hh.w) + bflo(ll.w), bfhi(hh.w) + bfhi(ll.w)};
;                     float av[8] = {acc[ai][bj][m][0][0], acc[ai][bj][m][0][1], acc[ai][bj][m][0][2], acc[ai][bj][m][0][3], acc[ai][bj][m][1][0], acc[ai][bj][m][1][1], acc[ai][bj][m][1][2], acc[ai][bj][m][1][3]};
;                     if (GATED) { const u32x4 pp = *(const u32x4*)(PP + off);
;                         const float pv[8] = {bflo(pp.x), bfhi(pp.x), bflo(pp.y), bfhi(pp.y), bflo(pp.z), bfhi(pp.z), bflo(pp.w), bfhi(pp.w)};
; #pragma unroll
;                         for (int e = 0; e < 8; ++e) av[e] = fast_sigmoid(av[e] * rs) * pv[e]; }
;                     else {
; #pragma unroll
;                         for (int e = 0; e < 8; ++e) av[e] *= alpha; }
;                     float lo[8];
; #pragma unroll
;                     for (int e = 0; e < 8; ++e) { hv[e] += av[e]; sq += hv[e] * hv[e]; }
;                     u32x4 wh; wh.x = pk2(hv[0], hv[1]); wh.y = pk2(hv[2], hv[3]); wh.z = pk2(hv[4], hv[5]); wh.w = pk2(hv[6], hv[7]);
;                     lo[0] = hv[0] - bflo(wh.x); lo[1] = hv[1] - bfhi(wh.x); lo[2] = hv[2] - bflo(wh.y); lo[3] = hv[3] - bfhi(wh.y);
;                     lo[4] = hv[4] - bflo(wh.z); lo[5] = hv[5] - bfhi(wh.z); lo[6] = hv[6] - bflo(wh.w); lo[7] = hv[7] - bfhi(wh.w);
;                     u32x4 wl; wl.x = pk2(lo[0], lo[1]); wl.y = pk2(lo[2], lo[3]); wl.z = pk2(lo[4], lo[5]); wl.w = pk2(lo[6], lo[7]);
;                     *(u32x4*)(HO + off) = wh; *(u32x4*)(LO + off) = wl;
;                 }
;                 sq += __shfl_xor(sq, 16); sq += __shfl_xor(sq, 32);
;                 if (fq == 0) ssq_out[(size_t)row * 16 + 4 * u.pn + wc] = sq;
	v_lshlrev_b32_e32 v156, 16, v164
	v_and_b32_e32 v157, 0xffff0000, v164
	v_lshlrev_b32_e32 v158, 16, v168
	v_and_b32_e32 v159, 0xffff0000, v168
	v_pk_add_f32 v[156:157], v[156:157], v[158:159]
	v_pk_fma_f32 v[156:157], v[14:15], 0.5, v[156:157] op_sel_hi:[1,0,1]
	v_cvt_pk_bf16_f32 v164, v156, v157
	v_pk_mul_f32 v[198:199], v[156:157], v[156:157]
	v_lshlrev_b32_e32 v158, 16, v164
	v_and_b32_e32 v159, 0xffff0000, v164
	v_pk_add_f32 v[196:197], v[156:157], v[158:159] neg_lo:[0,1] neg_hi:[0,1]
	v_cvt_pk_bf16_f32 v168, v196, v197
	v_lshlrev_b32_e32 v156, 16, v165
	v_and_b32_e32 v157, 0xffff0000, v165
	v_lshlrev_b32_e32 v158, 16, v169
	v_and_b32_e32 v159, 0xffff0000, v169
	v_pk_add_f32 v[156:157], v[156:157], v[158:159]
	v_pk_fma_f32 v[156:157], v[16:17], 0.5, v[156:157] op_sel_hi:[1,0,1]
	v_cvt_pk_bf16_f32 v165, v156, v157
	v_pk_fma_f32 v[198:199], v[156:157], v[156:157], v[198:199]
	v_lshlrev_b32_e32 v158, 16, v165
	v_and_b32_e32 v159, 0xffff0000, v165
	v_pk_add_f32 v[196:197], v[156:157], v[158:159] neg_lo:[0,1] neg_hi:[0,1]
	v_cvt_pk_bf16_f32 v169, v196, v197
	v_lshlrev_b32_e32 v156, 16, v166
	v_and_b32_e32 v157, 0xffff0000, v166
	v_lshlrev_b32_e32 v158, 16, v170
	v_and_b32_e32 v159, 0xffff0000, v170
	v_pk_add_f32 v[156:157], v[156:157], v[158:159]
	v_pk_fma_f32 v[156:157], v[10:11], 0.5, v[156:157] op_sel_hi:[1,0,1]
	v_cvt_pk_bf16_f32 v166, v156, v157
	v_pk_fma_f32 v[198:199], v[156:157], v[156:157], v[198:199]
	v_lshlrev_b32_e32 v158, 16, v166
	v_and_b32_e32 v159, 0xffff0000, v166
	v_pk_add_f32 v[196:197], v[156:157], v[158:159] neg_lo:[0,1] neg_hi:[0,1]
	v_cvt_pk_bf16_f32 v170, v196, v197
	v_lshlrev_b32_e32 v156, 16, v167
	v_and_b32_e32 v157, 0xffff0000, v167
	v_lshlrev_b32_e32 v158, 16, v171
	v_and_b32_e32 v159, 0xffff0000, v171
	v_pk_add_f32 v[156:157], v[156:157], v[158:159]
	v_pk_fma_f32 v[156:157], v[12:13], 0.5, v[156:157] op_sel_hi:[1,0,1]
	v_cvt_pk_bf16_f32 v167, v156, v157
	v_pk_fma_f32 v[198:199], v[156:157], v[156:157], v[198:199]
	v_lshlrev_b32_e32 v158, 16, v167
	v_and_b32_e32 v159, 0xffff0000, v167
	v_pk_add_f32 v[196:197], v[156:157], v[158:159] neg_lo:[0,1] neg_hi:[0,1]
	v_cvt_pk_bf16_f32 v171, v196, v197
	global_store_dwordx4 v211, v[164:167], s[10:11]
	global_store_dwordx4 v211, v[168:171], s[6:7]
	s_waitcnt vmcnt(10)
	v_lshlrev_b32_e32 v156, 16, v172
	v_and_b32_e32 v157, 0xffff0000, v172
	v_lshlrev_b32_e32 v158, 16, v176
	v_and_b32_e32 v159, 0xffff0000, v176
	v_pk_add_f32 v[156:157], v[156:157], v[158:159]
	v_pk_fma_f32 v[156:157], v[6:7], 0.5, v[156:157] op_sel_hi:[1,0,1]
	v_cvt_pk_bf16_f32 v172, v156, v157
	v_pk_fma_f32 v[198:199], v[156:157], v[156:157], v[198:199]
	v_lshlrev_b32_e32 v158, 16, v172
	v_and_b32_e32 v159, 0xffff0000, v172
	v_pk_add_f32 v[196:197], v[156:157], v[158:159] neg_lo:[0,1] neg_hi:[0,1]
	v_cvt_pk_bf16_f32 v176, v196, v197
	v_lshlrev_b32_e32 v156, 16, v173
	v_and_b32_e32 v157, 0xffff0000, v173
	v_lshlrev_b32_e32 v158, 16, v177
	v_and_b32_e32 v159, 0xffff0000, v177
	v_pk_add_f32 v[156:157], v[156:157], v[158:159]
	v_pk_fma_f32 v[156:157], v[8:9], 0.5, v[156:157] op_sel_hi:[1,0,1]
	v_cvt_pk_bf16_f32 v173, v156, v157
	v_pk_fma_f32 v[198:199], v[156:157], v[156:157], v[198:199]
	v_lshlrev_b32_e32 v158, 16, v173
	v_and_b32_e32 v159, 0xffff0000, v173
	v_pk_add_f32 v[196:197], v[156:157], v[158:159] neg_lo:[0,1] neg_hi:[0,1]
	v_cvt_pk_bf16_f32 v177, v196, v197
	v_lshlrev_b32_e32 v156, 16, v174
	v_and_b32_e32 v157, 0xffff0000, v174
	v_lshlrev_b32_e32 v158, 16, v178
	v_and_b32_e32 v159, 0xffff0000, v178
	v_pk_add_f32 v[156:157], v[156:157], v[158:159]
	v_pk_fma_f32 v[156:157], v[2:3], 0.5, v[156:157] op_sel_hi:[1,0,1]
	v_cvt_pk_bf16_f32 v174, v156, v157
	v_pk_fma_f32 v[198:199], v[156:157], v[156:157], v[198:199]
	v_lshlrev_b32_e32 v158, 16, v174
	v_and_b32_e32 v159, 0xffff0000, v174
	v_pk_add_f32 v[196:197], v[156:157], v[158:159] neg_lo:[0,1] neg_hi:[0,1]
	v_cvt_pk_bf16_f32 v178, v196, v197
	v_lshlrev_b32_e32 v156, 16, v175
	v_and_b32_e32 v157, 0xffff0000, v175
	v_lshlrev_b32_e32 v158, 16, v179
	v_and_b32_e32 v159, 0xffff0000, v179
	v_pk_add_f32 v[156:157], v[156:157], v[158:159]
	v_pk_fma_f32 v[156:157], v[4:5], 0.5, v[156:157] op_sel_hi:[1,0,1]
	v_cvt_pk_bf16_f32 v175, v156, v157
	v_pk_fma_f32 v[198:199], v[156:157], v[156:157], v[198:199]
	v_lshlrev_b32_e32 v158, 16, v175
	v_and_b32_e32 v159, 0xffff0000, v175
	v_pk_add_f32 v[196:197], v[156:157], v[158:159] neg_lo:[0,1] neg_hi:[0,1]
	v_cvt_pk_bf16_f32 v179, v196, v197
	global_store_dwordx4 v211, v[172:175], s[10:11] offset:256
	global_store_dwordx4 v211, v[176:179], s[6:7] offset:256
	v_add_f32_e32 v209, v198, v199
	v_mov_b32_e32 v140, v200
	s_nop 1
	v_permlane16_swap_b32_e32 v200, v140
	v_mov_b32_e32 v141, v201
	s_nop 1
	v_permlane16_swap_b32_e32 v201, v141
	v_mov_b32_e32 v142, v202
	s_nop 1
	v_permlane16_swap_b32_e32 v202, v142
	v_mov_b32_e32 v143, v203
	s_nop 1
	v_permlane16_swap_b32_e32 v203, v143
	v_mov_b32_e32 v144, v206
	s_nop 1
	v_permlane16_swap_b32_e32 v206, v144
	v_mov_b32_e32 v145, v207
	s_nop 1
	v_permlane16_swap_b32_e32 v207, v145
	v_mov_b32_e32 v146, v208
	s_nop 1
	v_permlane16_swap_b32_e32 v208, v146
	v_mov_b32_e32 v147, v209
	s_nop 1
	v_permlane16_swap_b32_e32 v209, v147
	v_readlane_b32 s52, v250, 35
	v_readlane_b32 s53, v250, 36
	s_waitcnt lgkmcnt(0)
	v_add_f32_e32 v200, v200, v140
	v_add_f32_e32 v201, v201, v141
	v_add_f32_e32 v202, v202, v142
	v_add_f32_e32 v203, v203, v143
	v_add_f32_e32 v206, v206, v144
	v_add_f32_e32 v207, v207, v145
	v_add_f32_e32 v208, v208, v146
	v_add_f32_e32 v209, v209, v147
	v_mov_b32_e32 v140, v200
	s_nop 1
	v_permlane32_swap_b32_e32 v200, v140
	v_mov_b32_e32 v141, v201
	s_nop 1
	v_permlane32_swap_b32_e32 v201, v141
	v_mov_b32_e32 v142, v202
	s_nop 1
	v_permlane32_swap_b32_e32 v202, v142
	v_mov_b32_e32 v143, v203
	s_nop 1
	v_permlane32_swap_b32_e32 v203, v143
	v_mov_b32_e32 v144, v206
	s_nop 1
	v_permlane32_swap_b32_e32 v206, v144
	v_mov_b32_e32 v145, v207
	s_nop 1
	v_permlane32_swap_b32_e32 v207, v145
	v_mov_b32_e32 v146, v208
	s_nop 1
	v_permlane32_swap_b32_e32 v208, v146
	v_mov_b32_e32 v147, v209
	s_nop 1
	v_permlane32_swap_b32_e32 v209, v147
	s_waitcnt lgkmcnt(0)
	v_add_f32_e32 v200, v200, v140
	v_add_f32_e32 v201, v201, v141
	v_add_f32_e32 v202, v202, v142
	v_add_f32_e32 v203, v203, v143
	v_add_f32_e32 v206, v206, v144
	v_add_f32_e32 v207, v207, v145
	v_add_f32_e32 v208, v208, v146
	v_add_f32_e32 v209, v209, v147
	s_and_saveexec_b64 s[12:13], s[44:45]
	s_cbranch_execz .Lepir_f1d_skip
	global_store_dword v216, v200, s[52:53]
	global_store_dword v216, v201, s[52:53] offset:1024
	global_store_dword v216, v202, s[52:53] offset:2048
	global_store_dword v216, v203, s[52:53] offset:3072
	global_store_dword v217, v206, s[52:53]
	global_store_dword v217, v207, s[52:53] offset:1024
	global_store_dword v217, v208, s[52:53] offset:2048
	global_store_dword v217, v209, s[52:53] offset:3072

; __device__ __forceinline__ float row_ssq(const float* part, int pitch, int n4, int row, int fq) {
;     f32x4 v = (f32x4){0.f, 0.f, 0.f, 0.f};
;     if (fq < n4) v = *(const f32x4*)(part + (size_t)row * pitch + 4 * fq);
;     float s = (v[0] + v[1]) + (v[2] + v[3]);
;     s += __shfl_xor(s, 16); s += __shfl_xor(s, 32);
;     return s;
;     __device__ __forceinline__ void operator()(const f32x4 (&acc)[2][2][4][2], const Unit& u, int wr, int wc, int fr, int fq) const {
;         const int row0 = u.pm * BM + wr * 64 + fr;
;         float rsv[2][4];
; #pragma unroll
;         for (int ai = 0; ai < 2; ++ai)
; #pragma unroll
;             for (int m = 0; m < 4; ++m) rsv[ai][m] = ssq_in ? rsqrtf(row_ssq(ssq_in, in_pitch, in_n4, row0 + ai * HALF + m * 16, fq) * inv_k + EPS) : 1.f;
.LBB0_331:
	v_readlane_b32 s0, v252, 23
	v_readlane_b32 s1, v252, 24
	v_lshl_add_u32 v156, s4, 8, v139
	v_mov_b32_e32 v163, 1.0
	v_cndmask_b32_e64 v0, 0, 1, s[0:1]
	v_cmp_ne_u32_e64 s[50:51], 1, v0
	s_andn2_b64 vcc, exec, s[0:1]
	v_ashrrev_i32_e32 v157, 31, v156
	v_mov_b32_e32 v164, 1.0
	v_mov_b32_e32 v162, 1.0
	v_mov_b32_e32 v161, 1.0
	v_mov_b32_e32 v160, 1.0
	v_mov_b32_e32 v155, 1.0
	v_mov_b32_e32 v153, 1.0
	v_mov_b32_e32 v151, 1.0
	v_or_b32_e32 v154, 16, v156
	v_or_b32_e32 v152, 32, v156
	v_or_b32_e32 v150, 48, v156
	v_add_u32_e32 v148, 0x80, v156
	v_ashrrev_i32_e32 v149, 31, v148
	s_cbranch_vccnz .Lrsv_win_done
	v_and_b32_e32 v166, 48, v241
	v_lshl_add_u32 v166, v139, 6, v166
	v_add_u32_e32 v166, 0x24000, v166
	ds_read_b128 v[168:171], v166
	ds_read_b128 v[172:175], v166 offset:1024
	ds_read_b128 v[176:179], v166 offset:2048
	ds_read_b128 v[180:183], v166 offset:3072
	v_and_b32_e32 v202, 64, v241
	v_xor_b32_e32 v200, 16, v241
	ds_read_b128 v[184:187], v166 offset:8192
	ds_read_b128 v[188:191], v166 offset:9216
	ds_read_b128 v[192:195], v166 offset:10240
	ds_read_b128 v[196:199], v166 offset:11264
	v_add_u32_e32 v202, 64, v202
	v_cmp_lt_i32_e32 vcc, v200, v202
	v_xor_b32_e32 v201, 32, v241
	s_nop 0
	v_cndmask_b32_e32 v200, v241, v200, vcc
	v_cmp_lt_i32_e32 vcc, v201, v202
	v_lshlrev_b32_e32 v200, 2, v200
	s_nop 0
	v_cndmask_b32_e32 v201, v241, v201, vcc
	v_lshlrev_b32_e32 v201, 2, v201
	s_waitcnt lgkmcnt(7)
	v_add_f32_e32 v168, v168, v169
	v_add_f32_e32 v170, v170, v171
	v_add_f32_e32 v168, v168, v170
	v_mov_b32_e32 v169, v168
	s_nop 1
	v_permlane16_swap_b32_e32 v168, v169
	s_waitcnt lgkmcnt(6)
	v_add_f32_e32 v172, v172, v173
	v_add_f32_e32 v174, v174, v175
	v_add_f32_e32 v172, v172, v174
	v_mov_b32_e32 v173, v172
	s_nop 1
	v_permlane16_swap_b32_e32 v172, v173
	s_waitcnt lgkmcnt(5)
	v_add_f32_e32 v176, v176, v177
	v_add_f32_e32 v178, v178, v179
	v_add_f32_e32 v176, v176, v178
	v_mov_b32_e32 v177, v176
	s_nop 1
	v_permlane16_swap_b32_e32 v176, v177
	s_waitcnt lgkmcnt(4)
	v_add_f32_e32 v180, v180, v181
	v_add_f32_e32 v182, v182, v183
	v_add_f32_e32 v180, v180, v182
	v_mov_b32_e32 v181, v180
	s_nop 1
	v_permlane16_swap_b32_e32 v180, v181
	s_waitcnt lgkmcnt(3)
	v_add_f32_e32 v184, v184, v185
	v_add_f32_e32 v186, v186, v187
	v_add_f32_e32 v184, v184, v186
	v_mov_b32_e32 v185, v184
	s_nop 1
	v_permlane16_swap_b32_e32 v184, v185
	s_waitcnt lgkmcnt(2)
	v_add_f32_e32 v188, v188, v189
	v_add_f32_e32 v190, v190, v191
	v_add_f32_e32 v188, v188, v190
	v_mov_b32_e32 v189, v188
	s_nop 1
	v_permlane16_swap_b32_e32 v188, v189
	s_waitcnt lgkmcnt(1)
	v_add_f32_e32 v192, v192, v193
	v_add_f32_e32 v194, v194, v195
	v_add_f32_e32 v192, v192, v194
	v_mov_b32_e32 v193, v192
	s_nop 1
	v_permlane16_swap_b32_e32 v192, v193
	s_waitcnt lgkmcnt(0)
	v_add_f32_e32 v196, v196, v197
	v_add_f32_e32 v198, v198, v199
	v_add_f32_e32 v196, v196, v198
	v_mov_b32_e32 v197, v196
	s_nop 1
	v_permlane16_swap_b32_e32 v196, v197
	s_waitcnt lgkmcnt(7)
	v_add_f32_e32 v168, v168, v169
	v_mov_b32_e32 v169, v168
	s_nop 1
	v_permlane32_swap_b32_e32 v168, v169
	s_waitcnt lgkmcnt(7)
	v_add_f32_e32 v172, v172, v173
	v_mov_b32_e32 v173, v172
	s_nop 1
	v_permlane32_swap_b32_e32 v172, v173
	s_waitcnt lgkmcnt(7)
	v_add_f32_e32 v176, v176, v177
	v_mov_b32_e32 v177, v176
	s_nop 1
	v_permlane32_swap_b32_e32 v176, v177
	s_waitcnt lgkmcnt(7)
	v_add_f32_e32 v180, v180, v181
	v_mov_b32_e32 v181, v180
	s_nop 1
	v_permlane32_swap_b32_e32 v180, v181
	s_waitcnt lgkmcnt(7)
	v_add_f32_e32 v184, v184, v185
	v_mov_b32_e32 v185, v184
	s_nop 1
	v_permlane32_swap_b32_e32 v184, v185
	s_waitcnt lgkmcnt(7)
	v_add_f32_e32 v188, v188, v189
	v_mov_b32_e32 v189, v188
	s_nop 1
	v_permlane32_swap_b32_e32 v188, v189
	s_waitcnt lgkmcnt(7)
	v_add_f32_e32 v192, v192, v193
	v_mov_b32_e32 v193, v192
	s_nop 1
	v_permlane32_swap_b32_e32 v192, v193
	s_waitcnt lgkmcnt(7)
	v_add_f32_e32 v196, v196, v197
	v_mov_b32_e32 v197, v196
	s_nop 1
	v_permlane32_swap_b32_e32 v196, v197
	s_waitcnt lgkmcnt(7)
	v_add_f32_e32 v168, v168, v169
	v_fmamk_f32 v168, v168, 0x3a800000, v239
	s_waitcnt lgkmcnt(6)
	v_add_f32_e32 v172, v172, v173
	v_fmamk_f32 v172, v172, 0x3a800000, v239
	s_waitcnt lgkmcnt(5)
	v_add_f32_e32 v176, v176, v177
	v_fmamk_f32 v176, v176, 0x3a800000, v239
	s_waitcnt lgkmcnt(4)
	v_add_f32_e32 v180, v180, v181
	v_fmamk_f32 v180, v180, 0x3a800000, v239
	s_waitcnt lgkmcnt(3)
	v_add_f32_e32 v184, v184, v185
	v_fmamk_f32 v184, v184, 0x3a800000, v239
	s_waitcnt lgkmcnt(2)
	v_add_f32_e32 v188, v188, v189
	v_fmamk_f32 v188, v188, 0x3a800000, v239
	s_waitcnt lgkmcnt(1)
	v_add_f32_e32 v192, v192, v193
	v_fmamk_f32 v192, v192, 0x3a800000, v239
	s_waitcnt lgkmcnt(0)
	v_add_f32_e32 v196, v196, v197
	v_fmamk_f32 v196, v196, 0x3a800000, v239
	v_cmp_gt_f32_e32 vcc, s55, v168
	v_mul_f32_e32 v169, 0x4b800000, v168
	s_nop 0
	v_cndmask_b32_e32 v168, v168, v169, vcc
	v_rsq_f32_e32 v168, v168
	s_nop 0
	v_mul_f32_e32 v169, 0x45800000, v168
	v_cndmask_b32_e32 v164, v168, v169, vcc
	v_cmp_gt_f32_e32 vcc, s55, v172
	v_mul_f32_e32 v173, 0x4b800000, v172
	s_nop 0
	v_cndmask_b32_e32 v172, v172, v173, vcc
	v_rsq_f32_e32 v172, v172
	s_nop 0
	v_mul_f32_e32 v173, 0x45800000, v172
	v_cndmask_b32_e32 v163, v172, v173, vcc
	v_cmp_gt_f32_e32 vcc, s55, v176
	v_mul_f32_e32 v177, 0x4b800000, v176
	s_nop 0
	v_cndmask_b32_e32 v176, v176, v177, vcc
	v_rsq_f32_e32 v176, v176
	s_nop 0
	v_mul_f32_e32 v177, 0x45800000, v176
	v_cndmask_b32_e32 v162, v176, v177, vcc
	v_cmp_gt_f32_e32 vcc, s55, v180
	v_mul_f32_e32 v181, 0x4b800000, v180
	s_nop 0
	v_cndmask_b32_e32 v180, v180, v181, vcc
	v_rsq_f32_e32 v180, v180
	s_nop 0
	v_mul_f32_e32 v181, 0x45800000, v180
	v_cndmask_b32_e32 v161, v180, v181, vcc
	v_cmp_gt_f32_e32 vcc, s55, v184
	v_mul_f32_e32 v185, 0x4b800000, v184
	s_nop 0
	v_cndmask_b32_e32 v184, v184, v185, vcc
	v_rsq_f32_e32 v184, v184
	s_nop 0
	v_mul_f32_e32 v185, 0x45800000, v184
	v_cndmask_b32_e32 v160, v184, v185, vcc
	v_cmp_gt_f32_e32 vcc, s55, v188
	v_mul_f32_e32 v189, 0x4b800000, v188
	s_nop 0
	v_cndmask_b32_e32 v188, v188, v189, vcc
	v_rsq_f32_e32 v188, v188
	s_nop 0
	v_mul_f32_e32 v189, 0x45800000, v188
	v_cndmask_b32_e32 v155, v188, v189, vcc
	v_cmp_gt_f32_e32 vcc, s55, v192
	v_mul_f32_e32 v193, 0x4b800000, v192
	s_nop 0
	v_cndmask_b32_e32 v192, v192, v193, vcc
	v_rsq_f32_e32 v192, v192
	s_nop 0
	v_mul_f32_e32 v193, 0x45800000, v192
	v_cndmask_b32_e32 v153, v192, v193, vcc
	v_cmp_gt_f32_e32 vcc, s55, v196
	v_mul_f32_e32 v197, 0x4b800000, v196
	s_nop 0
	v_cndmask_b32_e32 v196, v196, v197, vcc
	v_rsq_f32_e32 v196, v196
	s_nop 0
	v_mul_f32_e32 v197, 0x45800000, v196
	v_cndmask_b32_e32 v151, v196, v197, vcc

; __device__ __forceinline__ float row_ssq(const float* part, int pitch, int n4, int row, int fq) {
;     f32x4 v = (f32x4){0.f, 0.f, 0.f, 0.f};
;     if (fq < n4) v = *(const f32x4*)(part + (size_t)row * pitch + 4 * fq);
;     float s = (v[0] + v[1]) + (v[2] + v[3]);
;     s += __shfl_xor(s, 16); s += __shfl_xor(s, 32);
;     return s;
;     __device__ __forceinline__ void operator()(const f32x4 (&acc)[2][2][4][2], const Unit& u, int wr, int wc, int fr, int fq) const {
;     ...
;         for (int ai = 0; ai < 2; ++ai)
; #pragma unroll
;             for (int m = 0; m < 4; ++m) rsv[ai][m] = ssq_in ? rsqrtf(row_ssq(ssq_in, in_pitch, in_n4, row0 + ai * HALF + m * 16, fq) * inv_k + EPS) : 1.f;
.LBB0_568:
	v_lshl_add_u32 v154, s40, 8, v145
	v_mov_b32_e32 v130, 0
	v_ashrrev_i32_e32 v155, 31, v154
	s_and_saveexec_b64 s[98:99], s[44:45]
	v_and_b32_e32 v234, 48, v241
	v_lshl_add_u32 v234, v145, 6, v234
	v_add_u32_e32 v234, 0x24000, v234
	ds_read_b128 v[194:197], v234
	ds_read_b128 v[198:201], v234 offset:1024
	ds_read_b128 v[206:209], v234 offset:2048
	ds_read_b128 v[210:213], v234 offset:3072
	ds_read_b128 v[214:217], v234 offset:8192
	ds_read_b128 v[218:221], v234 offset:9216
	ds_read_b128 v[226:229], v234 offset:10240
	ds_read_b128 v[230:233], v234 offset:11264
	s_or_b64 exec, exec, s[98:99]
	v_mov_b32_e32 v132, 0
	v_mov_b32_e32 v156, 0
	v_mov_b32_e32 v157, 0
	v_mov_b32_e32 v133, 0
	s_and_saveexec_b64 s[18:19], s[44:45]
	s_cbranch_execz .LBB0_570
	v_lshlrev_b64 v[132:133], 6, v[154:155]
	v_lshl_add_u64 v[132:133], v[146:147], 0, v[132:133]
	s_waitcnt lgkmcnt(0)
	v_mov_b32_e32 v132, v194
	v_mov_b32_e32 v133, v195
	v_mov_b32_e32 v134, v196
	v_mov_b32_e32 v135, v197
	v_mov_b32_e32 v156, v133
	v_mov_b32_e32 v157, v134
	v_mov_b32_e32 v133, v135
.LBB0_570:
	s_or_b64 exec, exec, s[18:19]
	v_pk_add_f32 v[132:133], v[156:157], v[132:133]
	v_xor_b32_e32 v131, 16, v241
	v_add_f32_e32 v0, v132, v133
	v_and_b32_e32 v132, 64, v241
	v_add_u32_e32 v132, 64, v132
	v_cmp_lt_i32_e32 vcc, v131, v132
	v_or_b32_e32 v162, 16, v154
	v_mov_b32_e32 v134, 0
	v_cndmask_b32_e32 v131, v241, v131, vcc
	v_lshlrev_b32_e32 v176, 2, v131
	v_mov_b32_e32 v131, v0
	s_nop 1
	v_permlane16_swap_b32_e32 v0, v131
	v_mov_b32_e32 v135, 0
	s_waitcnt lgkmcnt(0)
	v_add_f32_e32 v177, v0, v131
	v_xor_b32_e32 v0, 32, v241
	v_cmp_lt_i32_e32 vcc, v0, v132
	v_mov_b32_e32 v131, 0
	s_nop 0
	v_cndmask_b32_e32 v0, v241, v0, vcc
	v_lshlrev_b32_e32 v168, 2, v0
	v_mov_b32_e32 v178, v177
	s_nop 1
	v_permlane32_swap_b32_e32 v177, v178
	s_and_saveexec_b64 s[18:19], s[44:45]
	s_cbranch_execz .LBB0_572
	v_ashrrev_i32_e32 v163, 31, v162
	v_lshlrev_b64 v[130:131], 6, v[162:163]
	v_lshl_add_u64 v[130:131], v[146:147], 0, v[130:131]
	s_waitcnt lgkmcnt(0)
	v_mov_b32_e32 v130, v198
	v_mov_b32_e32 v131, v199
	v_mov_b32_e32 v132, v200
	v_mov_b32_e32 v133, v201
	v_mov_b32_e32 v134, v131
	v_mov_b32_e32 v135, v132
	v_mov_b32_e32 v131, v133
.LBB0_572:
	s_or_b64 exec, exec, s[18:19]
	v_pk_add_f32 v[130:131], v[134:135], v[130:131]
	v_or_b32_e32 v160, 32, v154
	v_add_f32_e32 v0, v130, v131
	v_mov_b32_e32 v131, v0
	s_nop 1
	v_permlane16_swap_b32_e32 v0, v131
	v_mov_b32_e32 v130, 0
	v_mov_b32_e32 v132, 0
	v_mov_b32_e32 v156, 0
	v_mov_b32_e32 v157, 0
	s_waitcnt lgkmcnt(0)
	v_add_f32_e32 v0, v0, v131
	v_mov_b32_e32 v175, v0
	s_nop 1
	v_permlane32_swap_b32_e32 v0, v175
	v_mov_b32_e32 v133, 0
	s_and_saveexec_b64 s[18:19], s[44:45]
	s_cbranch_execz .LBB0_574
	v_ashrrev_i32_e32 v161, 31, v160
	v_lshlrev_b64 v[132:133], 6, v[160:161]
	v_lshl_add_u64 v[132:133], v[146:147], 0, v[132:133]
	s_waitcnt lgkmcnt(0)
	v_mov_b32_e32 v132, v206
	v_mov_b32_e32 v133, v207
	v_mov_b32_e32 v134, v208
	v_mov_b32_e32 v135, v209
	v_mov_b32_e32 v156, v133
	v_mov_b32_e32 v157, v134
	v_mov_b32_e32 v133, v135
.LBB0_574:
	s_or_b64 exec, exec, s[18:19]
	v_pk_add_f32 v[132:133], v[156:157], v[132:133]
	v_or_b32_e32 v158, 48, v154
	v_add_f32_e32 v131, v132, v133
	v_mov_b32_e32 v132, v131
	s_nop 1
	v_permlane16_swap_b32_e32 v131, v132
	v_mov_b32_e32 v134, 0
	v_mov_b32_e32 v135, 0
	s_waitcnt lgkmcnt(0)
	v_add_f32_e32 v173, v131, v132
	v_mov_b32_e32 v174, v173
	s_nop 1
	v_permlane32_swap_b32_e32 v173, v174
	v_mov_b32_e32 v131, 0
	s_and_saveexec_b64 s[18:19], s[44:45]
	s_cbranch_execz .LBB0_576
	v_ashrrev_i32_e32 v159, 31, v158
	v_lshlrev_b64 v[130:131], 6, v[158:159]
	v_lshl_add_u64 v[130:131], v[146:147], 0, v[130:131]
	s_waitcnt lgkmcnt(0)
	v_mov_b32_e32 v130, v210
	v_mov_b32_e32 v131, v211
	v_mov_b32_e32 v132, v212
	v_mov_b32_e32 v133, v213
	v_mov_b32_e32 v134, v131
	v_mov_b32_e32 v135, v132
	v_mov_b32_e32 v131, v133
.LBB0_576:
	s_or_b64 exec, exec, s[18:19]
	v_pk_add_f32 v[130:131], v[134:135], v[130:131]
	v_add_u32_e32 v156, 0x80, v154
	v_add_f32_e32 v130, v130, v131
	v_mov_b32_e32 v131, v130
	s_nop 1
	v_permlane16_swap_b32_e32 v130, v131
	v_mov_b32_e32 v132, 0
	v_mov_b32_e32 v164, 0
	v_mov_b32_e32 v165, 0
	v_mov_b32_e32 v133, 0
	s_waitcnt lgkmcnt(0)
	v_add_f32_e32 v171, v130, v131
	v_mov_b32_e32 v172, v171
	s_nop 1
	v_permlane32_swap_b32_e32 v171, v172
	v_mov_b32_e32 v130, 0
	s_and_saveexec_b64 s[18:19], s[44:45]
	s_cbranch_execz .LBB0_578
	v_ashrrev_i32_e32 v157, 31, v156
	v_lshlrev_b64 v[132:133], 6, v[156:157]
	v_lshl_add_u64 v[132:133], v[146:147], 0, v[132:133]
	s_waitcnt lgkmcnt(0)
	v_mov_b32_e32 v132, v214
	v_mov_b32_e32 v133, v215
	v_mov_b32_e32 v134, v216
	v_mov_b32_e32 v135, v217
	v_mov_b32_e32 v164, v133
	v_mov_b32_e32 v165, v134
	v_mov_b32_e32 v133, v135
.LBB0_578:
	s_or_b64 exec, exec, s[18:19]
	v_pk_add_f32 v[132:133], v[164:165], v[132:133]
	v_mov_b32_e32 v134, 0
	v_add_f32_e32 v131, v132, v133
	v_mov_b32_e32 v132, v131
	s_nop 1
	v_permlane16_swap_b32_e32 v131, v132
	v_mov_b32_e32 v135, 0
	s_waitcnt lgkmcnt(0)
	v_add_f32_e32 v169, v131, v132
	v_mov_b32_e32 v170, v169
	s_nop 1
	v_permlane32_swap_b32_e32 v169, v170
	v_mov_b32_e32 v131, 0
	s_and_saveexec_b64 s[18:19], s[44:45]
	s_cbranch_execz .LBB0_580
	v_lshlrev_b64 v[130:131], 6, v[154:155]
	v_lshl_add_u64 v[130:131], v[146:147], 0, v[130:131]
	v_add_co_u32_e32 v130, vcc, 0x2000, v130
	s_nop 1
	v_addc_co_u32_e32 v131, vcc, 0, v131, vcc
	s_waitcnt lgkmcnt(0)
	v_mov_b32_e32 v130, v218
	v_mov_b32_e32 v131, v219
	v_mov_b32_e32 v132, v220
	v_mov_b32_e32 v133, v221
	v_mov_b32_e32 v134, v131
	v_mov_b32_e32 v135, v132
	v_mov_b32_e32 v131, v133
;     __device__ __forceinline__ void operator()(const f32x4 (&acc)[2][2][4][2], const Unit& u, int wr, int wc, int fr, int fq) const {
;     ...
;             for (int m = 0; m < 4; ++m) rsv[ai][m] = ssq_in ? rsqrtf(row_ssq(ssq_in, in_pitch, in_n4, row0 + ai * HALF + m * 16, fq) * inv_k + EPS) : 1.f;
; #pragma unroll
;         for (int bj = 0; bj < 2; ++bj) {
;             const int c0 = u.pn * BM + bj * HALF + wc * 32;
;             float scale = 1.f; bool sig = false, rp = false, st = true; float* sq = nullptr; int sqp = 0;
;             if (mode == 1) { const int slab = c0 >> 7;
;                 if (slab < 3) { sq = ssq_q + 4 * slab + wc; sqp = 16; } else if (slab < 5) { sq = ssq_kv + 4 * (slab - 3) + wc; sqp = 8; } else if (slab == 5) { rp = (wc == 0); st = (wc == 0); }
;                 else if (slab < 14) scale = C2_64; else if (slab < 18) {} else if (slab < 26) scale = C2_64; else if (slab < 42) {} else sig = true;
;             } else if (mode == 2) { rp = ((c0 % 96) == 64); scale = C2_96; }
;             if (!st) continue;
; #pragma unroll
;             for (int ai = 0; ai < 2; ++ai)
; #pragma unroll
;                 for (int m = 0; m < 4; ++m) {
;                     const int row = row0 + ai * HALF + m * 16; const float rs = rsv[ai][m] * scale;
;                     f32x4 v0 = acc[ai][bj][m][0] * rs, v1 = acc[ai][bj][m][1] * rs;
;                     if (rp) {
;                         const int pos = row & (SEQ - 1); const float* rb = rope + pos * 32 + 8 * (fq & 1); const bool hi2 = (fq >> 1) != 0;
;                         const f32x4 cs0 = *(const f32x4*)(rb), cs1 = *(const f32x4*)(rb + 4), sn0 = *(const f32x4*)(rb + 16), sn1 = *(const f32x4*)(rb + 20);
; #pragma unroll
;                         for (int e = 0; e < 4; ++e) { const float q0 = __shfl_xor(v0[e], 32), q1 = __shfl_xor(v1[e], 32);
;                             v0[e] = hi2 ? v0[e] * cs0[e] + q0 * sn0[e] : v0[e] * cs0[e] - q0 * sn0[e];
;                             v1[e] = hi2 ? v1[e] * cs1[e] + q1 * sn1[e] : v1[e] * cs1[e] - q1 * sn1[e]; } }
.LBB0_580:
	s_or_b64 exec, exec, s[18:19]
	v_pk_add_f32 v[130:131], v[134:135], v[130:131]
	v_mov_b32_e32 v132, 0
	v_add_f32_e32 v130, v130, v131
	v_mov_b32_e32 v131, v130
	s_nop 1
	v_permlane16_swap_b32_e32 v130, v131
	v_mov_b32_e32 v164, 0
	v_mov_b32_e32 v165, 0
	v_mov_b32_e32 v133, 0
	s_waitcnt lgkmcnt(0)
	v_add_f32_e32 v161, v130, v131
	v_mov_b32_e32 v163, v161
	s_nop 1
	v_permlane32_swap_b32_e32 v161, v163
	v_mov_b32_e32 v130, 0
	s_and_saveexec_b64 s[18:19], s[44:45]
	s_cbranch_execz .LBB0_582
	v_lshlrev_b64 v[132:133], 6, v[154:155]
	v_lshl_add_u64 v[132:133], v[146:147], 0, v[132:133]
	v_add_co_u32_e32 v132, vcc, 0x2000, v132
	s_nop 1
	v_addc_co_u32_e32 v133, vcc, 0, v133, vcc
	s_waitcnt lgkmcnt(0)
	v_mov_b32_e32 v132, v226
	v_mov_b32_e32 v133, v227
	v_mov_b32_e32 v134, v228
	v_mov_b32_e32 v135, v229
	v_mov_b32_e32 v164, v133
	v_mov_b32_e32 v165, v134
	v_mov_b32_e32 v133, v135
.LBB0_582:
	s_or_b64 exec, exec, s[18:19]
	v_pk_add_f32 v[132:133], v[164:165], v[132:133]
	v_mov_b32_e32 v134, 0
	v_add_f32_e32 v131, v132, v133
	v_mov_b32_e32 v132, v131
	s_nop 1
	v_permlane16_swap_b32_e32 v131, v132
	v_mov_b32_e32 v135, 0
	s_waitcnt lgkmcnt(0)
	v_add_f32_e32 v157, v131, v132
	v_mov_b32_e32 v159, v157
	s_nop 1
	v_permlane32_swap_b32_e32 v157, v159
	v_mov_b32_e32 v131, 0
	s_and_saveexec_b64 s[18:19], s[44:45]
	s_cbranch_execz .LBB0_584
	v_lshlrev_b64 v[130:131], 6, v[154:155]
	v_lshl_add_u64 v[130:131], v[146:147], 0, v[130:131]
	v_add_co_u32_e32 v130, vcc, 0x2000, v130
	s_nop 1
	v_addc_co_u32_e32 v131, vcc, 0, v131, vcc
	s_waitcnt lgkmcnt(0)
	v_mov_b32_e32 v130, v230
	v_mov_b32_e32 v131, v231
	v_mov_b32_e32 v132, v232
	v_mov_b32_e32 v133, v233
	v_mov_b32_e32 v134, v131
	v_mov_b32_e32 v135, v132
	v_mov_b32_e32 v131, v133
.LBB0_584:
	s_or_b64 exec, exec, s[18:19]
	v_mov_b32_e32 v202, v154
	v_add_f32_e32 v132, v177, v178
	v_pk_add_f32 v[130:131], v[134:135], v[130:131]
	v_fmamk_f32 v132, v132, 0x3b2aaaab, v239
	v_add_f32_e32 v130, v130, v131
	v_mul_f32_e32 v133, 0x4b800000, v132
	v_cmp_gt_f32_e32 vcc, s55, v132
	v_mov_b32_e32 v131, v130
	s_nop 1
	v_permlane16_swap_b32_e32 v130, v131
	s_lshl_b32 s4, s4, 8
	v_cndmask_b32_e32 v132, v132, v133, vcc
	v_rsq_f32_e32 v132, v132
	s_or_b32 s18, s4, s31
	s_mul_hi_i32 s4, s18, 0x2aaaaaab
	s_waitcnt lgkmcnt(0)
	v_add_f32_e32 v131, v130, v131
	s_lshr_b32 s6, s4, 31
	s_lshr_b32 s4, s4, 4
	v_mul_f32_e32 v133, 0x45800000, v132
	ds_bpermute_b32 v134, v168, v131
	s_add_i32 s4, s4, s6
	v_cndmask_b32_e32 v132, v132, v133, vcc
	s_mulk_i32 s4, 0x60
	s_sub_i32 s4, s18, s4
	v_mul_f32_e32 v130, 0x3e16c740, v132
	s_cmp_eq_u32 s4, 64
	v_pk_mul_f32 v[132:133], v[122:123], v[130:131] op_sel_hi:[1,0]
	v_lshlrev_b32_e32 v122, 7, v154
	s_cselect_b64 s[20:21], -1, 0
	s_cmp_lg_u32 s4, 64
	v_pk_mul_f32 v[128:129], v[128:129], v[130:131] op_sel_hi:[1,0]
	v_pk_mul_f32 v[126:127], v[126:127], v[130:131] op_sel_hi:[1,0]
	v_pk_mul_f32 v[124:125], v[124:125], v[130:131] op_sel_hi:[1,0]
	v_and_b32_e32 v122, 0x3e780, v122
	s_cbranch_scc1 .LBB0_586
	v_mov_b32_e32 v123, v1
	v_lshl_add_u64 v[164:165], v[148:149], 0, v[122:123]
	global_load_dwordx4 v[176:179], v[164:165], off offset:16
	global_load_dwordx4 v[180:183], v[164:165], off
	global_load_dwordx4 v[184:187], v[164:165], off offset:80
	global_load_dwordx4 v[188:191], v[164:165], off offset:64
	v_add_u32_e32 v194, 0x10, v202
	v_lshlrev_b32_e32 v194, 7, v194
	v_and_b32_e32 v194, 0x3ff80, v194
	v_mov_b32_e32 v195, v1
	v_lshl_add_u64 v[194:195], v[148:149], 0, v[194:195]
	global_load_dwordx4 v[222:225], v[194:195], off offset:16
	global_load_dwordx4 v[226:229], v[194:195], off
	global_load_dwordx4 v[230:233], v[194:195], off offset:80
	global_load_dwordx4 v[234:237], v[194:195], off offset:64
	ds_bpermute_b32 v164, v168, v126
	ds_bpermute_b32 v192, v168, v132
	ds_bpermute_b32 v165, v168, v127
	ds_bpermute_b32 v193, v168, v133
	s_waitcnt vmcnt(4) lgkmcnt(0)
	v_pk_mul_f32 v[184:185], v[184:185], v[192:193]
	v_pk_mul_f32 v[164:165], v[188:189], v[164:165]
	ds_bpermute_b32 v188, v168, v128
	ds_bpermute_b32 v192, v168, v124
	ds_bpermute_b32 v189, v168, v129
	ds_bpermute_b32 v193, v168, v125
	v_cndmask_b32_e64 v165, v165, -v165, s[46:47]
	v_cndmask_b32_e64 v164, v164, -v164, s[46:47]
	v_pk_fma_f32 v[126:127], v[126:127], v[180:181], v[164:165]
	s_waitcnt lgkmcnt(1)
	v_pk_mul_f32 v[188:189], v[190:191], v[188:189]
	s_waitcnt lgkmcnt(0)
	v_pk_mul_f32 v[164:165], v[186:187], v[192:193]
	v_cndmask_b32_e64 v189, v189, -v189, s[46:47]
	v_cndmask_b32_e64 v188, v188, -v188, s[46:47]
	v_cndmask_b32_e64 v165, v165, -v165, s[46:47]
	v_cndmask_b32_e64 v164, v164, -v164, s[46:47]
	v_cndmask_b32_e64 v181, v185, -v185, s[46:47]
	v_cndmask_b32_e64 v180, v184, -v184, s[46:47]
	v_pk_fma_f32 v[128:129], v[128:129], v[182:183], v[188:189]
	v_pk_fma_f32 v[124:125], v[124:125], v[178:179], v[164:165]
	v_pk_fma_f32 v[132:133], v[132:133], v[176:177], v[180:181]

; __device__ __forceinline__ float row_ssq(const float* part, int pitch, int n4, int row, int fq) {
;     f32x4 v = (f32x4){0.f, 0.f, 0.f, 0.f};
;     if (fq < n4) v = *(const f32x4*)(part + (size_t)row * pitch + 4 * fq);
;     float s = (v[0] + v[1]) + (v[2] + v[3]);
;     s += __shfl_xor(s, 16); s += __shfl_xor(s, 32);
;     return s;
;     __device__ __forceinline__ void operator()(const f32x4 (&acc)[2][2][4][2], const Unit& u, int wr, int wc, int fr, int fq) const {
;     ...
;         for (int ai = 0; ai < 2; ++ai)
; #pragma unroll
;             for (int m = 0; m < 4; ++m) rsv[ai][m] = ssq_in ? rsqrtf(row_ssq(ssq_in, in_pitch, in_n4, row0 + ai * HALF + m * 16, fq) * inv_k + EPS) : 1.f;
.LBB0_638:
	v_lshl_add_u32 v146, s53, 8, v159
	v_mov_b32_e32 v130, 0
	v_ashrrev_i32_e32 v147, 31, v146
	s_and_saveexec_b64 s[98:99], s[44:45]
	v_and_b32_e32 v234, 48, v241
	v_lshl_add_u32 v234, v159, 5, v234
	v_add_u32_e32 v234, 0x24000, v234
	ds_read_b128 v[194:197], v234
	ds_read_b128 v[198:201], v234 offset:512
	ds_read_b128 v[206:209], v234 offset:1024
	ds_read_b128 v[210:213], v234 offset:1536
	ds_read_b128 v[214:217], v234 offset:4096
	ds_read_b128 v[218:221], v234 offset:4608
	ds_read_b128 v[226:229], v234 offset:5120
	ds_read_b128 v[230:233], v234 offset:5632
	s_or_b64 exec, exec, s[98:99]
	v_mov_b32_e32 v132, 0
	v_mov_b32_e32 v148, 0
	v_mov_b32_e32 v149, 0
	v_mov_b32_e32 v133, 0
	s_and_saveexec_b64 s[0:1], s[44:45]
	s_cbranch_execz .LBB0_640
	v_lshlrev_b64 v[132:133], 5, v[146:147]
	v_lshl_add_u64 v[132:133], v[144:145], 0, v[132:133]
	s_waitcnt lgkmcnt(0)
	v_mov_b32_e32 v132, v194
	v_mov_b32_e32 v133, v195
	v_mov_b32_e32 v134, v196
	v_mov_b32_e32 v135, v197
	v_mov_b32_e32 v148, v133
	v_mov_b32_e32 v149, v134
	v_mov_b32_e32 v133, v135
.LBB0_640:
	s_or_b64 exec, exec, s[0:1]
	v_pk_add_f32 v[132:133], v[148:149], v[132:133]
	v_or_b32_e32 v148, 16, v146
	v_add_f32_e32 v131, v132, v133
	v_and_b32_e32 v133, 64, v241
	v_xor_b32_e32 v132, 16, v241
	v_add_u32_e32 v133, 64, v133
	v_cmp_lt_i32_e32 vcc, v132, v133
	v_ashrrev_i32_e32 v149, 31, v148
	v_mov_b32_e32 v134, 0
	v_cndmask_b32_e32 v132, v241, v132, vcc
	v_lshlrev_b32_e32 v167, 2, v132
	v_mov_b32_e32 v132, v131
	s_nop 1
	v_permlane16_swap_b32_e32 v131, v132
	v_mov_b32_e32 v135, 0
	s_waitcnt lgkmcnt(0)
	v_add_f32_e32 v166, v131, v132
	v_xor_b32_e32 v131, 32, v241
	v_cmp_lt_i32_e32 vcc, v131, v133
	s_nop 1
	v_cndmask_b32_e32 v131, v241, v131, vcc
	v_lshlrev_b32_e32 v165, 2, v131
	v_mov_b32_e32 v170, v166
	s_nop 1
	v_permlane32_swap_b32_e32 v166, v170
	v_mov_b32_e32 v131, 0
	s_and_saveexec_b64 s[0:1], s[44:45]
	s_cbranch_execz .LBB0_642
	v_lshlrev_b64 v[130:131], 5, v[148:149]
	v_lshl_add_u64 v[130:131], v[144:145], 0, v[130:131]
	s_waitcnt lgkmcnt(0)
	v_mov_b32_e32 v130, v198
	v_mov_b32_e32 v131, v199
	v_mov_b32_e32 v132, v200
	v_mov_b32_e32 v133, v201
	v_mov_b32_e32 v134, v131
	v_mov_b32_e32 v135, v132
	v_mov_b32_e32 v131, v133
.LBB0_642:
	s_or_b64 exec, exec, s[0:1]
	v_pk_add_f32 v[130:131], v[134:135], v[130:131]
	v_or_b32_e32 v150, 32, v146
	v_add_f32_e32 v131, v130, v131
	v_mov_b32_e32 v132, v131
	s_nop 1
	v_permlane16_swap_b32_e32 v131, v132
	v_mov_b32_e32 v130, 0
	v_ashrrev_i32_e32 v151, 31, v150
	v_mov_b32_e32 v152, 0
	v_mov_b32_e32 v153, 0
	s_waitcnt lgkmcnt(0)
	v_add_f32_e32 v164, v131, v132
	v_mov_b32_e32 v171, v164
	s_nop 1
	v_permlane32_swap_b32_e32 v164, v171
	v_mov_b32_e32 v132, 0
	v_mov_b32_e32 v133, 0
	s_and_saveexec_b64 s[0:1], s[44:45]
	v_readlane_b32 s58, v254, 8
	v_readlane_b32 s30, v251, 4
	v_readlane_b32 s59, v254, 9
	v_readlane_b32 s31, v251, 5
	s_cbranch_execz .LBB0_644
	v_lshlrev_b64 v[132:133], 5, v[150:151]
	v_lshl_add_u64 v[132:133], v[144:145], 0, v[132:133]
	s_waitcnt lgkmcnt(0)
	v_mov_b32_e32 v132, v206
	v_mov_b32_e32 v133, v207
	v_mov_b32_e32 v134, v208
	v_mov_b32_e32 v135, v209
	v_mov_b32_e32 v152, v133
	v_mov_b32_e32 v153, v134
	v_mov_b32_e32 v133, v135
.LBB0_644:
	s_or_b64 exec, exec, s[0:1]
	v_pk_add_f32 v[132:133], v[152:153], v[132:133]
	v_or_b32_e32 v152, 48, v146
	v_add_f32_e32 v131, v132, v133
	v_mov_b32_e32 v132, v131
	s_nop 1
	v_permlane16_swap_b32_e32 v131, v132
	v_ashrrev_i32_e32 v153, 31, v152
	v_mov_b32_e32 v134, 0
	v_mov_b32_e32 v135, 0
	s_waitcnt lgkmcnt(0)
	v_add_f32_e32 v162, v131, v132
	v_mov_b32_e32 v172, v162
	s_nop 1
	v_permlane32_swap_b32_e32 v162, v172
	v_mov_b32_e32 v131, 0
	s_and_saveexec_b64 s[0:1], s[44:45]
	s_cbranch_execz .LBB0_646
	v_lshlrev_b64 v[130:131], 5, v[152:153]
	v_lshl_add_u64 v[130:131], v[144:145], 0, v[130:131]
	s_waitcnt lgkmcnt(0)
	v_mov_b32_e32 v130, v210
	v_mov_b32_e32 v131, v211
	v_mov_b32_e32 v132, v212
	v_mov_b32_e32 v133, v213
	v_mov_b32_e32 v134, v131
	v_mov_b32_e32 v135, v132
	v_mov_b32_e32 v131, v133
.LBB0_646:
	s_or_b64 exec, exec, s[0:1]
	v_pk_add_f32 v[130:131], v[134:135], v[130:131]
	v_add_u32_e32 v154, 0x80, v146
	v_add_f32_e32 v131, v130, v131
	v_mov_b32_e32 v132, v131
	s_nop 1
	v_permlane16_swap_b32_e32 v131, v132
	v_mov_b32_e32 v130, 0
	v_ashrrev_i32_e32 v155, 31, v154
	v_mov_b32_e32 v156, 0
	v_mov_b32_e32 v157, 0
	s_waitcnt lgkmcnt(0)
	v_add_f32_e32 v160, v131, v132
	v_mov_b32_e32 v173, v160
	s_nop 1
	v_permlane32_swap_b32_e32 v160, v173
	v_mov_b32_e32 v132, 0
	v_mov_b32_e32 v133, 0
	s_and_saveexec_b64 s[0:1], s[44:45]
	s_cbranch_execz .LBB0_648
	v_lshlrev_b64 v[132:133], 5, v[154:155]
	v_lshl_add_u64 v[132:133], v[144:145], 0, v[132:133]
	s_waitcnt lgkmcnt(0)
	v_mov_b32_e32 v132, v214
	v_mov_b32_e32 v133, v215
	v_mov_b32_e32 v134, v216
	v_mov_b32_e32 v135, v217
	v_mov_b32_e32 v156, v133
	v_mov_b32_e32 v157, v134
	v_mov_b32_e32 v133, v135
.LBB0_648:
	s_or_b64 exec, exec, s[0:1]
	v_pk_add_f32 v[132:133], v[156:157], v[132:133]
	v_mov_b32_e32 v134, 0
	v_add_f32_e32 v131, v132, v133
	v_mov_b32_e32 v132, v131
	s_nop 1
	v_permlane16_swap_b32_e32 v131, v132
	v_mov_b32_e32 v135, 0
	s_waitcnt lgkmcnt(0)
	v_add_f32_e32 v158, v131, v132
	v_mov_b32_e32 v174, v158
	s_nop 1
	v_permlane32_swap_b32_e32 v158, v174
	v_mov_b32_e32 v131, 0
	s_and_saveexec_b64 s[0:1], s[44:45]
	s_cbranch_execz .LBB0_650
	v_lshlrev_b64 v[130:131], 5, v[146:147]
	v_lshl_add_u64 v[130:131], v[144:145], 0, v[130:131]
	v_add_co_u32_e32 v130, vcc, 0x1000, v130
	s_nop 1
	v_addc_co_u32_e32 v131, vcc, 0, v131, vcc
	s_waitcnt lgkmcnt(0)
	v_mov_b32_e32 v130, v218
	v_mov_b32_e32 v131, v219
	v_mov_b32_e32 v132, v220
	v_mov_b32_e32 v133, v221
	v_mov_b32_e32 v134, v131
	v_mov_b32_e32 v135, v132
	v_mov_b32_e32 v131, v133
;     __device__ __forceinline__ void operator()(const f32x4 (&acc)[2][2][4][2], const Unit& u, int wr, int wc, int fr, int fq) const {
;     ...
;             for (int m = 0; m < 4; ++m) rsv[ai][m] = ssq_in ? rsqrtf(row_ssq(ssq_in, in_pitch, in_n4, row0 + ai * HALF + m * 16, fq) * inv_k + EPS) : 1.f;
; #pragma unroll
;         for (int bj = 0; bj < 2; ++bj) {
;             const int c0 = u.pn * BM + bj * HALF + wc * 32;
;             float scale = 1.f; bool sig = false, rp = false, st = true; float* sq = nullptr; int sqp = 0;
;             if (mode == 1) { const int slab = c0 >> 7;
;                 if (slab < 3) { sq = ssq_q + 4 * slab + wc; sqp = 16; } else if (slab < 5) { sq = ssq_kv + 4 * (slab - 3) + wc; sqp = 8; } else if (slab == 5) { rp = (wc == 0); st = (wc == 0); }
;                 else if (slab < 14) scale = C2_64; else if (slab < 18) {} else if (slab < 26) scale = C2_64; else if (slab < 42) {} else sig = true;
;             } else if (mode == 2) { rp = ((c0 % 96) == 64); scale = C2_96; }
;             if (!st) continue;
; #pragma unroll
;             for (int ai = 0; ai < 2; ++ai)
; #pragma unroll
;                 for (int m = 0; m < 4; ++m) {
;                     const int row = row0 + ai * HALF + m * 16; const float rs = rsv[ai][m] * scale;
;                     f32x4 v0 = acc[ai][bj][m][0] * rs, v1 = acc[ai][bj][m][1] * rs;
;                     if (rp) {
;                         const int pos = row & (SEQ - 1); const float* rb = rope + pos * 32 + 8 * (fq & 1); const bool hi2 = (fq >> 1) != 0;
;                         const f32x4 cs0 = *(const f32x4*)(rb), cs1 = *(const f32x4*)(rb + 4), sn0 = *(const f32x4*)(rb + 16), sn1 = *(const f32x4*)(rb + 20);
; #pragma unroll
;                         for (int e = 0; e < 4; ++e) { const float q0 = __shfl_xor(v0[e], 32), q1 = __shfl_xor(v1[e], 32);
;                             v0[e] = hi2 ? v0[e] * cs0[e] + q0 * sn0[e] : v0[e] * cs0[e] - q0 * sn0[e];
;                             v1[e] = hi2 ? v1[e] * cs1[e] + q1 * sn1[e] : v1[e] * cs1[e] - q1 * sn1[e]; } }
;                     if (sig) {
; #pragma unroll
;                         for (int e = 0; e < 4; ++e) { v0[e] = fast_sigmoid(v0[e]); v1[e] = fast_sigmoid(v1[e]); } }
;                     if (sq) { float s = (v0[0] * v0[0] + v0[1] * v0[1]) + (v0[2] * v0[2] + v0[3] * v0[3]) + (v1[0] * v1[0] + v1[1] * v1[1]) + (v1[2] * v1[2] + v1[3] * v1[3]);
.LBB0_650:
	s_or_b64 exec, exec, s[0:1]
	v_pk_add_f32 v[130:131], v[134:135], v[130:131]
	v_mov_b32_e32 v132, 0
	v_add_f32_e32 v130, v130, v131
	v_mov_b32_e32 v131, v130
	s_nop 1
	v_permlane16_swap_b32_e32 v130, v131
	v_mov_b32_e32 v156, 0
	v_mov_b32_e32 v157, 0
	v_mov_b32_e32 v133, 0
	s_waitcnt lgkmcnt(0)
	v_add_f32_e32 v175, v130, v131
	v_mov_b32_e32 v176, v175
	s_nop 1
	v_permlane32_swap_b32_e32 v175, v176
	v_mov_b32_e32 v130, 0
	s_and_saveexec_b64 s[0:1], s[44:45]
	s_cbranch_execz .LBB0_652
	v_lshlrev_b64 v[132:133], 5, v[146:147]
	v_lshl_add_u64 v[132:133], v[144:145], 0, v[132:133]
	v_add_co_u32_e32 v132, vcc, 0x1000, v132
	s_nop 1
	v_addc_co_u32_e32 v133, vcc, 0, v133, vcc
	s_waitcnt lgkmcnt(0)
	v_mov_b32_e32 v132, v226
	v_mov_b32_e32 v133, v227
	v_mov_b32_e32 v134, v228
	v_mov_b32_e32 v135, v229
	v_mov_b32_e32 v156, v133
	v_mov_b32_e32 v157, v134
	v_mov_b32_e32 v133, v135
.LBB0_652:
	s_or_b64 exec, exec, s[0:1]
	v_pk_add_f32 v[132:133], v[156:157], v[132:133]
	v_add_u32_e32 v156, 0xb0, v146
	v_add_f32_e32 v131, v132, v133
	v_mov_b32_e32 v132, v131
	s_nop 1
	v_permlane16_swap_b32_e32 v131, v132
	v_ashrrev_i32_e32 v157, 31, v156
	v_mov_b32_e32 v168, 0
	v_mov_b32_e32 v169, 0
	s_waitcnt lgkmcnt(0)
	v_add_f32_e32 v134, v131, v132
	v_mov_b32_e32 v135, v134
	s_nop 1
	v_permlane32_swap_b32_e32 v134, v135
	v_mov_b32_e32 v131, 0
	s_and_saveexec_b64 s[0:1], s[44:45]
	s_cbranch_execz .LBB0_654
	v_lshlrev_b64 v[130:131], 5, v[156:157]
	v_lshl_add_u64 v[130:131], v[144:145], 0, v[130:131]
	s_waitcnt lgkmcnt(0)
	v_mov_b32_e32 v130, v230
	v_mov_b32_e32 v131, v231
	v_mov_b32_e32 v132, v232
	v_mov_b32_e32 v133, v233
	v_mov_b32_e32 v168, v131
	v_mov_b32_e32 v169, v132
	v_mov_b32_e32 v131, v133
.LBB0_654:
	s_or_b64 exec, exec, s[0:1]
	s_waitcnt lgkmcnt(0)
	v_add_f32_e32 v132, v134, v135
	v_fmamk_f32 v132, v132, 0x3b800000, v239
	s_mov_b32 s0, 0x800000
	v_cmp_gt_f32_e32 vcc, s0, v132
	v_mul_f32_e32 v133, 0x4b800000, v132
	v_pk_add_f32 v[130:131], v[168:169], v[130:131]
	v_cndmask_b32_e32 v132, v132, v133, vcc
	v_rsq_f32_e32 v132, v132
	v_add_f32_e32 v130, v130, v131
	v_mov_b32_e32 v131, v130
	s_nop 1
	v_permlane16_swap_b32_e32 v130, v131
	v_readlane_b32 s1, v254, 20
	v_mul_f32_e32 v133, 0x45800000, v132
	v_cndmask_b32_e32 v132, v132, v133, vcc
	v_add_f32_e32 v133, v175, v176
	v_fmamk_f32 v133, v133, 0x3b800000, v239
	v_cmp_gt_f32_e32 vcc, s0, v133
	v_mul_f32_e32 v134, 0x4b800000, v133
	s_waitcnt lgkmcnt(0)
	v_add_f32_e32 v130, v130, v131
	v_cndmask_b32_e32 v133, v133, v134, vcc
	v_rsq_f32_e32 v133, v133
	v_mov_b32_e32 v131, v130
	s_nop 1
	v_permlane32_swap_b32_e32 v130, v131
	v_readlane_b32 s10, v250, 45
	v_readlane_b32 s11, v250, 46
	v_mul_f32_e32 v134, 0x45800000, v133
	v_cndmask_b32_e32 v134, v133, v134, vcc
	v_add_f32_e32 v133, v158, v174
	v_fmamk_f32 v133, v133, 0x3b800000, v239
	v_cmp_gt_f32_e32 vcc, s0, v133
	v_mul_f32_e32 v135, 0x4b800000, v133
	s_waitcnt lgkmcnt(0)
	v_add_f32_e32 v130, v130, v131
	v_cndmask_b32_e32 v133, v133, v135, vcc
	v_rsq_f32_e32 v133, v133
	v_fmamk_f32 v130, v130, 0x3b800000, v239
	v_mul_f32_e32 v131, 0x4b800000, v130
	s_mov_b64 s[6:7], 0x90000
	v_mul_f32_e32 v135, 0x45800000, v133
	v_cndmask_b32_e32 v158, v133, v135, vcc
	v_add_f32_e32 v133, v160, v173
	v_fmamk_f32 v133, v133, 0x3b800000, v239
	v_cmp_gt_f32_e32 vcc, s0, v133
	v_mul_f32_e32 v135, 0x4b800000, v133
	v_pk_mul_f32 v[94:95], v[94:95], v[158:159] op_sel_hi:[1,0]
	v_cndmask_b32_e32 v133, v133, v135, vcc
	v_rsq_f32_e32 v133, v133
	v_pk_mul_f32 v[96:97], v[96:97], v[158:159] op_sel_hi:[1,0]
	v_pk_mul_f32 v[32:33], v[32:33], v[158:159] op_sel_hi:[1,0]
	v_pk_mul_f32 v[30:31], v[30:31], v[158:159] op_sel_hi:[1,0]
	v_mul_f32_e32 v135, 0x45800000, v133
	v_cndmask_b32_e32 v160, v133, v135, vcc
	v_add_f32_e32 v133, v162, v172
	v_fmamk_f32 v133, v133, 0x3b800000, v239
	v_cmp_gt_f32_e32 vcc, s0, v133
	v_mul_f32_e32 v135, 0x4b800000, v133
	v_pk_mul_f32 v[102:103], v[102:103], v[160:161] op_sel_hi:[1,0]
	v_cndmask_b32_e32 v133, v133, v135, vcc
	v_rsq_f32_e32 v133, v133
	v_pk_mul_f32 v[104:105], v[104:105], v[160:161] op_sel_hi:[1,0]
	v_pk_mul_f32 v[40:41], v[40:41], v[160:161] op_sel_hi:[1,0]
	v_pk_mul_f32 v[38:39], v[38:39], v[160:161] op_sel_hi:[1,0]
	v_mul_f32_e32 v135, 0x45800000, v133
	v_cndmask_b32_e32 v162, v133, v135, vcc
	v_add_f32_e32 v133, v164, v171
	v_fmamk_f32 v133, v133, 0x3b800000, v239
	v_cmp_gt_f32_e32 vcc, s0, v133
	v_mul_f32_e32 v135, 0x4b800000, v133
	v_pk_mul_f32 v[110:111], v[110:111], v[162:163] op_sel_hi:[1,0]
	v_cndmask_b32_e32 v133, v133, v135, vcc
	v_rsq_f32_e32 v133, v133
	v_pk_mul_f32 v[112:113], v[112:113], v[162:163] op_sel_hi:[1,0]
	v_pk_mul_f32 v[48:49], v[48:49], v[162:163] op_sel_hi:[1,0]
	v_pk_mul_f32 v[46:47], v[46:47], v[162:163] op_sel_hi:[1,0]
	v_mul_f32_e32 v135, 0x45800000, v133
	v_cndmask_b32_e32 v164, v133, v135, vcc
	v_add_f32_e32 v133, v166, v170
	v_fmamk_f32 v133, v133, 0x3b800000, v239
	v_cmp_gt_f32_e32 vcc, s0, v133
	v_mul_f32_e32 v135, 0x4b800000, v133
	v_pk_mul_f32 v[118:119], v[118:119], v[164:165] op_sel_hi:[1,0]
	v_cndmask_b32_e32 v133, v133, v135, vcc
	v_rsq_f32_e32 v133, v133
	v_pk_mul_f32 v[120:121], v[120:121], v[164:165] op_sel_hi:[1,0]
	v_pk_mul_f32 v[58:59], v[58:59], v[164:165] op_sel_hi:[1,0]
	v_mul_f32_e32 v135, 0x45800000, v133
	v_cndmask_b32_e32 v166, v133, v135, vcc
	v_cmp_gt_f32_e32 vcc, s0, v130
	s_lshl_b32 s0, s4, 8
	s_or_b32 s0, s0, s1
	v_pk_mul_f32 v[126:127], v[126:127], v[166:167] op_sel_hi:[1,0]
	s_ashr_i32 s1, s0, 31
	v_pk_mul_f32 v[168:169], v[124:125], v[166:167] op_sel_hi:[1,0]
	v_pk_mul_f32 v[124:125], v[122:123], v[166:167] op_sel_hi:[1,0]
	v_cvt_pk_bf16_f32 v122, v126, v127
; __device__ __forceinline__ unsigned pk2(float lo, float hi) { f32x2_t v = {lo, hi}; bf16x2_t b = __builtin_convertvector(v, bf16x2_t); return __builtin_bit_cast(unsigned, b); }
; __device__ __forceinline__ float fast_sigmoid(float x) { return __builtin_amdgcn_rcpf(1.f + __expf(-x)); }
;     __device__ __forceinline__ void operator()(const f32x4 (&acc)[2][2][4][2], const Unit& u, int wr, int wc, int fr, int fq) const {
;     ...
; #pragma unroll
;             for (int ai = 0; ai < 2; ++ai)
; #pragma unroll
;                 for (int m = 0; m < 4; ++m) {
;                     const int row = row0 + ai * HALF + m * 16; const float rs = rsv[ai][m] * scale;
;                     f32x4 v0 = acc[ai][bj][m][0] * rs, v1 = acc[ai][bj][m][1] * rs;
;                     if (rp) {
;                         const int pos = row & (SEQ - 1); const float* rb = rope + pos * 32 + 8 * (fq & 1); const bool hi2 = (fq >> 1) != 0;
;                         const f32x4 cs0 = *(const f32x4*)(rb), cs1 = *(const f32x4*)(rb + 4), sn0 = *(const f32x4*)(rb + 16), sn1 = *(const f32x4*)(rb + 20);
; #pragma unroll
;                         for (int e = 0; e < 4; ++e) { const float q0 = __shfl_xor(v0[e], 32), q1 = __shfl_xor(v1[e], 32);
;                             v0[e] = hi2 ? v0[e] * cs0[e] + q0 * sn0[e] : v0[e] * cs0[e] - q0 * sn0[e];
;                             v1[e] = hi2 ? v1[e] * cs1[e] + q1 * sn1[e] : v1[e] * cs1[e] - q1 * sn1[e]; } }
;                     if (sig) {
; #pragma unroll
;                         for (int e = 0; e < 4; ++e) { v0[e] = fast_sigmoid(v0[e]); v1[e] = fast_sigmoid(v1[e]); } }
;                     if (sq) { float s = (v0[0] * v0[0] + v0[1] * v0[1]) + (v0[2] * v0[2] + v0[3] * v0[3]) + (v1[0] * v1[0] + v1[1] * v1[1]) + (v1[2] * v1[2] + v1[3] * v1[3]);
;                         s += __shfl_xor(s, 16); s += __shfl_xor(s, 32); if (fq == 0) sq[(size_t)row * sqp] = s; }
;                     u32x4 w; w.x = pk2(v0[0], v0[1]); w.y = pk2(v0[2], v0[3]); w.z = pk2(v1[0], v1[1]); w.w = pk2(v1[2], v1[3]);
;                     *(u32x4*)(O + (size_t)row * ldc + c0 + 8 * fq) = w;
;                 }
	v_lshlrev_b64 v[126:127], 12, v[146:147]
	v_lshl_add_u64 v[126:127], s[10:11], 0, v[126:127]
	s_lshl_b64 s[0:1], s[0:1], 1
	v_pk_mul_f32 v[128:129], v[128:129], v[166:167] op_sel_hi:[1,0]
	v_lshl_add_u64 v[126:127], v[126:127], 0, s[0:1]
	v_cvt_pk_bf16_f32 v123, v128, v129
	v_cvt_pk_bf16_f32 v124, v124, v125
	v_cvt_pk_bf16_f32 v125, v168, v169
	v_lshl_add_u64 v[126:127], v[126:127], 0, v[0:1]
	global_store_dwordx4 v[126:127], v[122:125], off
	v_cndmask_b32_e32 v130, v130, v131, vcc
	v_rsq_f32_e32 v130, v130
	v_pk_mul_f32 v[122:123], v[116:117], v[164:165] op_sel_hi:[1,0]
	v_pk_mul_f32 v[116:117], v[114:115], v[164:165] op_sel_hi:[1,0]
	v_cvt_pk_bf16_f32 v114, v118, v119
	v_lshlrev_b64 v[118:119], 12, v[148:149]
	v_lshl_add_u64 v[118:119], s[10:11], 0, v[118:119]
	v_lshl_add_u64 v[118:119], v[118:119], 0, s[0:1]
	v_cvt_pk_bf16_f32 v115, v120, v121
	v_cvt_pk_bf16_f32 v116, v116, v117
	v_cvt_pk_bf16_f32 v117, v122, v123
	v_lshl_add_u64 v[118:119], v[118:119], 0, v[0:1]
	global_store_dwordx4 v[118:119], v[114:117], off
	v_mul_f32_e32 v131, 0x45800000, v130
	v_pk_mul_f32 v[88:89], v[88:89], v[134:135] op_sel_hi:[1,0]
	v_pk_mul_f32 v[114:115], v[108:109], v[162:163] op_sel_hi:[1,0]
	v_pk_mul_f32 v[108:109], v[106:107], v[162:163] op_sel_hi:[1,0]
	v_cvt_pk_bf16_f32 v106, v110, v111
	v_lshlrev_b64 v[110:111], 12, v[150:151]
	v_lshl_add_u64 v[110:111], s[10:11], 0, v[110:111]
	v_lshl_add_u64 v[110:111], v[110:111], 0, s[0:1]
	v_cvt_pk_bf16_f32 v107, v112, v113
	v_cvt_pk_bf16_f32 v108, v108, v109
	v_cvt_pk_bf16_f32 v109, v114, v115
	v_lshl_add_u64 v[110:111], v[110:111], 0, v[0:1]
	global_store_dwordx4 v[110:111], v[106:109], off
	s_mov_b32 s4, 0x90000
	v_cndmask_b32_e32 v130, v130, v131, vcc
	v_pk_mul_f32 v[106:107], v[100:101], v[160:161] op_sel_hi:[1,0]
	v_pk_mul_f32 v[100:101], v[98:99], v[160:161] op_sel_hi:[1,0]
	v_cvt_pk_bf16_f32 v98, v102, v103
	v_lshlrev_b64 v[102:103], 12, v[152:153]
	v_lshl_add_u64 v[102:103], s[10:11], 0, v[102:103]
	v_lshl_add_u64 v[102:103], v[102:103], 0, s[0:1]
	v_cvt_pk_bf16_f32 v99, v104, v105
	v_cvt_pk_bf16_f32 v100, v100, v101
	v_cvt_pk_bf16_f32 v101, v106, v107
	v_lshl_add_u64 v[102:103], v[102:103], 0, v[0:1]
	global_store_dwordx4 v[102:103], v[98:101], off
	v_pk_mul_f32 v[86:87], v[86:87], v[134:135] op_sel_hi:[1,0]
	v_pk_mul_f32 v[76:77], v[76:77], v[132:133] op_sel_hi:[1,0]
	v_pk_mul_f32 v[98:99], v[92:93], v[158:159] op_sel_hi:[1,0]
	v_pk_mul_f32 v[92:93], v[90:91], v[158:159] op_sel_hi:[1,0]
	v_cvt_pk_bf16_f32 v90, v94, v95
	v_lshlrev_b64 v[94:95], 12, v[154:155]
	v_lshl_add_u64 v[94:95], s[10:11], 0, v[94:95]
	v_lshl_add_u64 v[94:95], v[94:95], 0, s[0:1]
	v_cvt_pk_bf16_f32 v91, v96, v97
	v_cvt_pk_bf16_f32 v92, v92, v93
	v_cvt_pk_bf16_f32 v93, v98, v99
	v_lshl_add_u64 v[94:95], v[94:95], 0, v[0:1]
	global_store_dwordx4 v[94:95], v[90:93], off
	v_pk_mul_f32 v[74:75], v[74:75], v[132:133] op_sel_hi:[1,0]
	v_pk_mul_f32 v[54:55], v[54:55], v[130:131] op_sel_hi:[1,0]
	v_pk_mul_f32 v[90:91], v[84:85], v[134:135] op_sel_hi:[1,0]
	v_pk_mul_f32 v[84:85], v[82:83], v[134:135] op_sel_hi:[1,0]
	v_cvt_pk_bf16_f32 v83, v88, v89
	v_add_co_u32_e32 v88, vcc, s4, v126
	v_cvt_pk_bf16_f32 v82, v86, v87
	v_cvt_pk_bf16_f32 v84, v84, v85
	v_cvt_pk_bf16_f32 v85, v90, v91
	v_addc_co_u32_e32 v89, vcc, 0, v127, vcc
	s_mov_b32 s4, 0xa0000
	global_store_dwordx4 v[88:89], v[82:85], off
	v_pk_mul_f32 v[56:57], v[56:57], v[130:131] op_sel_hi:[1,0]
	v_pk_mul_f32 v[24:25], v[24:25], v[134:135] op_sel_hi:[1,0]
	v_pk_mul_f32 v[82:83], v[68:69], v[132:133] op_sel_hi:[1,0]
	v_pk_mul_f32 v[68:69], v[66:67], v[132:133] op_sel_hi:[1,0]
	v_cvt_pk_bf16_f32 v67, v76, v77
	v_add_co_u32_e32 v76, vcc, s4, v126
	v_cvt_pk_bf16_f32 v66, v74, v75
	v_cvt_pk_bf16_f32 v68, v68, v69
	v_cvt_pk_bf16_f32 v69, v82, v83
	v_addc_co_u32_e32 v77, vcc, 0, v127, vcc
	global_store_dwordx4 v[76:77], v[66:69], off
; __device__ __forceinline__ float fast_sigmoid(float x) { return __builtin_amdgcn_rcpf(1.f + __expf(-x)); }
; template <class Epi>
; __device__ __forceinline__ void gemm_phase(LAS unsigned char* lds, int wave_s, const Gemm g, const StaticOrder S, const Epi E) {
;     ...
;         if (!has_next) break;
; #pragma unroll
;         for (int a = 0; a < 2; ++a)
; #pragma unroll
;             for (int b = 0; b < 2; ++b)
; #pragma unroll
;                 for (int m = 0; m < 4; ++m)
; #pragma unroll
;                     for (int n = 0; n < 2; ++n) acc[a][b][m][n] = (f32x4){0.f, 0.f, 0.f, 0.f};
;         cur = nxt; cA = nA; cB = nB; ++ui;
;         if (wr == 1) PG8_BAR;
;     __device__ __forceinline__ void operator()(const f32x4 (&acc)[2][2][4][2], const Unit& u, int wr, int wc, int fr, int fq) const {
;     ...
;                 for (int m = 0; m < 4; ++m) {
;                     const int row = row0 + ai * HALF + m * 16; const float rs = rsv[ai][m] * scale;
;                     f32x4 v0 = acc[ai][bj][m][0] * rs, v1 = acc[ai][bj][m][1] * rs;
;                     if (rp) {
;                         const int pos = row & (SEQ - 1); const float* rb = rope + pos * 32 + 8 * (fq & 1); const bool hi2 = (fq >> 1) != 0;
;                         const f32x4 cs0 = *(const f32x4*)(rb), cs1 = *(const f32x4*)(rb + 4), sn0 = *(const f32x4*)(rb + 16), sn1 = *(const f32x4*)(rb + 20);
; #pragma unroll
;                         for (int e = 0; e < 4; ++e) { const float q0 = __shfl_xor(v0[e], 32), q1 = __shfl_xor(v1[e], 32);
;                             v0[e] = hi2 ? v0[e] * cs0[e] + q0 * sn0[e] : v0[e] * cs0[e] - q0 * sn0[e];
;                             v1[e] = hi2 ? v1[e] * cs1[e] + q1 * sn1[e] : v1[e] * cs1[e] - q1 * sn1[e]; } }
;                     if (sig) {
; #pragma unroll
;                         for (int e = 0; e < 4; ++e) { v0[e] = fast_sigmoid(v0[e]); v1[e] = fast_sigmoid(v1[e]); } }
;                     if (sq) { float s = (v0[0] * v0[0] + v0[1] * v0[1]) + (v0[2] * v0[2] + v0[3] * v0[3]) + (v1[0] * v1[0] + v1[1] * v1[1]) + (v1[2] * v1[2] + v1[3] * v1[3]);
;                         s += __shfl_xor(s, 16); s += __shfl_xor(s, 32); if (fq == 0) sq[(size_t)row * sqp] = s; }
;                     u32x4 w; w.x = pk2(v0[0], v0[1]); w.y = pk2(v0[2], v0[3]); w.z = pk2(v1[0], v1[1]); w.w = pk2(v1[2], v1[3]);
;                     *(u32x4*)(O + (size_t)row * ldc + c0 + 8 * fq) = w;
	v_pk_mul_f32 v[22:23], v[22:23], v[134:135] op_sel_hi:[1,0]
	v_lshl_add_u64 v[86:87], v[126:127], 0, s[6:7]
	v_pk_mul_f32 v[66:67], v[52:53], v[130:131] op_sel_hi:[1,0]
	v_pk_mul_f32 v[52:53], v[50:51], v[130:131] op_sel_hi:[1,0]
	v_cvt_pk_bf16_f32 v50, v54, v55
	v_lshlrev_b64 v[54:55], 12, v[156:157]
	v_lshl_add_u64 v[54:55], s[10:11], 0, v[54:55]
	v_lshl_add_u64 v[54:55], v[54:55], 0, s[0:1]
	v_cvt_pk_bf16_f32 v51, v56, v57
	v_cvt_pk_bf16_f32 v52, v52, v53
	v_cvt_pk_bf16_f32 v53, v66, v67
	v_lshl_add_u64 v[54:55], v[54:55], 0, v[0:1]
	global_store_dwordx4 v[54:55], v[50:53], off
	v_pk_mul_f32 v[56:57], v[72:73], v[166:167] op_sel_hi:[1,0]
	v_pk_mul_f32 v[66:67], v[70:71], v[166:167] op_sel_hi:[1,0]
	v_pk_mul_f32 v[52:53], v[80:81], v[166:167] op_sel_hi:[1,0]
	v_pk_mul_f32 v[50:51], v[78:79], v[166:167] op_sel_hi:[1,0]
	s_mov_b64 s[6:7], 0xa0000
	v_cvt_pk_bf16_f32 v50, v50, v51
	v_cvt_pk_bf16_f32 v51, v52, v53
	v_cvt_pk_bf16_f32 v52, v66, v67
	v_cvt_pk_bf16_f32 v53, v56, v57
	global_store_dwordx4 v[126:127], v[50:53], off offset:256
	v_pk_mul_f32 v[56:57], v[60:61], v[164:165] op_sel_hi:[1,0]
	v_pk_mul_f32 v[16:17], v[16:17], v[132:133] op_sel_hi:[1,0]
	v_pk_mul_f32 v[52:53], v[64:65], v[164:165] op_sel_hi:[1,0]
	v_pk_mul_f32 v[50:51], v[62:63], v[164:165] op_sel_hi:[1,0]
	v_pk_mul_f32 v[14:15], v[14:15], v[132:133] op_sel_hi:[1,0]
	v_cvt_pk_bf16_f32 v50, v50, v51
	v_cvt_pk_bf16_f32 v51, v52, v53
	v_cvt_pk_bf16_f32 v52, v58, v59
	v_cvt_pk_bf16_f32 v53, v56, v57
	global_store_dwordx4 v[118:119], v[50:53], off offset:256
	v_lshl_add_u64 v[74:75], v[126:127], 0, s[6:7]
	v_pk_mul_f32 v[8:9], v[8:9], v[130:131] op_sel_hi:[1,0]
	v_pk_mul_f32 v[50:51], v[44:45], v[162:163] op_sel_hi:[1,0]
	v_pk_mul_f32 v[44:45], v[42:43], v[162:163] op_sel_hi:[1,0]
	v_cvt_pk_bf16_f32 v42, v46, v47
	v_cvt_pk_bf16_f32 v43, v48, v49
	v_cvt_pk_bf16_f32 v44, v44, v45
	v_cvt_pk_bf16_f32 v45, v50, v51
	global_store_dwordx4 v[110:111], v[42:45], off offset:256
	v_pk_mul_f32 v[6:7], v[6:7], v[130:131] op_sel_hi:[1,0]
	s_mov_b64 s[0:1], -1
	v_pk_mul_f32 v[42:43], v[36:37], v[160:161] op_sel_hi:[1,0]
	v_pk_mul_f32 v[36:37], v[34:35], v[160:161] op_sel_hi:[1,0]
	v_cvt_pk_bf16_f32 v34, v38, v39
	v_cvt_pk_bf16_f32 v35, v40, v41
	v_cvt_pk_bf16_f32 v36, v36, v37
	v_cvt_pk_bf16_f32 v37, v42, v43
	global_store_dwordx4 v[102:103], v[34:37], off offset:256
	s_and_b64 vcc, exec, s[46:47]
	s_nop 0
	v_pk_mul_f32 v[34:35], v[28:29], v[158:159] op_sel_hi:[1,0]
	v_pk_mul_f32 v[28:29], v[26:27], v[158:159] op_sel_hi:[1,0]
	v_cvt_pk_bf16_f32 v26, v30, v31
	v_cvt_pk_bf16_f32 v27, v32, v33
	v_cvt_pk_bf16_f32 v28, v28, v29
	v_cvt_pk_bf16_f32 v29, v34, v35
	global_store_dwordx4 v[94:95], v[26:29], off offset:256
	s_nop 1
	v_pk_mul_f32 v[26:27], v[20:21], v[134:135] op_sel_hi:[1,0]
	v_pk_mul_f32 v[20:21], v[18:19], v[134:135] op_sel_hi:[1,0]
	v_cvt_pk_bf16_f32 v18, v22, v23
	v_cvt_pk_bf16_f32 v19, v24, v25
	v_cvt_pk_bf16_f32 v20, v20, v21
	v_cvt_pk_bf16_f32 v21, v26, v27
	global_store_dwordx4 v[86:87], v[18:21], off offset:256
	s_nop 1
	v_pk_mul_f32 v[18:19], v[12:13], v[132:133] op_sel_hi:[1,0]
	v_pk_mul_f32 v[12:13], v[10:11], v[132:133] op_sel_hi:[1,0]
	v_cvt_pk_bf16_f32 v10, v14, v15
	v_cvt_pk_bf16_f32 v11, v16, v17
	v_cvt_pk_bf16_f32 v12, v12, v13
	v_cvt_pk_bf16_f32 v13, v18, v19
	global_store_dwordx4 v[74:75], v[10:13], off offset:256
	s_nop 1
	v_pk_mul_f32 v[10:11], v[4:5], v[130:131] op_sel_hi:[1,0]
	v_pk_mul_f32 v[4:5], v[2:3], v[130:131] op_sel_hi:[1,0]
	v_cvt_pk_bf16_f32 v2, v6, v7
	v_cvt_pk_bf16_f32 v3, v8, v9
	v_cvt_pk_bf16_f32 v4, v4, v5
	v_cvt_pk_bf16_f32 v5, v10, v11
	global_store_dwordx4 v[54:55], v[2:5], off offset:256
	s_cbranch_vccnz .LBB0_625
	v_readlane_b32 s0, v254, 22
	v_readlane_b32 s1, v254, 23
	s_andn2_b64 vcc, exec, s[0:1]
	s_cbranch_vccnz .LBB0_624
	s_barrier
	s_branch .LBB0_624

; __device__ __forceinline__ float bflo(unsigned u) { return __uint_as_float(u << 16); }
;     __device__ __forceinline__ void operator()(const f32x4 (&acc)[2][2][4][2], const Unit& u, int wr, int wc, int fr, int fq) const {
;         const int row0 = u.pm * BM + wr * 64 + fr, col0 = u.pn * BM + wc * 32 + 8 * fq;
; #pragma unroll
;         for (int ai = 0; ai < 2; ++ai)
; #pragma unroll
;             for (int m = 0; m < 4; ++m) {
;                 const int row = row0 + ai * HALF + m * 16;
;                 float rs = 0.f; if (GATED) rs = rsqrtf(row_ssq(ssq_in, 16, 4, row, fq) * (1.f / 1024.f) + EPS);
;                 float sq = 0.f;
; #pragma unroll
;                 for (int bj = 0; bj < 2; ++bj) {
;                     const size_t off = (size_t)row * DM + col0 + bj * HALF;
;                     const u32x4 hh = *(const u32x4*)(HI + off), ll = *(const u32x4*)(LO + off);
;                     float hv[8] = {bflo(hh.x) + bflo(ll.x), bfhi(hh.x) + bfhi(ll.x), bflo(hh.y) + bflo(ll.y), bfhi(hh.y) + bfhi(ll.y),
;                                    bflo(hh.z) + bflo(ll.z), bfhi(hh.z) + bfhi(ll.z), bflo(hh.w) + bflo(ll.w), bfhi(hh.w) + bfhi(ll.w)};
;                     float av[8] = {acc[ai][bj][m][0][0], acc[ai][bj][m][0][1], acc[ai][bj][m][0][2], acc[ai][bj][m][0][3], acc[ai][bj][m][1][0], acc[ai][bj][m][1][1], acc[ai][bj][m][1][2], acc[ai][bj][m][1][3]};
;                     if (GATED) { const u32x4 pp = *(const u32x4*)(PP + off);
;                         const float pv[8] = {bflo(pp.x), bfhi(pp.x), bflo(pp.y), bfhi(pp.y), bflo(pp.z), bfhi(pp.z), bflo(pp.w), bfhi(pp.w)};
; #pragma unroll
;                         for (int e = 0; e < 8; ++e) av[e] = fast_sigmoid(av[e] * rs) * pv[e]; }
;                     else {
; #pragma unroll
;                         for (int e = 0; e < 8; ++e) av[e] *= alpha; }
;                     float lo[8];
; #pragma unroll
;                     for (int e = 0; e < 8; ++e) { hv[e] += av[e]; sq += hv[e] * hv[e]; }
;                     u32x4 wh; wh.x = pk2(hv[0], hv[1]); wh.y = pk2(hv[2], hv[3]); wh.z = pk2(hv[4], hv[5]); wh.w = pk2(hv[6], hv[7]);
;                     lo[0] = hv[0] - bflo(wh.x); lo[1] = hv[1] - bfhi(wh.x); lo[2] = hv[2] - bflo(wh.y); lo[3] = hv[3] - bfhi(wh.y);
;                     lo[4] = hv[4] - bflo(wh.z); lo[5] = hv[5] - bfhi(wh.z); lo[6] = hv[6] - bflo(wh.w); lo[7] = hv[7] - bfhi(wh.w);
.LBB0_1071:
	v_and_b32_e32 v158, 64, v241
	v_xor_b32_e32 v214, 16, v241
	v_add_u32_e32 v158, 64, v158
	v_cmp_lt_i32_e32 vcc, v214, v158
	v_lshl_add_u32 v156, s40, 8, v160
	v_lshl_or_b32 v157, s4, 8, v162
	v_cndmask_b32_e32 v214, v241, v214, vcc
	v_lshlrev_b32_e32 v214, 2, v214
	v_xor_b32_e32 v215, 32, v241
	v_cmp_lt_i32_e32 vcc, v215, v158
	v_readlane_b32 s10, v254, 18
	v_readlane_b32 s11, v254, 19
	s_nop 1
	v_cndmask_b32_e32 v215, v241, v215, vcc
	v_lshlrev_b32_e32 v215, 2, v215
	v_lshl_add_u32 v213, v156, 10, v157
	v_lshlrev_b32_e32 v213, 1, v213
	s_lshl_b32 s40, s4, 4
	s_lshl_b32 s0, s48, 2
	s_add_i32 s40, s40, s0
	v_lshlrev_b32_e32 v216, 6, v156
	v_add_u32_e32 v216, s40, v216
	v_add_u32_e32 v217, 0x2000, v216
	v_readlane_b32 s30, v251, 4
	v_readlane_b32 s31, v251, 5
	s_nop 1
	v_mov_b32_e32 v210, v213
	global_load_dwordx4 v[140:143], v210, s[10:11]
	global_load_dwordx4 v[144:147], v210, s[14:15]
	global_load_dwordx4 v[148:151], v210, s[10:11] offset:256
	global_load_dwordx4 v[152:155], v210, s[14:15] offset:256
	v_add_u32_e32 v211, 0x8000, v213
	global_load_dwordx4 v[164:167], v211, s[10:11]
	global_load_dwordx4 v[168:171], v211, s[14:15]
	global_load_dwordx4 v[172:175], v211, s[10:11] offset:256
	global_load_dwordx4 v[176:179], v211, s[14:15] offset:256
	v_add_u32_e32 v212, 0x10000, v213
	global_load_dwordx4 v[180:183], v212, s[10:11]
	global_load_dwordx4 v[184:187], v212, s[14:15]
	global_load_dwordx4 v[188:191], v212, s[10:11] offset:256
	global_load_dwordx4 v[192:195], v212, s[14:15] offset:256
	s_waitcnt vmcnt(10)
	v_lshlrev_b32_e32 v156, 16, v140
	v_and_b32_e32 v157, 0xffff0000, v140
	v_lshlrev_b32_e32 v158, 16, v144
	v_and_b32_e32 v159, 0xffff0000, v144
	v_pk_add_f32 v[156:157], v[156:157], v[158:159]
	v_pk_add_f32 v[156:157], v[126:127], v[156:157]
	v_cvt_pk_bf16_f32 v140, v156, v157
	v_pk_mul_f32 v[198:199], v[156:157], v[156:157]
	v_lshlrev_b32_e32 v158, 16, v140
	v_and_b32_e32 v159, 0xffff0000, v140
	v_pk_add_f32 v[196:197], v[156:157], v[158:159] neg_lo:[0,1] neg_hi:[0,1]
	v_cvt_pk_bf16_f32 v144, v196, v197
	v_lshlrev_b32_e32 v156, 16, v141
	v_and_b32_e32 v157, 0xffff0000, v141
	v_lshlrev_b32_e32 v158, 16, v145
	v_and_b32_e32 v159, 0xffff0000, v145
	v_pk_add_f32 v[156:157], v[156:157], v[158:159]
	v_pk_add_f32 v[156:157], v[128:129], v[156:157]
	v_cvt_pk_bf16_f32 v141, v156, v157
	v_pk_fma_f32 v[198:199], v[156:157], v[156:157], v[198:199]
	v_lshlrev_b32_e32 v158, 16, v141
	v_and_b32_e32 v159, 0xffff0000, v141
	v_pk_add_f32 v[196:197], v[156:157], v[158:159] neg_lo:[0,1] neg_hi:[0,1]
	v_cvt_pk_bf16_f32 v145, v196, v197
	v_lshlrev_b32_e32 v156, 16, v142
	v_and_b32_e32 v157, 0xffff0000, v142
	v_lshlrev_b32_e32 v158, 16, v146
	v_and_b32_e32 v159, 0xffff0000, v146
	v_pk_add_f32 v[156:157], v[156:157], v[158:159]
	v_pk_add_f32 v[156:157], v[122:123], v[156:157]
	v_cvt_pk_bf16_f32 v142, v156, v157
	v_pk_fma_f32 v[198:199], v[156:157], v[156:157], v[198:199]
	v_lshlrev_b32_e32 v158, 16, v142
	v_and_b32_e32 v159, 0xffff0000, v142
	v_pk_add_f32 v[196:197], v[156:157], v[158:159] neg_lo:[0,1] neg_hi:[0,1]
	v_cvt_pk_bf16_f32 v146, v196, v197
	v_lshlrev_b32_e32 v156, 16, v143
	v_and_b32_e32 v157, 0xffff0000, v143
	v_lshlrev_b32_e32 v158, 16, v147
	v_and_b32_e32 v159, 0xffff0000, v147
	v_pk_add_f32 v[156:157], v[156:157], v[158:159]
	v_pk_add_f32 v[156:157], v[124:125], v[156:157]
	v_cvt_pk_bf16_f32 v143, v156, v157
	v_pk_fma_f32 v[198:199], v[156:157], v[156:157], v[198:199]
	v_lshlrev_b32_e32 v158, 16, v143
	v_and_b32_e32 v159, 0xffff0000, v143
	v_pk_add_f32 v[196:197], v[156:157], v[158:159] neg_lo:[0,1] neg_hi:[0,1]
	v_cvt_pk_bf16_f32 v147, v196, v197
	global_store_dwordx4 v210, v[140:143], s[10:11]
	global_store_dwordx4 v210, v[144:147], s[14:15]
	s_waitcnt vmcnt(10)
	v_lshlrev_b32_e32 v156, 16, v148
	v_and_b32_e32 v157, 0xffff0000, v148
	v_lshlrev_b32_e32 v158, 16, v152
	v_and_b32_e32 v159, 0xffff0000, v152
	v_pk_add_f32 v[156:157], v[156:157], v[158:159]
	v_pk_add_f32 v[156:157], v[118:119], v[156:157]
	v_cvt_pk_bf16_f32 v148, v156, v157
	v_pk_fma_f32 v[198:199], v[156:157], v[156:157], v[198:199]
	v_lshlrev_b32_e32 v158, 16, v148
	v_and_b32_e32 v159, 0xffff0000, v148
	v_pk_add_f32 v[196:197], v[156:157], v[158:159] neg_lo:[0,1] neg_hi:[0,1]
	v_cvt_pk_bf16_f32 v152, v196, v197
	v_lshlrev_b32_e32 v156, 16, v149
	v_and_b32_e32 v157, 0xffff0000, v149
	v_lshlrev_b32_e32 v158, 16, v153
	v_and_b32_e32 v159, 0xffff0000, v153
	v_pk_add_f32 v[156:157], v[156:157], v[158:159]
	v_pk_add_f32 v[156:157], v[120:121], v[156:157]
	v_cvt_pk_bf16_f32 v149, v156, v157
	v_pk_fma_f32 v[198:199], v[156:157], v[156:157], v[198:199]
	v_lshlrev_b32_e32 v158, 16, v149
	v_and_b32_e32 v159, 0xffff0000, v149
	v_pk_add_f32 v[196:197], v[156:157], v[158:159] neg_lo:[0,1] neg_hi:[0,1]
	v_cvt_pk_bf16_f32 v153, v196, v197
	v_lshlrev_b32_e32 v156, 16, v150
	v_and_b32_e32 v157, 0xffff0000, v150
	v_lshlrev_b32_e32 v158, 16, v154
	v_and_b32_e32 v159, 0xffff0000, v154
	v_pk_add_f32 v[156:157], v[156:157], v[158:159]
	v_pk_add_f32 v[156:157], v[114:115], v[156:157]
	v_cvt_pk_bf16_f32 v150, v156, v157
	v_pk_fma_f32 v[198:199], v[156:157], v[156:157], v[198:199]
	v_lshlrev_b32_e32 v158, 16, v150
	v_and_b32_e32 v159, 0xffff0000, v150
	v_pk_add_f32 v[196:197], v[156:157], v[158:159] neg_lo:[0,1] neg_hi:[0,1]
	v_cvt_pk_bf16_f32 v154, v196, v197
	v_lshlrev_b32_e32 v156, 16, v151
	v_and_b32_e32 v157, 0xffff0000, v151
	v_lshlrev_b32_e32 v158, 16, v155
	v_and_b32_e32 v159, 0xffff0000, v155
	v_pk_add_f32 v[156:157], v[156:157], v[158:159]
	v_pk_add_f32 v[156:157], v[116:117], v[156:157]
	v_cvt_pk_bf16_f32 v151, v156, v157
	v_pk_fma_f32 v[198:199], v[156:157], v[156:157], v[198:199]
	v_lshlrev_b32_e32 v158, 16, v151
	v_and_b32_e32 v159, 0xffff0000, v151
	v_pk_add_f32 v[196:197], v[156:157], v[158:159] neg_lo:[0,1] neg_hi:[0,1]
	v_cvt_pk_bf16_f32 v155, v196, v197
	global_store_dwordx4 v210, v[148:151], s[10:11] offset:256
	global_store_dwordx4 v210, v[152:155], s[14:15] offset:256
	v_add_f32_e32 v200, v198, v199
	s_nop 0
	v_add_u32_e32 v210, 0x18000, v213
	global_load_dwordx4 v[140:143], v210, s[10:11]
	global_load_dwordx4 v[144:147], v210, s[14:15]
	global_load_dwordx4 v[148:151], v210, s[10:11] offset:256
	global_load_dwordx4 v[152:155], v210, s[14:15] offset:256
	s_waitcnt vmcnt(14)
; __device__ __forceinline__ unsigned pk2(float lo, float hi) { f32x2_t v = {lo, hi}; bf16x2_t b = __builtin_convertvector(v, bf16x2_t); return __builtin_bit_cast(unsigned, b); }
; __device__ __forceinline__ float bflo(unsigned u) { return __uint_as_float(u << 16); }
;     __device__ __forceinline__ void operator()(const f32x4 (&acc)[2][2][4][2], const Unit& u, int wr, int wc, int fr, int fq) const {
;     ...
;                 for (int bj = 0; bj < 2; ++bj) {
;                     const size_t off = (size_t)row * DM + col0 + bj * HALF;
;                     const u32x4 hh = *(const u32x4*)(HI + off), ll = *(const u32x4*)(LO + off);
;                     float hv[8] = {bflo(hh.x) + bflo(ll.x), bfhi(hh.x) + bfhi(ll.x), bflo(hh.y) + bflo(ll.y), bfhi(hh.y) + bfhi(ll.y),
;                                    bflo(hh.z) + bflo(ll.z), bfhi(hh.z) + bfhi(ll.z), bflo(hh.w) + bflo(ll.w), bfhi(hh.w) + bfhi(ll.w)};
;                     float av[8] = {acc[ai][bj][m][0][0], acc[ai][bj][m][0][1], acc[ai][bj][m][0][2], acc[ai][bj][m][0][3], acc[ai][bj][m][1][0], acc[ai][bj][m][1][1], acc[ai][bj][m][1][2], acc[ai][bj][m][1][3]};
;                     if (GATED) { const u32x4 pp = *(const u32x4*)(PP + off);
;                         const float pv[8] = {bflo(pp.x), bfhi(pp.x), bflo(pp.y), bfhi(pp.y), bflo(pp.z), bfhi(pp.z), bflo(pp.w), bfhi(pp.w)};
; #pragma unroll
;                         for (int e = 0; e < 8; ++e) av[e] = fast_sigmoid(av[e] * rs) * pv[e]; }
;                     else {
; #pragma unroll
;                         for (int e = 0; e < 8; ++e) av[e] *= alpha; }
;                     float lo[8];
; #pragma unroll
;                     for (int e = 0; e < 8; ++e) { hv[e] += av[e]; sq += hv[e] * hv[e]; }
;                     u32x4 wh; wh.x = pk2(hv[0], hv[1]); wh.y = pk2(hv[2], hv[3]); wh.z = pk2(hv[4], hv[5]); wh.w = pk2(hv[6], hv[7]);
;                     lo[0] = hv[0] - bflo(wh.x); lo[1] = hv[1] - bfhi(wh.x); lo[2] = hv[2] - bflo(wh.y); lo[3] = hv[3] - bfhi(wh.y);
;                     lo[4] = hv[4] - bflo(wh.z); lo[5] = hv[5] - bfhi(wh.z); lo[6] = hv[6] - bflo(wh.w); lo[7] = hv[7] - bfhi(wh.w);
;                     u32x4 wl; wl.x = pk2(lo[0], lo[1]); wl.y = pk2(lo[2], lo[3]); wl.z = pk2(lo[4], lo[5]); wl.w = pk2(lo[6], lo[7]);
;                     *(u32x4*)(HO + off) = wh; *(u32x4*)(LO + off) = wl;
	v_lshlrev_b32_e32 v156, 16, v164
	v_and_b32_e32 v157, 0xffff0000, v164
	v_lshlrev_b32_e32 v158, 16, v168
	v_and_b32_e32 v159, 0xffff0000, v168
	v_pk_add_f32 v[156:157], v[156:157], v[158:159]
	v_pk_add_f32 v[156:157], v[110:111], v[156:157]
	v_cvt_pk_bf16_f32 v164, v156, v157
	v_pk_mul_f32 v[198:199], v[156:157], v[156:157]
	v_lshlrev_b32_e32 v158, 16, v164
	v_and_b32_e32 v159, 0xffff0000, v164
	v_pk_add_f32 v[196:197], v[156:157], v[158:159] neg_lo:[0,1] neg_hi:[0,1]
	v_cvt_pk_bf16_f32 v168, v196, v197
	v_lshlrev_b32_e32 v156, 16, v165
	v_and_b32_e32 v157, 0xffff0000, v165
	v_lshlrev_b32_e32 v158, 16, v169
	v_and_b32_e32 v159, 0xffff0000, v169
	v_pk_add_f32 v[156:157], v[156:157], v[158:159]
	v_pk_add_f32 v[156:157], v[112:113], v[156:157]
	v_cvt_pk_bf16_f32 v165, v156, v157
	v_pk_fma_f32 v[198:199], v[156:157], v[156:157], v[198:199]
	v_lshlrev_b32_e32 v158, 16, v165
	v_and_b32_e32 v159, 0xffff0000, v165
	v_pk_add_f32 v[196:197], v[156:157], v[158:159] neg_lo:[0,1] neg_hi:[0,1]
	v_cvt_pk_bf16_f32 v169, v196, v197
	v_lshlrev_b32_e32 v156, 16, v166
	v_and_b32_e32 v157, 0xffff0000, v166
	v_lshlrev_b32_e32 v158, 16, v170
	v_and_b32_e32 v159, 0xffff0000, v170
	v_pk_add_f32 v[156:157], v[156:157], v[158:159]
	v_pk_add_f32 v[156:157], v[106:107], v[156:157]
	v_cvt_pk_bf16_f32 v166, v156, v157
	v_pk_fma_f32 v[198:199], v[156:157], v[156:157], v[198:199]
	v_lshlrev_b32_e32 v158, 16, v166
	v_and_b32_e32 v159, 0xffff0000, v166
	v_pk_add_f32 v[196:197], v[156:157], v[158:159] neg_lo:[0,1] neg_hi:[0,1]
	v_cvt_pk_bf16_f32 v170, v196, v197
	v_lshlrev_b32_e32 v156, 16, v167
	v_and_b32_e32 v157, 0xffff0000, v167
	v_lshlrev_b32_e32 v158, 16, v171
	v_and_b32_e32 v159, 0xffff0000, v171
	v_pk_add_f32 v[156:157], v[156:157], v[158:159]
	v_pk_add_f32 v[156:157], v[108:109], v[156:157]
	v_cvt_pk_bf16_f32 v167, v156, v157
	v_pk_fma_f32 v[198:199], v[156:157], v[156:157], v[198:199]
	v_lshlrev_b32_e32 v158, 16, v167
	v_and_b32_e32 v159, 0xffff0000, v167
	v_pk_add_f32 v[196:197], v[156:157], v[158:159] neg_lo:[0,1] neg_hi:[0,1]
	v_cvt_pk_bf16_f32 v171, v196, v197
	global_store_dwordx4 v211, v[164:167], s[10:11]
	global_store_dwordx4 v211, v[168:171], s[14:15]
	s_waitcnt vmcnt(14)
	v_lshlrev_b32_e32 v156, 16, v172
	v_and_b32_e32 v157, 0xffff0000, v172
	v_lshlrev_b32_e32 v158, 16, v176
	v_and_b32_e32 v159, 0xffff0000, v176
	v_pk_add_f32 v[156:157], v[156:157], v[158:159]
	v_pk_add_f32 v[156:157], v[102:103], v[156:157]
	v_cvt_pk_bf16_f32 v172, v156, v157
	v_pk_fma_f32 v[198:199], v[156:157], v[156:157], v[198:199]
	v_lshlrev_b32_e32 v158, 16, v172
	v_and_b32_e32 v159, 0xffff0000, v172
	v_pk_add_f32 v[196:197], v[156:157], v[158:159] neg_lo:[0,1] neg_hi:[0,1]
	v_cvt_pk_bf16_f32 v176, v196, v197
	v_lshlrev_b32_e32 v156, 16, v173
	v_and_b32_e32 v157, 0xffff0000, v173
	v_lshlrev_b32_e32 v158, 16, v177
	v_and_b32_e32 v159, 0xffff0000, v177
	v_pk_add_f32 v[156:157], v[156:157], v[158:159]
	v_pk_add_f32 v[156:157], v[104:105], v[156:157]
	v_cvt_pk_bf16_f32 v173, v156, v157
	v_pk_fma_f32 v[198:199], v[156:157], v[156:157], v[198:199]
	v_lshlrev_b32_e32 v158, 16, v173
	v_and_b32_e32 v159, 0xffff0000, v173
	v_pk_add_f32 v[196:197], v[156:157], v[158:159] neg_lo:[0,1] neg_hi:[0,1]
	v_cvt_pk_bf16_f32 v177, v196, v197
	v_lshlrev_b32_e32 v156, 16, v174
	v_and_b32_e32 v157, 0xffff0000, v174
	v_lshlrev_b32_e32 v158, 16, v178
	v_and_b32_e32 v159, 0xffff0000, v178
	v_pk_add_f32 v[156:157], v[156:157], v[158:159]
	v_pk_add_f32 v[156:157], v[98:99], v[156:157]
	v_cvt_pk_bf16_f32 v174, v156, v157
	v_pk_fma_f32 v[198:199], v[156:157], v[156:157], v[198:199]
	v_lshlrev_b32_e32 v158, 16, v174
	v_and_b32_e32 v159, 0xffff0000, v174
	v_pk_add_f32 v[196:197], v[156:157], v[158:159] neg_lo:[0,1] neg_hi:[0,1]
	v_cvt_pk_bf16_f32 v178, v196, v197
	v_lshlrev_b32_e32 v156, 16, v175
	v_and_b32_e32 v157, 0xffff0000, v175
	v_lshlrev_b32_e32 v158, 16, v179
	v_and_b32_e32 v159, 0xffff0000, v179
	v_pk_add_f32 v[156:157], v[156:157], v[158:159]
	v_pk_add_f32 v[156:157], v[100:101], v[156:157]
	v_cvt_pk_bf16_f32 v175, v156, v157
	v_pk_fma_f32 v[198:199], v[156:157], v[156:157], v[198:199]
	v_lshlrev_b32_e32 v158, 16, v175
	v_and_b32_e32 v159, 0xffff0000, v175
	v_pk_add_f32 v[196:197], v[156:157], v[158:159] neg_lo:[0,1] neg_hi:[0,1]
	v_cvt_pk_bf16_f32 v179, v196, v197
	global_store_dwordx4 v211, v[172:175], s[10:11] offset:256
	global_store_dwordx4 v211, v[176:179], s[14:15] offset:256
	v_add_f32_e32 v201, v198, v199
	s_nop 0
	v_add_u32_e32 v211, 0x40000, v213
	global_load_dwordx4 v[164:167], v211, s[10:11]
	global_load_dwordx4 v[168:171], v211, s[14:15]
	global_load_dwordx4 v[172:175], v211, s[10:11] offset:256
	global_load_dwordx4 v[176:179], v211, s[14:15] offset:256
	s_waitcnt vmcnt(18)
; __device__ __forceinline__ unsigned pk2(float lo, float hi) { f32x2_t v = {lo, hi}; bf16x2_t b = __builtin_convertvector(v, bf16x2_t); return __builtin_bit_cast(unsigned, b); }
; __device__ __forceinline__ float bflo(unsigned u) { return __uint_as_float(u << 16); }
;     __device__ __forceinline__ void operator()(const f32x4 (&acc)[2][2][4][2], const Unit& u, int wr, int wc, int fr, int fq) const {
;     ...
;                 for (int bj = 0; bj < 2; ++bj) {
;                     const size_t off = (size_t)row * DM + col0 + bj * HALF;
;                     const u32x4 hh = *(const u32x4*)(HI + off), ll = *(const u32x4*)(LO + off);
;                     float hv[8] = {bflo(hh.x) + bflo(ll.x), bfhi(hh.x) + bfhi(ll.x), bflo(hh.y) + bflo(ll.y), bfhi(hh.y) + bfhi(ll.y),
;                                    bflo(hh.z) + bflo(ll.z), bfhi(hh.z) + bfhi(ll.z), bflo(hh.w) + bflo(ll.w), bfhi(hh.w) + bfhi(ll.w)};
;                     float av[8] = {acc[ai][bj][m][0][0], acc[ai][bj][m][0][1], acc[ai][bj][m][0][2], acc[ai][bj][m][0][3], acc[ai][bj][m][1][0], acc[ai][bj][m][1][1], acc[ai][bj][m][1][2], acc[ai][bj][m][1][3]};
;                     if (GATED) { const u32x4 pp = *(const u32x4*)(PP + off);
;                         const float pv[8] = {bflo(pp.x), bfhi(pp.x), bflo(pp.y), bfhi(pp.y), bflo(pp.z), bfhi(pp.z), bflo(pp.w), bfhi(pp.w)};
; #pragma unroll
;                         for (int e = 0; e < 8; ++e) av[e] = fast_sigmoid(av[e] * rs) * pv[e]; }
;                     else {
; #pragma unroll
;                         for (int e = 0; e < 8; ++e) av[e] *= alpha; }
;                     float lo[8];
; #pragma unroll
;                     for (int e = 0; e < 8; ++e) { hv[e] += av[e]; sq += hv[e] * hv[e]; }
;                     u32x4 wh; wh.x = pk2(hv[0], hv[1]); wh.y = pk2(hv[2], hv[3]); wh.z = pk2(hv[4], hv[5]); wh.w = pk2(hv[6], hv[7]);
;                     lo[0] = hv[0] - bflo(wh.x); lo[1] = hv[1] - bfhi(wh.x); lo[2] = hv[2] - bflo(wh.y); lo[3] = hv[3] - bfhi(wh.y);
;                     lo[4] = hv[4] - bflo(wh.z); lo[5] = hv[5] - bfhi(wh.z); lo[6] = hv[6] - bflo(wh.w); lo[7] = hv[7] - bfhi(wh.w);
;                     u32x4 wl; wl.x = pk2(lo[0], lo[1]); wl.y = pk2(lo[2], lo[3]); wl.z = pk2(lo[4], lo[5]); wl.w = pk2(lo[6], lo[7]);
;                     *(u32x4*)(HO + off) = wh; *(u32x4*)(LO + off) = wl;
	v_lshlrev_b32_e32 v156, 16, v180
	v_and_b32_e32 v157, 0xffff0000, v180
	v_lshlrev_b32_e32 v158, 16, v184
	v_and_b32_e32 v159, 0xffff0000, v184
	v_pk_add_f32 v[156:157], v[156:157], v[158:159]
	v_pk_add_f32 v[156:157], v[94:95], v[156:157]
	v_cvt_pk_bf16_f32 v180, v156, v157
	v_pk_mul_f32 v[198:199], v[156:157], v[156:157]
	v_lshlrev_b32_e32 v158, 16, v180
	v_and_b32_e32 v159, 0xffff0000, v180
	v_pk_add_f32 v[196:197], v[156:157], v[158:159] neg_lo:[0,1] neg_hi:[0,1]
	v_cvt_pk_bf16_f32 v184, v196, v197
	v_lshlrev_b32_e32 v156, 16, v181
	v_and_b32_e32 v157, 0xffff0000, v181
	v_lshlrev_b32_e32 v158, 16, v185
	v_and_b32_e32 v159, 0xffff0000, v185
	v_pk_add_f32 v[156:157], v[156:157], v[158:159]
	v_pk_add_f32 v[156:157], v[96:97], v[156:157]
	v_cvt_pk_bf16_f32 v181, v156, v157
	v_pk_fma_f32 v[198:199], v[156:157], v[156:157], v[198:199]
	v_lshlrev_b32_e32 v158, 16, v181
	v_and_b32_e32 v159, 0xffff0000, v181
	v_pk_add_f32 v[196:197], v[156:157], v[158:159] neg_lo:[0,1] neg_hi:[0,1]
	v_cvt_pk_bf16_f32 v185, v196, v197
	v_lshlrev_b32_e32 v156, 16, v182
	v_and_b32_e32 v157, 0xffff0000, v182
	v_lshlrev_b32_e32 v158, 16, v186
	v_and_b32_e32 v159, 0xffff0000, v186
	v_pk_add_f32 v[156:157], v[156:157], v[158:159]
	v_pk_add_f32 v[156:157], v[90:91], v[156:157]
	v_cvt_pk_bf16_f32 v182, v156, v157
	v_pk_fma_f32 v[198:199], v[156:157], v[156:157], v[198:199]
	v_lshlrev_b32_e32 v158, 16, v182
	v_and_b32_e32 v159, 0xffff0000, v182
	v_pk_add_f32 v[196:197], v[156:157], v[158:159] neg_lo:[0,1] neg_hi:[0,1]
	v_cvt_pk_bf16_f32 v186, v196, v197
	v_lshlrev_b32_e32 v156, 16, v183
	v_and_b32_e32 v157, 0xffff0000, v183
	v_lshlrev_b32_e32 v158, 16, v187
	v_and_b32_e32 v159, 0xffff0000, v187
	v_pk_add_f32 v[156:157], v[156:157], v[158:159]
	v_pk_add_f32 v[156:157], v[92:93], v[156:157]
	v_cvt_pk_bf16_f32 v183, v156, v157
	v_pk_fma_f32 v[198:199], v[156:157], v[156:157], v[198:199]
	v_lshlrev_b32_e32 v158, 16, v183
	v_and_b32_e32 v159, 0xffff0000, v183
	v_pk_add_f32 v[196:197], v[156:157], v[158:159] neg_lo:[0,1] neg_hi:[0,1]
	v_cvt_pk_bf16_f32 v187, v196, v197
	global_store_dwordx4 v212, v[180:183], s[10:11]
	global_store_dwordx4 v212, v[184:187], s[14:15]
	s_waitcnt vmcnt(18)
	v_lshlrev_b32_e32 v156, 16, v188
	v_and_b32_e32 v157, 0xffff0000, v188
	v_lshlrev_b32_e32 v158, 16, v192
	v_and_b32_e32 v159, 0xffff0000, v192
	v_pk_add_f32 v[156:157], v[156:157], v[158:159]
	v_pk_add_f32 v[156:157], v[86:87], v[156:157]
	v_cvt_pk_bf16_f32 v188, v156, v157
	v_pk_fma_f32 v[198:199], v[156:157], v[156:157], v[198:199]
	v_lshlrev_b32_e32 v158, 16, v188
	v_and_b32_e32 v159, 0xffff0000, v188
	v_pk_add_f32 v[196:197], v[156:157], v[158:159] neg_lo:[0,1] neg_hi:[0,1]
	v_cvt_pk_bf16_f32 v192, v196, v197
	v_lshlrev_b32_e32 v156, 16, v189
	v_and_b32_e32 v157, 0xffff0000, v189
	v_lshlrev_b32_e32 v158, 16, v193
	v_and_b32_e32 v159, 0xffff0000, v193
	v_pk_add_f32 v[156:157], v[156:157], v[158:159]
	v_pk_add_f32 v[156:157], v[88:89], v[156:157]
	v_cvt_pk_bf16_f32 v189, v156, v157
	v_pk_fma_f32 v[198:199], v[156:157], v[156:157], v[198:199]
	v_lshlrev_b32_e32 v158, 16, v189
	v_and_b32_e32 v159, 0xffff0000, v189
	v_pk_add_f32 v[196:197], v[156:157], v[158:159] neg_lo:[0,1] neg_hi:[0,1]
	v_cvt_pk_bf16_f32 v193, v196, v197
	v_lshlrev_b32_e32 v156, 16, v190
	v_and_b32_e32 v157, 0xffff0000, v190
	v_lshlrev_b32_e32 v158, 16, v194
	v_and_b32_e32 v159, 0xffff0000, v194
	v_pk_add_f32 v[156:157], v[156:157], v[158:159]
	v_pk_add_f32 v[156:157], v[82:83], v[156:157]
	v_cvt_pk_bf16_f32 v190, v156, v157
	v_pk_fma_f32 v[198:199], v[156:157], v[156:157], v[198:199]
	v_lshlrev_b32_e32 v158, 16, v190
	v_and_b32_e32 v159, 0xffff0000, v190
	v_pk_add_f32 v[196:197], v[156:157], v[158:159] neg_lo:[0,1] neg_hi:[0,1]
	v_cvt_pk_bf16_f32 v194, v196, v197
	v_lshlrev_b32_e32 v156, 16, v191
	v_and_b32_e32 v157, 0xffff0000, v191
	v_lshlrev_b32_e32 v158, 16, v195
	v_and_b32_e32 v159, 0xffff0000, v195
	v_pk_add_f32 v[156:157], v[156:157], v[158:159]
	v_pk_add_f32 v[156:157], v[84:85], v[156:157]
	v_cvt_pk_bf16_f32 v191, v156, v157
	v_pk_fma_f32 v[198:199], v[156:157], v[156:157], v[198:199]
	v_lshlrev_b32_e32 v158, 16, v191
	v_and_b32_e32 v159, 0xffff0000, v191
	v_pk_add_f32 v[196:197], v[156:157], v[158:159] neg_lo:[0,1] neg_hi:[0,1]
	v_cvt_pk_bf16_f32 v195, v196, v197
	global_store_dwordx4 v212, v[188:191], s[10:11] offset:256
	global_store_dwordx4 v212, v[192:195], s[14:15] offset:256
	v_add_f32_e32 v202, v198, v199
	s_nop 0
	v_add_u32_e32 v212, 0x48000, v213
	global_load_dwordx4 v[180:183], v212, s[10:11]
	global_load_dwordx4 v[184:187], v212, s[14:15]
	global_load_dwordx4 v[188:191], v212, s[10:11] offset:256
	global_load_dwordx4 v[192:195], v212, s[14:15] offset:256
	s_waitcnt vmcnt(18)
; __device__ __forceinline__ unsigned pk2(float lo, float hi) { f32x2_t v = {lo, hi}; bf16x2_t b = __builtin_convertvector(v, bf16x2_t); return __builtin_bit_cast(unsigned, b); }
; __device__ __forceinline__ float bflo(unsigned u) { return __uint_as_float(u << 16); }
;     __device__ __forceinline__ void operator()(const f32x4 (&acc)[2][2][4][2], const Unit& u, int wr, int wc, int fr, int fq) const {
;     ...
;                 for (int bj = 0; bj < 2; ++bj) {
;                     const size_t off = (size_t)row * DM + col0 + bj * HALF;
;                     const u32x4 hh = *(const u32x4*)(HI + off), ll = *(const u32x4*)(LO + off);
;                     float hv[8] = {bflo(hh.x) + bflo(ll.x), bfhi(hh.x) + bfhi(ll.x), bflo(hh.y) + bflo(ll.y), bfhi(hh.y) + bfhi(ll.y),
;                                    bflo(hh.z) + bflo(ll.z), bfhi(hh.z) + bfhi(ll.z), bflo(hh.w) + bflo(ll.w), bfhi(hh.w) + bfhi(ll.w)};
;                     float av[8] = {acc[ai][bj][m][0][0], acc[ai][bj][m][0][1], acc[ai][bj][m][0][2], acc[ai][bj][m][0][3], acc[ai][bj][m][1][0], acc[ai][bj][m][1][1], acc[ai][bj][m][1][2], acc[ai][bj][m][1][3]};
;                     if (GATED) { const u32x4 pp = *(const u32x4*)(PP + off);
;                         const float pv[8] = {bflo(pp.x), bfhi(pp.x), bflo(pp.y), bfhi(pp.y), bflo(pp.z), bfhi(pp.z), bflo(pp.w), bfhi(pp.w)};
; #pragma unroll
;                         for (int e = 0; e < 8; ++e) av[e] = fast_sigmoid(av[e] * rs) * pv[e]; }
;                     else {
; #pragma unroll
;                         for (int e = 0; e < 8; ++e) av[e] *= alpha; }
;                     float lo[8];
; #pragma unroll
;                     for (int e = 0; e < 8; ++e) { hv[e] += av[e]; sq += hv[e] * hv[e]; }
;                     u32x4 wh; wh.x = pk2(hv[0], hv[1]); wh.y = pk2(hv[2], hv[3]); wh.z = pk2(hv[4], hv[5]); wh.w = pk2(hv[6], hv[7]);
;                     lo[0] = hv[0] - bflo(wh.x); lo[1] = hv[1] - bfhi(wh.x); lo[2] = hv[2] - bflo(wh.y); lo[3] = hv[3] - bfhi(wh.y);
;                     lo[4] = hv[4] - bflo(wh.z); lo[5] = hv[5] - bfhi(wh.z); lo[6] = hv[6] - bflo(wh.w); lo[7] = hv[7] - bfhi(wh.w);
;                     u32x4 wl; wl.x = pk2(lo[0], lo[1]); wl.y = pk2(lo[2], lo[3]); wl.z = pk2(lo[4], lo[5]); wl.w = pk2(lo[6], lo[7]);
;                     *(u32x4*)(HO + off) = wh; *(u32x4*)(LO + off) = wl;
;                 }
	v_lshlrev_b32_e32 v156, 16, v140
	v_and_b32_e32 v157, 0xffff0000, v140
	v_lshlrev_b32_e32 v158, 16, v144
	v_and_b32_e32 v159, 0xffff0000, v144
	v_pk_add_f32 v[156:157], v[156:157], v[158:159]
	v_pk_add_f32 v[156:157], v[78:79], v[156:157]
	v_cvt_pk_bf16_f32 v140, v156, v157
	v_pk_mul_f32 v[198:199], v[156:157], v[156:157]
	v_lshlrev_b32_e32 v158, 16, v140
	v_and_b32_e32 v159, 0xffff0000, v140
	v_pk_add_f32 v[196:197], v[156:157], v[158:159] neg_lo:[0,1] neg_hi:[0,1]
	v_cvt_pk_bf16_f32 v144, v196, v197
	v_lshlrev_b32_e32 v156, 16, v141
	v_and_b32_e32 v157, 0xffff0000, v141
	v_lshlrev_b32_e32 v158, 16, v145
	v_and_b32_e32 v159, 0xffff0000, v145
	v_pk_add_f32 v[156:157], v[156:157], v[158:159]
	v_pk_add_f32 v[156:157], v[80:81], v[156:157]
	v_cvt_pk_bf16_f32 v141, v156, v157
	v_pk_fma_f32 v[198:199], v[156:157], v[156:157], v[198:199]
	v_lshlrev_b32_e32 v158, 16, v141
	v_and_b32_e32 v159, 0xffff0000, v141
	v_pk_add_f32 v[196:197], v[156:157], v[158:159] neg_lo:[0,1] neg_hi:[0,1]
	v_cvt_pk_bf16_f32 v145, v196, v197
	v_lshlrev_b32_e32 v156, 16, v142
	v_and_b32_e32 v157, 0xffff0000, v142
	v_lshlrev_b32_e32 v158, 16, v146
	v_and_b32_e32 v159, 0xffff0000, v146
	v_pk_add_f32 v[156:157], v[156:157], v[158:159]
	v_pk_add_f32 v[156:157], v[74:75], v[156:157]
	v_cvt_pk_bf16_f32 v142, v156, v157
	v_pk_fma_f32 v[198:199], v[156:157], v[156:157], v[198:199]
	v_lshlrev_b32_e32 v158, 16, v142
	v_and_b32_e32 v159, 0xffff0000, v142
	v_pk_add_f32 v[196:197], v[156:157], v[158:159] neg_lo:[0,1] neg_hi:[0,1]
	v_cvt_pk_bf16_f32 v146, v196, v197
	v_lshlrev_b32_e32 v156, 16, v143
	v_and_b32_e32 v157, 0xffff0000, v143
	v_lshlrev_b32_e32 v158, 16, v147
	v_and_b32_e32 v159, 0xffff0000, v147
	v_pk_add_f32 v[156:157], v[156:157], v[158:159]
	v_pk_add_f32 v[156:157], v[76:77], v[156:157]
	v_cvt_pk_bf16_f32 v143, v156, v157
	v_pk_fma_f32 v[198:199], v[156:157], v[156:157], v[198:199]
	v_lshlrev_b32_e32 v158, 16, v143
	v_and_b32_e32 v159, 0xffff0000, v143
	v_pk_add_f32 v[196:197], v[156:157], v[158:159] neg_lo:[0,1] neg_hi:[0,1]
	v_cvt_pk_bf16_f32 v147, v196, v197
	global_store_dwordx4 v210, v[140:143], s[10:11]
	global_store_dwordx4 v210, v[144:147], s[14:15]
	s_waitcnt vmcnt(18)
	v_lshlrev_b32_e32 v156, 16, v148
	v_and_b32_e32 v157, 0xffff0000, v148
	v_lshlrev_b32_e32 v158, 16, v152
	v_and_b32_e32 v159, 0xffff0000, v152
	v_pk_add_f32 v[156:157], v[156:157], v[158:159]
	v_pk_add_f32 v[156:157], v[70:71], v[156:157]
	v_cvt_pk_bf16_f32 v148, v156, v157
	v_pk_fma_f32 v[198:199], v[156:157], v[156:157], v[198:199]
	v_lshlrev_b32_e32 v158, 16, v148
	v_and_b32_e32 v159, 0xffff0000, v148
	v_pk_add_f32 v[196:197], v[156:157], v[158:159] neg_lo:[0,1] neg_hi:[0,1]
	v_cvt_pk_bf16_f32 v152, v196, v197
	v_lshlrev_b32_e32 v156, 16, v149
	v_and_b32_e32 v157, 0xffff0000, v149
	v_lshlrev_b32_e32 v158, 16, v153
	v_and_b32_e32 v159, 0xffff0000, v153
	v_pk_add_f32 v[156:157], v[156:157], v[158:159]
	v_pk_add_f32 v[156:157], v[72:73], v[156:157]
	v_cvt_pk_bf16_f32 v149, v156, v157
	v_pk_fma_f32 v[198:199], v[156:157], v[156:157], v[198:199]
	v_lshlrev_b32_e32 v158, 16, v149
	v_and_b32_e32 v159, 0xffff0000, v149
	v_pk_add_f32 v[196:197], v[156:157], v[158:159] neg_lo:[0,1] neg_hi:[0,1]
	v_cvt_pk_bf16_f32 v153, v196, v197
	v_lshlrev_b32_e32 v156, 16, v150
	v_and_b32_e32 v157, 0xffff0000, v150
	v_lshlrev_b32_e32 v158, 16, v154
	v_and_b32_e32 v159, 0xffff0000, v154
	v_pk_add_f32 v[156:157], v[156:157], v[158:159]
	v_pk_add_f32 v[156:157], v[66:67], v[156:157]
	v_cvt_pk_bf16_f32 v150, v156, v157
	v_pk_fma_f32 v[198:199], v[156:157], v[156:157], v[198:199]
	v_lshlrev_b32_e32 v158, 16, v150
	v_and_b32_e32 v159, 0xffff0000, v150
	v_pk_add_f32 v[196:197], v[156:157], v[158:159] neg_lo:[0,1] neg_hi:[0,1]
	v_cvt_pk_bf16_f32 v154, v196, v197
	v_lshlrev_b32_e32 v156, 16, v151
	v_and_b32_e32 v157, 0xffff0000, v151
	v_lshlrev_b32_e32 v158, 16, v155
	v_and_b32_e32 v159, 0xffff0000, v155
	v_pk_add_f32 v[156:157], v[156:157], v[158:159]
	v_pk_add_f32 v[156:157], v[68:69], v[156:157]
	v_cvt_pk_bf16_f32 v151, v156, v157
	v_pk_fma_f32 v[198:199], v[156:157], v[156:157], v[198:199]
	v_lshlrev_b32_e32 v158, 16, v151
	v_and_b32_e32 v159, 0xffff0000, v151
	v_pk_add_f32 v[196:197], v[156:157], v[158:159] neg_lo:[0,1] neg_hi:[0,1]
	v_cvt_pk_bf16_f32 v155, v196, v197
	global_store_dwordx4 v210, v[148:151], s[10:11] offset:256
	global_store_dwordx4 v210, v[152:155], s[14:15] offset:256
	v_add_f32_e32 v203, v198, v199
	s_nop 0
	v_add_u32_e32 v210, 0x50000, v213
	global_load_dwordx4 v[140:143], v210, s[10:11]
	global_load_dwordx4 v[144:147], v210, s[14:15]
	global_load_dwordx4 v[148:151], v210, s[10:11] offset:256
	global_load_dwordx4 v[152:155], v210, s[14:15] offset:256
	s_waitcnt vmcnt(18)
; __device__ __forceinline__ unsigned pk2(float lo, float hi) { f32x2_t v = {lo, hi}; bf16x2_t b = __builtin_convertvector(v, bf16x2_t); return __builtin_bit_cast(unsigned, b); }
; __device__ __forceinline__ float bflo(unsigned u) { return __uint_as_float(u << 16); }
;     __device__ __forceinline__ void operator()(const f32x4 (&acc)[2][2][4][2], const Unit& u, int wr, int wc, int fr, int fq) const {
;     ...
;                 for (int bj = 0; bj < 2; ++bj) {
;                     const size_t off = (size_t)row * DM + col0 + bj * HALF;
;                     const u32x4 hh = *(const u32x4*)(HI + off), ll = *(const u32x4*)(LO + off);
;                     float hv[8] = {bflo(hh.x) + bflo(ll.x), bfhi(hh.x) + bfhi(ll.x), bflo(hh.y) + bflo(ll.y), bfhi(hh.y) + bfhi(ll.y),
;                                    bflo(hh.z) + bflo(ll.z), bfhi(hh.z) + bfhi(ll.z), bflo(hh.w) + bflo(ll.w), bfhi(hh.w) + bfhi(ll.w)};
;                     float av[8] = {acc[ai][bj][m][0][0], acc[ai][bj][m][0][1], acc[ai][bj][m][0][2], acc[ai][bj][m][0][3], acc[ai][bj][m][1][0], acc[ai][bj][m][1][1], acc[ai][bj][m][1][2], acc[ai][bj][m][1][3]};
;                     if (GATED) { const u32x4 pp = *(const u32x4*)(PP + off);
;                         const float pv[8] = {bflo(pp.x), bfhi(pp.x), bflo(pp.y), bfhi(pp.y), bflo(pp.z), bfhi(pp.z), bflo(pp.w), bfhi(pp.w)};
; #pragma unroll
;                         for (int e = 0; e < 8; ++e) av[e] = fast_sigmoid(av[e] * rs) * pv[e]; }
;                     else {
; #pragma unroll
;                         for (int e = 0; e < 8; ++e) av[e] *= alpha; }
;                     float lo[8];
; #pragma unroll
;                     for (int e = 0; e < 8; ++e) { hv[e] += av[e]; sq += hv[e] * hv[e]; }
;                     u32x4 wh; wh.x = pk2(hv[0], hv[1]); wh.y = pk2(hv[2], hv[3]); wh.z = pk2(hv[4], hv[5]); wh.w = pk2(hv[6], hv[7]);
;                     lo[0] = hv[0] - bflo(wh.x); lo[1] = hv[1] - bfhi(wh.x); lo[2] = hv[2] - bflo(wh.y); lo[3] = hv[3] - bfhi(wh.y);
;                     lo[4] = hv[4] - bflo(wh.z); lo[5] = hv[5] - bfhi(wh.z); lo[6] = hv[6] - bflo(wh.w); lo[7] = hv[7] - bfhi(wh.w);
;                     u32x4 wl; wl.x = pk2(lo[0], lo[1]); wl.y = pk2(lo[2], lo[3]); wl.z = pk2(lo[4], lo[5]); wl.w = pk2(lo[6], lo[7]);
;                     *(u32x4*)(HO + off) = wh; *(u32x4*)(LO + off) = wl;
;                 }
	v_lshlrev_b32_e32 v156, 16, v164
	v_and_b32_e32 v157, 0xffff0000, v164
	v_lshlrev_b32_e32 v158, 16, v168
	v_and_b32_e32 v159, 0xffff0000, v168
	v_pk_add_f32 v[156:157], v[156:157], v[158:159]
	v_pk_add_f32 v[156:157], v[62:63], v[156:157]
	v_cvt_pk_bf16_f32 v164, v156, v157
	v_pk_mul_f32 v[198:199], v[156:157], v[156:157]
	v_lshlrev_b32_e32 v158, 16, v164
	v_and_b32_e32 v159, 0xffff0000, v164
	v_pk_add_f32 v[196:197], v[156:157], v[158:159] neg_lo:[0,1] neg_hi:[0,1]
	v_cvt_pk_bf16_f32 v168, v196, v197
	v_lshlrev_b32_e32 v156, 16, v165
	v_and_b32_e32 v157, 0xffff0000, v165
	v_lshlrev_b32_e32 v158, 16, v169
	v_and_b32_e32 v159, 0xffff0000, v169
	v_pk_add_f32 v[156:157], v[156:157], v[158:159]
	v_pk_add_f32 v[156:157], v[64:65], v[156:157]
	v_cvt_pk_bf16_f32 v165, v156, v157
	v_pk_fma_f32 v[198:199], v[156:157], v[156:157], v[198:199]
	v_lshlrev_b32_e32 v158, 16, v165
	v_and_b32_e32 v159, 0xffff0000, v165
	v_pk_add_f32 v[196:197], v[156:157], v[158:159] neg_lo:[0,1] neg_hi:[0,1]
	v_cvt_pk_bf16_f32 v169, v196, v197
	v_lshlrev_b32_e32 v156, 16, v166
	v_and_b32_e32 v157, 0xffff0000, v166
	v_lshlrev_b32_e32 v158, 16, v170
	v_and_b32_e32 v159, 0xffff0000, v170
	v_pk_add_f32 v[156:157], v[156:157], v[158:159]
	v_pk_add_f32 v[156:157], v[58:59], v[156:157]
	v_cvt_pk_bf16_f32 v166, v156, v157
	v_pk_fma_f32 v[198:199], v[156:157], v[156:157], v[198:199]
	v_lshlrev_b32_e32 v158, 16, v166
	v_and_b32_e32 v159, 0xffff0000, v166
	v_pk_add_f32 v[196:197], v[156:157], v[158:159] neg_lo:[0,1] neg_hi:[0,1]
	v_cvt_pk_bf16_f32 v170, v196, v197
	v_lshlrev_b32_e32 v156, 16, v167
	v_and_b32_e32 v157, 0xffff0000, v167
	v_lshlrev_b32_e32 v158, 16, v171
	v_and_b32_e32 v159, 0xffff0000, v171
	v_pk_add_f32 v[156:157], v[156:157], v[158:159]
	v_pk_add_f32 v[156:157], v[60:61], v[156:157]
	v_cvt_pk_bf16_f32 v167, v156, v157
	v_pk_fma_f32 v[198:199], v[156:157], v[156:157], v[198:199]
	v_lshlrev_b32_e32 v158, 16, v167
	v_and_b32_e32 v159, 0xffff0000, v167
	v_pk_add_f32 v[196:197], v[156:157], v[158:159] neg_lo:[0,1] neg_hi:[0,1]
	v_cvt_pk_bf16_f32 v171, v196, v197
	global_store_dwordx4 v211, v[164:167], s[10:11]
	global_store_dwordx4 v211, v[168:171], s[14:15]
	s_waitcnt vmcnt(18)
	v_lshlrev_b32_e32 v156, 16, v172
	v_and_b32_e32 v157, 0xffff0000, v172
	v_lshlrev_b32_e32 v158, 16, v176
	v_and_b32_e32 v159, 0xffff0000, v176
	v_pk_add_f32 v[156:157], v[156:157], v[158:159]
	v_pk_add_f32 v[156:157], v[54:55], v[156:157]
	v_cvt_pk_bf16_f32 v172, v156, v157
	v_pk_fma_f32 v[198:199], v[156:157], v[156:157], v[198:199]
	v_lshlrev_b32_e32 v158, 16, v172
	v_and_b32_e32 v159, 0xffff0000, v172
	v_pk_add_f32 v[196:197], v[156:157], v[158:159] neg_lo:[0,1] neg_hi:[0,1]
	v_cvt_pk_bf16_f32 v176, v196, v197
	v_lshlrev_b32_e32 v156, 16, v173
	v_and_b32_e32 v157, 0xffff0000, v173
	v_lshlrev_b32_e32 v158, 16, v177
	v_and_b32_e32 v159, 0xffff0000, v177
	v_pk_add_f32 v[156:157], v[156:157], v[158:159]
	v_pk_add_f32 v[156:157], v[56:57], v[156:157]
	v_cvt_pk_bf16_f32 v173, v156, v157
	v_pk_fma_f32 v[198:199], v[156:157], v[156:157], v[198:199]
	v_lshlrev_b32_e32 v158, 16, v173
	v_and_b32_e32 v159, 0xffff0000, v173
	v_pk_add_f32 v[196:197], v[156:157], v[158:159] neg_lo:[0,1] neg_hi:[0,1]
	v_cvt_pk_bf16_f32 v177, v196, v197
	v_lshlrev_b32_e32 v156, 16, v174
	v_and_b32_e32 v157, 0xffff0000, v174
	v_lshlrev_b32_e32 v158, 16, v178
	v_and_b32_e32 v159, 0xffff0000, v178
	v_pk_add_f32 v[156:157], v[156:157], v[158:159]
	v_pk_add_f32 v[156:157], v[50:51], v[156:157]
	v_cvt_pk_bf16_f32 v174, v156, v157
	v_pk_fma_f32 v[198:199], v[156:157], v[156:157], v[198:199]
	v_lshlrev_b32_e32 v158, 16, v174
	v_and_b32_e32 v159, 0xffff0000, v174
	v_pk_add_f32 v[196:197], v[156:157], v[158:159] neg_lo:[0,1] neg_hi:[0,1]
	v_cvt_pk_bf16_f32 v178, v196, v197
	v_lshlrev_b32_e32 v156, 16, v175
	v_and_b32_e32 v157, 0xffff0000, v175
	v_lshlrev_b32_e32 v158, 16, v179
	v_and_b32_e32 v159, 0xffff0000, v179
	v_pk_add_f32 v[156:157], v[156:157], v[158:159]
	v_pk_add_f32 v[156:157], v[52:53], v[156:157]
	v_cvt_pk_bf16_f32 v175, v156, v157
	v_pk_fma_f32 v[198:199], v[156:157], v[156:157], v[198:199]
	v_lshlrev_b32_e32 v158, 16, v175
	v_and_b32_e32 v159, 0xffff0000, v175
	v_pk_add_f32 v[196:197], v[156:157], v[158:159] neg_lo:[0,1] neg_hi:[0,1]
	v_cvt_pk_bf16_f32 v179, v196, v197
	global_store_dwordx4 v211, v[172:175], s[10:11] offset:256
	global_store_dwordx4 v211, v[176:179], s[14:15] offset:256
	v_add_f32_e32 v206, v198, v199
	s_nop 0
	v_add_u32_e32 v211, 0x58000, v213
	global_load_dwordx4 v[164:167], v211, s[10:11]
	global_load_dwordx4 v[168:171], v211, s[14:15]
	global_load_dwordx4 v[172:175], v211, s[10:11] offset:256
	global_load_dwordx4 v[176:179], v211, s[14:15] offset:256
	s_waitcnt vmcnt(18)
; __device__ __forceinline__ unsigned pk2(float lo, float hi) { f32x2_t v = {lo, hi}; bf16x2_t b = __builtin_convertvector(v, bf16x2_t); return __builtin_bit_cast(unsigned, b); }
; __device__ __forceinline__ float bflo(unsigned u) { return __uint_as_float(u << 16); }
;     __device__ __forceinline__ void operator()(const f32x4 (&acc)[2][2][4][2], const Unit& u, int wr, int wc, int fr, int fq) const {
;     ...
;                 for (int bj = 0; bj < 2; ++bj) {
;                     const size_t off = (size_t)row * DM + col0 + bj * HALF;
;                     const u32x4 hh = *(const u32x4*)(HI + off), ll = *(const u32x4*)(LO + off);
;                     float hv[8] = {bflo(hh.x) + bflo(ll.x), bfhi(hh.x) + bfhi(ll.x), bflo(hh.y) + bflo(ll.y), bfhi(hh.y) + bfhi(ll.y),
;                                    bflo(hh.z) + bflo(ll.z), bfhi(hh.z) + bfhi(ll.z), bflo(hh.w) + bflo(ll.w), bfhi(hh.w) + bfhi(ll.w)};
;                     float av[8] = {acc[ai][bj][m][0][0], acc[ai][bj][m][0][1], acc[ai][bj][m][0][2], acc[ai][bj][m][0][3], acc[ai][bj][m][1][0], acc[ai][bj][m][1][1], acc[ai][bj][m][1][2], acc[ai][bj][m][1][3]};
;                     if (GATED) { const u32x4 pp = *(const u32x4*)(PP + off);
;                         const float pv[8] = {bflo(pp.x), bfhi(pp.x), bflo(pp.y), bfhi(pp.y), bflo(pp.z), bfhi(pp.z), bflo(pp.w), bfhi(pp.w)};
; #pragma unroll
;                         for (int e = 0; e < 8; ++e) av[e] = fast_sigmoid(av[e] * rs) * pv[e]; }
;                     else {
; #pragma unroll
;                         for (int e = 0; e < 8; ++e) av[e] *= alpha; }
;                     float lo[8];
; #pragma unroll
;                     for (int e = 0; e < 8; ++e) { hv[e] += av[e]; sq += hv[e] * hv[e]; }
;                     u32x4 wh; wh.x = pk2(hv[0], hv[1]); wh.y = pk2(hv[2], hv[3]); wh.z = pk2(hv[4], hv[5]); wh.w = pk2(hv[6], hv[7]);
;                     lo[0] = hv[0] - bflo(wh.x); lo[1] = hv[1] - bfhi(wh.x); lo[2] = hv[2] - bflo(wh.y); lo[3] = hv[3] - bfhi(wh.y);
;                     lo[4] = hv[4] - bflo(wh.z); lo[5] = hv[5] - bfhi(wh.z); lo[6] = hv[6] - bflo(wh.w); lo[7] = hv[7] - bfhi(wh.w);
;                     u32x4 wl; wl.x = pk2(lo[0], lo[1]); wl.y = pk2(lo[2], lo[3]); wl.z = pk2(lo[4], lo[5]); wl.w = pk2(lo[6], lo[7]);
;                     *(u32x4*)(HO + off) = wh; *(u32x4*)(LO + off) = wl;
;                 }
	v_lshlrev_b32_e32 v156, 16, v180
	v_and_b32_e32 v157, 0xffff0000, v180
	v_lshlrev_b32_e32 v158, 16, v184
	v_and_b32_e32 v159, 0xffff0000, v184
	v_pk_add_f32 v[156:157], v[156:157], v[158:159]
	v_pk_add_f32 v[156:157], v[46:47], v[156:157]
	v_cvt_pk_bf16_f32 v180, v156, v157
	v_pk_mul_f32 v[198:199], v[156:157], v[156:157]
	v_lshlrev_b32_e32 v158, 16, v180
	v_and_b32_e32 v159, 0xffff0000, v180
	v_pk_add_f32 v[196:197], v[156:157], v[158:159] neg_lo:[0,1] neg_hi:[0,1]
	v_cvt_pk_bf16_f32 v184, v196, v197
	v_lshlrev_b32_e32 v156, 16, v181
	v_and_b32_e32 v157, 0xffff0000, v181
	v_lshlrev_b32_e32 v158, 16, v185
	v_and_b32_e32 v159, 0xffff0000, v185
	v_pk_add_f32 v[156:157], v[156:157], v[158:159]
	v_pk_add_f32 v[156:157], v[48:49], v[156:157]
	v_cvt_pk_bf16_f32 v181, v156, v157
	v_pk_fma_f32 v[198:199], v[156:157], v[156:157], v[198:199]
	v_lshlrev_b32_e32 v158, 16, v181
	v_and_b32_e32 v159, 0xffff0000, v181
	v_pk_add_f32 v[196:197], v[156:157], v[158:159] neg_lo:[0,1] neg_hi:[0,1]
	v_cvt_pk_bf16_f32 v185, v196, v197
	v_lshlrev_b32_e32 v156, 16, v182
	v_and_b32_e32 v157, 0xffff0000, v182
	v_lshlrev_b32_e32 v158, 16, v186
	v_and_b32_e32 v159, 0xffff0000, v186
	v_pk_add_f32 v[156:157], v[156:157], v[158:159]
	v_pk_add_f32 v[156:157], v[42:43], v[156:157]
	v_cvt_pk_bf16_f32 v182, v156, v157
	v_pk_fma_f32 v[198:199], v[156:157], v[156:157], v[198:199]
	v_lshlrev_b32_e32 v158, 16, v182
	v_and_b32_e32 v159, 0xffff0000, v182
	v_pk_add_f32 v[196:197], v[156:157], v[158:159] neg_lo:[0,1] neg_hi:[0,1]
	v_cvt_pk_bf16_f32 v186, v196, v197
	v_lshlrev_b32_e32 v156, 16, v183
	v_and_b32_e32 v157, 0xffff0000, v183
	v_lshlrev_b32_e32 v158, 16, v187
	v_and_b32_e32 v159, 0xffff0000, v187
	v_pk_add_f32 v[156:157], v[156:157], v[158:159]
	v_pk_add_f32 v[156:157], v[44:45], v[156:157]
	v_cvt_pk_bf16_f32 v183, v156, v157
	v_pk_fma_f32 v[198:199], v[156:157], v[156:157], v[198:199]
	v_lshlrev_b32_e32 v158, 16, v183
	v_and_b32_e32 v159, 0xffff0000, v183
	v_pk_add_f32 v[196:197], v[156:157], v[158:159] neg_lo:[0,1] neg_hi:[0,1]
	v_cvt_pk_bf16_f32 v187, v196, v197
	global_store_dwordx4 v212, v[180:183], s[10:11]
	global_store_dwordx4 v212, v[184:187], s[14:15]
	s_waitcnt vmcnt(18)
	v_lshlrev_b32_e32 v156, 16, v188
	v_and_b32_e32 v157, 0xffff0000, v188
	v_lshlrev_b32_e32 v158, 16, v192
	v_and_b32_e32 v159, 0xffff0000, v192
	v_pk_add_f32 v[156:157], v[156:157], v[158:159]
	v_pk_add_f32 v[156:157], v[38:39], v[156:157]
	v_cvt_pk_bf16_f32 v188, v156, v157
	v_pk_fma_f32 v[198:199], v[156:157], v[156:157], v[198:199]
	v_lshlrev_b32_e32 v158, 16, v188
	v_and_b32_e32 v159, 0xffff0000, v188
	v_pk_add_f32 v[196:197], v[156:157], v[158:159] neg_lo:[0,1] neg_hi:[0,1]
	v_cvt_pk_bf16_f32 v192, v196, v197
	v_lshlrev_b32_e32 v156, 16, v189
	v_and_b32_e32 v157, 0xffff0000, v189
	v_lshlrev_b32_e32 v158, 16, v193
	v_and_b32_e32 v159, 0xffff0000, v193
	v_pk_add_f32 v[156:157], v[156:157], v[158:159]
	v_pk_add_f32 v[156:157], v[40:41], v[156:157]
	v_cvt_pk_bf16_f32 v189, v156, v157
	v_pk_fma_f32 v[198:199], v[156:157], v[156:157], v[198:199]
	v_lshlrev_b32_e32 v158, 16, v189
	v_and_b32_e32 v159, 0xffff0000, v189
	v_pk_add_f32 v[196:197], v[156:157], v[158:159] neg_lo:[0,1] neg_hi:[0,1]
	v_cvt_pk_bf16_f32 v193, v196, v197
	v_lshlrev_b32_e32 v156, 16, v190
	v_and_b32_e32 v157, 0xffff0000, v190
	v_lshlrev_b32_e32 v158, 16, v194
	v_and_b32_e32 v159, 0xffff0000, v194
	v_pk_add_f32 v[156:157], v[156:157], v[158:159]
	v_pk_add_f32 v[156:157], v[34:35], v[156:157]
	v_cvt_pk_bf16_f32 v190, v156, v157
	v_pk_fma_f32 v[198:199], v[156:157], v[156:157], v[198:199]
	v_lshlrev_b32_e32 v158, 16, v190
	v_and_b32_e32 v159, 0xffff0000, v190
	v_pk_add_f32 v[196:197], v[156:157], v[158:159] neg_lo:[0,1] neg_hi:[0,1]
	v_cvt_pk_bf16_f32 v194, v196, v197
	v_lshlrev_b32_e32 v156, 16, v191
	v_and_b32_e32 v157, 0xffff0000, v191
	v_lshlrev_b32_e32 v158, 16, v195
	v_and_b32_e32 v159, 0xffff0000, v195
	v_pk_add_f32 v[156:157], v[156:157], v[158:159]
	v_pk_add_f32 v[156:157], v[36:37], v[156:157]
	v_cvt_pk_bf16_f32 v191, v156, v157
	v_pk_fma_f32 v[198:199], v[156:157], v[156:157], v[198:199]
	v_lshlrev_b32_e32 v158, 16, v191
	v_and_b32_e32 v159, 0xffff0000, v191
	v_pk_add_f32 v[196:197], v[156:157], v[158:159] neg_lo:[0,1] neg_hi:[0,1]
	v_cvt_pk_bf16_f32 v195, v196, v197
	global_store_dwordx4 v212, v[188:191], s[10:11] offset:256
	global_store_dwordx4 v212, v[192:195], s[14:15] offset:256
	v_add_f32_e32 v207, v198, v199
	s_waitcnt vmcnt(14)
	v_lshlrev_b32_e32 v156, 16, v140
	v_and_b32_e32 v157, 0xffff0000, v140
	v_lshlrev_b32_e32 v158, 16, v144
	v_and_b32_e32 v159, 0xffff0000, v144
	v_pk_add_f32 v[156:157], v[156:157], v[158:159]
	v_pk_add_f32 v[156:157], v[30:31], v[156:157]
	v_cvt_pk_bf16_f32 v140, v156, v157
	v_pk_mul_f32 v[198:199], v[156:157], v[156:157]
	v_lshlrev_b32_e32 v158, 16, v140
	v_and_b32_e32 v159, 0xffff0000, v140
	v_pk_add_f32 v[196:197], v[156:157], v[158:159] neg_lo:[0,1] neg_hi:[0,1]
	v_cvt_pk_bf16_f32 v144, v196, v197
	v_lshlrev_b32_e32 v156, 16, v141
	v_and_b32_e32 v157, 0xffff0000, v141
	v_lshlrev_b32_e32 v158, 16, v145
	v_and_b32_e32 v159, 0xffff0000, v145
	v_pk_add_f32 v[156:157], v[156:157], v[158:159]
	v_pk_add_f32 v[156:157], v[32:33], v[156:157]
	v_cvt_pk_bf16_f32 v141, v156, v157
	v_pk_fma_f32 v[198:199], v[156:157], v[156:157], v[198:199]
	v_lshlrev_b32_e32 v158, 16, v141
	v_and_b32_e32 v159, 0xffff0000, v141
	v_pk_add_f32 v[196:197], v[156:157], v[158:159] neg_lo:[0,1] neg_hi:[0,1]
	v_cvt_pk_bf16_f32 v145, v196, v197
	v_lshlrev_b32_e32 v156, 16, v142
	v_and_b32_e32 v157, 0xffff0000, v142
	v_lshlrev_b32_e32 v158, 16, v146
	v_and_b32_e32 v159, 0xffff0000, v146
	v_pk_add_f32 v[156:157], v[156:157], v[158:159]
	v_pk_add_f32 v[156:157], v[26:27], v[156:157]
	v_cvt_pk_bf16_f32 v142, v156, v157
	v_pk_fma_f32 v[198:199], v[156:157], v[156:157], v[198:199]
	v_lshlrev_b32_e32 v158, 16, v142
	v_and_b32_e32 v159, 0xffff0000, v142
	v_pk_add_f32 v[196:197], v[156:157], v[158:159] neg_lo:[0,1] neg_hi:[0,1]
	v_cvt_pk_bf16_f32 v146, v196, v197
	v_lshlrev_b32_e32 v156, 16, v143
	v_and_b32_e32 v157, 0xffff0000, v143
	v_lshlrev_b32_e32 v158, 16, v147
	v_and_b32_e32 v159, 0xffff0000, v147
	v_pk_add_f32 v[156:157], v[156:157], v[158:159]
	v_pk_add_f32 v[156:157], v[28:29], v[156:157]
	v_cvt_pk_bf16_f32 v143, v156, v157
	v_pk_fma_f32 v[198:199], v[156:157], v[156:157], v[198:199]
	v_lshlrev_b32_e32 v158, 16, v143
	v_and_b32_e32 v159, 0xffff0000, v143
	v_pk_add_f32 v[196:197], v[156:157], v[158:159] neg_lo:[0,1] neg_hi:[0,1]
	v_cvt_pk_bf16_f32 v147, v196, v197
	global_store_dwordx4 v210, v[140:143], s[10:11]
	global_store_dwordx4 v210, v[144:147], s[14:15]
	s_waitcnt vmcnt(14)
; __device__ __forceinline__ unsigned pk2(float lo, float hi) { f32x2_t v = {lo, hi}; bf16x2_t b = __builtin_convertvector(v, bf16x2_t); return __builtin_bit_cast(unsigned, b); }
; __device__ __forceinline__ float bflo(unsigned u) { return __uint_as_float(u << 16); }
;     __device__ __forceinline__ void operator()(const f32x4 (&acc)[2][2][4][2], const Unit& u, int wr, int wc, int fr, int fq) const {
;     ...
;                 for (int bj = 0; bj < 2; ++bj) {
;                     const size_t off = (size_t)row * DM + col0 + bj * HALF;
;                     const u32x4 hh = *(const u32x4*)(HI + off), ll = *(const u32x4*)(LO + off);
;                     float hv[8] = {bflo(hh.x) + bflo(ll.x), bfhi(hh.x) + bfhi(ll.x), bflo(hh.y) + bflo(ll.y), bfhi(hh.y) + bfhi(ll.y),
;                                    bflo(hh.z) + bflo(ll.z), bfhi(hh.z) + bfhi(ll.z), bflo(hh.w) + bflo(ll.w), bfhi(hh.w) + bfhi(ll.w)};
;                     float av[8] = {acc[ai][bj][m][0][0], acc[ai][bj][m][0][1], acc[ai][bj][m][0][2], acc[ai][bj][m][0][3], acc[ai][bj][m][1][0], acc[ai][bj][m][1][1], acc[ai][bj][m][1][2], acc[ai][bj][m][1][3]};
;                     if (GATED) { const u32x4 pp = *(const u32x4*)(PP + off);
;                         const float pv[8] = {bflo(pp.x), bfhi(pp.x), bflo(pp.y), bfhi(pp.y), bflo(pp.z), bfhi(pp.z), bflo(pp.w), bfhi(pp.w)};
; #pragma unroll
;                         for (int e = 0; e < 8; ++e) av[e] = fast_sigmoid(av[e] * rs) * pv[e]; }
;                     else {
; #pragma unroll
;                         for (int e = 0; e < 8; ++e) av[e] *= alpha; }
;                     float lo[8];
; #pragma unroll
;                     for (int e = 0; e < 8; ++e) { hv[e] += av[e]; sq += hv[e] * hv[e]; }
;                     u32x4 wh; wh.x = pk2(hv[0], hv[1]); wh.y = pk2(hv[2], hv[3]); wh.z = pk2(hv[4], hv[5]); wh.w = pk2(hv[6], hv[7]);
;                     lo[0] = hv[0] - bflo(wh.x); lo[1] = hv[1] - bfhi(wh.x); lo[2] = hv[2] - bflo(wh.y); lo[3] = hv[3] - bfhi(wh.y);
;                     lo[4] = hv[4] - bflo(wh.z); lo[5] = hv[5] - bfhi(wh.z); lo[6] = hv[6] - bflo(wh.w); lo[7] = hv[7] - bfhi(wh.w);
;                     u32x4 wl; wl.x = pk2(lo[0], lo[1]); wl.y = pk2(lo[2], lo[3]); wl.z = pk2(lo[4], lo[5]); wl.w = pk2(lo[6], lo[7]);
;                     *(u32x4*)(HO + off) = wh; *(u32x4*)(LO + off) = wl;
;                 }
	v_lshlrev_b32_e32 v156, 16, v148
	v_and_b32_e32 v157, 0xffff0000, v148
	v_lshlrev_b32_e32 v158, 16, v152
	v_and_b32_e32 v159, 0xffff0000, v152
	v_pk_add_f32 v[156:157], v[156:157], v[158:159]
	v_pk_add_f32 v[156:157], v[22:23], v[156:157]
	v_cvt_pk_bf16_f32 v148, v156, v157
	v_pk_fma_f32 v[198:199], v[156:157], v[156:157], v[198:199]
	v_lshlrev_b32_e32 v158, 16, v148
	v_and_b32_e32 v159, 0xffff0000, v148
	v_pk_add_f32 v[196:197], v[156:157], v[158:159] neg_lo:[0,1] neg_hi:[0,1]
	v_cvt_pk_bf16_f32 v152, v196, v197
	v_lshlrev_b32_e32 v156, 16, v149
	v_and_b32_e32 v157, 0xffff0000, v149
	v_lshlrev_b32_e32 v158, 16, v153
	v_and_b32_e32 v159, 0xffff0000, v153
	v_pk_add_f32 v[156:157], v[156:157], v[158:159]
	v_pk_add_f32 v[156:157], v[24:25], v[156:157]
	v_cvt_pk_bf16_f32 v149, v156, v157
	v_pk_fma_f32 v[198:199], v[156:157], v[156:157], v[198:199]
	v_lshlrev_b32_e32 v158, 16, v149
	v_and_b32_e32 v159, 0xffff0000, v149
	v_pk_add_f32 v[196:197], v[156:157], v[158:159] neg_lo:[0,1] neg_hi:[0,1]
	v_cvt_pk_bf16_f32 v153, v196, v197
	v_lshlrev_b32_e32 v156, 16, v150
	v_and_b32_e32 v157, 0xffff0000, v150
	v_lshlrev_b32_e32 v158, 16, v154
	v_and_b32_e32 v159, 0xffff0000, v154
	v_pk_add_f32 v[156:157], v[156:157], v[158:159]
	v_pk_add_f32 v[156:157], v[18:19], v[156:157]
	v_cvt_pk_bf16_f32 v150, v156, v157
	v_pk_fma_f32 v[198:199], v[156:157], v[156:157], v[198:199]
	v_lshlrev_b32_e32 v158, 16, v150
	v_and_b32_e32 v159, 0xffff0000, v150
	v_pk_add_f32 v[196:197], v[156:157], v[158:159] neg_lo:[0,1] neg_hi:[0,1]
	v_cvt_pk_bf16_f32 v154, v196, v197
	v_lshlrev_b32_e32 v156, 16, v151
	v_and_b32_e32 v157, 0xffff0000, v151
	v_lshlrev_b32_e32 v158, 16, v155
	v_and_b32_e32 v159, 0xffff0000, v155
	v_pk_add_f32 v[156:157], v[156:157], v[158:159]
	v_pk_add_f32 v[156:157], v[20:21], v[156:157]
	v_cvt_pk_bf16_f32 v151, v156, v157
	v_pk_fma_f32 v[198:199], v[156:157], v[156:157], v[198:199]
	v_lshlrev_b32_e32 v158, 16, v151
	v_and_b32_e32 v159, 0xffff0000, v151
	v_pk_add_f32 v[196:197], v[156:157], v[158:159] neg_lo:[0,1] neg_hi:[0,1]
	v_cvt_pk_bf16_f32 v155, v196, v197
	global_store_dwordx4 v210, v[148:151], s[10:11] offset:256
	global_store_dwordx4 v210, v[152:155], s[14:15] offset:256
	v_add_f32_e32 v208, v198, v199
	s_waitcnt vmcnt(10)
	v_lshlrev_b32_e32 v156, 16, v164
	v_and_b32_e32 v157, 0xffff0000, v164
	v_lshlrev_b32_e32 v158, 16, v168
	v_and_b32_e32 v159, 0xffff0000, v168
	v_pk_add_f32 v[156:157], v[156:157], v[158:159]
	v_pk_add_f32 v[156:157], v[14:15], v[156:157]
	v_cvt_pk_bf16_f32 v164, v156, v157
	v_pk_mul_f32 v[198:199], v[156:157], v[156:157]
	v_lshlrev_b32_e32 v158, 16, v164
	v_and_b32_e32 v159, 0xffff0000, v164
	v_pk_add_f32 v[196:197], v[156:157], v[158:159] neg_lo:[0,1] neg_hi:[0,1]
	v_cvt_pk_bf16_f32 v168, v196, v197
	v_lshlrev_b32_e32 v156, 16, v165
	v_and_b32_e32 v157, 0xffff0000, v165
	v_lshlrev_b32_e32 v158, 16, v169
	v_and_b32_e32 v159, 0xffff0000, v169
	v_pk_add_f32 v[156:157], v[156:157], v[158:159]
	v_pk_add_f32 v[156:157], v[16:17], v[156:157]
	v_cvt_pk_bf16_f32 v165, v156, v157
	v_pk_fma_f32 v[198:199], v[156:157], v[156:157], v[198:199]
	v_lshlrev_b32_e32 v158, 16, v165
	v_and_b32_e32 v159, 0xffff0000, v165
	v_pk_add_f32 v[196:197], v[156:157], v[158:159] neg_lo:[0,1] neg_hi:[0,1]
	v_cvt_pk_bf16_f32 v169, v196, v197
	v_lshlrev_b32_e32 v156, 16, v166
	v_and_b32_e32 v157, 0xffff0000, v166
	v_lshlrev_b32_e32 v158, 16, v170
	v_and_b32_e32 v159, 0xffff0000, v170
	v_pk_add_f32 v[156:157], v[156:157], v[158:159]
	v_pk_add_f32 v[156:157], v[10:11], v[156:157]
	v_cvt_pk_bf16_f32 v166, v156, v157
	v_pk_fma_f32 v[198:199], v[156:157], v[156:157], v[198:199]
	v_lshlrev_b32_e32 v158, 16, v166
	v_and_b32_e32 v159, 0xffff0000, v166
	v_pk_add_f32 v[196:197], v[156:157], v[158:159] neg_lo:[0,1] neg_hi:[0,1]
	v_cvt_pk_bf16_f32 v170, v196, v197
	v_lshlrev_b32_e32 v156, 16, v167
	v_and_b32_e32 v157, 0xffff0000, v167
	v_lshlrev_b32_e32 v158, 16, v171
	v_and_b32_e32 v159, 0xffff0000, v171
	v_pk_add_f32 v[156:157], v[156:157], v[158:159]
	v_pk_add_f32 v[156:157], v[12:13], v[156:157]
	v_cvt_pk_bf16_f32 v167, v156, v157
	v_pk_fma_f32 v[198:199], v[156:157], v[156:157], v[198:199]
	v_lshlrev_b32_e32 v158, 16, v167
	v_and_b32_e32 v159, 0xffff0000, v167
	v_pk_add_f32 v[196:197], v[156:157], v[158:159] neg_lo:[0,1] neg_hi:[0,1]
	v_cvt_pk_bf16_f32 v171, v196, v197
	global_store_dwordx4 v211, v[164:167], s[10:11]
	global_store_dwordx4 v211, v[168:171], s[14:15]
	s_waitcnt vmcnt(10)
; __device__ __forceinline__ unsigned pk2(float lo, float hi) { f32x2_t v = {lo, hi}; bf16x2_t b = __builtin_convertvector(v, bf16x2_t); return __builtin_bit_cast(unsigned, b); }
; __device__ __forceinline__ float bflo(unsigned u) { return __uint_as_float(u << 16); }
; __device__ __forceinline__ float bfhi(unsigned u) { return __uint_as_float(u & 0xffff0000u); }
;     __device__ __forceinline__ void operator()(const f32x4 (&acc)[2][2][4][2], const Unit& u, int wr, int wc, int fr, int fq) const {
;     ...
;                     float lo[8];
; #pragma unroll
;                     for (int e = 0; e < 8; ++e) { hv[e] += av[e]; sq += hv[e] * hv[e]; }
;                     u32x4 wh; wh.x = pk2(hv[0], hv[1]); wh.y = pk2(hv[2], hv[3]); wh.z = pk2(hv[4], hv[5]); wh.w = pk2(hv[6], hv[7]);
;                     lo[0] = hv[0] - bflo(wh.x); lo[1] = hv[1] - bfhi(wh.x); lo[2] = hv[2] - bflo(wh.y); lo[3] = hv[3] - bfhi(wh.y);
;                     lo[4] = hv[4] - bflo(wh.z); lo[5] = hv[5] - bfhi(wh.z); lo[6] = hv[6] - bflo(wh.w); lo[7] = hv[7] - bfhi(wh.w);
;                     u32x4 wl; wl.x = pk2(lo[0], lo[1]); wl.y = pk2(lo[2], lo[3]); wl.z = pk2(lo[4], lo[5]); wl.w = pk2(lo[6], lo[7]);
;                     *(u32x4*)(HO + off) = wh; *(u32x4*)(LO + off) = wl;
;                 }
;                 sq += __shfl_xor(sq, 16); sq += __shfl_xor(sq, 32);
;                 if (fq == 0) ssq_out[(size_t)row * 16 + 4 * u.pn + wc] = sq;
	v_lshlrev_b32_e32 v156, 16, v172
	v_and_b32_e32 v157, 0xffff0000, v172
	v_lshlrev_b32_e32 v158, 16, v176
	v_and_b32_e32 v159, 0xffff0000, v176
	v_pk_add_f32 v[156:157], v[156:157], v[158:159]
	v_pk_add_f32 v[156:157], v[6:7], v[156:157]
	v_cvt_pk_bf16_f32 v172, v156, v157
	v_pk_fma_f32 v[198:199], v[156:157], v[156:157], v[198:199]
	v_lshlrev_b32_e32 v158, 16, v172
	v_and_b32_e32 v159, 0xffff0000, v172
	v_pk_add_f32 v[196:197], v[156:157], v[158:159] neg_lo:[0,1] neg_hi:[0,1]
	v_cvt_pk_bf16_f32 v176, v196, v197
	v_lshlrev_b32_e32 v156, 16, v173
	v_and_b32_e32 v157, 0xffff0000, v173
	v_lshlrev_b32_e32 v158, 16, v177
	v_and_b32_e32 v159, 0xffff0000, v177
	v_pk_add_f32 v[156:157], v[156:157], v[158:159]
	v_pk_add_f32 v[156:157], v[8:9], v[156:157]
	v_cvt_pk_bf16_f32 v173, v156, v157
	v_pk_fma_f32 v[198:199], v[156:157], v[156:157], v[198:199]
	v_lshlrev_b32_e32 v158, 16, v173
	v_and_b32_e32 v159, 0xffff0000, v173
	v_pk_add_f32 v[196:197], v[156:157], v[158:159] neg_lo:[0,1] neg_hi:[0,1]
	v_cvt_pk_bf16_f32 v177, v196, v197
	v_lshlrev_b32_e32 v156, 16, v174
	v_and_b32_e32 v157, 0xffff0000, v174
	v_lshlrev_b32_e32 v158, 16, v178
	v_and_b32_e32 v159, 0xffff0000, v178
	v_pk_add_f32 v[156:157], v[156:157], v[158:159]
	v_pk_add_f32 v[156:157], v[2:3], v[156:157]
	v_cvt_pk_bf16_f32 v174, v156, v157
	v_pk_fma_f32 v[198:199], v[156:157], v[156:157], v[198:199]
	v_lshlrev_b32_e32 v158, 16, v174
	v_and_b32_e32 v159, 0xffff0000, v174
	v_pk_add_f32 v[196:197], v[156:157], v[158:159] neg_lo:[0,1] neg_hi:[0,1]
	v_cvt_pk_bf16_f32 v178, v196, v197
	v_lshlrev_b32_e32 v156, 16, v175
	v_and_b32_e32 v157, 0xffff0000, v175
	v_lshlrev_b32_e32 v158, 16, v179
	v_and_b32_e32 v159, 0xffff0000, v179
	v_pk_add_f32 v[156:157], v[156:157], v[158:159]
	v_pk_add_f32 v[156:157], v[4:5], v[156:157]
	v_cvt_pk_bf16_f32 v175, v156, v157
	v_pk_fma_f32 v[198:199], v[156:157], v[156:157], v[198:199]
	v_lshlrev_b32_e32 v158, 16, v175
	v_and_b32_e32 v159, 0xffff0000, v175
	v_pk_add_f32 v[196:197], v[156:157], v[158:159] neg_lo:[0,1] neg_hi:[0,1]
	v_cvt_pk_bf16_f32 v179, v196, v197
	global_store_dwordx4 v211, v[172:175], s[10:11] offset:256
	global_store_dwordx4 v211, v[176:179], s[14:15] offset:256
	v_add_f32_e32 v209, v198, v199
	v_mov_b32_e32 v140, v200
	s_nop 1
	v_permlane16_swap_b32_e32 v200, v140
	v_mov_b32_e32 v141, v201
	s_nop 1
	v_permlane16_swap_b32_e32 v201, v141
	v_mov_b32_e32 v142, v202
	s_nop 1
	v_permlane16_swap_b32_e32 v202, v142
	v_mov_b32_e32 v143, v203
	s_nop 1
	v_permlane16_swap_b32_e32 v203, v143
	v_mov_b32_e32 v144, v206
	s_nop 1
	v_permlane16_swap_b32_e32 v206, v144
	v_mov_b32_e32 v145, v207
	s_nop 1
	v_permlane16_swap_b32_e32 v207, v145
	v_mov_b32_e32 v146, v208
	s_nop 1
	v_permlane16_swap_b32_e32 v208, v146
	v_mov_b32_e32 v147, v209
	s_nop 1
	v_permlane16_swap_b32_e32 v209, v147
	s_waitcnt lgkmcnt(0)
	v_add_f32_e32 v200, v200, v140
	v_add_f32_e32 v201, v201, v141
	v_add_f32_e32 v202, v202, v142
	v_add_f32_e32 v203, v203, v143
	v_add_f32_e32 v206, v206, v144
	v_add_f32_e32 v207, v207, v145
	v_add_f32_e32 v208, v208, v146
	v_add_f32_e32 v209, v209, v147
	v_mov_b32_e32 v140, v200
	s_nop 1
	v_permlane32_swap_b32_e32 v200, v140
	v_mov_b32_e32 v141, v201
	s_nop 1
	v_permlane32_swap_b32_e32 v201, v141
	v_mov_b32_e32 v142, v202
	s_nop 1
	v_permlane32_swap_b32_e32 v202, v142
	v_mov_b32_e32 v143, v203
	s_nop 1
	v_permlane32_swap_b32_e32 v203, v143
	v_mov_b32_e32 v144, v206
	s_nop 1
	v_permlane32_swap_b32_e32 v206, v144
	v_mov_b32_e32 v145, v207
	s_nop 1
	v_permlane32_swap_b32_e32 v207, v145
	v_mov_b32_e32 v146, v208
	s_nop 1
	v_permlane32_swap_b32_e32 v208, v146
	v_mov_b32_e32 v147, v209
	s_nop 1
	v_permlane32_swap_b32_e32 v209, v147
	s_waitcnt lgkmcnt(0)
	v_add_f32_e32 v200, v200, v140
	v_add_f32_e32 v201, v201, v141
	v_add_f32_e32 v202, v202, v142
	v_add_f32_e32 v203, v203, v143
	v_add_f32_e32 v206, v206, v144
	v_add_f32_e32 v207, v207, v145
	v_add_f32_e32 v208, v208, v146
	v_add_f32_e32 v209, v209, v147
	s_and_saveexec_b64 s[26:27], s[44:45]
	s_cbranch_execz .Lepir_wout_skip
	global_store_dword v216, v200, s[16:17]
	global_store_dword v216, v201, s[16:17] offset:1024
	global_store_dword v216, v202, s[16:17] offset:2048
	global_store_dword v216, v203, s[16:17] offset:3072
	global_store_dword v217, v206, s[16:17]
	global_store_dword v217, v207, s[16:17] offset:1024
	global_store_dword v217, v208, s[16:17] offset:2048
	global_store_dword v217, v209, s[16:17] offset:3072

; __device__ __forceinline__ float row_ssq(const float* part, int pitch, int n4, int row, int fq) {
;     f32x4 v = (f32x4){0.f, 0.f, 0.f, 0.f};
;     if (fq < n4) v = *(const f32x4*)(part + (size_t)row * pitch + 4 * fq);
;     float s = (v[0] + v[1]) + (v[2] + v[3]);
;     s += __shfl_xor(s, 16); s += __shfl_xor(s, 32);
;     return s;
;     __device__ __forceinline__ void operator()(const f32x4 (&acc)[2][2][4][2], const Unit& u, int wr, int wc, int fr, int fq) const {
;         const int row0 = u.pm * BM + wr * 64 + fr, col0 = u.pn * 128 + wc * 32 + 8 * fq;
; #pragma unroll
;         for (int ai = 0; ai < 2; ++ai)
; #pragma unroll
;             for (int m = 0; m < 4; ++m) {
;                 const int row = row0 + ai * HALF + m * 16;
;                 const float rs = rsqrtf(row_ssq(ssq, 16, 4, row, fq) * (1.f / 1024.f) + EPS);
.LBB0_1154:
	v_and_b32_e32 v145, 64, v241
	v_xor_b32_e32 v143, 16, v241
	v_add_u32_e32 v145, 64, v145
	v_cmp_lt_i32_e32 vcc, v143, v145
	v_lshl_add_u32 v144, s39, 8, v146
	v_lshl_or_b32 v142, s4, 7, v148
	v_cndmask_b32_e32 v143, v241, v143, vcc
	v_lshlrev_b32_e32 v150, 2, v143
	v_xor_b32_e32 v143, 32, v241
	v_cmp_lt_i32_e32 vcc, v143, v145
	v_ashrrev_i32_e32 v145, 31, v144
	v_and_b32_e32 v166, 48, v241
	v_lshl_add_u32 v166, v146, 6, v166
	v_add_u32_e32 v166, 0x24000, v166
	ds_read_b128 v[168:171], v166
	ds_read_b128 v[172:175], v166 offset:1024
	ds_read_b128 v[176:179], v166 offset:2048
	ds_read_b128 v[180:183], v166 offset:3072
	v_cndmask_b32_e32 v143, v241, v143, vcc
	v_lshlrev_b32_e32 v151, 2, v143
	ds_read_b128 v[184:187], v166 offset:8192
	ds_read_b128 v[188:191], v166 offset:9216
	ds_read_b128 v[192:195], v166 offset:10240
	ds_read_b128 v[196:199], v166 offset:11264
	v_ashrrev_i32_e32 v143, 31, v142
	v_lshl_add_u64 v[142:143], v[142:143], 1, s[96:97]
	s_movk_i32 s4, 0x1600
	s_mov_b64 s[22:23], -1
	s_waitcnt lgkmcnt(7)
	v_add_f32_e32 v168, v169, v168
	v_add_f32_e32 v170, v170, v171
	v_add_f32_e32 v168, v168, v170
	v_mov_b32_e32 v169, v168
	s_nop 1
	v_permlane16_swap_b32_e32 v168, v169
	s_waitcnt lgkmcnt(6)
	v_add_f32_e32 v172, v173, v172
	v_add_f32_e32 v174, v174, v175
	v_add_f32_e32 v172, v172, v174
	v_mov_b32_e32 v173, v172
	s_nop 1
	v_permlane16_swap_b32_e32 v172, v173
	s_waitcnt lgkmcnt(5)
	v_add_f32_e32 v176, v177, v176
	v_add_f32_e32 v178, v178, v179
	v_add_f32_e32 v176, v176, v178
	v_mov_b32_e32 v177, v176
	s_nop 1
	v_permlane16_swap_b32_e32 v176, v177
	s_waitcnt lgkmcnt(4)
	v_add_f32_e32 v180, v181, v180
	v_add_f32_e32 v182, v182, v183
	v_add_f32_e32 v180, v180, v182
	v_mov_b32_e32 v181, v180
	s_nop 1
	v_permlane16_swap_b32_e32 v180, v181
	s_waitcnt lgkmcnt(3)
	v_add_f32_e32 v184, v185, v184
	v_add_f32_e32 v186, v186, v187
	v_add_f32_e32 v184, v184, v186
	v_mov_b32_e32 v185, v184
	s_nop 1
	v_permlane16_swap_b32_e32 v184, v185
	s_waitcnt lgkmcnt(2)
	v_add_f32_e32 v188, v189, v188
	v_add_f32_e32 v190, v190, v191
	v_add_f32_e32 v188, v188, v190
	v_mov_b32_e32 v189, v188
	s_nop 1
	v_permlane16_swap_b32_e32 v188, v189
	s_waitcnt lgkmcnt(1)
	v_add_f32_e32 v192, v193, v192
	v_add_f32_e32 v194, v194, v195
	v_add_f32_e32 v192, v192, v194
	v_mov_b32_e32 v193, v192
	s_nop 1
	v_permlane16_swap_b32_e32 v192, v193
	s_waitcnt lgkmcnt(0)
	v_add_f32_e32 v196, v197, v196
	v_add_f32_e32 v198, v198, v199
	v_add_f32_e32 v196, v196, v198
	v_mov_b32_e32 v197, v196
	s_nop 1
	v_permlane16_swap_b32_e32 v196, v197
	s_waitcnt lgkmcnt(7)
	v_add_f32_e32 v168, v168, v169
	v_mov_b32_e32 v169, v168
	s_nop 1
	v_permlane32_swap_b32_e32 v168, v169
	s_waitcnt lgkmcnt(7)
	v_add_f32_e32 v172, v172, v173
	v_mov_b32_e32 v173, v172
	s_nop 1
	v_permlane32_swap_b32_e32 v172, v173
	s_waitcnt lgkmcnt(7)
	v_add_f32_e32 v176, v176, v177
	v_mov_b32_e32 v177, v176
	s_nop 1
	v_permlane32_swap_b32_e32 v176, v177
	s_waitcnt lgkmcnt(7)
	v_add_f32_e32 v180, v180, v181
	v_mov_b32_e32 v181, v180
	s_nop 1
	v_permlane32_swap_b32_e32 v180, v181
	s_waitcnt lgkmcnt(7)
	v_add_f32_e32 v184, v184, v185
	v_mov_b32_e32 v185, v184
	s_nop 1
	v_permlane32_swap_b32_e32 v184, v185
	s_waitcnt lgkmcnt(7)
	v_add_f32_e32 v188, v188, v189
	v_mov_b32_e32 v189, v188
	s_nop 1
	v_permlane32_swap_b32_e32 v188, v189
	s_waitcnt lgkmcnt(7)
	v_add_f32_e32 v192, v192, v193
	v_mov_b32_e32 v193, v192
	s_nop 1
	v_permlane32_swap_b32_e32 v192, v193
	s_waitcnt lgkmcnt(7)
	v_add_f32_e32 v196, v196, v197
	v_mov_b32_e32 v197, v196
	s_nop 1
	v_permlane32_swap_b32_e32 v196, v197
	s_waitcnt lgkmcnt(7)
	v_add_f32_e32 v168, v168, v169
	v_fmamk_f32 v168, v168, 0x3a800000, v239
	s_waitcnt lgkmcnt(6)
	v_add_f32_e32 v172, v172, v173
	v_fmamk_f32 v172, v172, 0x3a800000, v239
	s_waitcnt lgkmcnt(5)
	v_add_f32_e32 v176, v176, v177
	v_fmamk_f32 v176, v176, 0x3a800000, v239
	s_waitcnt lgkmcnt(4)
	v_add_f32_e32 v180, v180, v181
	v_fmamk_f32 v180, v180, 0x3a800000, v239
	s_waitcnt lgkmcnt(3)
	v_add_f32_e32 v184, v184, v185
	v_fmamk_f32 v184, v184, 0x3a800000, v239
	s_waitcnt lgkmcnt(2)
	v_add_f32_e32 v188, v188, v189
	v_fmamk_f32 v188, v188, 0x3a800000, v239
	s_waitcnt lgkmcnt(1)
	v_add_f32_e32 v192, v192, v193
	v_fmamk_f32 v192, v192, 0x3a800000, v239
	s_waitcnt lgkmcnt(0)
; __device__ __forceinline__ unsigned pk2(float lo, float hi) { f32x2_t v = {lo, hi}; bf16x2_t b = __builtin_convertvector(v, bf16x2_t); return __builtin_bit_cast(unsigned, b); }
; __device__ __forceinline__ float fast_sigmoid(float x) { return __builtin_amdgcn_rcpf(1.f + __expf(-x)); }
;     __device__ __forceinline__ void operator()(const f32x4 (&acc)[2][2][4][2], const Unit& u, int wr, int wc, int fr, int fq) const {
;     ...
;                 const float rs = rsqrtf(row_ssq(ssq, 16, 4, row, fq) * (1.f / 1024.f) + EPS);
;                 float r[8];
; #pragma unroll
;                 for (int n = 0; n < 2; ++n)
; #pragma unroll
;                     for (int e = 0; e < 4; ++e) { const float gv = acc[ai][0][m][n][e] * rs, uv = acc[ai][1][m][n][e] * rs; r[n * 4 + e] = gv * fast_sigmoid(gv) * uv; }
;                 u32x4 w; w.x = pk2(r[0], r[1]); w.y = pk2(r[2], r[3]); w.z = pk2(r[4], r[5]); w.w = pk2(r[6], r[7]);
;                 *(u32x4*)(O + (size_t)row * DFF + col0) = w;
	v_add_f32_e32 v196, v196, v197
	v_fmamk_f32 v196, v196, 0x3a800000, v239
	v_cmp_gt_f32_e32 vcc, s55, v168
	v_mul_f32_e32 v169, 0x4b800000, v168
	s_nop 0
	v_cndmask_b32_e32 v168, v168, v169, vcc
	v_rsq_f32_e32 v168, v168
	s_nop 0
	v_mul_f32_e32 v169, 0x45800000, v168
	v_cndmask_b32_e32 v158, v168, v169, vcc
	v_cmp_gt_f32_e32 vcc, s55, v172
	v_mul_f32_e32 v173, 0x4b800000, v172
	s_nop 0
	v_cndmask_b32_e32 v172, v172, v173, vcc
	v_rsq_f32_e32 v172, v172
	s_nop 0
	v_mul_f32_e32 v173, 0x45800000, v172
	v_cndmask_b32_e32 v159, v172, v173, vcc
	v_cmp_gt_f32_e32 vcc, s55, v176
	v_mul_f32_e32 v177, 0x4b800000, v176
	s_nop 0
	v_cndmask_b32_e32 v176, v176, v177, vcc
	v_rsq_f32_e32 v176, v176
	s_nop 0
	v_mul_f32_e32 v177, 0x45800000, v176
	v_cndmask_b32_e32 v160, v176, v177, vcc
	v_cmp_gt_f32_e32 vcc, s55, v180
	v_mul_f32_e32 v181, 0x4b800000, v180
	s_nop 0
	v_cndmask_b32_e32 v180, v180, v181, vcc
	v_rsq_f32_e32 v180, v180
	s_nop 0
	v_mul_f32_e32 v181, 0x45800000, v180
	v_cndmask_b32_e32 v161, v180, v181, vcc
	v_cmp_gt_f32_e32 vcc, s55, v184
	v_mul_f32_e32 v185, 0x4b800000, v184
	s_nop 0
	v_cndmask_b32_e32 v184, v184, v185, vcc
	v_rsq_f32_e32 v184, v184
	s_nop 0
	v_mul_f32_e32 v185, 0x45800000, v184
	v_cndmask_b32_e32 v162, v184, v185, vcc
	v_cmp_gt_f32_e32 vcc, s55, v188
	v_mul_f32_e32 v189, 0x4b800000, v188
	s_nop 0
	v_cndmask_b32_e32 v188, v188, v189, vcc
	v_rsq_f32_e32 v188, v188
	s_nop 0
	v_mul_f32_e32 v189, 0x45800000, v188
	v_cndmask_b32_e32 v163, v188, v189, vcc
	v_cmp_gt_f32_e32 vcc, s55, v192
	v_mul_f32_e32 v193, 0x4b800000, v192
	s_nop 0
	v_cndmask_b32_e32 v192, v192, v193, vcc
	v_rsq_f32_e32 v192, v192
	s_nop 0
	v_mul_f32_e32 v193, 0x45800000, v192
	v_cndmask_b32_e32 v164, v192, v193, vcc
	v_cmp_gt_f32_e32 vcc, s55, v196
	v_mul_f32_e32 v197, 0x4b800000, v196
	s_nop 0
	v_cndmask_b32_e32 v196, v196, v197, vcc
	v_rsq_f32_e32 v196, v196
	s_nop 0
	v_mul_f32_e32 v197, 0x45800000, v196
	v_cndmask_b32_e32 v165, v196, v197, vcc
	v_mov_b32_e32 v152, v158
	v_pk_mul_f32 v[126:127], v[126:127], v[152:153] op_sel_hi:[1,0]
	v_pk_mul_f32 v[118:119], v[118:119], v[152:153] op_sel_hi:[1,0]
	v_mul_f32_e32 v145, 0xbfb8aa3b, v126
	v_exp_f32_e32 v145, v145
	v_pk_mul_f32 v[120:121], v[120:121], v[152:153] op_sel_hi:[1,0]
	v_pk_mul_f32 v[122:123], v[122:123], v[152:153] op_sel_hi:[1,0]
	v_pk_mul_f32 v[114:115], v[114:115], v[152:153] op_sel_hi:[1,0]
	v_add_f32_e32 v145, 1.0, v145
	v_rcp_f32_e32 v154, v145
	v_mul_f32_e32 v145, 0xbfb8aa3b, v127
	v_exp_f32_e32 v145, v145
	v_pk_mul_f32 v[116:117], v[116:117], v[152:153] op_sel_hi:[1,0]
	v_add_f32_e32 v145, 1.0, v145
	v_rcp_f32_e32 v155, v145
	s_nop 0
	v_pk_mul_f32 v[126:127], v[126:127], v[154:155]
	s_nop 0
	v_pk_mul_f32 v[118:119], v[118:119], v[126:127]
	v_pk_mul_f32 v[126:127], v[128:129], v[152:153] op_sel_hi:[1,0]
	s_nop 0
	v_mul_f32_e32 v128, 0xbfb8aa3b, v126
	v_mul_f32_e32 v129, 0xbfb8aa3b, v127
	v_exp_f32_e32 v128, v128
	v_exp_f32_e32 v129, v129
	v_add_f32_e32 v128, 1.0, v128
	v_add_f32_e32 v129, 1.0, v129
	v_rcp_f32_e32 v128, v128
	v_rcp_f32_e32 v129, v129
	s_nop 0
	v_pk_mul_f32 v[126:127], v[126:127], v[128:129]
	s_nop 0
	v_pk_mul_f32 v[120:121], v[120:121], v[126:127]
	v_mul_f32_e32 v126, 0xbfb8aa3b, v122
	v_mul_f32_e32 v127, 0xbfb8aa3b, v123
	v_exp_f32_e32 v126, v126
	v_exp_f32_e32 v127, v127
	v_add_f32_e32 v126, 1.0, v126
	v_add_f32_e32 v127, 1.0, v127
	v_rcp_f32_e32 v126, v126
	v_rcp_f32_e32 v127, v127
	s_nop 0
	v_pk_mul_f32 v[122:123], v[122:123], v[126:127]
	s_nop 0
	v_pk_mul_f32 v[122:123], v[114:115], v[122:123]
	v_pk_mul_f32 v[114:115], v[124:125], v[152:153] op_sel_hi:[1,0]
	s_nop 0
	v_mul_f32_e32 v124, 0xbfb8aa3b, v114
	v_mul_f32_e32 v125, 0xbfb8aa3b, v115
	v_exp_f32_e32 v124, v124
	v_exp_f32_e32 v125, v125
	v_add_f32_e32 v124, 1.0, v124
	v_add_f32_e32 v125, 1.0, v125
	v_rcp_f32_e32 v124, v124
	v_rcp_f32_e32 v125, v125
	s_nop 0
	v_pk_mul_f32 v[114:115], v[114:115], v[124:125]
	s_nop 0
	v_pk_mul_f32 v[124:125], v[116:117], v[114:115]
	v_cvt_pk_bf16_f32 v114, v118, v119
	v_cvt_pk_bf16_f32 v115, v120, v121
	v_cvt_pk_bf16_f32 v116, v122, v123
	v_cvt_pk_bf16_f32 v117, v124, v125
	v_mad_i64_i32 v[118:119], s[6:7], v144, s4, v[142:143]
	global_store_dwordx4 v[118:119], v[114:117], off
	s_nop 1
	v_or_b32_e32 v114, 16, v144
	v_mov_b32_e32 v116, v159
	v_pk_mul_f32 v[110:111], v[110:111], v[116:117] op_sel_hi:[1,0]
	v_pk_mul_f32 v[102:103], v[102:103], v[116:117] op_sel_hi:[1,0]
	v_mul_f32_e32 v115, 0xbfb8aa3b, v110
	v_exp_f32_e32 v115, v115
	v_pk_mul_f32 v[104:105], v[104:105], v[116:117] op_sel_hi:[1,0]
	v_pk_mul_f32 v[106:107], v[106:107], v[116:117] op_sel_hi:[1,0]
	v_pk_mul_f32 v[98:99], v[98:99], v[116:117] op_sel_hi:[1,0]
	v_add_f32_e32 v115, 1.0, v115
	v_rcp_f32_e32 v118, v115
	v_mul_f32_e32 v115, 0xbfb8aa3b, v111
	v_exp_f32_e32 v115, v115
	v_pk_mul_f32 v[100:101], v[100:101], v[116:117] op_sel_hi:[1,0]
	v_add_f32_e32 v115, 1.0, v115
	v_rcp_f32_e32 v119, v115
	s_nop 0
	v_pk_mul_f32 v[110:111], v[110:111], v[118:119]
	s_nop 0
	v_pk_mul_f32 v[102:103], v[102:103], v[110:111]
	v_pk_mul_f32 v[110:111], v[112:113], v[116:117] op_sel_hi:[1,0]
	s_nop 0
	v_mul_f32_e32 v112, 0xbfb8aa3b, v110
	v_mul_f32_e32 v113, 0xbfb8aa3b, v111
	v_exp_f32_e32 v112, v112
	v_exp_f32_e32 v113, v113
	v_add_f32_e32 v112, 1.0, v112
	v_add_f32_e32 v113, 1.0, v113
	v_rcp_f32_e32 v112, v112
	v_rcp_f32_e32 v113, v113
	s_nop 0
	v_pk_mul_f32 v[110:111], v[110:111], v[112:113]
	s_nop 0
	v_pk_mul_f32 v[104:105], v[104:105], v[110:111]
	v_mul_f32_e32 v110, 0xbfb8aa3b, v106
	v_mul_f32_e32 v111, 0xbfb8aa3b, v107
	v_exp_f32_e32 v110, v110
	v_exp_f32_e32 v111, v111
	v_add_f32_e32 v110, 1.0, v110
	v_add_f32_e32 v111, 1.0, v111
; __device__ __forceinline__ unsigned pk2(float lo, float hi) { f32x2_t v = {lo, hi}; bf16x2_t b = __builtin_convertvector(v, bf16x2_t); return __builtin_bit_cast(unsigned, b); }
; __device__ __forceinline__ float fast_sigmoid(float x) { return __builtin_amdgcn_rcpf(1.f + __expf(-x)); }
;     __device__ __forceinline__ void operator()(const f32x4 (&acc)[2][2][4][2], const Unit& u, int wr, int wc, int fr, int fq) const {
;     ...
;             for (int m = 0; m < 4; ++m) {
;                 const int row = row0 + ai * HALF + m * 16;
;                 const float rs = rsqrtf(row_ssq(ssq, 16, 4, row, fq) * (1.f / 1024.f) + EPS);
;                 float r[8];
; #pragma unroll
;                 for (int n = 0; n < 2; ++n)
; #pragma unroll
;                     for (int e = 0; e < 4; ++e) { const float gv = acc[ai][0][m][n][e] * rs, uv = acc[ai][1][m][n][e] * rs; r[n * 4 + e] = gv * fast_sigmoid(gv) * uv; }
;                 u32x4 w; w.x = pk2(r[0], r[1]); w.y = pk2(r[2], r[3]); w.z = pk2(r[4], r[5]); w.w = pk2(r[6], r[7]);
;                 *(u32x4*)(O + (size_t)row * DFF + col0) = w;
	v_rcp_f32_e32 v110, v110
	v_rcp_f32_e32 v111, v111
	s_nop 0
	v_pk_mul_f32 v[106:107], v[106:107], v[110:111]
	s_nop 0
	v_pk_mul_f32 v[106:107], v[98:99], v[106:107]
	v_pk_mul_f32 v[98:99], v[108:109], v[116:117] op_sel_hi:[1,0]
	s_nop 0
	v_mul_f32_e32 v108, 0xbfb8aa3b, v98
	v_mul_f32_e32 v109, 0xbfb8aa3b, v99
	v_exp_f32_e32 v108, v108
	v_exp_f32_e32 v109, v109
	v_add_f32_e32 v108, 1.0, v108
	v_add_f32_e32 v109, 1.0, v109
	v_rcp_f32_e32 v108, v108
	v_rcp_f32_e32 v109, v109
	s_nop 0
	v_pk_mul_f32 v[98:99], v[98:99], v[108:109]
	s_nop 0
	v_pk_mul_f32 v[108:109], v[100:101], v[98:99]
	v_cvt_pk_bf16_f32 v98, v102, v103
	v_cvt_pk_bf16_f32 v99, v104, v105
	v_cvt_pk_bf16_f32 v100, v106, v107
	v_cvt_pk_bf16_f32 v101, v108, v109
	v_mad_i64_i32 v[102:103], s[6:7], v114, s4, v[142:143]
	global_store_dwordx4 v[102:103], v[98:101], off
	s_nop 1
	v_or_b32_e32 v98, 32, v144
	v_mov_b32_e32 v100, v160
	v_pk_mul_f32 v[94:95], v[94:95], v[100:101] op_sel_hi:[1,0]
	v_pk_mul_f32 v[86:87], v[86:87], v[100:101] op_sel_hi:[1,0]
	v_mul_f32_e32 v99, 0xbfb8aa3b, v94
	v_exp_f32_e32 v99, v99
	v_pk_mul_f32 v[88:89], v[88:89], v[100:101] op_sel_hi:[1,0]
	v_pk_mul_f32 v[90:91], v[90:91], v[100:101] op_sel_hi:[1,0]
	v_pk_mul_f32 v[82:83], v[82:83], v[100:101] op_sel_hi:[1,0]
	v_add_f32_e32 v99, 1.0, v99
	v_rcp_f32_e32 v102, v99
	v_mul_f32_e32 v99, 0xbfb8aa3b, v95
	v_exp_f32_e32 v99, v99
	v_pk_mul_f32 v[84:85], v[84:85], v[100:101] op_sel_hi:[1,0]
	v_add_f32_e32 v99, 1.0, v99
	v_rcp_f32_e32 v103, v99
	s_nop 0
	v_pk_mul_f32 v[94:95], v[94:95], v[102:103]
	s_nop 0
	v_pk_mul_f32 v[86:87], v[86:87], v[94:95]
	v_pk_mul_f32 v[94:95], v[96:97], v[100:101] op_sel_hi:[1,0]
	s_nop 0
	v_mul_f32_e32 v96, 0xbfb8aa3b, v94
	v_mul_f32_e32 v97, 0xbfb8aa3b, v95
	v_exp_f32_e32 v96, v96
	v_exp_f32_e32 v97, v97
	v_add_f32_e32 v96, 1.0, v96
	v_add_f32_e32 v97, 1.0, v97
	v_rcp_f32_e32 v96, v96
	v_rcp_f32_e32 v97, v97
	s_nop 0
	v_pk_mul_f32 v[94:95], v[94:95], v[96:97]
	s_nop 0
	v_pk_mul_f32 v[88:89], v[88:89], v[94:95]
	v_mul_f32_e32 v94, 0xbfb8aa3b, v90
	v_mul_f32_e32 v95, 0xbfb8aa3b, v91
	v_exp_f32_e32 v94, v94
	v_exp_f32_e32 v95, v95
	v_add_f32_e32 v94, 1.0, v94
	v_add_f32_e32 v95, 1.0, v95
	v_rcp_f32_e32 v94, v94
	v_rcp_f32_e32 v95, v95
	s_nop 0
	v_pk_mul_f32 v[90:91], v[90:91], v[94:95]
	s_nop 0
	v_pk_mul_f32 v[90:91], v[82:83], v[90:91]
	v_pk_mul_f32 v[82:83], v[92:93], v[100:101] op_sel_hi:[1,0]
	s_nop 0
	v_mul_f32_e32 v92, 0xbfb8aa3b, v82
	v_mul_f32_e32 v93, 0xbfb8aa3b, v83
	v_exp_f32_e32 v92, v92
	v_exp_f32_e32 v93, v93
	v_add_f32_e32 v92, 1.0, v92
	v_add_f32_e32 v93, 1.0, v93
	v_rcp_f32_e32 v92, v92
	v_rcp_f32_e32 v93, v93
	s_nop 0
	v_pk_mul_f32 v[82:83], v[82:83], v[92:93]
	s_nop 0
	v_pk_mul_f32 v[92:93], v[84:85], v[82:83]
	v_cvt_pk_bf16_f32 v82, v86, v87
	v_cvt_pk_bf16_f32 v83, v88, v89
	v_cvt_pk_bf16_f32 v84, v90, v91
	v_cvt_pk_bf16_f32 v85, v92, v93
	v_mad_i64_i32 v[86:87], s[6:7], v98, s4, v[142:143]
	global_store_dwordx4 v[86:87], v[82:85], off
	s_nop 1
	v_or_b32_e32 v82, 48, v144
	v_mov_b32_e32 v84, v161
	v_pk_mul_f32 v[78:79], v[78:79], v[84:85] op_sel_hi:[1,0]
	v_pk_mul_f32 v[70:71], v[70:71], v[84:85] op_sel_hi:[1,0]
	v_mul_f32_e32 v83, 0xbfb8aa3b, v78
	v_exp_f32_e32 v83, v83
	v_pk_mul_f32 v[72:73], v[72:73], v[84:85] op_sel_hi:[1,0]
	v_pk_mul_f32 v[74:75], v[74:75], v[84:85] op_sel_hi:[1,0]
	v_pk_mul_f32 v[66:67], v[66:67], v[84:85] op_sel_hi:[1,0]
	v_add_f32_e32 v83, 1.0, v83
	v_rcp_f32_e32 v86, v83
	v_mul_f32_e32 v83, 0xbfb8aa3b, v79
	v_exp_f32_e32 v83, v83
	v_pk_mul_f32 v[68:69], v[68:69], v[84:85] op_sel_hi:[1,0]
	v_add_f32_e32 v83, 1.0, v83
	v_rcp_f32_e32 v87, v83
	s_nop 0
	v_pk_mul_f32 v[78:79], v[78:79], v[86:87]
	s_nop 0
	v_pk_mul_f32 v[70:71], v[70:71], v[78:79]
	v_pk_mul_f32 v[78:79], v[80:81], v[84:85] op_sel_hi:[1,0]
	s_nop 0
	v_mul_f32_e32 v80, 0xbfb8aa3b, v78
	v_mul_f32_e32 v81, 0xbfb8aa3b, v79
	v_exp_f32_e32 v80, v80
	v_exp_f32_e32 v81, v81
	v_add_f32_e32 v80, 1.0, v80
	v_add_f32_e32 v81, 1.0, v81
	v_rcp_f32_e32 v80, v80
	v_rcp_f32_e32 v81, v81
	s_nop 0
	v_pk_mul_f32 v[78:79], v[78:79], v[80:81]
	s_nop 0
	v_pk_mul_f32 v[72:73], v[72:73], v[78:79]
	v_mul_f32_e32 v78, 0xbfb8aa3b, v74
	v_mul_f32_e32 v79, 0xbfb8aa3b, v75
	v_exp_f32_e32 v78, v78
	v_exp_f32_e32 v79, v79
	v_add_f32_e32 v78, 1.0, v78
	v_add_f32_e32 v79, 1.0, v79
	v_rcp_f32_e32 v78, v78
	v_rcp_f32_e32 v79, v79
	s_nop 0
	v_pk_mul_f32 v[74:75], v[74:75], v[78:79]
	s_nop 0
	v_pk_mul_f32 v[74:75], v[66:67], v[74:75]
	v_pk_mul_f32 v[66:67], v[76:77], v[84:85] op_sel_hi:[1,0]
	s_nop 0
	v_mul_f32_e32 v76, 0xbfb8aa3b, v66
	v_mul_f32_e32 v77, 0xbfb8aa3b, v67
	v_exp_f32_e32 v76, v76
	v_exp_f32_e32 v77, v77
	v_add_f32_e32 v76, 1.0, v76
	v_add_f32_e32 v77, 1.0, v77
	v_rcp_f32_e32 v76, v76
	v_rcp_f32_e32 v77, v77
	s_nop 0
	v_pk_mul_f32 v[66:67], v[66:67], v[76:77]
	s_nop 0
	v_pk_mul_f32 v[76:77], v[68:69], v[66:67]
	v_cvt_pk_bf16_f32 v66, v70, v71
	v_cvt_pk_bf16_f32 v67, v72, v73
	v_cvt_pk_bf16_f32 v68, v74, v75
	v_cvt_pk_bf16_f32 v69, v76, v77
	v_mad_i64_i32 v[70:71], s[6:7], v82, s4, v[142:143]
	global_store_dwordx4 v[70:71], v[66:69], off
	s_nop 1
	v_add_u32_e32 v66, 0x80, v144
	v_mov_b32_e32 v68, v162
	v_pk_mul_f32 v[62:63], v[62:63], v[68:69] op_sel_hi:[1,0]
	v_pk_mul_f32 v[54:55], v[54:55], v[68:69] op_sel_hi:[1,0]
	v_mul_f32_e32 v67, 0xbfb8aa3b, v62
	v_exp_f32_e32 v67, v67
	v_pk_mul_f32 v[56:57], v[56:57], v[68:69] op_sel_hi:[1,0]
	v_pk_mul_f32 v[58:59], v[58:59], v[68:69] op_sel_hi:[1,0]
	v_pk_mul_f32 v[50:51], v[50:51], v[68:69] op_sel_hi:[1,0]
	v_add_f32_e32 v67, 1.0, v67
	v_rcp_f32_e32 v70, v67
	v_mul_f32_e32 v67, 0xbfb8aa3b, v63
	v_exp_f32_e32 v67, v67
	v_pk_mul_f32 v[52:53], v[52:53], v[68:69] op_sel_hi:[1,0]
; __device__ __forceinline__ unsigned pk2(float lo, float hi) { f32x2_t v = {lo, hi}; bf16x2_t b = __builtin_convertvector(v, bf16x2_t); return __builtin_bit_cast(unsigned, b); }
; __device__ __forceinline__ float fast_sigmoid(float x) { return __builtin_amdgcn_rcpf(1.f + __expf(-x)); }
;     __device__ __forceinline__ void operator()(const f32x4 (&acc)[2][2][4][2], const Unit& u, int wr, int wc, int fr, int fq) const {
;     ...
;             for (int m = 0; m < 4; ++m) {
;                 const int row = row0 + ai * HALF + m * 16;
;                 const float rs = rsqrtf(row_ssq(ssq, 16, 4, row, fq) * (1.f / 1024.f) + EPS);
;                 float r[8];
; #pragma unroll
;                 for (int n = 0; n < 2; ++n)
; #pragma unroll
;                     for (int e = 0; e < 4; ++e) { const float gv = acc[ai][0][m][n][e] * rs, uv = acc[ai][1][m][n][e] * rs; r[n * 4 + e] = gv * fast_sigmoid(gv) * uv; }
;                 u32x4 w; w.x = pk2(r[0], r[1]); w.y = pk2(r[2], r[3]); w.z = pk2(r[4], r[5]); w.w = pk2(r[6], r[7]);
;                 *(u32x4*)(O + (size_t)row * DFF + col0) = w;
	v_add_f32_e32 v67, 1.0, v67
	v_rcp_f32_e32 v71, v67
	s_nop 0
	v_pk_mul_f32 v[62:63], v[62:63], v[70:71]
	s_nop 0
	v_pk_mul_f32 v[54:55], v[54:55], v[62:63]
	v_pk_mul_f32 v[62:63], v[64:65], v[68:69] op_sel_hi:[1,0]
	s_nop 0
	v_mul_f32_e32 v64, 0xbfb8aa3b, v62
	v_mul_f32_e32 v65, 0xbfb8aa3b, v63
	v_exp_f32_e32 v64, v64
	v_exp_f32_e32 v65, v65
	v_add_f32_e32 v64, 1.0, v64
	v_add_f32_e32 v65, 1.0, v65
	v_rcp_f32_e32 v64, v64
	v_rcp_f32_e32 v65, v65
	s_nop 0
	v_pk_mul_f32 v[62:63], v[62:63], v[64:65]
	s_nop 0
	v_pk_mul_f32 v[56:57], v[56:57], v[62:63]
	v_mul_f32_e32 v62, 0xbfb8aa3b, v58
	v_mul_f32_e32 v63, 0xbfb8aa3b, v59
	v_exp_f32_e32 v62, v62
	v_exp_f32_e32 v63, v63
	v_add_f32_e32 v62, 1.0, v62
	v_add_f32_e32 v63, 1.0, v63
	v_rcp_f32_e32 v62, v62
	v_rcp_f32_e32 v63, v63
	s_nop 0
	v_pk_mul_f32 v[58:59], v[58:59], v[62:63]
	s_nop 0
	v_pk_mul_f32 v[58:59], v[50:51], v[58:59]
	v_pk_mul_f32 v[50:51], v[60:61], v[68:69] op_sel_hi:[1,0]
	s_nop 0
	v_mul_f32_e32 v60, 0xbfb8aa3b, v50
	v_mul_f32_e32 v61, 0xbfb8aa3b, v51
	v_exp_f32_e32 v60, v60
	v_exp_f32_e32 v61, v61
	v_add_f32_e32 v60, 1.0, v60
	v_add_f32_e32 v61, 1.0, v61
	v_rcp_f32_e32 v60, v60
	v_rcp_f32_e32 v61, v61
	s_nop 0
	v_pk_mul_f32 v[50:51], v[50:51], v[60:61]
	s_nop 0
	v_pk_mul_f32 v[60:61], v[52:53], v[50:51]
	v_cvt_pk_bf16_f32 v50, v54, v55
	v_cvt_pk_bf16_f32 v51, v56, v57
	v_cvt_pk_bf16_f32 v52, v58, v59
	v_cvt_pk_bf16_f32 v53, v60, v61
	v_mad_i64_i32 v[54:55], s[6:7], v66, s4, v[142:143]
	global_store_dwordx4 v[54:55], v[50:53], off
	s_nop 1
	v_add_u32_e32 v50, 0x90, v144
	v_mov_b32_e32 v52, v163
	v_pk_mul_f32 v[46:47], v[46:47], v[52:53] op_sel_hi:[1,0]
	v_pk_mul_f32 v[38:39], v[38:39], v[52:53] op_sel_hi:[1,0]
	v_mul_f32_e32 v51, 0xbfb8aa3b, v46
	v_exp_f32_e32 v51, v51
	v_pk_mul_f32 v[40:41], v[40:41], v[52:53] op_sel_hi:[1,0]
	v_pk_mul_f32 v[42:43], v[42:43], v[52:53] op_sel_hi:[1,0]
	v_pk_mul_f32 v[34:35], v[34:35], v[52:53] op_sel_hi:[1,0]
	v_add_f32_e32 v51, 1.0, v51
	v_rcp_f32_e32 v54, v51
	v_mul_f32_e32 v51, 0xbfb8aa3b, v47
	v_exp_f32_e32 v51, v51
	v_pk_mul_f32 v[36:37], v[36:37], v[52:53] op_sel_hi:[1,0]
	v_add_f32_e32 v51, 1.0, v51
	v_rcp_f32_e32 v55, v51
	s_nop 0
	v_pk_mul_f32 v[46:47], v[46:47], v[54:55]
	s_nop 0
	v_pk_mul_f32 v[38:39], v[38:39], v[46:47]
	v_pk_mul_f32 v[46:47], v[48:49], v[52:53] op_sel_hi:[1,0]
	s_nop 0
	v_mul_f32_e32 v48, 0xbfb8aa3b, v46
	v_mul_f32_e32 v49, 0xbfb8aa3b, v47
	v_exp_f32_e32 v48, v48
	v_exp_f32_e32 v49, v49
	v_add_f32_e32 v48, 1.0, v48
	v_add_f32_e32 v49, 1.0, v49
	v_rcp_f32_e32 v48, v48
	v_rcp_f32_e32 v49, v49
	s_nop 0
	v_pk_mul_f32 v[46:47], v[46:47], v[48:49]
	s_nop 0
	v_pk_mul_f32 v[40:41], v[40:41], v[46:47]
	v_mul_f32_e32 v46, 0xbfb8aa3b, v42
	v_mul_f32_e32 v47, 0xbfb8aa3b, v43
	v_exp_f32_e32 v46, v46
	v_exp_f32_e32 v47, v47
	v_add_f32_e32 v46, 1.0, v46
	v_add_f32_e32 v47, 1.0, v47
	v_rcp_f32_e32 v46, v46
	v_rcp_f32_e32 v47, v47
	s_nop 0
	v_pk_mul_f32 v[42:43], v[42:43], v[46:47]
	s_nop 0
	v_pk_mul_f32 v[42:43], v[34:35], v[42:43]
	v_pk_mul_f32 v[34:35], v[44:45], v[52:53] op_sel_hi:[1,0]
	s_nop 0
	v_mul_f32_e32 v44, 0xbfb8aa3b, v34
	v_mul_f32_e32 v45, 0xbfb8aa3b, v35
	v_exp_f32_e32 v44, v44
	v_exp_f32_e32 v45, v45
	v_add_f32_e32 v44, 1.0, v44
	v_add_f32_e32 v45, 1.0, v45
	v_rcp_f32_e32 v44, v44
	v_rcp_f32_e32 v45, v45
	s_nop 0
	v_pk_mul_f32 v[34:35], v[34:35], v[44:45]
	s_nop 0
	v_pk_mul_f32 v[44:45], v[36:37], v[34:35]
	v_cvt_pk_bf16_f32 v34, v38, v39
	v_cvt_pk_bf16_f32 v35, v40, v41
	v_cvt_pk_bf16_f32 v36, v42, v43
	v_cvt_pk_bf16_f32 v37, v44, v45
	v_mad_i64_i32 v[38:39], s[6:7], v50, s4, v[142:143]
	global_store_dwordx4 v[38:39], v[34:37], off
	s_nop 1
	v_add_u32_e32 v34, 0xa0, v144
	v_mov_b32_e32 v36, v164
	v_pk_mul_f32 v[30:31], v[30:31], v[36:37] op_sel_hi:[1,0]
	v_pk_mul_f32 v[22:23], v[22:23], v[36:37] op_sel_hi:[1,0]
	v_mul_f32_e32 v35, 0xbfb8aa3b, v30
	v_exp_f32_e32 v35, v35
	v_pk_mul_f32 v[24:25], v[24:25], v[36:37] op_sel_hi:[1,0]
	v_pk_mul_f32 v[26:27], v[26:27], v[36:37] op_sel_hi:[1,0]
; __device__ __forceinline__ unsigned pk2(float lo, float hi) { f32x2_t v = {lo, hi}; bf16x2_t b = __builtin_convertvector(v, bf16x2_t); return __builtin_bit_cast(unsigned, b); }
; __device__ __forceinline__ float fast_sigmoid(float x) { return __builtin_amdgcn_rcpf(1.f + __expf(-x)); }
; #define PG8_BAR __builtin_amdgcn_s_barrier()
; template <class Epi>
; __device__ __forceinline__ void gemm_phase(LAS unsigned char* lds, int wave_s, const Gemm g, const StaticOrder S, const Epi E) {
;     ...
;         if (!has_next) break;
; #pragma unroll
;         for (int a = 0; a < 2; ++a)
; #pragma unroll
;             for (int b = 0; b < 2; ++b)
; #pragma unroll
;                 for (int m = 0; m < 4; ++m)
; #pragma unroll
;                     for (int n = 0; n < 2; ++n) acc[a][b][m][n] = (f32x4){0.f, 0.f, 0.f, 0.f};
;         cur = nxt; cA = nA; cB = nB; ++ui;
;         if (wr == 1) PG8_BAR;
;     __device__ __forceinline__ void operator()(const f32x4 (&acc)[2][2][4][2], const Unit& u, int wr, int wc, int fr, int fq) const {
;     ...
;             for (int m = 0; m < 4; ++m) {
;                 const int row = row0 + ai * HALF + m * 16;
;                 const float rs = rsqrtf(row_ssq(ssq, 16, 4, row, fq) * (1.f / 1024.f) + EPS);
;                 float r[8];
; #pragma unroll
;                 for (int n = 0; n < 2; ++n)
; #pragma unroll
;                     for (int e = 0; e < 4; ++e) { const float gv = acc[ai][0][m][n][e] * rs, uv = acc[ai][1][m][n][e] * rs; r[n * 4 + e] = gv * fast_sigmoid(gv) * uv; }
;                 u32x4 w; w.x = pk2(r[0], r[1]); w.y = pk2(r[2], r[3]); w.z = pk2(r[4], r[5]); w.w = pk2(r[6], r[7]);
;                 *(u32x4*)(O + (size_t)row * DFF + col0) = w;
	v_pk_mul_f32 v[18:19], v[18:19], v[36:37] op_sel_hi:[1,0]
	v_add_f32_e32 v35, 1.0, v35
	v_rcp_f32_e32 v38, v35
	v_mul_f32_e32 v35, 0xbfb8aa3b, v31
	v_exp_f32_e32 v35, v35
	v_pk_mul_f32 v[20:21], v[20:21], v[36:37] op_sel_hi:[1,0]
	v_add_f32_e32 v35, 1.0, v35
	v_rcp_f32_e32 v39, v35
	s_nop 0
	v_pk_mul_f32 v[30:31], v[30:31], v[38:39]
	s_nop 0
	v_pk_mul_f32 v[22:23], v[22:23], v[30:31]
	v_pk_mul_f32 v[30:31], v[32:33], v[36:37] op_sel_hi:[1,0]
	s_nop 0
	v_mul_f32_e32 v32, 0xbfb8aa3b, v30
	v_mul_f32_e32 v33, 0xbfb8aa3b, v31
	v_exp_f32_e32 v32, v32
	v_exp_f32_e32 v33, v33
	v_add_f32_e32 v32, 1.0, v32
	v_add_f32_e32 v33, 1.0, v33
	v_rcp_f32_e32 v32, v32
	v_rcp_f32_e32 v33, v33
	s_nop 0
	v_pk_mul_f32 v[30:31], v[30:31], v[32:33]
	s_nop 0
	v_pk_mul_f32 v[24:25], v[24:25], v[30:31]
	v_mul_f32_e32 v30, 0xbfb8aa3b, v26
	v_mul_f32_e32 v31, 0xbfb8aa3b, v27
	v_exp_f32_e32 v30, v30
	v_exp_f32_e32 v31, v31
	v_add_f32_e32 v30, 1.0, v30
	v_add_f32_e32 v31, 1.0, v31
	v_rcp_f32_e32 v30, v30
	v_rcp_f32_e32 v31, v31
	s_nop 0
	v_pk_mul_f32 v[26:27], v[26:27], v[30:31]
	s_nop 0
	v_pk_mul_f32 v[26:27], v[18:19], v[26:27]
	v_pk_mul_f32 v[18:19], v[28:29], v[36:37] op_sel_hi:[1,0]
	s_nop 0
	v_mul_f32_e32 v28, 0xbfb8aa3b, v18
	v_mul_f32_e32 v29, 0xbfb8aa3b, v19
	v_exp_f32_e32 v28, v28
	v_exp_f32_e32 v29, v29
	v_add_f32_e32 v28, 1.0, v28
	v_add_f32_e32 v29, 1.0, v29
	v_rcp_f32_e32 v28, v28
	v_rcp_f32_e32 v29, v29
	s_nop 0
	v_pk_mul_f32 v[18:19], v[18:19], v[28:29]
	s_nop 0
	v_pk_mul_f32 v[28:29], v[20:21], v[18:19]
	v_cvt_pk_bf16_f32 v18, v22, v23
	v_cvt_pk_bf16_f32 v19, v24, v25
	v_cvt_pk_bf16_f32 v20, v26, v27
	v_cvt_pk_bf16_f32 v21, v28, v29
	v_mad_i64_i32 v[22:23], s[6:7], v34, s4, v[142:143]
	global_store_dwordx4 v[22:23], v[18:21], off
	s_nop 1
	v_add_u32_e32 v18, 0xb0, v144
	v_mov_b32_e32 v20, v165
	v_pk_mul_f32 v[14:15], v[14:15], v[20:21] op_sel_hi:[1,0]
	v_pk_mul_f32 v[6:7], v[6:7], v[20:21] op_sel_hi:[1,0]
	v_mul_f32_e32 v19, 0xbfb8aa3b, v14
	v_exp_f32_e32 v19, v19
	v_pk_mul_f32 v[8:9], v[8:9], v[20:21] op_sel_hi:[1,0]
	v_pk_mul_f32 v[10:11], v[10:11], v[20:21] op_sel_hi:[1,0]
	v_pk_mul_f32 v[2:3], v[2:3], v[20:21] op_sel_hi:[1,0]
	v_add_f32_e32 v19, 1.0, v19
	v_rcp_f32_e32 v22, v19
	v_mul_f32_e32 v19, 0xbfb8aa3b, v15
	v_exp_f32_e32 v19, v19
	v_pk_mul_f32 v[4:5], v[4:5], v[20:21] op_sel_hi:[1,0]
	s_andn2_b64 vcc, exec, s[42:43]
	v_add_f32_e32 v19, 1.0, v19
	v_rcp_f32_e32 v23, v19
	s_nop 0
	v_pk_mul_f32 v[14:15], v[14:15], v[22:23]
	s_nop 0
	v_pk_mul_f32 v[6:7], v[6:7], v[14:15]
	v_pk_mul_f32 v[14:15], v[16:17], v[20:21] op_sel_hi:[1,0]
	s_nop 0
	v_mul_f32_e32 v16, 0xbfb8aa3b, v14
	v_mul_f32_e32 v17, 0xbfb8aa3b, v15
	v_exp_f32_e32 v16, v16
	v_exp_f32_e32 v17, v17
	v_add_f32_e32 v16, 1.0, v16
	v_add_f32_e32 v17, 1.0, v17
	v_rcp_f32_e32 v16, v16
	v_rcp_f32_e32 v17, v17
	s_nop 0
	v_pk_mul_f32 v[14:15], v[14:15], v[16:17]
	s_nop 0
	v_pk_mul_f32 v[8:9], v[8:9], v[14:15]
	v_mul_f32_e32 v14, 0xbfb8aa3b, v10
	v_mul_f32_e32 v15, 0xbfb8aa3b, v11
	v_exp_f32_e32 v14, v14
	v_exp_f32_e32 v15, v15
	v_add_f32_e32 v14, 1.0, v14
	v_add_f32_e32 v15, 1.0, v15
	v_rcp_f32_e32 v14, v14
	v_rcp_f32_e32 v15, v15
	s_nop 0
	v_pk_mul_f32 v[10:11], v[10:11], v[14:15]
	s_nop 0
	v_pk_mul_f32 v[10:11], v[2:3], v[10:11]
	v_pk_mul_f32 v[2:3], v[12:13], v[20:21] op_sel_hi:[1,0]
	s_nop 0
	v_mul_f32_e32 v12, 0xbfb8aa3b, v2
	v_mul_f32_e32 v13, 0xbfb8aa3b, v3
	v_exp_f32_e32 v12, v12
	v_exp_f32_e32 v13, v13
	v_add_f32_e32 v12, 1.0, v12
	v_add_f32_e32 v13, 1.0, v13
	v_rcp_f32_e32 v12, v12
	v_rcp_f32_e32 v13, v13
	s_nop 0
	v_pk_mul_f32 v[2:3], v[2:3], v[12:13]
	s_nop 0
	v_pk_mul_f32 v[12:13], v[4:5], v[2:3]
	v_cvt_pk_bf16_f32 v2, v6, v7
	v_cvt_pk_bf16_f32 v3, v8, v9
	v_cvt_pk_bf16_f32 v4, v10, v11
	v_cvt_pk_bf16_f32 v5, v12, v13
	v_mad_i64_i32 v[6:7], s[6:7], v18, s4, v[142:143]
	global_store_dwordx4 v[6:7], v[2:5], off
	s_cbranch_vccnz .LBB0_1147
	s_andn2_b64 vcc, exec, s[0:1]
	s_cbranch_vccnz .LBB0_1146
	s_barrier
	s_branch .LBB0_1146

; __device__ __forceinline__ float bflo(unsigned u) { return __uint_as_float(u << 16); }
;     __device__ __forceinline__ void operator()(const f32x4 (&acc)[2][2][4][2], const Unit& u, int wr, int wc, int fr, int fq) const {
;         const int row0 = u.pm * BM + wr * 64 + fr, col0 = u.pn * BM + wc * 32 + 8 * fq;
; #pragma unroll
;         for (int ai = 0; ai < 2; ++ai)
; #pragma unroll
;             for (int m = 0; m < 4; ++m) {
;                 const int row = row0 + ai * HALF + m * 16;
;                 float rs = 0.f; if (GATED) rs = rsqrtf(row_ssq(ssq_in, 16, 4, row, fq) * (1.f / 1024.f) + EPS);
;                 float sq = 0.f;
; #pragma unroll
;                 for (int bj = 0; bj < 2; ++bj) {
;                     const size_t off = (size_t)row * DM + col0 + bj * HALF;
;                     const u32x4 hh = *(const u32x4*)(HI + off), ll = *(const u32x4*)(LO + off);
;                     float hv[8] = {bflo(hh.x) + bflo(ll.x), bfhi(hh.x) + bfhi(ll.x), bflo(hh.y) + bflo(ll.y), bfhi(hh.y) + bfhi(ll.y),
;                                    bflo(hh.z) + bflo(ll.z), bfhi(hh.z) + bfhi(ll.z), bflo(hh.w) + bflo(ll.w), bfhi(hh.w) + bfhi(ll.w)};
;                     float av[8] = {acc[ai][bj][m][0][0], acc[ai][bj][m][0][1], acc[ai][bj][m][0][2], acc[ai][bj][m][0][3], acc[ai][bj][m][1][0], acc[ai][bj][m][1][1], acc[ai][bj][m][1][2], acc[ai][bj][m][1][3]};
;                     if (GATED) { const u32x4 pp = *(const u32x4*)(PP + off);
;                         const float pv[8] = {bflo(pp.x), bfhi(pp.x), bflo(pp.y), bfhi(pp.y), bflo(pp.z), bfhi(pp.z), bflo(pp.w), bfhi(pp.w)};
; #pragma unroll
;                         for (int e = 0; e < 8; ++e) av[e] = fast_sigmoid(av[e] * rs) * pv[e]; }
;                     else {
; #pragma unroll
;                         for (int e = 0; e < 8; ++e) av[e] *= alpha; }
;                     float lo[8];
; #pragma unroll
;                     for (int e = 0; e < 8; ++e) { hv[e] += av[e]; sq += hv[e] * hv[e]; }
;                     u32x4 wh; wh.x = pk2(hv[0], hv[1]); wh.y = pk2(hv[2], hv[3]); wh.z = pk2(hv[4], hv[5]); wh.w = pk2(hv[6], hv[7]);
;                     lo[0] = hv[0] - bflo(wh.x); lo[1] = hv[1] - bfhi(wh.x); lo[2] = hv[2] - bflo(wh.y); lo[3] = hv[3] - bfhi(wh.y);
;                     lo[4] = hv[4] - bflo(wh.z); lo[5] = hv[5] - bfhi(wh.z); lo[6] = hv[6] - bflo(wh.w); lo[7] = hv[7] - bfhi(wh.w);
.LBB0_1250:
	v_and_b32_e32 v158, 64, v241
	v_xor_b32_e32 v214, 16, v241
	v_add_u32_e32 v158, 64, v158
	v_cmp_lt_i32_e32 vcc, v214, v158
	v_lshl_add_u32 v156, s31, 8, v160
	v_lshl_or_b32 v157, s4, 8, v162
	v_cndmask_b32_e32 v214, v241, v214, vcc
	v_lshlrev_b32_e32 v214, 2, v214
	v_xor_b32_e32 v215, 32, v241
	v_cmp_lt_i32_e32 vcc, v215, v158
	v_readlane_b32 s10, v253, 35
	v_readlane_b32 s11, v253, 36
	v_readlane_b32 s6, v250, 49
	v_readlane_b32 s7, v250, 50
	s_nop 1
	v_cndmask_b32_e32 v215, v241, v215, vcc
	v_lshlrev_b32_e32 v215, 2, v215
	v_lshl_add_u32 v213, v156, 10, v157
	v_lshlrev_b32_e32 v213, 1, v213
	s_lshl_b32 s40, s4, 4
	s_lshl_b32 s50, s25, 2
	s_add_i32 s40, s40, s50
	v_lshlrev_b32_e32 v216, 6, v156
	v_add_u32_e32 v216, s40, v216
	v_add_u32_e32 v217, 0x2000, v216
	s_nop 1
	v_mov_b32_e32 v210, v213
	global_load_dwordx4 v[140:143], v210, s[10:11]
	global_load_dwordx4 v[144:147], v210, s[6:7]
	global_load_dwordx4 v[148:151], v210, s[10:11] offset:256
	global_load_dwordx4 v[152:155], v210, s[6:7] offset:256
	v_add_u32_e32 v211, 0x8000, v213
	global_load_dwordx4 v[164:167], v211, s[10:11]
	global_load_dwordx4 v[168:171], v211, s[6:7]
	global_load_dwordx4 v[172:175], v211, s[10:11] offset:256
	global_load_dwordx4 v[176:179], v211, s[6:7] offset:256
	v_add_u32_e32 v212, 0x10000, v213
	global_load_dwordx4 v[180:183], v212, s[10:11]
	global_load_dwordx4 v[184:187], v212, s[6:7]
	global_load_dwordx4 v[188:191], v212, s[10:11] offset:256
	global_load_dwordx4 v[192:195], v212, s[6:7] offset:256
	s_waitcnt vmcnt(10)
	v_lshlrev_b32_e32 v156, 16, v140
	v_and_b32_e32 v157, 0xffff0000, v140
	v_lshlrev_b32_e32 v158, 16, v144
	v_and_b32_e32 v159, 0xffff0000, v144
	v_pk_add_f32 v[156:157], v[156:157], v[158:159]
	v_pk_fma_f32 v[156:157], v[126:127], 0.5, v[156:157] op_sel_hi:[1,0,1]
	v_cvt_pk_bf16_f32 v140, v156, v157
	v_pk_mul_f32 v[198:199], v[156:157], v[156:157]
	v_lshlrev_b32_e32 v158, 16, v140
	v_and_b32_e32 v159, 0xffff0000, v140
	v_pk_add_f32 v[196:197], v[156:157], v[158:159] neg_lo:[0,1] neg_hi:[0,1]
	v_cvt_pk_bf16_f32 v144, v196, v197
	v_lshlrev_b32_e32 v156, 16, v141
	v_and_b32_e32 v157, 0xffff0000, v141
	v_lshlrev_b32_e32 v158, 16, v145
	v_and_b32_e32 v159, 0xffff0000, v145
	v_pk_add_f32 v[156:157], v[156:157], v[158:159]
	v_pk_fma_f32 v[156:157], v[128:129], 0.5, v[156:157] op_sel_hi:[1,0,1]
	v_cvt_pk_bf16_f32 v141, v156, v157
	v_pk_fma_f32 v[198:199], v[156:157], v[156:157], v[198:199]
	v_lshlrev_b32_e32 v158, 16, v141
	v_and_b32_e32 v159, 0xffff0000, v141
	v_pk_add_f32 v[196:197], v[156:157], v[158:159] neg_lo:[0,1] neg_hi:[0,1]
	v_cvt_pk_bf16_f32 v145, v196, v197
	v_lshlrev_b32_e32 v156, 16, v142
	v_and_b32_e32 v157, 0xffff0000, v142
	v_lshlrev_b32_e32 v158, 16, v146
	v_and_b32_e32 v159, 0xffff0000, v146
	v_pk_add_f32 v[156:157], v[156:157], v[158:159]
	v_pk_fma_f32 v[156:157], v[122:123], 0.5, v[156:157] op_sel_hi:[1,0,1]
	v_cvt_pk_bf16_f32 v142, v156, v157
	v_pk_fma_f32 v[198:199], v[156:157], v[156:157], v[198:199]
	v_lshlrev_b32_e32 v158, 16, v142
	v_and_b32_e32 v159, 0xffff0000, v142
	v_pk_add_f32 v[196:197], v[156:157], v[158:159] neg_lo:[0,1] neg_hi:[0,1]
	v_cvt_pk_bf16_f32 v146, v196, v197
	v_lshlrev_b32_e32 v156, 16, v143
	v_and_b32_e32 v157, 0xffff0000, v143
	v_lshlrev_b32_e32 v158, 16, v147
	v_and_b32_e32 v159, 0xffff0000, v147
	v_pk_add_f32 v[156:157], v[156:157], v[158:159]
	v_pk_fma_f32 v[156:157], v[124:125], 0.5, v[156:157] op_sel_hi:[1,0,1]
	v_cvt_pk_bf16_f32 v143, v156, v157
	v_pk_fma_f32 v[198:199], v[156:157], v[156:157], v[198:199]
	v_lshlrev_b32_e32 v158, 16, v143
	v_and_b32_e32 v159, 0xffff0000, v143
	v_pk_add_f32 v[196:197], v[156:157], v[158:159] neg_lo:[0,1] neg_hi:[0,1]
	v_cvt_pk_bf16_f32 v147, v196, v197
	global_store_dwordx4 v210, v[140:143], s[10:11]
	global_store_dwordx4 v210, v[144:147], s[6:7]
	s_waitcnt vmcnt(10)
	v_lshlrev_b32_e32 v156, 16, v148
	v_and_b32_e32 v157, 0xffff0000, v148
	v_lshlrev_b32_e32 v158, 16, v152
	v_and_b32_e32 v159, 0xffff0000, v152
	v_pk_add_f32 v[156:157], v[156:157], v[158:159]
	v_pk_fma_f32 v[156:157], v[118:119], 0.5, v[156:157] op_sel_hi:[1,0,1]
	v_cvt_pk_bf16_f32 v148, v156, v157
	v_pk_fma_f32 v[198:199], v[156:157], v[156:157], v[198:199]
	v_lshlrev_b32_e32 v158, 16, v148
	v_and_b32_e32 v159, 0xffff0000, v148
	v_pk_add_f32 v[196:197], v[156:157], v[158:159] neg_lo:[0,1] neg_hi:[0,1]
	v_cvt_pk_bf16_f32 v152, v196, v197
	v_lshlrev_b32_e32 v156, 16, v149
	v_and_b32_e32 v157, 0xffff0000, v149
	v_lshlrev_b32_e32 v158, 16, v153
	v_and_b32_e32 v159, 0xffff0000, v153
	v_pk_add_f32 v[156:157], v[156:157], v[158:159]
	v_pk_fma_f32 v[156:157], v[120:121], 0.5, v[156:157] op_sel_hi:[1,0,1]
	v_cvt_pk_bf16_f32 v149, v156, v157
	v_pk_fma_f32 v[198:199], v[156:157], v[156:157], v[198:199]
	v_lshlrev_b32_e32 v158, 16, v149
	v_and_b32_e32 v159, 0xffff0000, v149
	v_pk_add_f32 v[196:197], v[156:157], v[158:159] neg_lo:[0,1] neg_hi:[0,1]
	v_cvt_pk_bf16_f32 v153, v196, v197
	v_lshlrev_b32_e32 v156, 16, v150
	v_and_b32_e32 v157, 0xffff0000, v150
	v_lshlrev_b32_e32 v158, 16, v154
	v_and_b32_e32 v159, 0xffff0000, v154
	v_pk_add_f32 v[156:157], v[156:157], v[158:159]
	v_pk_fma_f32 v[156:157], v[114:115], 0.5, v[156:157] op_sel_hi:[1,0,1]
	v_cvt_pk_bf16_f32 v150, v156, v157
	v_pk_fma_f32 v[198:199], v[156:157], v[156:157], v[198:199]
	v_lshlrev_b32_e32 v158, 16, v150
	v_and_b32_e32 v159, 0xffff0000, v150
	v_pk_add_f32 v[196:197], v[156:157], v[158:159] neg_lo:[0,1] neg_hi:[0,1]
	v_cvt_pk_bf16_f32 v154, v196, v197
	v_lshlrev_b32_e32 v156, 16, v151
	v_and_b32_e32 v157, 0xffff0000, v151
	v_lshlrev_b32_e32 v158, 16, v155
	v_and_b32_e32 v159, 0xffff0000, v155
	v_pk_add_f32 v[156:157], v[156:157], v[158:159]
	v_pk_fma_f32 v[156:157], v[116:117], 0.5, v[156:157] op_sel_hi:[1,0,1]
	v_cvt_pk_bf16_f32 v151, v156, v157
	v_pk_fma_f32 v[198:199], v[156:157], v[156:157], v[198:199]
	v_lshlrev_b32_e32 v158, 16, v151
	v_and_b32_e32 v159, 0xffff0000, v151
	v_pk_add_f32 v[196:197], v[156:157], v[158:159] neg_lo:[0,1] neg_hi:[0,1]
	v_cvt_pk_bf16_f32 v155, v196, v197
	global_store_dwordx4 v210, v[148:151], s[10:11] offset:256
	global_store_dwordx4 v210, v[152:155], s[6:7] offset:256
	v_add_f32_e32 v200, v198, v199
	s_nop 0
	v_add_u32_e32 v210, 0x18000, v213
	global_load_dwordx4 v[140:143], v210, s[10:11]
	global_load_dwordx4 v[144:147], v210, s[6:7]
	global_load_dwordx4 v[148:151], v210, s[10:11] offset:256
	global_load_dwordx4 v[152:155], v210, s[6:7] offset:256
	s_waitcnt vmcnt(14)
; __device__ __forceinline__ unsigned pk2(float lo, float hi) { f32x2_t v = {lo, hi}; bf16x2_t b = __builtin_convertvector(v, bf16x2_t); return __builtin_bit_cast(unsigned, b); }
; __device__ __forceinline__ float bflo(unsigned u) { return __uint_as_float(u << 16); }
;     __device__ __forceinline__ void operator()(const f32x4 (&acc)[2][2][4][2], const Unit& u, int wr, int wc, int fr, int fq) const {
;     ...
;                 for (int bj = 0; bj < 2; ++bj) {
;                     const size_t off = (size_t)row * DM + col0 + bj * HALF;
;                     const u32x4 hh = *(const u32x4*)(HI + off), ll = *(const u32x4*)(LO + off);
;                     float hv[8] = {bflo(hh.x) + bflo(ll.x), bfhi(hh.x) + bfhi(ll.x), bflo(hh.y) + bflo(ll.y), bfhi(hh.y) + bfhi(ll.y),
;                                    bflo(hh.z) + bflo(ll.z), bfhi(hh.z) + bfhi(ll.z), bflo(hh.w) + bflo(ll.w), bfhi(hh.w) + bfhi(ll.w)};
;                     float av[8] = {acc[ai][bj][m][0][0], acc[ai][bj][m][0][1], acc[ai][bj][m][0][2], acc[ai][bj][m][0][3], acc[ai][bj][m][1][0], acc[ai][bj][m][1][1], acc[ai][bj][m][1][2], acc[ai][bj][m][1][3]};
;                     if (GATED) { const u32x4 pp = *(const u32x4*)(PP + off);
;                         const float pv[8] = {bflo(pp.x), bfhi(pp.x), bflo(pp.y), bfhi(pp.y), bflo(pp.z), bfhi(pp.z), bflo(pp.w), bfhi(pp.w)};
; #pragma unroll
;                         for (int e = 0; e < 8; ++e) av[e] = fast_sigmoid(av[e] * rs) * pv[e]; }
;                     else {
; #pragma unroll
;                         for (int e = 0; e < 8; ++e) av[e] *= alpha; }
;                     float lo[8];
; #pragma unroll
;                     for (int e = 0; e < 8; ++e) { hv[e] += av[e]; sq += hv[e] * hv[e]; }
;                     u32x4 wh; wh.x = pk2(hv[0], hv[1]); wh.y = pk2(hv[2], hv[3]); wh.z = pk2(hv[4], hv[5]); wh.w = pk2(hv[6], hv[7]);
;                     lo[0] = hv[0] - bflo(wh.x); lo[1] = hv[1] - bfhi(wh.x); lo[2] = hv[2] - bflo(wh.y); lo[3] = hv[3] - bfhi(wh.y);
;                     lo[4] = hv[4] - bflo(wh.z); lo[5] = hv[5] - bfhi(wh.z); lo[6] = hv[6] - bflo(wh.w); lo[7] = hv[7] - bfhi(wh.w);
;                     u32x4 wl; wl.x = pk2(lo[0], lo[1]); wl.y = pk2(lo[2], lo[3]); wl.z = pk2(lo[4], lo[5]); wl.w = pk2(lo[6], lo[7]);
;                     *(u32x4*)(HO + off) = wh; *(u32x4*)(LO + off) = wl;
;                 }
	v_lshlrev_b32_e32 v156, 16, v164
	v_and_b32_e32 v157, 0xffff0000, v164
	v_lshlrev_b32_e32 v158, 16, v168
	v_and_b32_e32 v159, 0xffff0000, v168
	v_pk_add_f32 v[156:157], v[156:157], v[158:159]
	v_pk_fma_f32 v[156:157], v[110:111], 0.5, v[156:157] op_sel_hi:[1,0,1]
	v_cvt_pk_bf16_f32 v164, v156, v157
	v_pk_mul_f32 v[198:199], v[156:157], v[156:157]
	v_lshlrev_b32_e32 v158, 16, v164
	v_and_b32_e32 v159, 0xffff0000, v164
	v_pk_add_f32 v[196:197], v[156:157], v[158:159] neg_lo:[0,1] neg_hi:[0,1]
	v_cvt_pk_bf16_f32 v168, v196, v197
	v_lshlrev_b32_e32 v156, 16, v165
	v_and_b32_e32 v157, 0xffff0000, v165
	v_lshlrev_b32_e32 v158, 16, v169
	v_and_b32_e32 v159, 0xffff0000, v169
	v_pk_add_f32 v[156:157], v[156:157], v[158:159]
	v_pk_fma_f32 v[156:157], v[112:113], 0.5, v[156:157] op_sel_hi:[1,0,1]
	v_cvt_pk_bf16_f32 v165, v156, v157
	v_pk_fma_f32 v[198:199], v[156:157], v[156:157], v[198:199]
	v_lshlrev_b32_e32 v158, 16, v165
	v_and_b32_e32 v159, 0xffff0000, v165
	v_pk_add_f32 v[196:197], v[156:157], v[158:159] neg_lo:[0,1] neg_hi:[0,1]
	v_cvt_pk_bf16_f32 v169, v196, v197
	v_lshlrev_b32_e32 v156, 16, v166
	v_and_b32_e32 v157, 0xffff0000, v166
	v_lshlrev_b32_e32 v158, 16, v170
	v_and_b32_e32 v159, 0xffff0000, v170
	v_pk_add_f32 v[156:157], v[156:157], v[158:159]
	v_pk_fma_f32 v[156:157], v[106:107], 0.5, v[156:157] op_sel_hi:[1,0,1]
	v_cvt_pk_bf16_f32 v166, v156, v157
	v_pk_fma_f32 v[198:199], v[156:157], v[156:157], v[198:199]
	v_lshlrev_b32_e32 v158, 16, v166
	v_and_b32_e32 v159, 0xffff0000, v166
	v_pk_add_f32 v[196:197], v[156:157], v[158:159] neg_lo:[0,1] neg_hi:[0,1]
	v_cvt_pk_bf16_f32 v170, v196, v197
	v_lshlrev_b32_e32 v156, 16, v167
	v_and_b32_e32 v157, 0xffff0000, v167
	v_lshlrev_b32_e32 v158, 16, v171
	v_and_b32_e32 v159, 0xffff0000, v171
	v_pk_add_f32 v[156:157], v[156:157], v[158:159]
	v_pk_fma_f32 v[156:157], v[108:109], 0.5, v[156:157] op_sel_hi:[1,0,1]
	v_cvt_pk_bf16_f32 v167, v156, v157
	v_pk_fma_f32 v[198:199], v[156:157], v[156:157], v[198:199]
	v_lshlrev_b32_e32 v158, 16, v167
	v_and_b32_e32 v159, 0xffff0000, v167
	v_pk_add_f32 v[196:197], v[156:157], v[158:159] neg_lo:[0,1] neg_hi:[0,1]
	v_cvt_pk_bf16_f32 v171, v196, v197
	global_store_dwordx4 v211, v[164:167], s[10:11]
	global_store_dwordx4 v211, v[168:171], s[6:7]
	s_waitcnt vmcnt(14)
	v_lshlrev_b32_e32 v156, 16, v172
	v_and_b32_e32 v157, 0xffff0000, v172
	v_lshlrev_b32_e32 v158, 16, v176
	v_and_b32_e32 v159, 0xffff0000, v176
	v_pk_add_f32 v[156:157], v[156:157], v[158:159]
	v_pk_fma_f32 v[156:157], v[102:103], 0.5, v[156:157] op_sel_hi:[1,0,1]
	v_cvt_pk_bf16_f32 v172, v156, v157
	v_pk_fma_f32 v[198:199], v[156:157], v[156:157], v[198:199]
	v_lshlrev_b32_e32 v158, 16, v172
	v_and_b32_e32 v159, 0xffff0000, v172
	v_pk_add_f32 v[196:197], v[156:157], v[158:159] neg_lo:[0,1] neg_hi:[0,1]
	v_cvt_pk_bf16_f32 v176, v196, v197
	v_lshlrev_b32_e32 v156, 16, v173
	v_and_b32_e32 v157, 0xffff0000, v173
	v_lshlrev_b32_e32 v158, 16, v177
	v_and_b32_e32 v159, 0xffff0000, v177
	v_pk_add_f32 v[156:157], v[156:157], v[158:159]
	v_pk_fma_f32 v[156:157], v[104:105], 0.5, v[156:157] op_sel_hi:[1,0,1]
	v_cvt_pk_bf16_f32 v173, v156, v157
	v_pk_fma_f32 v[198:199], v[156:157], v[156:157], v[198:199]
	v_lshlrev_b32_e32 v158, 16, v173
	v_and_b32_e32 v159, 0xffff0000, v173
	v_pk_add_f32 v[196:197], v[156:157], v[158:159] neg_lo:[0,1] neg_hi:[0,1]
	v_cvt_pk_bf16_f32 v177, v196, v197
	v_lshlrev_b32_e32 v156, 16, v174
	v_and_b32_e32 v157, 0xffff0000, v174
	v_lshlrev_b32_e32 v158, 16, v178
	v_and_b32_e32 v159, 0xffff0000, v178
	v_pk_add_f32 v[156:157], v[156:157], v[158:159]
	v_pk_fma_f32 v[156:157], v[98:99], 0.5, v[156:157] op_sel_hi:[1,0,1]
	v_cvt_pk_bf16_f32 v174, v156, v157
	v_pk_fma_f32 v[198:199], v[156:157], v[156:157], v[198:199]
	v_lshlrev_b32_e32 v158, 16, v174
	v_and_b32_e32 v159, 0xffff0000, v174
	v_pk_add_f32 v[196:197], v[156:157], v[158:159] neg_lo:[0,1] neg_hi:[0,1]
	v_cvt_pk_bf16_f32 v178, v196, v197
	v_lshlrev_b32_e32 v156, 16, v175
	v_and_b32_e32 v157, 0xffff0000, v175
	v_lshlrev_b32_e32 v158, 16, v179
	v_and_b32_e32 v159, 0xffff0000, v179
	v_pk_add_f32 v[156:157], v[156:157], v[158:159]
	v_pk_fma_f32 v[156:157], v[100:101], 0.5, v[156:157] op_sel_hi:[1,0,1]
	v_cvt_pk_bf16_f32 v175, v156, v157
	v_pk_fma_f32 v[198:199], v[156:157], v[156:157], v[198:199]
	v_lshlrev_b32_e32 v158, 16, v175
	v_and_b32_e32 v159, 0xffff0000, v175
	v_pk_add_f32 v[196:197], v[156:157], v[158:159] neg_lo:[0,1] neg_hi:[0,1]
	v_cvt_pk_bf16_f32 v179, v196, v197
	global_store_dwordx4 v211, v[172:175], s[10:11] offset:256
	global_store_dwordx4 v211, v[176:179], s[6:7] offset:256
	v_add_f32_e32 v201, v198, v199
	s_nop 0
	v_add_u32_e32 v211, 0x40000, v213
	global_load_dwordx4 v[164:167], v211, s[10:11]
	global_load_dwordx4 v[168:171], v211, s[6:7]
	global_load_dwordx4 v[172:175], v211, s[10:11] offset:256
	global_load_dwordx4 v[176:179], v211, s[6:7] offset:256
	s_waitcnt vmcnt(18)
; __device__ __forceinline__ unsigned pk2(float lo, float hi) { f32x2_t v = {lo, hi}; bf16x2_t b = __builtin_convertvector(v, bf16x2_t); return __builtin_bit_cast(unsigned, b); }
; __device__ __forceinline__ float bflo(unsigned u) { return __uint_as_float(u << 16); }
;     __device__ __forceinline__ void operator()(const f32x4 (&acc)[2][2][4][2], const Unit& u, int wr, int wc, int fr, int fq) const {
;     ...
;                 for (int bj = 0; bj < 2; ++bj) {
;                     const size_t off = (size_t)row * DM + col0 + bj * HALF;
;                     const u32x4 hh = *(const u32x4*)(HI + off), ll = *(const u32x4*)(LO + off);
;                     float hv[8] = {bflo(hh.x) + bflo(ll.x), bfhi(hh.x) + bfhi(ll.x), bflo(hh.y) + bflo(ll.y), bfhi(hh.y) + bfhi(ll.y),
;                                    bflo(hh.z) + bflo(ll.z), bfhi(hh.z) + bfhi(ll.z), bflo(hh.w) + bflo(ll.w), bfhi(hh.w) + bfhi(ll.w)};
;                     float av[8] = {acc[ai][bj][m][0][0], acc[ai][bj][m][0][1], acc[ai][bj][m][0][2], acc[ai][bj][m][0][3], acc[ai][bj][m][1][0], acc[ai][bj][m][1][1], acc[ai][bj][m][1][2], acc[ai][bj][m][1][3]};
;                     if (GATED) { const u32x4 pp = *(const u32x4*)(PP + off);
;                         const float pv[8] = {bflo(pp.x), bfhi(pp.x), bflo(pp.y), bfhi(pp.y), bflo(pp.z), bfhi(pp.z), bflo(pp.w), bfhi(pp.w)};
; #pragma unroll
;                         for (int e = 0; e < 8; ++e) av[e] = fast_sigmoid(av[e] * rs) * pv[e]; }
;                     else {
; #pragma unroll
;                         for (int e = 0; e < 8; ++e) av[e] *= alpha; }
;                     float lo[8];
; #pragma unroll
;                     for (int e = 0; e < 8; ++e) { hv[e] += av[e]; sq += hv[e] * hv[e]; }
;                     u32x4 wh; wh.x = pk2(hv[0], hv[1]); wh.y = pk2(hv[2], hv[3]); wh.z = pk2(hv[4], hv[5]); wh.w = pk2(hv[6], hv[7]);
;                     lo[0] = hv[0] - bflo(wh.x); lo[1] = hv[1] - bfhi(wh.x); lo[2] = hv[2] - bflo(wh.y); lo[3] = hv[3] - bfhi(wh.y);
;                     lo[4] = hv[4] - bflo(wh.z); lo[5] = hv[5] - bfhi(wh.z); lo[6] = hv[6] - bflo(wh.w); lo[7] = hv[7] - bfhi(wh.w);
;                     u32x4 wl; wl.x = pk2(lo[0], lo[1]); wl.y = pk2(lo[2], lo[3]); wl.z = pk2(lo[4], lo[5]); wl.w = pk2(lo[6], lo[7]);
;                     *(u32x4*)(HO + off) = wh; *(u32x4*)(LO + off) = wl;
;                 }
	v_lshlrev_b32_e32 v156, 16, v180
	v_and_b32_e32 v157, 0xffff0000, v180
	v_lshlrev_b32_e32 v158, 16, v184
	v_and_b32_e32 v159, 0xffff0000, v184
	v_pk_add_f32 v[156:157], v[156:157], v[158:159]
	v_pk_fma_f32 v[156:157], v[94:95], 0.5, v[156:157] op_sel_hi:[1,0,1]
	v_cvt_pk_bf16_f32 v180, v156, v157
	v_pk_mul_f32 v[198:199], v[156:157], v[156:157]
	v_lshlrev_b32_e32 v158, 16, v180
	v_and_b32_e32 v159, 0xffff0000, v180
	v_pk_add_f32 v[196:197], v[156:157], v[158:159] neg_lo:[0,1] neg_hi:[0,1]
	v_cvt_pk_bf16_f32 v184, v196, v197
	v_lshlrev_b32_e32 v156, 16, v181
	v_and_b32_e32 v157, 0xffff0000, v181
	v_lshlrev_b32_e32 v158, 16, v185
	v_and_b32_e32 v159, 0xffff0000, v185
	v_pk_add_f32 v[156:157], v[156:157], v[158:159]
	v_pk_fma_f32 v[156:157], v[96:97], 0.5, v[156:157] op_sel_hi:[1,0,1]
	v_cvt_pk_bf16_f32 v181, v156, v157
	v_pk_fma_f32 v[198:199], v[156:157], v[156:157], v[198:199]
	v_lshlrev_b32_e32 v158, 16, v181
	v_and_b32_e32 v159, 0xffff0000, v181
	v_pk_add_f32 v[196:197], v[156:157], v[158:159] neg_lo:[0,1] neg_hi:[0,1]
	v_cvt_pk_bf16_f32 v185, v196, v197
	v_lshlrev_b32_e32 v156, 16, v182
	v_and_b32_e32 v157, 0xffff0000, v182
	v_lshlrev_b32_e32 v158, 16, v186
	v_and_b32_e32 v159, 0xffff0000, v186
	v_pk_add_f32 v[156:157], v[156:157], v[158:159]
	v_pk_fma_f32 v[156:157], v[90:91], 0.5, v[156:157] op_sel_hi:[1,0,1]
	v_cvt_pk_bf16_f32 v182, v156, v157
	v_pk_fma_f32 v[198:199], v[156:157], v[156:157], v[198:199]
	v_lshlrev_b32_e32 v158, 16, v182
	v_and_b32_e32 v159, 0xffff0000, v182
	v_pk_add_f32 v[196:197], v[156:157], v[158:159] neg_lo:[0,1] neg_hi:[0,1]
	v_cvt_pk_bf16_f32 v186, v196, v197
	v_lshlrev_b32_e32 v156, 16, v183
	v_and_b32_e32 v157, 0xffff0000, v183
	v_lshlrev_b32_e32 v158, 16, v187
	v_and_b32_e32 v159, 0xffff0000, v187
	v_pk_add_f32 v[156:157], v[156:157], v[158:159]
	v_pk_fma_f32 v[156:157], v[92:93], 0.5, v[156:157] op_sel_hi:[1,0,1]
	v_cvt_pk_bf16_f32 v183, v156, v157
	v_pk_fma_f32 v[198:199], v[156:157], v[156:157], v[198:199]
	v_lshlrev_b32_e32 v158, 16, v183
	v_and_b32_e32 v159, 0xffff0000, v183
	v_pk_add_f32 v[196:197], v[156:157], v[158:159] neg_lo:[0,1] neg_hi:[0,1]
	v_cvt_pk_bf16_f32 v187, v196, v197
	global_store_dwordx4 v212, v[180:183], s[10:11]
	global_store_dwordx4 v212, v[184:187], s[6:7]
	s_waitcnt vmcnt(18)
	v_lshlrev_b32_e32 v156, 16, v188
	v_and_b32_e32 v157, 0xffff0000, v188
	v_lshlrev_b32_e32 v158, 16, v192
	v_and_b32_e32 v159, 0xffff0000, v192
	v_pk_add_f32 v[156:157], v[156:157], v[158:159]
	v_pk_fma_f32 v[156:157], v[86:87], 0.5, v[156:157] op_sel_hi:[1,0,1]
	v_cvt_pk_bf16_f32 v188, v156, v157
	v_pk_fma_f32 v[198:199], v[156:157], v[156:157], v[198:199]
	v_lshlrev_b32_e32 v158, 16, v188
	v_and_b32_e32 v159, 0xffff0000, v188
	v_pk_add_f32 v[196:197], v[156:157], v[158:159] neg_lo:[0,1] neg_hi:[0,1]
	v_cvt_pk_bf16_f32 v192, v196, v197
	v_lshlrev_b32_e32 v156, 16, v189
	v_and_b32_e32 v157, 0xffff0000, v189
	v_lshlrev_b32_e32 v158, 16, v193
	v_and_b32_e32 v159, 0xffff0000, v193
	v_pk_add_f32 v[156:157], v[156:157], v[158:159]
	v_pk_fma_f32 v[156:157], v[88:89], 0.5, v[156:157] op_sel_hi:[1,0,1]
	v_cvt_pk_bf16_f32 v189, v156, v157
	v_pk_fma_f32 v[198:199], v[156:157], v[156:157], v[198:199]
	v_lshlrev_b32_e32 v158, 16, v189
	v_and_b32_e32 v159, 0xffff0000, v189
	v_pk_add_f32 v[196:197], v[156:157], v[158:159] neg_lo:[0,1] neg_hi:[0,1]
	v_cvt_pk_bf16_f32 v193, v196, v197
	v_lshlrev_b32_e32 v156, 16, v190
	v_and_b32_e32 v157, 0xffff0000, v190
	v_lshlrev_b32_e32 v158, 16, v194
	v_and_b32_e32 v159, 0xffff0000, v194
	v_pk_add_f32 v[156:157], v[156:157], v[158:159]
	v_pk_fma_f32 v[156:157], v[82:83], 0.5, v[156:157] op_sel_hi:[1,0,1]
	v_cvt_pk_bf16_f32 v190, v156, v157
	v_pk_fma_f32 v[198:199], v[156:157], v[156:157], v[198:199]
	v_lshlrev_b32_e32 v158, 16, v190
	v_and_b32_e32 v159, 0xffff0000, v190
	v_pk_add_f32 v[196:197], v[156:157], v[158:159] neg_lo:[0,1] neg_hi:[0,1]
	v_cvt_pk_bf16_f32 v194, v196, v197
	v_lshlrev_b32_e32 v156, 16, v191
	v_and_b32_e32 v157, 0xffff0000, v191
	v_lshlrev_b32_e32 v158, 16, v195
	v_and_b32_e32 v159, 0xffff0000, v195
	v_pk_add_f32 v[156:157], v[156:157], v[158:159]
	v_pk_fma_f32 v[156:157], v[84:85], 0.5, v[156:157] op_sel_hi:[1,0,1]
	v_cvt_pk_bf16_f32 v191, v156, v157
	v_pk_fma_f32 v[198:199], v[156:157], v[156:157], v[198:199]
	v_lshlrev_b32_e32 v158, 16, v191
	v_and_b32_e32 v159, 0xffff0000, v191
	v_pk_add_f32 v[196:197], v[156:157], v[158:159] neg_lo:[0,1] neg_hi:[0,1]
	v_cvt_pk_bf16_f32 v195, v196, v197
	global_store_dwordx4 v212, v[188:191], s[10:11] offset:256
	global_store_dwordx4 v212, v[192:195], s[6:7] offset:256
	v_add_f32_e32 v202, v198, v199
	s_nop 0
	v_add_u32_e32 v212, 0x48000, v213
	global_load_dwordx4 v[180:183], v212, s[10:11]
	global_load_dwordx4 v[184:187], v212, s[6:7]
	global_load_dwordx4 v[188:191], v212, s[10:11] offset:256
	global_load_dwordx4 v[192:195], v212, s[6:7] offset:256
	s_waitcnt vmcnt(18)
; __device__ __forceinline__ unsigned pk2(float lo, float hi) { f32x2_t v = {lo, hi}; bf16x2_t b = __builtin_convertvector(v, bf16x2_t); return __builtin_bit_cast(unsigned, b); }
; __device__ __forceinline__ float bflo(unsigned u) { return __uint_as_float(u << 16); }
;     __device__ __forceinline__ void operator()(const f32x4 (&acc)[2][2][4][2], const Unit& u, int wr, int wc, int fr, int fq) const {
;     ...
;                 for (int bj = 0; bj < 2; ++bj) {
;                     const size_t off = (size_t)row * DM + col0 + bj * HALF;
;                     const u32x4 hh = *(const u32x4*)(HI + off), ll = *(const u32x4*)(LO + off);
;                     float hv[8] = {bflo(hh.x) + bflo(ll.x), bfhi(hh.x) + bfhi(ll.x), bflo(hh.y) + bflo(ll.y), bfhi(hh.y) + bfhi(ll.y),
;                                    bflo(hh.z) + bflo(ll.z), bfhi(hh.z) + bfhi(ll.z), bflo(hh.w) + bflo(ll.w), bfhi(hh.w) + bfhi(ll.w)};
;                     float av[8] = {acc[ai][bj][m][0][0], acc[ai][bj][m][0][1], acc[ai][bj][m][0][2], acc[ai][bj][m][0][3], acc[ai][bj][m][1][0], acc[ai][bj][m][1][1], acc[ai][bj][m][1][2], acc[ai][bj][m][1][3]};
;                     if (GATED) { const u32x4 pp = *(const u32x4*)(PP + off);
;                         const float pv[8] = {bflo(pp.x), bfhi(pp.x), bflo(pp.y), bfhi(pp.y), bflo(pp.z), bfhi(pp.z), bflo(pp.w), bfhi(pp.w)};
; #pragma unroll
;                         for (int e = 0; e < 8; ++e) av[e] = fast_sigmoid(av[e] * rs) * pv[e]; }
;                     else {
; #pragma unroll
;                         for (int e = 0; e < 8; ++e) av[e] *= alpha; }
;                     float lo[8];
; #pragma unroll
;                     for (int e = 0; e < 8; ++e) { hv[e] += av[e]; sq += hv[e] * hv[e]; }
;                     u32x4 wh; wh.x = pk2(hv[0], hv[1]); wh.y = pk2(hv[2], hv[3]); wh.z = pk2(hv[4], hv[5]); wh.w = pk2(hv[6], hv[7]);
;                     lo[0] = hv[0] - bflo(wh.x); lo[1] = hv[1] - bfhi(wh.x); lo[2] = hv[2] - bflo(wh.y); lo[3] = hv[3] - bfhi(wh.y);
;                     lo[4] = hv[4] - bflo(wh.z); lo[5] = hv[5] - bfhi(wh.z); lo[6] = hv[6] - bflo(wh.w); lo[7] = hv[7] - bfhi(wh.w);
;                     u32x4 wl; wl.x = pk2(lo[0], lo[1]); wl.y = pk2(lo[2], lo[3]); wl.z = pk2(lo[4], lo[5]); wl.w = pk2(lo[6], lo[7]);
;                     *(u32x4*)(HO + off) = wh; *(u32x4*)(LO + off) = wl;
;                 }
	v_lshlrev_b32_e32 v156, 16, v140
	v_and_b32_e32 v157, 0xffff0000, v140
	v_lshlrev_b32_e32 v158, 16, v144
	v_and_b32_e32 v159, 0xffff0000, v144
	v_pk_add_f32 v[156:157], v[156:157], v[158:159]
	v_pk_fma_f32 v[156:157], v[78:79], 0.5, v[156:157] op_sel_hi:[1,0,1]
	v_cvt_pk_bf16_f32 v140, v156, v157
	v_pk_mul_f32 v[198:199], v[156:157], v[156:157]
	v_lshlrev_b32_e32 v158, 16, v140
	v_and_b32_e32 v159, 0xffff0000, v140
	v_pk_add_f32 v[196:197], v[156:157], v[158:159] neg_lo:[0,1] neg_hi:[0,1]
	v_cvt_pk_bf16_f32 v144, v196, v197
	v_lshlrev_b32_e32 v156, 16, v141
	v_and_b32_e32 v157, 0xffff0000, v141
	v_lshlrev_b32_e32 v158, 16, v145
	v_and_b32_e32 v159, 0xffff0000, v145
	v_pk_add_f32 v[156:157], v[156:157], v[158:159]
	v_pk_fma_f32 v[156:157], v[80:81], 0.5, v[156:157] op_sel_hi:[1,0,1]
	v_cvt_pk_bf16_f32 v141, v156, v157
	v_pk_fma_f32 v[198:199], v[156:157], v[156:157], v[198:199]
	v_lshlrev_b32_e32 v158, 16, v141
	v_and_b32_e32 v159, 0xffff0000, v141
	v_pk_add_f32 v[196:197], v[156:157], v[158:159] neg_lo:[0,1] neg_hi:[0,1]
	v_cvt_pk_bf16_f32 v145, v196, v197
	v_lshlrev_b32_e32 v156, 16, v142
	v_and_b32_e32 v157, 0xffff0000, v142
	v_lshlrev_b32_e32 v158, 16, v146
	v_and_b32_e32 v159, 0xffff0000, v146
	v_pk_add_f32 v[156:157], v[156:157], v[158:159]
	v_pk_fma_f32 v[156:157], v[74:75], 0.5, v[156:157] op_sel_hi:[1,0,1]
	v_cvt_pk_bf16_f32 v142, v156, v157
	v_pk_fma_f32 v[198:199], v[156:157], v[156:157], v[198:199]
	v_lshlrev_b32_e32 v158, 16, v142
	v_and_b32_e32 v159, 0xffff0000, v142
	v_pk_add_f32 v[196:197], v[156:157], v[158:159] neg_lo:[0,1] neg_hi:[0,1]
	v_cvt_pk_bf16_f32 v146, v196, v197
	v_lshlrev_b32_e32 v156, 16, v143
	v_and_b32_e32 v157, 0xffff0000, v143
	v_lshlrev_b32_e32 v158, 16, v147
	v_and_b32_e32 v159, 0xffff0000, v147
	v_pk_add_f32 v[156:157], v[156:157], v[158:159]
	v_pk_fma_f32 v[156:157], v[76:77], 0.5, v[156:157] op_sel_hi:[1,0,1]
	v_cvt_pk_bf16_f32 v143, v156, v157
	v_pk_fma_f32 v[198:199], v[156:157], v[156:157], v[198:199]
	v_lshlrev_b32_e32 v158, 16, v143
	v_and_b32_e32 v159, 0xffff0000, v143
	v_pk_add_f32 v[196:197], v[156:157], v[158:159] neg_lo:[0,1] neg_hi:[0,1]
	v_cvt_pk_bf16_f32 v147, v196, v197
	global_store_dwordx4 v210, v[140:143], s[10:11]
	global_store_dwordx4 v210, v[144:147], s[6:7]
	s_waitcnt vmcnt(18)
	v_lshlrev_b32_e32 v156, 16, v148
	v_and_b32_e32 v157, 0xffff0000, v148
	v_lshlrev_b32_e32 v158, 16, v152
	v_and_b32_e32 v159, 0xffff0000, v152
	v_pk_add_f32 v[156:157], v[156:157], v[158:159]
	v_pk_fma_f32 v[156:157], v[70:71], 0.5, v[156:157] op_sel_hi:[1,0,1]
	v_cvt_pk_bf16_f32 v148, v156, v157
	v_pk_fma_f32 v[198:199], v[156:157], v[156:157], v[198:199]
	v_lshlrev_b32_e32 v158, 16, v148
	v_and_b32_e32 v159, 0xffff0000, v148
	v_pk_add_f32 v[196:197], v[156:157], v[158:159] neg_lo:[0,1] neg_hi:[0,1]
	v_cvt_pk_bf16_f32 v152, v196, v197
	v_lshlrev_b32_e32 v156, 16, v149
	v_and_b32_e32 v157, 0xffff0000, v149
	v_lshlrev_b32_e32 v158, 16, v153
	v_and_b32_e32 v159, 0xffff0000, v153
	v_pk_add_f32 v[156:157], v[156:157], v[158:159]
	v_pk_fma_f32 v[156:157], v[72:73], 0.5, v[156:157] op_sel_hi:[1,0,1]
	v_cvt_pk_bf16_f32 v149, v156, v157
	v_pk_fma_f32 v[198:199], v[156:157], v[156:157], v[198:199]
	v_lshlrev_b32_e32 v158, 16, v149
	v_and_b32_e32 v159, 0xffff0000, v149
	v_pk_add_f32 v[196:197], v[156:157], v[158:159] neg_lo:[0,1] neg_hi:[0,1]
	v_cvt_pk_bf16_f32 v153, v196, v197
	v_lshlrev_b32_e32 v156, 16, v150
	v_and_b32_e32 v157, 0xffff0000, v150
	v_lshlrev_b32_e32 v158, 16, v154
	v_and_b32_e32 v159, 0xffff0000, v154
	v_pk_add_f32 v[156:157], v[156:157], v[158:159]
	v_pk_fma_f32 v[156:157], v[66:67], 0.5, v[156:157] op_sel_hi:[1,0,1]
	v_cvt_pk_bf16_f32 v150, v156, v157
	v_pk_fma_f32 v[198:199], v[156:157], v[156:157], v[198:199]
	v_lshlrev_b32_e32 v158, 16, v150
	v_and_b32_e32 v159, 0xffff0000, v150
	v_pk_add_f32 v[196:197], v[156:157], v[158:159] neg_lo:[0,1] neg_hi:[0,1]
	v_cvt_pk_bf16_f32 v154, v196, v197
	v_lshlrev_b32_e32 v156, 16, v151
	v_and_b32_e32 v157, 0xffff0000, v151
	v_lshlrev_b32_e32 v158, 16, v155
	v_and_b32_e32 v159, 0xffff0000, v155
	v_pk_add_f32 v[156:157], v[156:157], v[158:159]
	v_pk_fma_f32 v[156:157], v[68:69], 0.5, v[156:157] op_sel_hi:[1,0,1]
	v_cvt_pk_bf16_f32 v151, v156, v157
	v_pk_fma_f32 v[198:199], v[156:157], v[156:157], v[198:199]
	v_lshlrev_b32_e32 v158, 16, v151
	v_and_b32_e32 v159, 0xffff0000, v151
	v_pk_add_f32 v[196:197], v[156:157], v[158:159] neg_lo:[0,1] neg_hi:[0,1]
	v_cvt_pk_bf16_f32 v155, v196, v197
	global_store_dwordx4 v210, v[148:151], s[10:11] offset:256
	global_store_dwordx4 v210, v[152:155], s[6:7] offset:256
	v_add_f32_e32 v203, v198, v199
	s_nop 0
	v_add_u32_e32 v210, 0x50000, v213
	global_load_dwordx4 v[140:143], v210, s[10:11]
	global_load_dwordx4 v[144:147], v210, s[6:7]
	global_load_dwordx4 v[148:151], v210, s[10:11] offset:256
	global_load_dwordx4 v[152:155], v210, s[6:7] offset:256
	s_waitcnt vmcnt(18)
; __device__ __forceinline__ unsigned pk2(float lo, float hi) { f32x2_t v = {lo, hi}; bf16x2_t b = __builtin_convertvector(v, bf16x2_t); return __builtin_bit_cast(unsigned, b); }
; __device__ __forceinline__ float bflo(unsigned u) { return __uint_as_float(u << 16); }
;     __device__ __forceinline__ void operator()(const f32x4 (&acc)[2][2][4][2], const Unit& u, int wr, int wc, int fr, int fq) const {
;     ...
;                 for (int bj = 0; bj < 2; ++bj) {
;                     const size_t off = (size_t)row * DM + col0 + bj * HALF;
;                     const u32x4 hh = *(const u32x4*)(HI + off), ll = *(const u32x4*)(LO + off);
;                     float hv[8] = {bflo(hh.x) + bflo(ll.x), bfhi(hh.x) + bfhi(ll.x), bflo(hh.y) + bflo(ll.y), bfhi(hh.y) + bfhi(ll.y),
;                                    bflo(hh.z) + bflo(ll.z), bfhi(hh.z) + bfhi(ll.z), bflo(hh.w) + bflo(ll.w), bfhi(hh.w) + bfhi(ll.w)};
;                     float av[8] = {acc[ai][bj][m][0][0], acc[ai][bj][m][0][1], acc[ai][bj][m][0][2], acc[ai][bj][m][0][3], acc[ai][bj][m][1][0], acc[ai][bj][m][1][1], acc[ai][bj][m][1][2], acc[ai][bj][m][1][3]};
;                     if (GATED) { const u32x4 pp = *(const u32x4*)(PP + off);
;                         const float pv[8] = {bflo(pp.x), bfhi(pp.x), bflo(pp.y), bfhi(pp.y), bflo(pp.z), bfhi(pp.z), bflo(pp.w), bfhi(pp.w)};
; #pragma unroll
;                         for (int e = 0; e < 8; ++e) av[e] = fast_sigmoid(av[e] * rs) * pv[e]; }
;                     else {
; #pragma unroll
;                         for (int e = 0; e < 8; ++e) av[e] *= alpha; }
;                     float lo[8];
; #pragma unroll
;                     for (int e = 0; e < 8; ++e) { hv[e] += av[e]; sq += hv[e] * hv[e]; }
;                     u32x4 wh; wh.x = pk2(hv[0], hv[1]); wh.y = pk2(hv[2], hv[3]); wh.z = pk2(hv[4], hv[5]); wh.w = pk2(hv[6], hv[7]);
;                     lo[0] = hv[0] - bflo(wh.x); lo[1] = hv[1] - bfhi(wh.x); lo[2] = hv[2] - bflo(wh.y); lo[3] = hv[3] - bfhi(wh.y);
;                     lo[4] = hv[4] - bflo(wh.z); lo[5] = hv[5] - bfhi(wh.z); lo[6] = hv[6] - bflo(wh.w); lo[7] = hv[7] - bfhi(wh.w);
;                     u32x4 wl; wl.x = pk2(lo[0], lo[1]); wl.y = pk2(lo[2], lo[3]); wl.z = pk2(lo[4], lo[5]); wl.w = pk2(lo[6], lo[7]);
;                     *(u32x4*)(HO + off) = wh; *(u32x4*)(LO + off) = wl;
;                 }
	v_lshlrev_b32_e32 v156, 16, v164
	v_and_b32_e32 v157, 0xffff0000, v164
	v_lshlrev_b32_e32 v158, 16, v168
	v_and_b32_e32 v159, 0xffff0000, v168
	v_pk_add_f32 v[156:157], v[156:157], v[158:159]
	v_pk_fma_f32 v[156:157], v[62:63], 0.5, v[156:157] op_sel_hi:[1,0,1]
	v_cvt_pk_bf16_f32 v164, v156, v157
	v_pk_mul_f32 v[198:199], v[156:157], v[156:157]
	v_lshlrev_b32_e32 v158, 16, v164
	v_and_b32_e32 v159, 0xffff0000, v164
	v_pk_add_f32 v[196:197], v[156:157], v[158:159] neg_lo:[0,1] neg_hi:[0,1]
	v_cvt_pk_bf16_f32 v168, v196, v197
	v_lshlrev_b32_e32 v156, 16, v165
	v_and_b32_e32 v157, 0xffff0000, v165
	v_lshlrev_b32_e32 v158, 16, v169
	v_and_b32_e32 v159, 0xffff0000, v169
	v_pk_add_f32 v[156:157], v[156:157], v[158:159]
	v_pk_fma_f32 v[156:157], v[64:65], 0.5, v[156:157] op_sel_hi:[1,0,1]
	v_cvt_pk_bf16_f32 v165, v156, v157
	v_pk_fma_f32 v[198:199], v[156:157], v[156:157], v[198:199]
	v_lshlrev_b32_e32 v158, 16, v165
	v_and_b32_e32 v159, 0xffff0000, v165
	v_pk_add_f32 v[196:197], v[156:157], v[158:159] neg_lo:[0,1] neg_hi:[0,1]
	v_cvt_pk_bf16_f32 v169, v196, v197
	v_lshlrev_b32_e32 v156, 16, v166
	v_and_b32_e32 v157, 0xffff0000, v166
	v_lshlrev_b32_e32 v158, 16, v170
	v_and_b32_e32 v159, 0xffff0000, v170
	v_pk_add_f32 v[156:157], v[156:157], v[158:159]
	v_pk_fma_f32 v[156:157], v[58:59], 0.5, v[156:157] op_sel_hi:[1,0,1]
	v_cvt_pk_bf16_f32 v166, v156, v157
	v_pk_fma_f32 v[198:199], v[156:157], v[156:157], v[198:199]
	v_lshlrev_b32_e32 v158, 16, v166
	v_and_b32_e32 v159, 0xffff0000, v166
	v_pk_add_f32 v[196:197], v[156:157], v[158:159] neg_lo:[0,1] neg_hi:[0,1]
	v_cvt_pk_bf16_f32 v170, v196, v197
	v_lshlrev_b32_e32 v156, 16, v167
	v_and_b32_e32 v157, 0xffff0000, v167
	v_lshlrev_b32_e32 v158, 16, v171
	v_and_b32_e32 v159, 0xffff0000, v171
	v_pk_add_f32 v[156:157], v[156:157], v[158:159]
	v_pk_fma_f32 v[156:157], v[60:61], 0.5, v[156:157] op_sel_hi:[1,0,1]
	v_cvt_pk_bf16_f32 v167, v156, v157
	v_pk_fma_f32 v[198:199], v[156:157], v[156:157], v[198:199]
	v_lshlrev_b32_e32 v158, 16, v167
	v_and_b32_e32 v159, 0xffff0000, v167
	v_pk_add_f32 v[196:197], v[156:157], v[158:159] neg_lo:[0,1] neg_hi:[0,1]
	v_cvt_pk_bf16_f32 v171, v196, v197
	global_store_dwordx4 v211, v[164:167], s[10:11]
	global_store_dwordx4 v211, v[168:171], s[6:7]
	s_waitcnt vmcnt(18)
	v_lshlrev_b32_e32 v156, 16, v172
	v_and_b32_e32 v157, 0xffff0000, v172
	v_lshlrev_b32_e32 v158, 16, v176
	v_and_b32_e32 v159, 0xffff0000, v176
	v_pk_add_f32 v[156:157], v[156:157], v[158:159]
	v_pk_fma_f32 v[156:157], v[54:55], 0.5, v[156:157] op_sel_hi:[1,0,1]
	v_cvt_pk_bf16_f32 v172, v156, v157
	v_pk_fma_f32 v[198:199], v[156:157], v[156:157], v[198:199]
	v_lshlrev_b32_e32 v158, 16, v172
	v_and_b32_e32 v159, 0xffff0000, v172
	v_pk_add_f32 v[196:197], v[156:157], v[158:159] neg_lo:[0,1] neg_hi:[0,1]
	v_cvt_pk_bf16_f32 v176, v196, v197
	v_lshlrev_b32_e32 v156, 16, v173
	v_and_b32_e32 v157, 0xffff0000, v173
	v_lshlrev_b32_e32 v158, 16, v177
	v_and_b32_e32 v159, 0xffff0000, v177
	v_pk_add_f32 v[156:157], v[156:157], v[158:159]
	v_pk_fma_f32 v[156:157], v[56:57], 0.5, v[156:157] op_sel_hi:[1,0,1]
	v_cvt_pk_bf16_f32 v173, v156, v157
	v_pk_fma_f32 v[198:199], v[156:157], v[156:157], v[198:199]
	v_lshlrev_b32_e32 v158, 16, v173
	v_and_b32_e32 v159, 0xffff0000, v173
	v_pk_add_f32 v[196:197], v[156:157], v[158:159] neg_lo:[0,1] neg_hi:[0,1]
	v_cvt_pk_bf16_f32 v177, v196, v197
	v_lshlrev_b32_e32 v156, 16, v174
	v_and_b32_e32 v157, 0xffff0000, v174
	v_lshlrev_b32_e32 v158, 16, v178
	v_and_b32_e32 v159, 0xffff0000, v178
	v_pk_add_f32 v[156:157], v[156:157], v[158:159]
	v_pk_fma_f32 v[156:157], v[50:51], 0.5, v[156:157] op_sel_hi:[1,0,1]
	v_cvt_pk_bf16_f32 v174, v156, v157
	v_pk_fma_f32 v[198:199], v[156:157], v[156:157], v[198:199]
	v_lshlrev_b32_e32 v158, 16, v174
	v_and_b32_e32 v159, 0xffff0000, v174
	v_pk_add_f32 v[196:197], v[156:157], v[158:159] neg_lo:[0,1] neg_hi:[0,1]
	v_cvt_pk_bf16_f32 v178, v196, v197
	v_lshlrev_b32_e32 v156, 16, v175
	v_and_b32_e32 v157, 0xffff0000, v175
	v_lshlrev_b32_e32 v158, 16, v179
	v_and_b32_e32 v159, 0xffff0000, v179
	v_pk_add_f32 v[156:157], v[156:157], v[158:159]
	v_pk_fma_f32 v[156:157], v[52:53], 0.5, v[156:157] op_sel_hi:[1,0,1]
	v_cvt_pk_bf16_f32 v175, v156, v157
	v_pk_fma_f32 v[198:199], v[156:157], v[156:157], v[198:199]
	v_lshlrev_b32_e32 v158, 16, v175
	v_and_b32_e32 v159, 0xffff0000, v175
	v_pk_add_f32 v[196:197], v[156:157], v[158:159] neg_lo:[0,1] neg_hi:[0,1]
	v_cvt_pk_bf16_f32 v179, v196, v197
	global_store_dwordx4 v211, v[172:175], s[10:11] offset:256
	global_store_dwordx4 v211, v[176:179], s[6:7] offset:256
	v_add_f32_e32 v206, v198, v199
	s_nop 0
	v_add_u32_e32 v211, 0x58000, v213
	global_load_dwordx4 v[164:167], v211, s[10:11]
	global_load_dwordx4 v[168:171], v211, s[6:7]
	global_load_dwordx4 v[172:175], v211, s[10:11] offset:256
	global_load_dwordx4 v[176:179], v211, s[6:7] offset:256
	s_waitcnt vmcnt(18)
; __device__ __forceinline__ unsigned pk2(float lo, float hi) { f32x2_t v = {lo, hi}; bf16x2_t b = __builtin_convertvector(v, bf16x2_t); return __builtin_bit_cast(unsigned, b); }
; __device__ __forceinline__ float bflo(unsigned u) { return __uint_as_float(u << 16); }
;     __device__ __forceinline__ void operator()(const f32x4 (&acc)[2][2][4][2], const Unit& u, int wr, int wc, int fr, int fq) const {
;     ...
;                 for (int bj = 0; bj < 2; ++bj) {
;                     const size_t off = (size_t)row * DM + col0 + bj * HALF;
;                     const u32x4 hh = *(const u32x4*)(HI + off), ll = *(const u32x4*)(LO + off);
;                     float hv[8] = {bflo(hh.x) + bflo(ll.x), bfhi(hh.x) + bfhi(ll.x), bflo(hh.y) + bflo(ll.y), bfhi(hh.y) + bfhi(ll.y),
;                                    bflo(hh.z) + bflo(ll.z), bfhi(hh.z) + bfhi(ll.z), bflo(hh.w) + bflo(ll.w), bfhi(hh.w) + bfhi(ll.w)};
;                     float av[8] = {acc[ai][bj][m][0][0], acc[ai][bj][m][0][1], acc[ai][bj][m][0][2], acc[ai][bj][m][0][3], acc[ai][bj][m][1][0], acc[ai][bj][m][1][1], acc[ai][bj][m][1][2], acc[ai][bj][m][1][3]};
;                     if (GATED) { const u32x4 pp = *(const u32x4*)(PP + off);
;                         const float pv[8] = {bflo(pp.x), bfhi(pp.x), bflo(pp.y), bfhi(pp.y), bflo(pp.z), bfhi(pp.z), bflo(pp.w), bfhi(pp.w)};
; #pragma unroll
;                         for (int e = 0; e < 8; ++e) av[e] = fast_sigmoid(av[e] * rs) * pv[e]; }
;                     else {
; #pragma unroll
;                         for (int e = 0; e < 8; ++e) av[e] *= alpha; }
;                     float lo[8];
; #pragma unroll
;                     for (int e = 0; e < 8; ++e) { hv[e] += av[e]; sq += hv[e] * hv[e]; }
;                     u32x4 wh; wh.x = pk2(hv[0], hv[1]); wh.y = pk2(hv[2], hv[3]); wh.z = pk2(hv[4], hv[5]); wh.w = pk2(hv[6], hv[7]);
;                     lo[0] = hv[0] - bflo(wh.x); lo[1] = hv[1] - bfhi(wh.x); lo[2] = hv[2] - bflo(wh.y); lo[3] = hv[3] - bfhi(wh.y);
;                     lo[4] = hv[4] - bflo(wh.z); lo[5] = hv[5] - bfhi(wh.z); lo[6] = hv[6] - bflo(wh.w); lo[7] = hv[7] - bfhi(wh.w);
;                     u32x4 wl; wl.x = pk2(lo[0], lo[1]); wl.y = pk2(lo[2], lo[3]); wl.z = pk2(lo[4], lo[5]); wl.w = pk2(lo[6], lo[7]);
;                     *(u32x4*)(HO + off) = wh; *(u32x4*)(LO + off) = wl;
;                 }
	v_lshlrev_b32_e32 v156, 16, v180
	v_and_b32_e32 v157, 0xffff0000, v180
	v_lshlrev_b32_e32 v158, 16, v184
	v_and_b32_e32 v159, 0xffff0000, v184
	v_pk_add_f32 v[156:157], v[156:157], v[158:159]
	v_pk_fma_f32 v[156:157], v[46:47], 0.5, v[156:157] op_sel_hi:[1,0,1]
	v_cvt_pk_bf16_f32 v180, v156, v157
	v_pk_mul_f32 v[198:199], v[156:157], v[156:157]
	v_lshlrev_b32_e32 v158, 16, v180
	v_and_b32_e32 v159, 0xffff0000, v180
	v_pk_add_f32 v[196:197], v[156:157], v[158:159] neg_lo:[0,1] neg_hi:[0,1]
	v_cvt_pk_bf16_f32 v184, v196, v197
	v_lshlrev_b32_e32 v156, 16, v181
	v_and_b32_e32 v157, 0xffff0000, v181
	v_lshlrev_b32_e32 v158, 16, v185
	v_and_b32_e32 v159, 0xffff0000, v185
	v_pk_add_f32 v[156:157], v[156:157], v[158:159]
	v_pk_fma_f32 v[156:157], v[48:49], 0.5, v[156:157] op_sel_hi:[1,0,1]
	v_cvt_pk_bf16_f32 v181, v156, v157
	v_pk_fma_f32 v[198:199], v[156:157], v[156:157], v[198:199]
	v_lshlrev_b32_e32 v158, 16, v181
	v_and_b32_e32 v159, 0xffff0000, v181
	v_pk_add_f32 v[196:197], v[156:157], v[158:159] neg_lo:[0,1] neg_hi:[0,1]
	v_cvt_pk_bf16_f32 v185, v196, v197
	v_lshlrev_b32_e32 v156, 16, v182
	v_and_b32_e32 v157, 0xffff0000, v182
	v_lshlrev_b32_e32 v158, 16, v186
	v_and_b32_e32 v159, 0xffff0000, v186
	v_pk_add_f32 v[156:157], v[156:157], v[158:159]
	v_pk_fma_f32 v[156:157], v[42:43], 0.5, v[156:157] op_sel_hi:[1,0,1]
	v_cvt_pk_bf16_f32 v182, v156, v157
	v_pk_fma_f32 v[198:199], v[156:157], v[156:157], v[198:199]
	v_lshlrev_b32_e32 v158, 16, v182
	v_and_b32_e32 v159, 0xffff0000, v182
	v_pk_add_f32 v[196:197], v[156:157], v[158:159] neg_lo:[0,1] neg_hi:[0,1]
	v_cvt_pk_bf16_f32 v186, v196, v197
	v_lshlrev_b32_e32 v156, 16, v183
	v_and_b32_e32 v157, 0xffff0000, v183
	v_lshlrev_b32_e32 v158, 16, v187
	v_and_b32_e32 v159, 0xffff0000, v187
	v_pk_add_f32 v[156:157], v[156:157], v[158:159]
	v_pk_fma_f32 v[156:157], v[44:45], 0.5, v[156:157] op_sel_hi:[1,0,1]
	v_cvt_pk_bf16_f32 v183, v156, v157
	v_pk_fma_f32 v[198:199], v[156:157], v[156:157], v[198:199]
	v_lshlrev_b32_e32 v158, 16, v183
	v_and_b32_e32 v159, 0xffff0000, v183
	v_pk_add_f32 v[196:197], v[156:157], v[158:159] neg_lo:[0,1] neg_hi:[0,1]
	v_cvt_pk_bf16_f32 v187, v196, v197
	global_store_dwordx4 v212, v[180:183], s[10:11]
	global_store_dwordx4 v212, v[184:187], s[6:7]
	s_waitcnt vmcnt(18)
	v_lshlrev_b32_e32 v156, 16, v188
	v_and_b32_e32 v157, 0xffff0000, v188
	v_lshlrev_b32_e32 v158, 16, v192
	v_and_b32_e32 v159, 0xffff0000, v192
	v_pk_add_f32 v[156:157], v[156:157], v[158:159]
	v_pk_fma_f32 v[156:157], v[38:39], 0.5, v[156:157] op_sel_hi:[1,0,1]
	v_cvt_pk_bf16_f32 v188, v156, v157
	v_pk_fma_f32 v[198:199], v[156:157], v[156:157], v[198:199]
	v_lshlrev_b32_e32 v158, 16, v188
	v_and_b32_e32 v159, 0xffff0000, v188
	v_pk_add_f32 v[196:197], v[156:157], v[158:159] neg_lo:[0,1] neg_hi:[0,1]
	v_cvt_pk_bf16_f32 v192, v196, v197
	v_lshlrev_b32_e32 v156, 16, v189
	v_and_b32_e32 v157, 0xffff0000, v189
	v_lshlrev_b32_e32 v158, 16, v193
	v_and_b32_e32 v159, 0xffff0000, v193
	v_pk_add_f32 v[156:157], v[156:157], v[158:159]
	v_pk_fma_f32 v[156:157], v[40:41], 0.5, v[156:157] op_sel_hi:[1,0,1]
	v_cvt_pk_bf16_f32 v189, v156, v157
	v_pk_fma_f32 v[198:199], v[156:157], v[156:157], v[198:199]
	v_lshlrev_b32_e32 v158, 16, v189
	v_and_b32_e32 v159, 0xffff0000, v189
	v_pk_add_f32 v[196:197], v[156:157], v[158:159] neg_lo:[0,1] neg_hi:[0,1]
	v_cvt_pk_bf16_f32 v193, v196, v197
	v_lshlrev_b32_e32 v156, 16, v190
	v_and_b32_e32 v157, 0xffff0000, v190
	v_lshlrev_b32_e32 v158, 16, v194
	v_and_b32_e32 v159, 0xffff0000, v194
	v_pk_add_f32 v[156:157], v[156:157], v[158:159]
	v_pk_fma_f32 v[156:157], v[34:35], 0.5, v[156:157] op_sel_hi:[1,0,1]
	v_cvt_pk_bf16_f32 v190, v156, v157
	v_pk_fma_f32 v[198:199], v[156:157], v[156:157], v[198:199]
	v_lshlrev_b32_e32 v158, 16, v190
	v_and_b32_e32 v159, 0xffff0000, v190
	v_pk_add_f32 v[196:197], v[156:157], v[158:159] neg_lo:[0,1] neg_hi:[0,1]
	v_cvt_pk_bf16_f32 v194, v196, v197
	v_lshlrev_b32_e32 v156, 16, v191
	v_and_b32_e32 v157, 0xffff0000, v191
	v_lshlrev_b32_e32 v158, 16, v195
	v_and_b32_e32 v159, 0xffff0000, v195
	v_pk_add_f32 v[156:157], v[156:157], v[158:159]
	v_pk_fma_f32 v[156:157], v[36:37], 0.5, v[156:157] op_sel_hi:[1,0,1]
	v_cvt_pk_bf16_f32 v191, v156, v157
	v_pk_fma_f32 v[198:199], v[156:157], v[156:157], v[198:199]
	v_lshlrev_b32_e32 v158, 16, v191
	v_and_b32_e32 v159, 0xffff0000, v191
	v_pk_add_f32 v[196:197], v[156:157], v[158:159] neg_lo:[0,1] neg_hi:[0,1]
	v_cvt_pk_bf16_f32 v195, v196, v197
	global_store_dwordx4 v212, v[188:191], s[10:11] offset:256
	global_store_dwordx4 v212, v[192:195], s[6:7] offset:256
	v_add_f32_e32 v207, v198, v199
	s_waitcnt vmcnt(14)
; __device__ __forceinline__ unsigned pk2(float lo, float hi) { f32x2_t v = {lo, hi}; bf16x2_t b = __builtin_convertvector(v, bf16x2_t); return __builtin_bit_cast(unsigned, b); }
; __device__ __forceinline__ float bflo(unsigned u) { return __uint_as_float(u << 16); }
;     __device__ __forceinline__ void operator()(const f32x4 (&acc)[2][2][4][2], const Unit& u, int wr, int wc, int fr, int fq) const {
;     ...
;                 for (int bj = 0; bj < 2; ++bj) {
;                     const size_t off = (size_t)row * DM + col0 + bj * HALF;
;                     const u32x4 hh = *(const u32x4*)(HI + off), ll = *(const u32x4*)(LO + off);
;                     float hv[8] = {bflo(hh.x) + bflo(ll.x), bfhi(hh.x) + bfhi(ll.x), bflo(hh.y) + bflo(ll.y), bfhi(hh.y) + bfhi(ll.y),
;                                    bflo(hh.z) + bflo(ll.z), bfhi(hh.z) + bfhi(ll.z), bflo(hh.w) + bflo(ll.w), bfhi(hh.w) + bfhi(ll.w)};
;                     float av[8] = {acc[ai][bj][m][0][0], acc[ai][bj][m][0][1], acc[ai][bj][m][0][2], acc[ai][bj][m][0][3], acc[ai][bj][m][1][0], acc[ai][bj][m][1][1], acc[ai][bj][m][1][2], acc[ai][bj][m][1][3]};
;                     if (GATED) { const u32x4 pp = *(const u32x4*)(PP + off);
;                         const float pv[8] = {bflo(pp.x), bfhi(pp.x), bflo(pp.y), bfhi(pp.y), bflo(pp.z), bfhi(pp.z), bflo(pp.w), bfhi(pp.w)};
; #pragma unroll
;                         for (int e = 0; e < 8; ++e) av[e] = fast_sigmoid(av[e] * rs) * pv[e]; }
;                     else {
; #pragma unroll
;                         for (int e = 0; e < 8; ++e) av[e] *= alpha; }
;                     float lo[8];
; #pragma unroll
;                     for (int e = 0; e < 8; ++e) { hv[e] += av[e]; sq += hv[e] * hv[e]; }
;                     u32x4 wh; wh.x = pk2(hv[0], hv[1]); wh.y = pk2(hv[2], hv[3]); wh.z = pk2(hv[4], hv[5]); wh.w = pk2(hv[6], hv[7]);
;                     lo[0] = hv[0] - bflo(wh.x); lo[1] = hv[1] - bfhi(wh.x); lo[2] = hv[2] - bflo(wh.y); lo[3] = hv[3] - bfhi(wh.y);
;                     lo[4] = hv[4] - bflo(wh.z); lo[5] = hv[5] - bfhi(wh.z); lo[6] = hv[6] - bflo(wh.w); lo[7] = hv[7] - bfhi(wh.w);
;                     u32x4 wl; wl.x = pk2(lo[0], lo[1]); wl.y = pk2(lo[2], lo[3]); wl.z = pk2(lo[4], lo[5]); wl.w = pk2(lo[6], lo[7]);
;                     *(u32x4*)(HO + off) = wh; *(u32x4*)(LO + off) = wl;
;                 }
	v_lshlrev_b32_e32 v156, 16, v140
	v_and_b32_e32 v157, 0xffff0000, v140
	v_lshlrev_b32_e32 v158, 16, v144
	v_and_b32_e32 v159, 0xffff0000, v144
	v_pk_add_f32 v[156:157], v[156:157], v[158:159]
	v_pk_fma_f32 v[156:157], v[30:31], 0.5, v[156:157] op_sel_hi:[1,0,1]
	v_cvt_pk_bf16_f32 v140, v156, v157
	v_pk_mul_f32 v[198:199], v[156:157], v[156:157]
	v_lshlrev_b32_e32 v158, 16, v140
	v_and_b32_e32 v159, 0xffff0000, v140
	v_pk_add_f32 v[196:197], v[156:157], v[158:159] neg_lo:[0,1] neg_hi:[0,1]
	v_cvt_pk_bf16_f32 v144, v196, v197
	v_lshlrev_b32_e32 v156, 16, v141
	v_and_b32_e32 v157, 0xffff0000, v141
	v_lshlrev_b32_e32 v158, 16, v145
	v_and_b32_e32 v159, 0xffff0000, v145
	v_pk_add_f32 v[156:157], v[156:157], v[158:159]
	v_pk_fma_f32 v[156:157], v[32:33], 0.5, v[156:157] op_sel_hi:[1,0,1]
	v_cvt_pk_bf16_f32 v141, v156, v157
	v_pk_fma_f32 v[198:199], v[156:157], v[156:157], v[198:199]
	v_lshlrev_b32_e32 v158, 16, v141
	v_and_b32_e32 v159, 0xffff0000, v141
	v_pk_add_f32 v[196:197], v[156:157], v[158:159] neg_lo:[0,1] neg_hi:[0,1]
	v_cvt_pk_bf16_f32 v145, v196, v197
	v_lshlrev_b32_e32 v156, 16, v142
	v_and_b32_e32 v157, 0xffff0000, v142
	v_lshlrev_b32_e32 v158, 16, v146
	v_and_b32_e32 v159, 0xffff0000, v146
	v_pk_add_f32 v[156:157], v[156:157], v[158:159]
	v_pk_fma_f32 v[156:157], v[26:27], 0.5, v[156:157] op_sel_hi:[1,0,1]
	v_cvt_pk_bf16_f32 v142, v156, v157
	v_pk_fma_f32 v[198:199], v[156:157], v[156:157], v[198:199]
	v_lshlrev_b32_e32 v158, 16, v142
	v_and_b32_e32 v159, 0xffff0000, v142
	v_pk_add_f32 v[196:197], v[156:157], v[158:159] neg_lo:[0,1] neg_hi:[0,1]
	v_cvt_pk_bf16_f32 v146, v196, v197
	v_lshlrev_b32_e32 v156, 16, v143
	v_and_b32_e32 v157, 0xffff0000, v143
	v_lshlrev_b32_e32 v158, 16, v147
	v_and_b32_e32 v159, 0xffff0000, v147
	v_pk_add_f32 v[156:157], v[156:157], v[158:159]
	v_pk_fma_f32 v[156:157], v[28:29], 0.5, v[156:157] op_sel_hi:[1,0,1]
	v_cvt_pk_bf16_f32 v143, v156, v157
	v_pk_fma_f32 v[198:199], v[156:157], v[156:157], v[198:199]
	v_lshlrev_b32_e32 v158, 16, v143
	v_and_b32_e32 v159, 0xffff0000, v143
	v_pk_add_f32 v[196:197], v[156:157], v[158:159] neg_lo:[0,1] neg_hi:[0,1]
	v_cvt_pk_bf16_f32 v147, v196, v197
	global_store_dwordx4 v210, v[140:143], s[10:11]
	global_store_dwordx4 v210, v[144:147], s[6:7]
	s_waitcnt vmcnt(14)
	v_lshlrev_b32_e32 v156, 16, v148
	v_and_b32_e32 v157, 0xffff0000, v148
	v_lshlrev_b32_e32 v158, 16, v152
	v_and_b32_e32 v159, 0xffff0000, v152
	v_pk_add_f32 v[156:157], v[156:157], v[158:159]
	v_pk_fma_f32 v[156:157], v[22:23], 0.5, v[156:157] op_sel_hi:[1,0,1]
	v_cvt_pk_bf16_f32 v148, v156, v157
	v_pk_fma_f32 v[198:199], v[156:157], v[156:157], v[198:199]
	v_lshlrev_b32_e32 v158, 16, v148
	v_and_b32_e32 v159, 0xffff0000, v148
	v_pk_add_f32 v[196:197], v[156:157], v[158:159] neg_lo:[0,1] neg_hi:[0,1]
	v_cvt_pk_bf16_f32 v152, v196, v197
	v_lshlrev_b32_e32 v156, 16, v149
	v_and_b32_e32 v157, 0xffff0000, v149
	v_lshlrev_b32_e32 v158, 16, v153
	v_and_b32_e32 v159, 0xffff0000, v153
	v_pk_add_f32 v[156:157], v[156:157], v[158:159]
	v_pk_fma_f32 v[156:157], v[24:25], 0.5, v[156:157] op_sel_hi:[1,0,1]
	v_cvt_pk_bf16_f32 v149, v156, v157
	v_pk_fma_f32 v[198:199], v[156:157], v[156:157], v[198:199]
	v_lshlrev_b32_e32 v158, 16, v149
	v_and_b32_e32 v159, 0xffff0000, v149
	v_pk_add_f32 v[196:197], v[156:157], v[158:159] neg_lo:[0,1] neg_hi:[0,1]
	v_cvt_pk_bf16_f32 v153, v196, v197
	v_lshlrev_b32_e32 v156, 16, v150
	v_and_b32_e32 v157, 0xffff0000, v150
	v_lshlrev_b32_e32 v158, 16, v154
	v_and_b32_e32 v159, 0xffff0000, v154
	v_pk_add_f32 v[156:157], v[156:157], v[158:159]
	v_pk_fma_f32 v[156:157], v[18:19], 0.5, v[156:157] op_sel_hi:[1,0,1]
	v_cvt_pk_bf16_f32 v150, v156, v157
	v_pk_fma_f32 v[198:199], v[156:157], v[156:157], v[198:199]
	v_lshlrev_b32_e32 v158, 16, v150
	v_and_b32_e32 v159, 0xffff0000, v150
	v_pk_add_f32 v[196:197], v[156:157], v[158:159] neg_lo:[0,1] neg_hi:[0,1]
	v_cvt_pk_bf16_f32 v154, v196, v197
	v_lshlrev_b32_e32 v156, 16, v151
	v_and_b32_e32 v157, 0xffff0000, v151
	v_lshlrev_b32_e32 v158, 16, v155
	v_and_b32_e32 v159, 0xffff0000, v155
	v_pk_add_f32 v[156:157], v[156:157], v[158:159]
	v_pk_fma_f32 v[156:157], v[20:21], 0.5, v[156:157] op_sel_hi:[1,0,1]
	v_cvt_pk_bf16_f32 v151, v156, v157
	v_pk_fma_f32 v[198:199], v[156:157], v[156:157], v[198:199]
	v_lshlrev_b32_e32 v158, 16, v151
	v_and_b32_e32 v159, 0xffff0000, v151
	v_pk_add_f32 v[196:197], v[156:157], v[158:159] neg_lo:[0,1] neg_hi:[0,1]
	v_cvt_pk_bf16_f32 v155, v196, v197
	global_store_dwordx4 v210, v[148:151], s[10:11] offset:256
	global_store_dwordx4 v210, v[152:155], s[6:7] offset:256
	v_add_f32_e32 v208, v198, v199
	s_waitcnt vmcnt(10)
; __device__ __forceinline__ unsigned pk2(float lo, float hi) { f32x2_t v = {lo, hi}; bf16x2_t b = __builtin_convertvector(v, bf16x2_t); return __builtin_bit_cast(unsigned, b); }
; __device__ __forceinline__ float bflo(unsigned u) { return __uint_as_float(u << 16); }
; __device__ __forceinline__ float bfhi(unsigned u) { return __uint_as_float(u & 0xffff0000u); }
;     __device__ __forceinline__ void operator()(const f32x4 (&acc)[2][2][4][2], const Unit& u, int wr, int wc, int fr, int fq) const {
;     ...
;                     float lo[8];
; #pragma unroll
;                     for (int e = 0; e < 8; ++e) { hv[e] += av[e]; sq += hv[e] * hv[e]; }
;                     u32x4 wh; wh.x = pk2(hv[0], hv[1]); wh.y = pk2(hv[2], hv[3]); wh.z = pk2(hv[4], hv[5]); wh.w = pk2(hv[6], hv[7]);
;                     lo[0] = hv[0] - bflo(wh.x); lo[1] = hv[1] - bfhi(wh.x); lo[2] = hv[2] - bflo(wh.y); lo[3] = hv[3] - bfhi(wh.y);
;                     lo[4] = hv[4] - bflo(wh.z); lo[5] = hv[5] - bfhi(wh.z); lo[6] = hv[6] - bflo(wh.w); lo[7] = hv[7] - bfhi(wh.w);
;                     u32x4 wl; wl.x = pk2(lo[0], lo[1]); wl.y = pk2(lo[2], lo[3]); wl.z = pk2(lo[4], lo[5]); wl.w = pk2(lo[6], lo[7]);
;                     *(u32x4*)(HO + off) = wh; *(u32x4*)(LO + off) = wl;
;                 }
;                 sq += __shfl_xor(sq, 16); sq += __shfl_xor(sq, 32);
;                 if (fq == 0) ssq_out[(size_t)row * 16 + 4 * u.pn + wc] = sq;
	v_lshlrev_b32_e32 v156, 16, v164
	v_and_b32_e32 v157, 0xffff0000, v164
	v_lshlrev_b32_e32 v158, 16, v168
	v_and_b32_e32 v159, 0xffff0000, v168
	v_pk_add_f32 v[156:157], v[156:157], v[158:159]
	v_pk_fma_f32 v[156:157], v[14:15], 0.5, v[156:157] op_sel_hi:[1,0,1]
	v_cvt_pk_bf16_f32 v164, v156, v157
	v_pk_mul_f32 v[198:199], v[156:157], v[156:157]
	v_lshlrev_b32_e32 v158, 16, v164
	v_and_b32_e32 v159, 0xffff0000, v164
	v_pk_add_f32 v[196:197], v[156:157], v[158:159] neg_lo:[0,1] neg_hi:[0,1]
	v_cvt_pk_bf16_f32 v168, v196, v197
	v_lshlrev_b32_e32 v156, 16, v165
	v_and_b32_e32 v157, 0xffff0000, v165
	v_lshlrev_b32_e32 v158, 16, v169
	v_and_b32_e32 v159, 0xffff0000, v169
	v_pk_add_f32 v[156:157], v[156:157], v[158:159]
	v_pk_fma_f32 v[156:157], v[16:17], 0.5, v[156:157] op_sel_hi:[1,0,1]
	v_cvt_pk_bf16_f32 v165, v156, v157
	v_pk_fma_f32 v[198:199], v[156:157], v[156:157], v[198:199]
	v_lshlrev_b32_e32 v158, 16, v165
	v_and_b32_e32 v159, 0xffff0000, v165
	v_pk_add_f32 v[196:197], v[156:157], v[158:159] neg_lo:[0,1] neg_hi:[0,1]
	v_cvt_pk_bf16_f32 v169, v196, v197
	v_lshlrev_b32_e32 v156, 16, v166
	v_and_b32_e32 v157, 0xffff0000, v166
	v_lshlrev_b32_e32 v158, 16, v170
	v_and_b32_e32 v159, 0xffff0000, v170
	v_pk_add_f32 v[156:157], v[156:157], v[158:159]
	v_pk_fma_f32 v[156:157], v[10:11], 0.5, v[156:157] op_sel_hi:[1,0,1]
	v_cvt_pk_bf16_f32 v166, v156, v157
	v_pk_fma_f32 v[198:199], v[156:157], v[156:157], v[198:199]
	v_lshlrev_b32_e32 v158, 16, v166
	v_and_b32_e32 v159, 0xffff0000, v166
	v_pk_add_f32 v[196:197], v[156:157], v[158:159] neg_lo:[0,1] neg_hi:[0,1]
	v_cvt_pk_bf16_f32 v170, v196, v197
	v_lshlrev_b32_e32 v156, 16, v167
	v_and_b32_e32 v157, 0xffff0000, v167
	v_lshlrev_b32_e32 v158, 16, v171
	v_and_b32_e32 v159, 0xffff0000, v171
	v_pk_add_f32 v[156:157], v[156:157], v[158:159]
	v_pk_fma_f32 v[156:157], v[12:13], 0.5, v[156:157] op_sel_hi:[1,0,1]
	v_cvt_pk_bf16_f32 v167, v156, v157
	v_pk_fma_f32 v[198:199], v[156:157], v[156:157], v[198:199]
	v_lshlrev_b32_e32 v158, 16, v167
	v_and_b32_e32 v159, 0xffff0000, v167
	v_pk_add_f32 v[196:197], v[156:157], v[158:159] neg_lo:[0,1] neg_hi:[0,1]
	v_cvt_pk_bf16_f32 v171, v196, v197
	global_store_dwordx4 v211, v[164:167], s[10:11]
	global_store_dwordx4 v211, v[168:171], s[6:7]
	s_waitcnt vmcnt(10)
	v_lshlrev_b32_e32 v156, 16, v172
	v_and_b32_e32 v157, 0xffff0000, v172
	v_lshlrev_b32_e32 v158, 16, v176
	v_and_b32_e32 v159, 0xffff0000, v176
	v_pk_add_f32 v[156:157], v[156:157], v[158:159]
	v_pk_fma_f32 v[156:157], v[6:7], 0.5, v[156:157] op_sel_hi:[1,0,1]
	v_cvt_pk_bf16_f32 v172, v156, v157
	v_pk_fma_f32 v[198:199], v[156:157], v[156:157], v[198:199]
	v_lshlrev_b32_e32 v158, 16, v172
	v_and_b32_e32 v159, 0xffff0000, v172
	v_pk_add_f32 v[196:197], v[156:157], v[158:159] neg_lo:[0,1] neg_hi:[0,1]
	v_cvt_pk_bf16_f32 v176, v196, v197
	v_lshlrev_b32_e32 v156, 16, v173
	v_and_b32_e32 v157, 0xffff0000, v173
	v_lshlrev_b32_e32 v158, 16, v177
	v_and_b32_e32 v159, 0xffff0000, v177
	v_pk_add_f32 v[156:157], v[156:157], v[158:159]
	v_pk_fma_f32 v[156:157], v[8:9], 0.5, v[156:157] op_sel_hi:[1,0,1]
	v_cvt_pk_bf16_f32 v173, v156, v157
	v_pk_fma_f32 v[198:199], v[156:157], v[156:157], v[198:199]
	v_lshlrev_b32_e32 v158, 16, v173
	v_and_b32_e32 v159, 0xffff0000, v173
	v_pk_add_f32 v[196:197], v[156:157], v[158:159] neg_lo:[0,1] neg_hi:[0,1]
	v_cvt_pk_bf16_f32 v177, v196, v197
	v_lshlrev_b32_e32 v156, 16, v174
	v_and_b32_e32 v157, 0xffff0000, v174
	v_lshlrev_b32_e32 v158, 16, v178
	v_and_b32_e32 v159, 0xffff0000, v178
	v_pk_add_f32 v[156:157], v[156:157], v[158:159]
	v_pk_fma_f32 v[156:157], v[2:3], 0.5, v[156:157] op_sel_hi:[1,0,1]
	v_cvt_pk_bf16_f32 v174, v156, v157
	v_pk_fma_f32 v[198:199], v[156:157], v[156:157], v[198:199]
	v_lshlrev_b32_e32 v158, 16, v174
	v_and_b32_e32 v159, 0xffff0000, v174
	v_pk_add_f32 v[196:197], v[156:157], v[158:159] neg_lo:[0,1] neg_hi:[0,1]
	v_cvt_pk_bf16_f32 v178, v196, v197
	v_lshlrev_b32_e32 v156, 16, v175
	v_and_b32_e32 v157, 0xffff0000, v175
	v_lshlrev_b32_e32 v158, 16, v179
	v_and_b32_e32 v159, 0xffff0000, v179
	v_pk_add_f32 v[156:157], v[156:157], v[158:159]
	v_pk_fma_f32 v[156:157], v[4:5], 0.5, v[156:157] op_sel_hi:[1,0,1]
	v_cvt_pk_bf16_f32 v175, v156, v157
	v_pk_fma_f32 v[198:199], v[156:157], v[156:157], v[198:199]
	v_lshlrev_b32_e32 v158, 16, v175
	v_and_b32_e32 v159, 0xffff0000, v175
	v_pk_add_f32 v[196:197], v[156:157], v[158:159] neg_lo:[0,1] neg_hi:[0,1]
	v_cvt_pk_bf16_f32 v179, v196, v197
	global_store_dwordx4 v211, v[172:175], s[10:11] offset:256
	global_store_dwordx4 v211, v[176:179], s[6:7] offset:256
	v_add_f32_e32 v209, v198, v199
	v_mov_b32_e32 v140, v200
	s_nop 1
	v_permlane16_swap_b32_e32 v200, v140
	v_mov_b32_e32 v141, v201
	s_nop 1
	v_permlane16_swap_b32_e32 v201, v141
	v_mov_b32_e32 v142, v202
	s_nop 1
	v_permlane16_swap_b32_e32 v202, v142
	v_mov_b32_e32 v143, v203
	s_nop 1
	v_permlane16_swap_b32_e32 v203, v143
	v_mov_b32_e32 v144, v206
	s_nop 1
	v_permlane16_swap_b32_e32 v206, v144
	v_mov_b32_e32 v145, v207
	s_nop 1
	v_permlane16_swap_b32_e32 v207, v145
	v_mov_b32_e32 v146, v208
	s_nop 1
	v_permlane16_swap_b32_e32 v208, v146
	v_mov_b32_e32 v147, v209
	s_nop 1
	v_permlane16_swap_b32_e32 v209, v147
	v_readlane_b32 s50, v250, 39
	v_readlane_b32 s51, v250, 40
	s_waitcnt lgkmcnt(0)
	v_add_f32_e32 v200, v200, v140
	v_add_f32_e32 v201, v201, v141
	v_add_f32_e32 v202, v202, v142
	v_add_f32_e32 v203, v203, v143
	v_add_f32_e32 v206, v206, v144
	v_add_f32_e32 v207, v207, v145
	v_add_f32_e32 v208, v208, v146
	v_add_f32_e32 v209, v209, v147
	v_mov_b32_e32 v140, v200
	s_nop 1
	v_permlane32_swap_b32_e32 v200, v140
	v_mov_b32_e32 v141, v201
	s_nop 1
	v_permlane32_swap_b32_e32 v201, v141
	v_mov_b32_e32 v142, v202
	s_nop 1
	v_permlane32_swap_b32_e32 v202, v142
	v_mov_b32_e32 v143, v203
	s_nop 1
	v_permlane32_swap_b32_e32 v203, v143
	v_mov_b32_e32 v144, v206
	s_nop 1
	v_permlane32_swap_b32_e32 v206, v144
	v_mov_b32_e32 v145, v207
	s_nop 1
	v_permlane32_swap_b32_e32 v207, v145
	v_mov_b32_e32 v146, v208
	s_nop 1
	v_permlane32_swap_b32_e32 v208, v146
	v_mov_b32_e32 v147, v209
	s_nop 1
	v_permlane32_swap_b32_e32 v209, v147
	s_waitcnt lgkmcnt(0)
	v_add_f32_e32 v200, v200, v140
	v_add_f32_e32 v201, v201, v141
	v_add_f32_e32 v202, v202, v142
	v_add_f32_e32 v203, v203, v143
	v_add_f32_e32 v206, v206, v144
	v_add_f32_e32 v207, v207, v145
	v_add_f32_e32 v208, v208, v146
	v_add_f32_e32 v209, v209, v147
	s_and_saveexec_b64 s[12:13], s[42:43]
	s_cbranch_execz .Lepir_f2d_skip
	global_store_dword v216, v200, s[50:51]
	global_store_dword v216, v201, s[50:51] offset:1024
	global_store_dword v216, v202, s[50:51] offset:2048
	global_store_dword v216, v203, s[50:51] offset:3072
	global_store_dword v217, v206, s[50:51]
	global_store_dword v217, v207, s[50:51] offset:1024
	global_store_dword v217, v208, s[50:51] offset:2048
	global_store_dword v217, v209, s[50:51] offset:3072

; __device__ __forceinline__ float bflo(unsigned u) { return __uint_as_float(u << 16); }
;     __device__ __forceinline__ void operator()(const f32x4 (&acc)[2][2][4][2], const Unit& u, int wr, int wc, int fr, int fq) const {
;     ...
;                 const int row = row0 + ai * HALF + m * 16;
;                 float rs = 0.f; if (GATED) rs = rsqrtf(row_ssq(ssq_in, 16, 4, row, fq) * (1.f / 1024.f) + EPS);
;                 float sq = 0.f;
; #pragma unroll
;                 for (int bj = 0; bj < 2; ++bj) {
;                     const size_t off = (size_t)row * DM + col0 + bj * HALF;
;                     const u32x4 hh = *(const u32x4*)(HI + off), ll = *(const u32x4*)(LO + off);
;                     float hv[8] = {bflo(hh.x) + bflo(ll.x), bfhi(hh.x) + bfhi(ll.x), bflo(hh.y) + bflo(ll.y), bfhi(hh.y) + bfhi(ll.y),
;                                    bflo(hh.z) + bflo(ll.z), bfhi(hh.z) + bfhi(ll.z), bflo(hh.w) + bflo(ll.w), bfhi(hh.w) + bfhi(ll.w)};
;                     float av[8] = {acc[ai][bj][m][0][0], acc[ai][bj][m][0][1], acc[ai][bj][m][0][2], acc[ai][bj][m][0][3], acc[ai][bj][m][1][0], acc[ai][bj][m][1][1], acc[ai][bj][m][1][2], acc[ai][bj][m][1][3]};
;                     if (GATED) { const u32x4 pp = *(const u32x4*)(PP + off);
;                         const float pv[8] = {bflo(pp.x), bfhi(pp.x), bflo(pp.y), bfhi(pp.y), bflo(pp.z), bfhi(pp.z), bflo(pp.w), bfhi(pp.w)};
; #pragma unroll
;                         for (int e = 0; e < 8; ++e) av[e] = fast_sigmoid(av[e] * rs) * pv[e]; }
;                     else {
; #pragma unroll
;                         for (int e = 0; e < 8; ++e) av[e] *= alpha; }
;                     float lo[8];
; #pragma unroll
;                     for (int e = 0; e < 8; ++e) { hv[e] += av[e]; sq += hv[e] * hv[e]; }
;                     u32x4 wh; wh.x = pk2(hv[0], hv[1]); wh.y = pk2(hv[2], hv[3]); wh.z = pk2(hv[4], hv[5]); wh.w = pk2(hv[6], hv[7]);
;                     lo[0] = hv[0] - bflo(wh.x); lo[1] = hv[1] - bfhi(wh.x); lo[2] = hv[2] - bflo(wh.y); lo[3] = hv[3] - bfhi(wh.y);
;                     lo[4] = hv[4] - bflo(wh.z); lo[5] = hv[5] - bfhi(wh.z); lo[6] = hv[6] - bflo(wh.w); lo[7] = hv[7] - bfhi(wh.w);
;                     u32x4 wl; wl.x = pk2(lo[0], lo[1]); wl.y = pk2(lo[2], lo[3]); wl.z = pk2(lo[4], lo[5]); wl.w = pk2(lo[6], lo[7]);
;                     *(u32x4*)(HO + off) = wh; *(u32x4*)(LO + off) = wl;
;                 }
.LBB0_1338:
	v_lshl_add_u32 v144, s27, 8, v154
	v_ashrrev_i32_e32 v145, 31, v144
	v_lshlrev_b64 v[146:147], 6, v[144:145]
	v_lshl_add_u64 v[148:149], v[136:137], 0, v[146:147]
	global_load_dwordx4 v[150:153], v[148:149], off
	v_lshl_or_b32 v142, s4, 8, v156
	v_ashrrev_i32_e32 v143, 31, v142
	v_lshlrev_b64 v[148:149], 10, v[144:145]
	v_lshl_add_u64 v[148:149], v[148:149], 0, v[142:143]
	v_readlane_b32 s10, v253, 35
	v_lshlrev_b64 v[148:149], 1, v[148:149]
	v_readlane_b32 s11, v253, 36
	v_readlane_b32 s14, v250, 47
	v_readlane_b32 s15, v250, 48
	v_lshl_add_u64 v[158:159], s[10:11], 0, v[148:149]
	global_load_dwordx4 v[160:163], v[158:159], off
	v_lshl_add_u64 v[158:159], s[14:15], 0, v[148:149]
	global_load_dwordx4 v[168:171], v[158:159], off
	v_readlane_b32 s6, v250, 49
	v_readlane_b32 s7, v250, 50
	v_and_b32_e32 v158, 64, v241
	v_xor_b32_e32 v145, 16, v241
	v_lshl_add_u64 v[172:173], s[6:7], 0, v[148:149]
	global_load_dwordx4 v[164:167], v[172:173], off
	v_add_u32_e32 v158, 64, v158
	v_xor_b32_e32 v159, 32, v241
	v_cmp_lt_i32_e32 vcc, v145, v158
	s_lshl_b32 s54, s4, 2
	s_mov_b32 s16, 0x800000
	v_cndmask_b32_e32 v145, v241, v145, vcc
	v_cmp_lt_i32_e32 vcc, v159, v158
	v_lshlrev_b32_e32 v158, 2, v145
	s_waitcnt vmcnt(0)
	v_mov_b32_e32 v174, v151
	v_mov_b32_e32 v175, v152
	v_mov_b32_e32 v151, v153
	v_cndmask_b32_e32 v159, v241, v159, vcc
	v_pk_add_f32 v[150:151], v[174:175], v[150:151]
	v_lshlrev_b32_e32 v145, 2, v159
	v_add_f32_e32 v159, v150, v151
	v_mov_b32_e32 v182, v159
	s_nop 1
	v_permlane16_swap_b32_e32 v159, v182
	v_lshlrev_b32_e32 v150, 16, v160
	s_waitcnt lgkmcnt(0)
	v_add_f32_e32 v159, v159, v182
	v_lshlrev_b32_e32 v180, 16, v170
	v_and_b32_e32 v181, 0xffff0000, v170
	v_mov_b32_e32 v170, v159
	s_nop 1
	v_permlane32_swap_b32_e32 v159, v170
	v_and_b32_e32 v151, 0xffff0000, v160
	v_lshlrev_b32_e32 v160, 16, v161
	v_and_b32_e32 v161, 0xffff0000, v161
	v_lshlrev_b32_e32 v152, 16, v164
	v_and_b32_e32 v153, 0xffff0000, v164
	v_pk_add_f32 v[150:151], v[150:151], v[152:153]
	s_waitcnt lgkmcnt(0)
	v_add_f32_e32 v152, v159, v170
	v_fmamk_f32 v152, v152, 0x3a800000, v239
	v_mul_f32_e32 v153, 0x4b800000, v152
	v_cmp_gt_f32_e32 vcc, s55, v152
	v_lshlrev_b32_e32 v164, 16, v165
	v_and_b32_e32 v165, 0xffff0000, v165
	v_cndmask_b32_e32 v152, v152, v153, vcc
	v_rsq_f32_e32 v159, v152
	v_pk_add_f32 v[152:153], v[160:161], v[164:165]
	v_lshlrev_b32_e32 v176, 16, v162
	v_and_b32_e32 v177, 0xffff0000, v162
	v_mul_f32_e32 v164, 0x45800000, v159
	v_cndmask_b32_e32 v159, v159, v164, vcc
	v_mul_f32_e32 v128, v128, v159
	v_mul_f32_e32 v129, v129, v159
	v_mul_f32_e32 v126, v126, v159
	v_mul_f32_e32 v127, v127, v159
	v_mul_f32_e32 v122, v122, v159
	v_mul_f32_e32 v123, v123, v159
	v_mul_f32_e32 v124, v124, v159
	v_mul_f32_e32 v125, v125, v159
	v_mul_f32_e32 v128, 0xbfb8aa3b, v128
	v_mul_f32_e32 v129, 0xbfb8aa3b, v129
	v_mul_f32_e32 v126, 0xbfb8aa3b, v126
	v_mul_f32_e32 v127, 0xbfb8aa3b, v127
	v_mul_f32_e32 v122, 0xbfb8aa3b, v122
	v_mul_f32_e32 v123, 0xbfb8aa3b, v123
	v_mul_f32_e32 v124, 0xbfb8aa3b, v124
	v_mul_f32_e32 v125, 0xbfb8aa3b, v125
	v_exp_f32_e32 v128, v128
	v_exp_f32_e32 v129, v129
	v_exp_f32_e32 v126, v126
	v_exp_f32_e32 v127, v127
	v_exp_f32_e32 v122, v122
	v_exp_f32_e32 v123, v123
	v_exp_f32_e32 v124, v124
	v_exp_f32_e32 v125, v125
	v_lshlrev_b32_e32 v178, 16, v166
	v_and_b32_e32 v179, 0xffff0000, v166
	v_lshlrev_b32_e32 v162, 16, v163
	v_and_b32_e32 v163, 0xffff0000, v163
	v_lshlrev_b32_e32 v166, 16, v167
	v_and_b32_e32 v167, 0xffff0000, v167
	v_add_f32_e32 v128, 1.0, v128
	v_add_f32_e32 v129, 1.0, v129
	v_pk_add_f32 v[162:163], v[162:163], v[166:167]
	v_add_f32_e32 v126, 1.0, v126
	v_add_f32_e32 v127, 1.0, v127
	v_add_f32_e32 v164, 1.0, v122
	v_add_f32_e32 v165, 1.0, v123
	v_add_f32_e32 v166, 1.0, v124
	v_add_f32_e32 v167, 1.0, v125
	v_rcp_f32_e32 v124, v128
	v_rcp_f32_e32 v125, v129
	v_rcp_f32_e32 v122, v126
	v_rcp_f32_e32 v123, v127
	v_rcp_f32_e32 v126, v164
	v_rcp_f32_e32 v127, v165
	v_rcp_f32_e32 v128, v166
	v_rcp_f32_e32 v129, v167
	v_lshlrev_b32_e32 v174, 16, v168
	v_and_b32_e32 v175, 0xffff0000, v168
	v_lshlrev_b32_e32 v168, 16, v169
	v_and_b32_e32 v169, 0xffff0000, v169
	v_pk_add_f32 v[160:161], v[176:177], v[178:179]
	v_pk_fma_f32 v[166:167], v[124:125], v[168:169], v[152:153]
	v_lshlrev_b32_e32 v168, 16, v171
	v_and_b32_e32 v169, 0xffff0000, v171
	v_pk_fma_f32 v[164:165], v[122:123], v[174:175], v[150:151]
	v_pk_fma_f32 v[160:161], v[126:127], v[180:181], v[160:161]
	v_pk_fma_f32 v[162:163], v[128:129], v[168:169], v[162:163]
	v_cvt_pk_bf16_f32 v122, v164, v165
	v_cvt_pk_bf16_f32 v123, v166, v167
	v_cvt_pk_bf16_f32 v124, v160, v161
	v_cvt_pk_bf16_f32 v125, v162, v163
	v_lshlrev_b32_e32 v126, 16, v122
	v_and_b32_e32 v127, 0xffff0000, v122
	v_lshlrev_b32_e32 v150, 16, v123
	v_and_b32_e32 v151, 0xffff0000, v123
	v_lshlrev_b32_e32 v152, 16, v124
	v_and_b32_e32 v153, 0xffff0000, v124
	v_lshlrev_b32_e32 v128, 16, v125
	v_and_b32_e32 v129, 0xffff0000, v125
	v_pk_add_f32 v[126:127], v[164:165], v[126:127] neg_lo:[0,1] neg_hi:[0,1]
	v_pk_add_f32 v[150:151], v[166:167], v[150:151] neg_lo:[0,1] neg_hi:[0,1]
	v_pk_add_f32 v[152:153], v[160:161], v[152:153] neg_lo:[0,1] neg_hi:[0,1]
	v_pk_add_f32 v[168:169], v[162:163], v[128:129] neg_lo:[0,1] neg_hi:[0,1]
	v_cvt_pk_bf16_f32 v126, v126, v127
	v_cvt_pk_bf16_f32 v127, v150, v151
	v_cvt_pk_bf16_f32 v128, v152, v153
	v_lshl_add_u64 v[150:151], s[58:59], 0, v[148:149]
	v_or_b32_e32 v148, 0x100, v148
	v_cvt_pk_bf16_f32 v129, v168, v169
	global_store_dwordx4 v[150:151], v[122:125], off
	v_lshl_add_u64 v[170:171], s[6:7], 0, v[148:149]
	global_store_dwordx4 v[172:173], v[126:129], off
; __device__ __forceinline__ unsigned pk2(float lo, float hi) { f32x2_t v = {lo, hi}; bf16x2_t b = __builtin_convertvector(v, bf16x2_t); return __builtin_bit_cast(unsigned, b); }
; __device__ __forceinline__ float bflo(unsigned u) { return __uint_as_float(u << 16); }
; __device__ __forceinline__ float bfhi(unsigned u) { return __uint_as_float(u & 0xffff0000u); }
; __device__ __forceinline__ float fast_sigmoid(float x) { return __builtin_amdgcn_rcpf(1.f + __expf(-x)); }
;     __device__ __forceinline__ void operator()(const f32x4 (&acc)[2][2][4][2], const Unit& u, int wr, int wc, int fr, int fq) const {
;     ...
;                     if (GATED) { const u32x4 pp = *(const u32x4*)(PP + off);
;                         const float pv[8] = {bflo(pp.x), bfhi(pp.x), bflo(pp.y), bfhi(pp.y), bflo(pp.z), bfhi(pp.z), bflo(pp.w), bfhi(pp.w)};
; #pragma unroll
;                         for (int e = 0; e < 8; ++e) av[e] = fast_sigmoid(av[e] * rs) * pv[e]; }
;                     else {
; #pragma unroll
;                         for (int e = 0; e < 8; ++e) av[e] *= alpha; }
;                     float lo[8];
; #pragma unroll
;                     for (int e = 0; e < 8; ++e) { hv[e] += av[e]; sq += hv[e] * hv[e]; }
;                     u32x4 wh; wh.x = pk2(hv[0], hv[1]); wh.y = pk2(hv[2], hv[3]); wh.z = pk2(hv[4], hv[5]); wh.w = pk2(hv[6], hv[7]);
;                     lo[0] = hv[0] - bflo(wh.x); lo[1] = hv[1] - bfhi(wh.x); lo[2] = hv[2] - bflo(wh.y); lo[3] = hv[3] - bfhi(wh.y);
;                     lo[4] = hv[4] - bflo(wh.z); lo[5] = hv[5] - bfhi(wh.z); lo[6] = hv[6] - bflo(wh.w); lo[7] = hv[7] - bfhi(wh.w);
;                     u32x4 wl; wl.x = pk2(lo[0], lo[1]); wl.y = pk2(lo[2], lo[3]); wl.z = pk2(lo[4], lo[5]); wl.w = pk2(lo[6], lo[7]);
;                     *(u32x4*)(HO + off) = wh; *(u32x4*)(LO + off) = wl;
;                 }
;                 sq += __shfl_xor(sq, 16); sq += __shfl_xor(sq, 32);
;                 if (fq == 0) ssq_out[(size_t)row * 16 + 4 * u.pn + wc] = sq;
	global_load_dwordx4 v[122:125], v[170:171], off
	v_lshl_add_u64 v[150:151], s[14:15], 0, v[148:149]
	v_lshl_add_u64 v[126:127], s[10:11], 0, v[148:149]
	global_load_dwordx4 v[126:129], v[126:127], off
	v_mul_f32_e32 v118, v118, v159
	global_load_dwordx4 v[150:153], v[150:151], off
	v_mul_f32_e32 v119, v119, v159
	v_mul_f32_e32 v120, v120, v159
	v_mul_f32_e32 v121, v121, v159
	v_mul_f32_e32 v114, v114, v159
	v_mul_f32_e32 v115, v115, v159
	v_mul_f32_e32 v116, v116, v159
	v_mul_f32_e32 v117, v117, v159
	v_mul_f32_e32 v118, 0xbfb8aa3b, v118
	v_mul_f32_e32 v119, 0xbfb8aa3b, v119
	v_mul_f32_e32 v120, 0xbfb8aa3b, v120
	v_mul_f32_e32 v121, 0xbfb8aa3b, v121
	v_mul_f32_e32 v114, 0xbfb8aa3b, v114
	v_mul_f32_e32 v115, 0xbfb8aa3b, v115
	v_mul_f32_e32 v116, 0xbfb8aa3b, v116
	v_mul_f32_e32 v117, 0xbfb8aa3b, v117
	v_exp_f32_e32 v118, v118
	v_exp_f32_e32 v119, v119
	v_exp_f32_e32 v120, v120
	v_exp_f32_e32 v121, v121
	v_exp_f32_e32 v114, v114
	v_exp_f32_e32 v115, v115
	v_exp_f32_e32 v116, v116
	v_exp_f32_e32 v117, v117
	v_add_f32_e32 v118, 1.0, v118
	v_add_f32_e32 v119, 1.0, v119
	v_add_f32_e32 v120, 1.0, v120
	v_add_f32_e32 v121, 1.0, v121
	v_add_f32_e32 v159, 1.0, v114
	v_add_f32_e32 v168, 1.0, v115
	v_add_f32_e32 v169, 1.0, v116
	v_add_f32_e32 v172, 1.0, v117
	v_rcp_f32_e32 v114, v118
	v_rcp_f32_e32 v115, v119
	v_rcp_f32_e32 v116, v120
	v_rcp_f32_e32 v117, v121
	v_rcp_f32_e32 v119, v168
	v_rcp_f32_e32 v120, v169
	v_rcp_f32_e32 v121, v172
	v_rcp_f32_e32 v118, v159
	v_pk_mul_f32 v[164:165], v[164:165], v[164:165]
	v_pk_mul_f32 v[166:167], v[166:167], v[166:167]
	v_pk_mul_f32 v[160:161], v[160:161], v[160:161]
	v_pk_mul_f32 v[162:163], v[162:163], v[162:163]
	s_ashr_i32 s55, s54, 31
	s_waitcnt vmcnt(2)
	v_lshlrev_b32_e32 v168, 16, v122
	v_and_b32_e32 v169, 0xffff0000, v122
	v_lshlrev_b32_e32 v122, 16, v123
	v_and_b32_e32 v123, 0xffff0000, v123
	s_waitcnt vmcnt(1)
	v_lshlrev_b32_e32 v172, 16, v126
	v_and_b32_e32 v173, 0xffff0000, v126
	v_lshlrev_b32_e32 v126, 16, v127
	v_and_b32_e32 v127, 0xffff0000, v127
	s_waitcnt vmcnt(0)
	v_lshlrev_b32_e32 v174, 16, v150
	v_and_b32_e32 v175, 0xffff0000, v150
	v_lshlrev_b32_e32 v150, 16, v151
	v_and_b32_e32 v151, 0xffff0000, v151
	v_pk_add_f32 v[168:169], v[172:173], v[168:169]
	v_pk_add_f32 v[122:123], v[126:127], v[122:123]
	v_pk_fma_f32 v[114:115], v[114:115], v[174:175], v[168:169]
	v_pk_fma_f32 v[122:123], v[116:117], v[150:151], v[122:123]
	v_cvt_pk_bf16_f32 v116, v114, v115
	v_cvt_pk_bf16_f32 v117, v122, v123
	v_lshlrev_b32_e32 v150, 16, v116
	v_and_b32_e32 v151, 0xffff0000, v116
	v_lshlrev_b32_e32 v168, 16, v117
	v_and_b32_e32 v169, 0xffff0000, v117
	v_pk_mul_f32 v[126:127], v[114:115], v[114:115]
	v_pk_add_f32 v[114:115], v[114:115], v[150:151] neg_lo:[0,1] neg_hi:[0,1]
	v_pk_mul_f32 v[150:151], v[122:123], v[122:123]
	v_pk_add_f32 v[122:123], v[122:123], v[168:169] neg_lo:[0,1] neg_hi:[0,1]
	v_lshlrev_b32_e32 v168, 16, v128
	v_and_b32_e32 v169, 0xffff0000, v128
	v_lshlrev_b32_e32 v172, 16, v124
	v_and_b32_e32 v173, 0xffff0000, v124
	v_pk_add_f32 v[168:169], v[168:169], v[172:173]
	v_lshlrev_b32_e32 v172, 16, v152
	v_and_b32_e32 v173, 0xffff0000, v152
	v_pk_fma_f32 v[168:169], v[118:119], v[172:173], v[168:169]
	v_add_f32_e32 v119, v164, v165
	v_add_f32_e32 v119, v166, v119
	v_add_f32_e32 v119, v167, v119
	v_add_f32_e32 v119, v160, v119
	v_add_f32_e32 v119, v161, v119
	v_add_f32_e32 v119, v162, v119
	v_add_f32_e32 v119, v163, v119
	v_add_f32_e32 v119, v126, v119
	v_add_f32_e32 v119, v127, v119
	v_lshlrev_b32_e32 v128, 16, v129
	v_and_b32_e32 v129, 0xffff0000, v129
	v_lshlrev_b32_e32 v124, 16, v125
	v_and_b32_e32 v125, 0xffff0000, v125
	v_add_f32_e32 v119, v150, v119
	v_pk_mul_f32 v[172:173], v[168:169], v[168:169]
	v_pk_add_f32 v[124:125], v[128:129], v[124:125]
	v_lshlrev_b32_e32 v128, 16, v153
	v_and_b32_e32 v129, 0xffff0000, v153
	v_add_f32_e32 v119, v151, v119
	v_pk_fma_f32 v[120:121], v[120:121], v[128:129], v[124:125]
	v_add_f32_e32 v119, v172, v119
	v_pk_mul_f32 v[124:125], v[120:121], v[120:121]
	v_add_f32_e32 v119, v173, v119
	v_add_f32_e32 v119, v124, v119
	v_add_f32_e32 v126, v125, v119
	v_mov_b32_e32 v127, v126
	s_nop 1
	v_permlane16_swap_b32_e32 v126, v127
	v_cvt_pk_bf16_f32 v119, v120, v121
	v_lshlrev_b32_e32 v124, 16, v119
	v_and_b32_e32 v125, 0xffff0000, v119
	v_pk_add_f32 v[124:125], v[120:121], v[124:125] neg_lo:[0,1] neg_hi:[0,1]
	v_cvt_pk_bf16_f32 v120, v114, v115
	s_waitcnt lgkmcnt(0)
	v_add_f32_e32 v114, v126, v127
	ds_bpermute_b32 v115, v145, v114
	v_cvt_pk_bf16_f32 v118, v168, v169
	v_lshlrev_b32_e32 v174, 16, v118
	v_and_b32_e32 v175, 0xffff0000, v118
	v_pk_add_f32 v[168:169], v[168:169], v[174:175] neg_lo:[0,1] neg_hi:[0,1]
	v_cvt_pk_bf16_f32 v121, v122, v123
	v_cvt_pk_bf16_f32 v123, v124, v125
	v_lshl_add_u64 v[124:125], s[58:59], 0, v[148:149]
	v_cvt_pk_bf16_f32 v122, v168, v169
	global_store_dwordx4 v[124:125], v[116:119], off
	global_store_dwordx4 v[170:171], v[120:123], off
	s_and_saveexec_b64 s[12:13], s[0:1]
	v_readlane_b32 s30, v251, 4
	v_readlane_b32 s31, v251, 5
	s_cbranch_execz .LBB0_1340
	v_readlane_b32 s44, v250, 8
	v_readlane_b32 s46, v250, 10
	v_readlane_b32 s47, v250, 11
	s_waitcnt lgkmcnt(0)
	v_add_f32_e32 v116, v114, v115
	s_lshl_b32 s40, s25, 2
	v_lshl_add_u64 v[114:115], s[46:47], 0, v[146:147]
	v_lshl_add_u64 v[114:115], s[54:55], 2, v[114:115]
	v_lshl_add_u64 v[114:115], v[114:115], 0, s[40:41]
	v_readlane_b32 s45, v250, 9
	global_store_dword v[114:115], v116, off
; __device__ __forceinline__ float bflo(unsigned u) { return __uint_as_float(u << 16); }
;     __device__ __forceinline__ void operator()(const f32x4 (&acc)[2][2][4][2], const Unit& u, int wr, int wc, int fr, int fq) const {
;     ...
;                 const int row = row0 + ai * HALF + m * 16;
;                 float rs = 0.f; if (GATED) rs = rsqrtf(row_ssq(ssq_in, 16, 4, row, fq) * (1.f / 1024.f) + EPS);
;                 float sq = 0.f;
; #pragma unroll
;                 for (int bj = 0; bj < 2; ++bj) {
;                     const size_t off = (size_t)row * DM + col0 + bj * HALF;
;                     const u32x4 hh = *(const u32x4*)(HI + off), ll = *(const u32x4*)(LO + off);
;                     float hv[8] = {bflo(hh.x) + bflo(ll.x), bfhi(hh.x) + bfhi(ll.x), bflo(hh.y) + bflo(ll.y), bfhi(hh.y) + bfhi(ll.y),
;                                    bflo(hh.z) + bflo(ll.z), bfhi(hh.z) + bfhi(ll.z), bflo(hh.w) + bflo(ll.w), bfhi(hh.w) + bfhi(ll.w)};
;                     float av[8] = {acc[ai][bj][m][0][0], acc[ai][bj][m][0][1], acc[ai][bj][m][0][2], acc[ai][bj][m][0][3], acc[ai][bj][m][1][0], acc[ai][bj][m][1][1], acc[ai][bj][m][1][2], acc[ai][bj][m][1][3]};
;                     if (GATED) { const u32x4 pp = *(const u32x4*)(PP + off);
;                         const float pv[8] = {bflo(pp.x), bfhi(pp.x), bflo(pp.y), bfhi(pp.y), bflo(pp.z), bfhi(pp.z), bflo(pp.w), bfhi(pp.w)};
; #pragma unroll
;                         for (int e = 0; e < 8; ++e) av[e] = fast_sigmoid(av[e] * rs) * pv[e]; }
;                     else {
; #pragma unroll
;                         for (int e = 0; e < 8; ++e) av[e] *= alpha; }
;                     float lo[8];
; #pragma unroll
;                     for (int e = 0; e < 8; ++e) { hv[e] += av[e]; sq += hv[e] * hv[e]; }
;                     u32x4 wh; wh.x = pk2(hv[0], hv[1]); wh.y = pk2(hv[2], hv[3]); wh.z = pk2(hv[4], hv[5]); wh.w = pk2(hv[6], hv[7]);
;                     lo[0] = hv[0] - bflo(wh.x); lo[1] = hv[1] - bfhi(wh.x); lo[2] = hv[2] - bflo(wh.y); lo[3] = hv[3] - bfhi(wh.y);
;                     lo[4] = hv[4] - bflo(wh.z); lo[5] = hv[5] - bfhi(wh.z); lo[6] = hv[6] - bflo(wh.w); lo[7] = hv[7] - bfhi(wh.w);
;                     u32x4 wl; wl.x = pk2(lo[0], lo[1]); wl.y = pk2(lo[2], lo[3]); wl.z = pk2(lo[4], lo[5]); wl.w = pk2(lo[6], lo[7]);
;                     *(u32x4*)(HO + off) = wh; *(u32x4*)(LO + off) = wl;
;                 }
.LBB0_1340:
	s_or_b64 exec, exec, s[12:13]
	v_or_b32_e32 v120, 16, v144
	v_ashrrev_i32_e32 v121, 31, v120
	v_lshlrev_b64 v[118:119], 6, v[120:121]
	s_waitcnt lgkmcnt(0)
	v_lshl_add_u64 v[114:115], v[136:137], 0, v[118:119]
	global_load_dwordx4 v[114:117], v[114:115], off
	v_readlane_b32 s10, v253, 35
	v_readlane_b32 s11, v253, 36
	v_readlane_b32 s6, v250, 49
	v_readlane_b32 s7, v250, 50
	s_waitcnt vmcnt(0)
	v_mov_b32_e32 v122, v115
	v_mov_b32_e32 v123, v116
	v_mov_b32_e32 v115, v117
	v_pk_add_f32 v[114:115], v[122:123], v[114:115]
	s_nop 0
	v_add_f32_e32 v114, v114, v115
	v_mov_b32_e32 v115, v114
	s_nop 1
	v_permlane16_swap_b32_e32 v114, v115
	s_waitcnt lgkmcnt(0)
	v_add_f32_e32 v114, v114, v115
	v_mov_b32_e32 v115, v114
	s_nop 1
	v_permlane32_swap_b32_e32 v114, v115
	s_waitcnt lgkmcnt(0)
	v_add_f32_e32 v114, v114, v115
	v_fmamk_f32 v114, v114, 0x3a800000, v239
	v_cmp_gt_f32_e32 vcc, s16, v114
	v_mul_f32_e32 v115, 0x4b800000, v114
	s_nop 0
	v_cndmask_b32_e32 v114, v114, v115, vcc
	v_rsq_f32_e32 v114, v114
	s_nop 0
	v_mul_f32_e32 v115, 0x45800000, v114
	v_cndmask_b32_e32 v152, v114, v115, vcc
	v_lshlrev_b64 v[114:115], 10, v[120:121]
	v_lshl_add_u64 v[114:115], v[114:115], 0, v[142:143]
	v_lshlrev_b64 v[120:121], 1, v[114:115]
	v_lshl_add_u64 v[114:115], s[10:11], 0, v[120:121]
	v_lshl_add_u64 v[116:117], s[14:15], 0, v[120:121]
	global_load_dwordx4 v[126:129], v[114:115], off
	global_load_dwordx4 v[160:163], v[116:117], off
	v_lshl_add_u64 v[114:115], s[6:7], 0, v[120:121]
	global_load_dwordx4 v[146:149], v[114:115], off
	v_mul_f32_e32 v106, v106, v152
	v_mul_f32_e32 v106, 0xbfb8aa3b, v106
	v_exp_f32_e32 v106, v106
	v_mul_f32_e32 v110, v110, v152
	v_mul_f32_e32 v111, v111, v152
	v_mul_f32_e32 v110, 0xbfb8aa3b, v110
	v_add_f32_e32 v106, 1.0, v106
	v_rcp_f32_e32 v116, v106
	v_mul_f32_e32 v106, v107, v152
	v_mul_f32_e32 v106, 0xbfb8aa3b, v106
	v_exp_f32_e32 v106, v106
	v_mul_f32_e32 v111, 0xbfb8aa3b, v111
	v_exp_f32_e32 v110, v110
	v_exp_f32_e32 v111, v111
	v_add_f32_e32 v106, 1.0, v106
	v_rcp_f32_e32 v117, v106
	v_mul_f32_e32 v106, v108, v152
	v_mul_f32_e32 v106, 0xbfb8aa3b, v106
	v_exp_f32_e32 v106, v106
	v_mul_f32_e32 v112, v112, v152
	v_mul_f32_e32 v113, v113, v152
	v_add_f32_e32 v110, 1.0, v110
	v_add_f32_e32 v106, 1.0, v106
	v_rcp_f32_e32 v150, v106
	v_mul_f32_e32 v106, v109, v152
	v_mul_f32_e32 v106, 0xbfb8aa3b, v106
	v_exp_f32_e32 v106, v106
	v_add_f32_e32 v111, 1.0, v111
	v_mul_f32_e32 v112, 0xbfb8aa3b, v112
	v_mul_f32_e32 v113, 0xbfb8aa3b, v113
	v_rcp_f32_e32 v110, v110
	v_rcp_f32_e32 v111, v111
	v_exp_f32_e32 v112, v112
	v_exp_f32_e32 v113, v113
	v_add_f32_e32 v106, 1.0, v106
	v_rcp_f32_e32 v151, v106
	v_add_f32_e32 v112, 1.0, v112
	v_add_f32_e32 v113, 1.0, v113
	v_rcp_f32_e32 v112, v112
	v_rcp_f32_e32 v113, v113
	v_mul_f32_e32 v102, v102, v152
	v_mul_f32_e32 v102, 0xbfb8aa3b, v102
	v_exp_f32_e32 v102, v102
	v_mul_f32_e32 v98, v98, v152
	v_mul_f32_e32 v98, 0xbfb8aa3b, v98
	v_exp_f32_e32 v98, v98
	v_add_f32_e32 v102, 1.0, v102
	v_add_f32_e32 v98, 1.0, v98
	s_waitcnt vmcnt(2)
	v_lshlrev_b32_e32 v106, 16, v126
	v_and_b32_e32 v107, 0xffff0000, v126
	s_waitcnt vmcnt(0)
	v_lshlrev_b32_e32 v108, 16, v146
	v_and_b32_e32 v109, 0xffff0000, v146
	v_pk_add_f32 v[106:107], v[106:107], v[108:109]
	v_lshlrev_b32_e32 v108, 16, v160
	v_and_b32_e32 v109, 0xffff0000, v160
	v_pk_fma_f32 v[108:109], v[110:111], v[108:109], v[106:107]
	v_lshlrev_b32_e32 v124, 16, v147
	v_cvt_pk_bf16_f32 v106, v108, v109
	v_lshlrev_b32_e32 v110, 16, v106
	v_and_b32_e32 v111, 0xffff0000, v106
	v_pk_mul_f32 v[122:123], v[108:109], v[108:109]
	v_pk_add_f32 v[110:111], v[108:109], v[110:111] neg_lo:[0,1] neg_hi:[0,1]
	v_lshlrev_b32_e32 v108, 16, v127
	v_and_b32_e32 v109, 0xffff0000, v127
	v_and_b32_e32 v125, 0xffff0000, v147
	v_pk_add_f32 v[108:109], v[108:109], v[124:125]
	v_lshlrev_b32_e32 v124, 16, v161
	v_and_b32_e32 v125, 0xffff0000, v161
	v_pk_fma_f32 v[108:109], v[112:113], v[124:125], v[108:109]
	v_lshlrev_b32_e32 v126, 16, v148
	v_cvt_pk_bf16_f32 v107, v108, v109
	v_lshlrev_b32_e32 v112, 16, v107
	v_and_b32_e32 v113, 0xffff0000, v107
	v_pk_mul_f32 v[124:125], v[108:109], v[108:109]
	v_pk_add_f32 v[112:113], v[108:109], v[112:113] neg_lo:[0,1] neg_hi:[0,1]
	v_lshlrev_b32_e32 v108, 16, v128
	v_and_b32_e32 v109, 0xffff0000, v128
	v_and_b32_e32 v127, 0xffff0000, v148
	v_pk_add_f32 v[108:109], v[108:109], v[126:127]
	v_lshlrev_b32_e32 v126, 16, v162
	v_and_b32_e32 v127, 0xffff0000, v162
	v_pk_fma_f32 v[116:117], v[116:117], v[126:127], v[108:109]
	v_lshlrev_b32_e32 v128, 16, v129
	v_cvt_pk_bf16_f32 v108, v116, v117
	v_lshlrev_b32_e32 v146, 16, v108
	v_and_b32_e32 v147, 0xffff0000, v108
	v_pk_mul_f32 v[126:127], v[116:117], v[116:117]
	v_pk_add_f32 v[116:117], v[116:117], v[146:147] neg_lo:[0,1] neg_hi:[0,1]
	v_and_b32_e32 v129, 0xffff0000, v129
	v_lshlrev_b32_e32 v146, 16, v149
	v_and_b32_e32 v147, 0xffff0000, v149
	v_pk_add_f32 v[128:129], v[128:129], v[146:147]
	v_lshlrev_b32_e32 v146, 16, v163
	v_and_b32_e32 v147, 0xffff0000, v163
	v_pk_fma_f32 v[146:147], v[150:151], v[146:147], v[128:129]
	v_cvt_pk_bf16_f32 v110, v110, v111
	v_cvt_pk_bf16_f32 v109, v146, v147
	v_lshlrev_b32_e32 v148, 16, v109
	v_and_b32_e32 v149, 0xffff0000, v109
	v_pk_mul_f32 v[128:129], v[146:147], v[146:147]
	v_pk_add_f32 v[146:147], v[146:147], v[148:149] neg_lo:[0,1] neg_hi:[0,1]
	v_cvt_pk_bf16_f32 v111, v112, v113
	v_cvt_pk_bf16_f32 v112, v116, v117
	v_lshl_add_u64 v[116:117], s[58:59], 0, v[120:121]
	v_or_b32_e32 v120, 0x100, v120
	v_cvt_pk_bf16_f32 v113, v146, v147
	global_store_dwordx4 v[116:117], v[106:109], off
	global_store_dwordx4 v[114:115], v[110:113], off
	v_lshl_add_u64 v[146:147], s[6:7], 0, v[120:121]
	v_lshl_add_u64 v[106:107], s[10:11], 0, v[120:121]
	global_load_dwordx4 v[106:109], v[106:107], off
	v_lshl_add_u64 v[114:115], s[14:15], 0, v[120:121]
	global_load_dwordx4 v[110:113], v[146:147], off
	v_rcp_f32_e32 v150, v102
	global_load_dwordx4 v[114:117], v[114:115], off
	v_mul_f32_e32 v102, v103, v152
	v_mul_f32_e32 v102, 0xbfb8aa3b, v102
	v_exp_f32_e32 v102, v102
	s_nop 0
	v_add_f32_e32 v102, 1.0, v102
	v_rcp_f32_e32 v151, v102
	v_mul_f32_e32 v102, v104, v152
	v_rcp_f32_e32 v104, v98
	v_mul_f32_e32 v98, v99, v152
	v_mul_f32_e32 v102, 0xbfb8aa3b, v102
	v_mul_f32_e32 v98, 0xbfb8aa3b, v98
	v_exp_f32_e32 v102, v102
	v_exp_f32_e32 v98, v98
	v_add_f32_e32 v102, 1.0, v102
	v_add_f32_e32 v98, 1.0, v98
	v_rcp_f32_e32 v148, v102
	v_mul_f32_e32 v102, v105, v152
	v_rcp_f32_e32 v105, v98
	v_mul_f32_e32 v98, v100, v152
	v_mul_f32_e32 v102, 0xbfb8aa3b, v102
	v_mul_f32_e32 v98, 0xbfb8aa3b, v98
	v_exp_f32_e32 v102, v102
	v_exp_f32_e32 v98, v98
	v_add_f32_e32 v102, 1.0, v102
	v_add_f32_e32 v98, 1.0, v98
	v_rcp_f32_e32 v149, v102
	v_rcp_f32_e32 v102, v98
	v_mul_f32_e32 v98, v101, v152
	v_mul_f32_e32 v98, 0xbfb8aa3b, v98
	v_exp_f32_e32 v98, v98
	s_waitcnt vmcnt(2)
; __device__ __forceinline__ unsigned pk2(float lo, float hi) { f32x2_t v = {lo, hi}; bf16x2_t b = __builtin_convertvector(v, bf16x2_t); return __builtin_bit_cast(unsigned, b); }
; __device__ __forceinline__ float bflo(unsigned u) { return __uint_as_float(u << 16); }
; __device__ __forceinline__ float bfhi(unsigned u) { return __uint_as_float(u & 0xffff0000u); }
; __device__ __forceinline__ float row_ssq(const float* part, int pitch, int n4, int row, int fq) {
;     f32x4 v = (f32x4){0.f, 0.f, 0.f, 0.f};
;     if (fq < n4) v = *(const f32x4*)(part + (size_t)row * pitch + 4 * fq);
;     float s = (v[0] + v[1]) + (v[2] + v[3]);
;     s += __shfl_xor(s, 16); s += __shfl_xor(s, 32);
;     return s;
;     __device__ __forceinline__ void operator()(const f32x4 (&acc)[2][2][4][2], const Unit& u, int wr, int wc, int fr, int fq) const {
;     ...
;                     float lo[8];
; #pragma unroll
;                     for (int e = 0; e < 8; ++e) { hv[e] += av[e]; sq += hv[e] * hv[e]; }
;                     u32x4 wh; wh.x = pk2(hv[0], hv[1]); wh.y = pk2(hv[2], hv[3]); wh.z = pk2(hv[4], hv[5]); wh.w = pk2(hv[6], hv[7]);
;                     lo[0] = hv[0] - bflo(wh.x); lo[1] = hv[1] - bfhi(wh.x); lo[2] = hv[2] - bflo(wh.y); lo[3] = hv[3] - bfhi(wh.y);
;                     lo[4] = hv[4] - bflo(wh.z); lo[5] = hv[5] - bfhi(wh.z); lo[6] = hv[6] - bflo(wh.w); lo[7] = hv[7] - bfhi(wh.w);
;                     u32x4 wl; wl.x = pk2(lo[0], lo[1]); wl.y = pk2(lo[2], lo[3]); wl.z = pk2(lo[4], lo[5]); wl.w = pk2(lo[6], lo[7]);
;                     *(u32x4*)(HO + off) = wh; *(u32x4*)(LO + off) = wl;
;                 }
;                 sq += __shfl_xor(sq, 16); sq += __shfl_xor(sq, 32);
;                 if (fq == 0) ssq_out[(size_t)row * 16 + 4 * u.pn + wc] = sq;
	v_and_b32_e32 v99, 0xffff0000, v106
	v_add_f32_e32 v98, 1.0, v98
	v_rcp_f32_e32 v103, v98
	v_lshlrev_b32_e32 v98, 16, v106
	s_waitcnt vmcnt(1)
	v_lshlrev_b32_e32 v100, 16, v110
	v_and_b32_e32 v101, 0xffff0000, v110
	v_pk_add_f32 v[98:99], v[98:99], v[100:101]
	s_waitcnt vmcnt(0)
	v_lshlrev_b32_e32 v100, 16, v114
	v_and_b32_e32 v101, 0xffff0000, v114
	v_pk_fma_f32 v[100:101], v[150:151], v[100:101], v[98:99]
	v_lshlrev_b32_e32 v106, 16, v111
	v_cvt_pk_bf16_f32 v98, v100, v101
	v_lshlrev_b32_e32 v150, 16, v98
	v_and_b32_e32 v151, 0xffff0000, v98
	v_pk_mul_f32 v[152:153], v[100:101], v[100:101]
	v_pk_add_f32 v[150:151], v[100:101], v[150:151] neg_lo:[0,1] neg_hi:[0,1]
	v_lshlrev_b32_e32 v100, 16, v107
	v_and_b32_e32 v101, 0xffff0000, v107
	v_and_b32_e32 v107, 0xffff0000, v111
	v_pk_add_f32 v[100:101], v[100:101], v[106:107]
	v_lshlrev_b32_e32 v106, 16, v115
	v_and_b32_e32 v107, 0xffff0000, v115
	v_pk_fma_f32 v[100:101], v[148:149], v[106:107], v[100:101]
	v_lshlrev_b32_e32 v114, 16, v112
	v_cvt_pk_bf16_f32 v99, v100, v101
	v_lshlrev_b32_e32 v110, 16, v99
	v_and_b32_e32 v111, 0xffff0000, v99
	v_pk_mul_f32 v[106:107], v[100:101], v[100:101]
	v_pk_add_f32 v[110:111], v[100:101], v[110:111] neg_lo:[0,1] neg_hi:[0,1]
	v_lshlrev_b32_e32 v100, 16, v108
	v_and_b32_e32 v101, 0xffff0000, v108
	v_and_b32_e32 v115, 0xffff0000, v112
	v_pk_add_f32 v[100:101], v[100:101], v[114:115]
	v_lshlrev_b32_e32 v114, 16, v116
	v_and_b32_e32 v115, 0xffff0000, v116
	v_pk_fma_f32 v[104:105], v[104:105], v[114:115], v[100:101]
	v_add_f32_e32 v101, v122, v123
	v_add_f32_e32 v101, v124, v101
	v_add_f32_e32 v101, v125, v101
	v_add_f32_e32 v101, v126, v101
	v_add_f32_e32 v101, v127, v101
	v_add_f32_e32 v101, v128, v101
	v_add_f32_e32 v101, v129, v101
	v_add_f32_e32 v101, v152, v101
	v_add_f32_e32 v101, v153, v101
	v_lshlrev_b32_e32 v108, 16, v109
	v_and_b32_e32 v109, 0xffff0000, v109
	v_lshlrev_b32_e32 v112, 16, v113
	v_and_b32_e32 v113, 0xffff0000, v113
	v_add_f32_e32 v101, v106, v101
	v_pk_mul_f32 v[114:115], v[104:105], v[104:105]
	v_pk_add_f32 v[108:109], v[108:109], v[112:113]
	v_lshlrev_b32_e32 v112, 16, v117
	v_and_b32_e32 v113, 0xffff0000, v117
	v_add_f32_e32 v101, v107, v101
	v_pk_fma_f32 v[102:103], v[102:103], v[112:113], v[108:109]
	v_add_f32_e32 v101, v114, v101
	v_pk_mul_f32 v[108:109], v[102:103], v[102:103]
	v_add_f32_e32 v101, v115, v101
	v_add_f32_e32 v101, v108, v101
	v_cvt_pk_bf16_f32 v100, v104, v105
	v_add_f32_e32 v108, v109, v101
	v_cvt_pk_bf16_f32 v101, v102, v103
	v_lshlrev_b32_e32 v148, 16, v100
	v_and_b32_e32 v149, 0xffff0000, v100
	v_lshlrev_b32_e32 v106, 16, v101
	v_and_b32_e32 v107, 0xffff0000, v101
	v_pk_add_f32 v[104:105], v[104:105], v[148:149] neg_lo:[0,1] neg_hi:[0,1]
	v_pk_add_f32 v[106:107], v[102:103], v[106:107] neg_lo:[0,1] neg_hi:[0,1]
	v_cvt_pk_bf16_f32 v104, v104, v105
	v_cvt_pk_bf16_f32 v105, v106, v107
	v_lshl_add_u64 v[106:107], s[58:59], 0, v[120:121]
	v_cvt_pk_bf16_f32 v102, v150, v151
	v_cvt_pk_bf16_f32 v103, v110, v111
	global_store_dwordx4 v[106:107], v[98:101], off
	global_store_dwordx4 v[146:147], v[102:105], off
	v_mov_b32_e32 v98, v108
	s_nop 1
	v_permlane16_swap_b32_e32 v108, v98
	s_waitcnt lgkmcnt(0)
	v_add_f32_e32 v98, v108, v98
	ds_bpermute_b32 v99, v145, v98
	s_and_saveexec_b64 s[12:13], s[0:1]
	s_cbranch_execz .LBB0_1342
	v_readlane_b32 s44, v250, 8
	v_readlane_b32 s46, v250, 10
	v_readlane_b32 s47, v250, 11
	s_waitcnt lgkmcnt(0)
	v_add_f32_e32 v100, v98, v99
	s_lshl_b32 s40, s25, 2
	v_lshl_add_u64 v[98:99], s[46:47], 0, v[118:119]
	v_lshl_add_u64 v[98:99], s[54:55], 2, v[98:99]
	v_lshl_add_u64 v[98:99], v[98:99], 0, s[40:41]
	v_readlane_b32 s45, v250, 9
	global_store_dword v[98:99], v100, off
.LBB0_1342:
	s_or_b64 exec, exec, s[12:13]
	v_or_b32_e32 v104, 32, v144
	v_ashrrev_i32_e32 v105, 31, v104
	v_lshlrev_b64 v[102:103], 6, v[104:105]
	s_waitcnt lgkmcnt(0)
	v_lshl_add_u64 v[98:99], v[136:137], 0, v[102:103]
	global_load_dwordx4 v[98:101], v[98:99], off
	v_readlane_b32 s10, v253, 35
	v_readlane_b32 s11, v253, 36
	v_readlane_b32 s6, v250, 49
	v_readlane_b32 s7, v250, 50
	s_waitcnt vmcnt(0)
	v_mov_b32_e32 v106, v99
	v_mov_b32_e32 v107, v100
	v_mov_b32_e32 v99, v101
	v_pk_add_f32 v[98:99], v[106:107], v[98:99]
	s_nop 0
	v_add_f32_e32 v98, v98, v99
	v_mov_b32_e32 v99, v98
	s_nop 1
	v_permlane16_swap_b32_e32 v98, v99
	s_waitcnt lgkmcnt(0)
	v_add_f32_e32 v98, v98, v99
	v_mov_b32_e32 v99, v98
	s_nop 1
	v_permlane32_swap_b32_e32 v98, v99
	s_waitcnt lgkmcnt(0)
	v_add_f32_e32 v98, v98, v99
	v_fmamk_f32 v98, v98, 0x3a800000, v239
	v_cmp_gt_f32_e32 vcc, s16, v98
	v_mul_f32_e32 v99, 0x4b800000, v98
	s_nop 0
	v_cndmask_b32_e32 v98, v98, v99, vcc
	v_rsq_f32_e32 v98, v98
	s_nop 0
	v_mul_f32_e32 v99, 0x45800000, v98
	v_cndmask_b32_e32 v120, v98, v99, vcc
	v_lshlrev_b64 v[98:99], 10, v[104:105]
	v_lshl_add_u64 v[98:99], v[98:99], 0, v[142:143]
	v_lshlrev_b64 v[104:105], 1, v[98:99]
	v_lshl_add_u64 v[98:99], s[10:11], 0, v[104:105]
	v_lshl_add_u64 v[100:101], s[14:15], 0, v[104:105]
	global_load_dwordx4 v[110:113], v[98:99], off
	global_load_dwordx4 v[122:125], v[100:101], off
	v_lshl_add_u64 v[98:99], s[6:7], 0, v[104:105]
	global_load_dwordx4 v[114:117], v[98:99], off
	v_mul_f32_e32 v90, v90, v120
	v_mul_f32_e32 v90, 0xbfb8aa3b, v90
	v_exp_f32_e32 v90, v90
	v_mul_f32_e32 v94, v94, v120
	v_mul_f32_e32 v95, v95, v120
	v_mul_f32_e32 v94, 0xbfb8aa3b, v94
	v_add_f32_e32 v90, 1.0, v90
	v_rcp_f32_e32 v100, v90
	v_mul_f32_e32 v90, v91, v120
	v_mul_f32_e32 v90, 0xbfb8aa3b, v90
	v_exp_f32_e32 v90, v90
	v_mul_f32_e32 v95, 0xbfb8aa3b, v95
	v_exp_f32_e32 v94, v94
	v_exp_f32_e32 v95, v95
	v_add_f32_e32 v90, 1.0, v90
	v_rcp_f32_e32 v101, v90
	v_mul_f32_e32 v90, v92, v120
	v_mul_f32_e32 v90, 0xbfb8aa3b, v90
	v_exp_f32_e32 v90, v90
	v_mul_f32_e32 v96, v96, v120
	v_mul_f32_e32 v97, v97, v120
	v_add_f32_e32 v94, 1.0, v94
	v_add_f32_e32 v90, 1.0, v90
	v_rcp_f32_e32 v118, v90
	v_mul_f32_e32 v90, v93, v120
	v_mul_f32_e32 v90, 0xbfb8aa3b, v90
	v_exp_f32_e32 v90, v90
	v_add_f32_e32 v95, 1.0, v95
	v_mul_f32_e32 v96, 0xbfb8aa3b, v96
	v_mul_f32_e32 v97, 0xbfb8aa3b, v97
	v_rcp_f32_e32 v94, v94
	v_rcp_f32_e32 v95, v95
	v_exp_f32_e32 v96, v96
	v_exp_f32_e32 v97, v97
	v_add_f32_e32 v90, 1.0, v90
	v_rcp_f32_e32 v119, v90
	v_add_f32_e32 v96, 1.0, v96
	v_add_f32_e32 v97, 1.0, v97
	v_rcp_f32_e32 v96, v96
	v_rcp_f32_e32 v97, v97
	v_mul_f32_e32 v86, v86, v120
	v_mul_f32_e32 v86, 0xbfb8aa3b, v86
	v_exp_f32_e32 v86, v86
	v_mul_f32_e32 v82, v82, v120
	v_mul_f32_e32 v82, 0xbfb8aa3b, v82
	v_exp_f32_e32 v82, v82
	v_add_f32_e32 v86, 1.0, v86
	v_add_f32_e32 v82, 1.0, v82
	s_waitcnt vmcnt(2)
; __device__ __forceinline__ unsigned pk2(float lo, float hi) { f32x2_t v = {lo, hi}; bf16x2_t b = __builtin_convertvector(v, bf16x2_t); return __builtin_bit_cast(unsigned, b); }
; __device__ __forceinline__ float bflo(unsigned u) { return __uint_as_float(u << 16); }
;     __device__ __forceinline__ void operator()(const f32x4 (&acc)[2][2][4][2], const Unit& u, int wr, int wc, int fr, int fq) const {
;     ...
;                     const u32x4 hh = *(const u32x4*)(HI + off), ll = *(const u32x4*)(LO + off);
;                     float hv[8] = {bflo(hh.x) + bflo(ll.x), bfhi(hh.x) + bfhi(ll.x), bflo(hh.y) + bflo(ll.y), bfhi(hh.y) + bfhi(ll.y),
;                                    bflo(hh.z) + bflo(ll.z), bfhi(hh.z) + bfhi(ll.z), bflo(hh.w) + bflo(ll.w), bfhi(hh.w) + bfhi(ll.w)};
;                     float av[8] = {acc[ai][bj][m][0][0], acc[ai][bj][m][0][1], acc[ai][bj][m][0][2], acc[ai][bj][m][0][3], acc[ai][bj][m][1][0], acc[ai][bj][m][1][1], acc[ai][bj][m][1][2], acc[ai][bj][m][1][3]};
;                     if (GATED) { const u32x4 pp = *(const u32x4*)(PP + off);
;                         const float pv[8] = {bflo(pp.x), bfhi(pp.x), bflo(pp.y), bfhi(pp.y), bflo(pp.z), bfhi(pp.z), bflo(pp.w), bfhi(pp.w)};
; #pragma unroll
;                         for (int e = 0; e < 8; ++e) av[e] = fast_sigmoid(av[e] * rs) * pv[e]; }
;                     else {
; #pragma unroll
;                         for (int e = 0; e < 8; ++e) av[e] *= alpha; }
;                     float lo[8];
; #pragma unroll
;                     for (int e = 0; e < 8; ++e) { hv[e] += av[e]; sq += hv[e] * hv[e]; }
;                     u32x4 wh; wh.x = pk2(hv[0], hv[1]); wh.y = pk2(hv[2], hv[3]); wh.z = pk2(hv[4], hv[5]); wh.w = pk2(hv[6], hv[7]);
;                     lo[0] = hv[0] - bflo(wh.x); lo[1] = hv[1] - bfhi(wh.x); lo[2] = hv[2] - bflo(wh.y); lo[3] = hv[3] - bfhi(wh.y);
;                     lo[4] = hv[4] - bflo(wh.z); lo[5] = hv[5] - bfhi(wh.z); lo[6] = hv[6] - bflo(wh.w); lo[7] = hv[7] - bfhi(wh.w);
;                     u32x4 wl; wl.x = pk2(lo[0], lo[1]); wl.y = pk2(lo[2], lo[3]); wl.z = pk2(lo[4], lo[5]); wl.w = pk2(lo[6], lo[7]);
;                     *(u32x4*)(HO + off) = wh; *(u32x4*)(LO + off) = wl;
;                 }
;                 sq += __shfl_xor(sq, 16); sq += __shfl_xor(sq, 32);
;                 if (fq == 0) ssq_out[(size_t)row * 16 + 4 * u.pn + wc] = sq;
	v_lshlrev_b32_e32 v90, 16, v110
	v_and_b32_e32 v91, 0xffff0000, v110
	s_waitcnt vmcnt(0)
	v_lshlrev_b32_e32 v92, 16, v114
	v_and_b32_e32 v93, 0xffff0000, v114
	v_pk_add_f32 v[90:91], v[90:91], v[92:93]
	v_lshlrev_b32_e32 v92, 16, v122
	v_and_b32_e32 v93, 0xffff0000, v122
	v_pk_fma_f32 v[92:93], v[94:95], v[92:93], v[90:91]
	v_lshlrev_b32_e32 v108, 16, v115
	v_cvt_pk_bf16_f32 v90, v92, v93
	v_lshlrev_b32_e32 v94, 16, v90
	v_and_b32_e32 v95, 0xffff0000, v90
	v_pk_mul_f32 v[106:107], v[92:93], v[92:93]
	v_pk_add_f32 v[94:95], v[92:93], v[94:95] neg_lo:[0,1] neg_hi:[0,1]
	v_lshlrev_b32_e32 v92, 16, v111
	v_and_b32_e32 v93, 0xffff0000, v111
	v_and_b32_e32 v109, 0xffff0000, v115
	v_pk_add_f32 v[92:93], v[92:93], v[108:109]
	v_lshlrev_b32_e32 v108, 16, v123
	v_and_b32_e32 v109, 0xffff0000, v123
	v_pk_fma_f32 v[92:93], v[96:97], v[108:109], v[92:93]
	v_lshlrev_b32_e32 v110, 16, v116
	v_cvt_pk_bf16_f32 v91, v92, v93
	v_lshlrev_b32_e32 v96, 16, v91
	v_and_b32_e32 v97, 0xffff0000, v91
	v_pk_mul_f32 v[108:109], v[92:93], v[92:93]
	v_pk_add_f32 v[96:97], v[92:93], v[96:97] neg_lo:[0,1] neg_hi:[0,1]
	v_lshlrev_b32_e32 v92, 16, v112
	v_and_b32_e32 v93, 0xffff0000, v112
	v_and_b32_e32 v111, 0xffff0000, v116
	v_pk_add_f32 v[92:93], v[92:93], v[110:111]
	v_lshlrev_b32_e32 v110, 16, v124
	v_and_b32_e32 v111, 0xffff0000, v124
	v_pk_fma_f32 v[100:101], v[100:101], v[110:111], v[92:93]
	v_lshlrev_b32_e32 v112, 16, v113
	v_cvt_pk_bf16_f32 v92, v100, v101
	v_lshlrev_b32_e32 v114, 16, v92
	v_and_b32_e32 v115, 0xffff0000, v92
	v_pk_mul_f32 v[110:111], v[100:101], v[100:101]
	v_pk_add_f32 v[100:101], v[100:101], v[114:115] neg_lo:[0,1] neg_hi:[0,1]
	v_and_b32_e32 v113, 0xffff0000, v113
	v_lshlrev_b32_e32 v114, 16, v117
	v_and_b32_e32 v115, 0xffff0000, v117
	v_pk_add_f32 v[112:113], v[112:113], v[114:115]
	v_lshlrev_b32_e32 v114, 16, v125
	v_and_b32_e32 v115, 0xffff0000, v125
	v_pk_fma_f32 v[114:115], v[118:119], v[114:115], v[112:113]
	v_cvt_pk_bf16_f32 v94, v94, v95
	v_cvt_pk_bf16_f32 v93, v114, v115
	v_lshlrev_b32_e32 v116, 16, v93
	v_and_b32_e32 v117, 0xffff0000, v93
	v_pk_mul_f32 v[112:113], v[114:115], v[114:115]
	v_pk_add_f32 v[114:115], v[114:115], v[116:117] neg_lo:[0,1] neg_hi:[0,1]
	v_cvt_pk_bf16_f32 v95, v96, v97
	v_cvt_pk_bf16_f32 v96, v100, v101
	v_lshl_add_u64 v[100:101], s[58:59], 0, v[104:105]
	v_or_b32_e32 v104, 0x100, v104
	v_cvt_pk_bf16_f32 v97, v114, v115
	global_store_dwordx4 v[100:101], v[90:93], off
	global_store_dwordx4 v[98:99], v[94:97], off
	v_lshl_add_u64 v[114:115], s[6:7], 0, v[104:105]
	v_lshl_add_u64 v[90:91], s[10:11], 0, v[104:105]
	global_load_dwordx4 v[90:93], v[90:91], off
	v_lshl_add_u64 v[98:99], s[14:15], 0, v[104:105]
	global_load_dwordx4 v[94:97], v[114:115], off
	v_rcp_f32_e32 v118, v86
	global_load_dwordx4 v[98:101], v[98:99], off
	v_mul_f32_e32 v86, v87, v120
	v_mul_f32_e32 v86, 0xbfb8aa3b, v86
	v_exp_f32_e32 v86, v86
	s_nop 0
	v_add_f32_e32 v86, 1.0, v86
	v_rcp_f32_e32 v119, v86
	v_mul_f32_e32 v86, v88, v120
	v_rcp_f32_e32 v88, v82
	v_mul_f32_e32 v82, v83, v120
	v_mul_f32_e32 v86, 0xbfb8aa3b, v86
	v_mul_f32_e32 v82, 0xbfb8aa3b, v82
	v_exp_f32_e32 v86, v86
	v_exp_f32_e32 v82, v82
	v_add_f32_e32 v86, 1.0, v86
	v_add_f32_e32 v82, 1.0, v82
	v_rcp_f32_e32 v116, v86
	v_mul_f32_e32 v86, v89, v120
	v_rcp_f32_e32 v89, v82
	v_mul_f32_e32 v82, v84, v120
	v_mul_f32_e32 v86, 0xbfb8aa3b, v86
	v_mul_f32_e32 v82, 0xbfb8aa3b, v82
	v_exp_f32_e32 v86, v86
	v_exp_f32_e32 v82, v82
	v_add_f32_e32 v86, 1.0, v86
	v_add_f32_e32 v82, 1.0, v82
	v_rcp_f32_e32 v117, v86
	v_rcp_f32_e32 v86, v82
	v_mul_f32_e32 v82, v85, v120
	v_mul_f32_e32 v82, 0xbfb8aa3b, v82
	v_exp_f32_e32 v82, v82
	s_waitcnt vmcnt(2)
	v_and_b32_e32 v83, 0xffff0000, v90
	v_add_f32_e32 v82, 1.0, v82
	v_rcp_f32_e32 v87, v82
	v_lshlrev_b32_e32 v82, 16, v90
	s_waitcnt vmcnt(1)
	v_lshlrev_b32_e32 v84, 16, v94
	v_and_b32_e32 v85, 0xffff0000, v94
	v_pk_add_f32 v[82:83], v[82:83], v[84:85]
	s_waitcnt vmcnt(0)
	v_lshlrev_b32_e32 v84, 16, v98
	v_and_b32_e32 v85, 0xffff0000, v98
	v_pk_fma_f32 v[84:85], v[118:119], v[84:85], v[82:83]
	v_lshlrev_b32_e32 v90, 16, v95
	v_cvt_pk_bf16_f32 v82, v84, v85
	v_lshlrev_b32_e32 v118, 16, v82
	v_and_b32_e32 v119, 0xffff0000, v82
	v_pk_mul_f32 v[120:121], v[84:85], v[84:85]
	v_pk_add_f32 v[118:119], v[84:85], v[118:119] neg_lo:[0,1] neg_hi:[0,1]
	v_lshlrev_b32_e32 v84, 16, v91
	v_and_b32_e32 v85, 0xffff0000, v91
	v_and_b32_e32 v91, 0xffff0000, v95
	v_pk_add_f32 v[84:85], v[84:85], v[90:91]
	v_lshlrev_b32_e32 v90, 16, v99
	v_and_b32_e32 v91, 0xffff0000, v99
	v_pk_fma_f32 v[84:85], v[116:117], v[90:91], v[84:85]
	v_lshlrev_b32_e32 v98, 16, v96
	v_cvt_pk_bf16_f32 v83, v84, v85
	v_lshlrev_b32_e32 v94, 16, v83
	v_and_b32_e32 v95, 0xffff0000, v83
	v_pk_mul_f32 v[90:91], v[84:85], v[84:85]
	v_pk_add_f32 v[94:95], v[84:85], v[94:95] neg_lo:[0,1] neg_hi:[0,1]
	v_lshlrev_b32_e32 v84, 16, v92
	v_and_b32_e32 v85, 0xffff0000, v92
	v_and_b32_e32 v99, 0xffff0000, v96
	v_pk_add_f32 v[84:85], v[84:85], v[98:99]
	v_lshlrev_b32_e32 v98, 16, v100
	v_and_b32_e32 v99, 0xffff0000, v100
	v_pk_fma_f32 v[88:89], v[88:89], v[98:99], v[84:85]
	v_add_f32_e32 v85, v106, v107
	v_add_f32_e32 v85, v108, v85
	v_add_f32_e32 v85, v109, v85
	v_add_f32_e32 v85, v110, v85
	v_add_f32_e32 v85, v111, v85
	v_add_f32_e32 v85, v112, v85
	v_add_f32_e32 v85, v113, v85
	v_add_f32_e32 v85, v120, v85
	v_add_f32_e32 v85, v121, v85
	v_lshlrev_b32_e32 v92, 16, v93
	v_and_b32_e32 v93, 0xffff0000, v93
	v_lshlrev_b32_e32 v96, 16, v97
	v_and_b32_e32 v97, 0xffff0000, v97
	v_add_f32_e32 v85, v90, v85
	v_pk_mul_f32 v[98:99], v[88:89], v[88:89]
	v_pk_add_f32 v[92:93], v[92:93], v[96:97]
	v_lshlrev_b32_e32 v96, 16, v101
	v_and_b32_e32 v97, 0xffff0000, v101
	v_add_f32_e32 v85, v91, v85
	v_pk_fma_f32 v[86:87], v[86:87], v[96:97], v[92:93]
	v_add_f32_e32 v85, v98, v85
	v_pk_mul_f32 v[92:93], v[86:87], v[86:87]
	v_add_f32_e32 v85, v99, v85
	v_add_f32_e32 v85, v92, v85
	v_cvt_pk_bf16_f32 v84, v88, v89
	v_add_f32_e32 v92, v93, v85
	v_cvt_pk_bf16_f32 v85, v86, v87
	v_lshlrev_b32_e32 v116, 16, v84
	v_and_b32_e32 v117, 0xffff0000, v84
	v_lshlrev_b32_e32 v90, 16, v85
	v_and_b32_e32 v91, 0xffff0000, v85
	v_pk_add_f32 v[88:89], v[88:89], v[116:117] neg_lo:[0,1] neg_hi:[0,1]
	v_pk_add_f32 v[90:91], v[86:87], v[90:91] neg_lo:[0,1] neg_hi:[0,1]
	v_cvt_pk_bf16_f32 v88, v88, v89
	v_cvt_pk_bf16_f32 v89, v90, v91
	v_lshl_add_u64 v[90:91], s[58:59], 0, v[104:105]
	v_cvt_pk_bf16_f32 v86, v118, v119
	v_cvt_pk_bf16_f32 v87, v94, v95
	global_store_dwordx4 v[90:91], v[82:85], off
	global_store_dwordx4 v[114:115], v[86:89], off
	v_mov_b32_e32 v82, v92
	s_nop 1
	v_permlane16_swap_b32_e32 v92, v82
	s_waitcnt lgkmcnt(0)
	v_add_f32_e32 v82, v92, v82
	ds_bpermute_b32 v83, v145, v82
	s_and_saveexec_b64 s[12:13], s[0:1]
	s_cbranch_execz .LBB0_1344
; __device__ __forceinline__ float row_ssq(const float* part, int pitch, int n4, int row, int fq) {
;     f32x4 v = (f32x4){0.f, 0.f, 0.f, 0.f};
;     if (fq < n4) v = *(const f32x4*)(part + (size_t)row * pitch + 4 * fq);
;     float s = (v[0] + v[1]) + (v[2] + v[3]);
;     s += __shfl_xor(s, 16); s += __shfl_xor(s, 32);
;     return s;
;     __device__ __forceinline__ void operator()(const f32x4 (&acc)[2][2][4][2], const Unit& u, int wr, int wc, int fr, int fq) const {
;     ...
;                 float rs = 0.f; if (GATED) rs = rsqrtf(row_ssq(ssq_in, 16, 4, row, fq) * (1.f / 1024.f) + EPS);
;                 float sq = 0.f;
; #pragma unroll
;                 for (int bj = 0; bj < 2; ++bj) {
;                     const size_t off = (size_t)row * DM + col0 + bj * HALF;
;                     const u32x4 hh = *(const u32x4*)(HI + off), ll = *(const u32x4*)(LO + off);
;                     float hv[8] = {bflo(hh.x) + bflo(ll.x), bfhi(hh.x) + bfhi(ll.x), bflo(hh.y) + bflo(ll.y), bfhi(hh.y) + bfhi(ll.y),
;                                    bflo(hh.z) + bflo(ll.z), bfhi(hh.z) + bfhi(ll.z), bflo(hh.w) + bflo(ll.w), bfhi(hh.w) + bfhi(ll.w)};
;                     float av[8] = {acc[ai][bj][m][0][0], acc[ai][bj][m][0][1], acc[ai][bj][m][0][2], acc[ai][bj][m][0][3], acc[ai][bj][m][1][0], acc[ai][bj][m][1][1], acc[ai][bj][m][1][2], acc[ai][bj][m][1][3]};
;                     if (GATED) { const u32x4 pp = *(const u32x4*)(PP + off);
;                         const float pv[8] = {bflo(pp.x), bfhi(pp.x), bflo(pp.y), bfhi(pp.y), bflo(pp.z), bfhi(pp.z), bflo(pp.w), bfhi(pp.w)};
; #pragma unroll
;                         for (int e = 0; e < 8; ++e) av[e] = fast_sigmoid(av[e] * rs) * pv[e]; }
;                     else {
; #pragma unroll
;                         for (int e = 0; e < 8; ++e) av[e] *= alpha; }
;                     float lo[8];
; #pragma unroll
;                     for (int e = 0; e < 8; ++e) { hv[e] += av[e]; sq += hv[e] * hv[e]; }
;                     u32x4 wh; wh.x = pk2(hv[0], hv[1]); wh.y = pk2(hv[2], hv[3]); wh.z = pk2(hv[4], hv[5]); wh.w = pk2(hv[6], hv[7]);
;                     lo[0] = hv[0] - bflo(wh.x); lo[1] = hv[1] - bfhi(wh.x); lo[2] = hv[2] - bflo(wh.y); lo[3] = hv[3] - bfhi(wh.y);
;                     lo[4] = hv[4] - bflo(wh.z); lo[5] = hv[5] - bfhi(wh.z); lo[6] = hv[6] - bflo(wh.w); lo[7] = hv[7] - bfhi(wh.w);
	v_readlane_b32 s44, v250, 8
	v_readlane_b32 s46, v250, 10
	v_readlane_b32 s47, v250, 11
	s_waitcnt lgkmcnt(0)
	v_add_f32_e32 v84, v82, v83
	s_lshl_b32 s40, s25, 2
	v_lshl_add_u64 v[82:83], s[46:47], 0, v[102:103]
	v_lshl_add_u64 v[82:83], s[54:55], 2, v[82:83]
	v_lshl_add_u64 v[82:83], v[82:83], 0, s[40:41]
	v_readlane_b32 s45, v250, 9
	global_store_dword v[82:83], v84, off
.LBB0_1344:
	s_or_b64 exec, exec, s[12:13]
	v_or_b32_e32 v88, 48, v144
	v_ashrrev_i32_e32 v89, 31, v88
	v_lshlrev_b64 v[86:87], 6, v[88:89]
	s_waitcnt lgkmcnt(0)
	v_lshl_add_u64 v[82:83], v[136:137], 0, v[86:87]
	global_load_dwordx4 v[82:85], v[82:83], off
	v_readlane_b32 s10, v253, 35
	v_readlane_b32 s11, v253, 36
	v_readlane_b32 s6, v250, 49
	v_readlane_b32 s7, v250, 50
	s_waitcnt vmcnt(0)
	v_mov_b32_e32 v90, v83
	v_mov_b32_e32 v91, v84
	v_mov_b32_e32 v83, v85
	v_pk_add_f32 v[82:83], v[90:91], v[82:83]
	s_nop 0
	v_add_f32_e32 v82, v82, v83
	v_mov_b32_e32 v83, v82
	s_nop 1
	v_permlane16_swap_b32_e32 v82, v83
	s_waitcnt lgkmcnt(0)
	v_add_f32_e32 v82, v82, v83
	v_mov_b32_e32 v83, v82
	s_nop 1
	v_permlane32_swap_b32_e32 v82, v83
	s_waitcnt lgkmcnt(0)
	v_add_f32_e32 v82, v82, v83
	v_fmamk_f32 v82, v82, 0x3a800000, v239
	v_cmp_gt_f32_e32 vcc, s16, v82
	v_mul_f32_e32 v83, 0x4b800000, v82
	s_nop 0
	v_cndmask_b32_e32 v82, v82, v83, vcc
	v_rsq_f32_e32 v82, v82
	s_nop 0
	v_mul_f32_e32 v83, 0x45800000, v82
	v_cndmask_b32_e32 v104, v82, v83, vcc
	v_lshlrev_b64 v[82:83], 10, v[88:89]
	v_lshl_add_u64 v[82:83], v[82:83], 0, v[142:143]
	v_lshlrev_b64 v[88:89], 1, v[82:83]
	v_lshl_add_u64 v[82:83], s[10:11], 0, v[88:89]
	v_lshl_add_u64 v[84:85], s[14:15], 0, v[88:89]
	global_load_dwordx4 v[94:97], v[82:83], off
	global_load_dwordx4 v[106:109], v[84:85], off
	v_lshl_add_u64 v[82:83], s[6:7], 0, v[88:89]
	global_load_dwordx4 v[98:101], v[82:83], off
	v_mul_f32_e32 v74, v74, v104
	v_mul_f32_e32 v74, 0xbfb8aa3b, v74
	v_exp_f32_e32 v74, v74
	v_mul_f32_e32 v78, v78, v104
	v_mul_f32_e32 v79, v79, v104
	v_mul_f32_e32 v78, 0xbfb8aa3b, v78
	v_add_f32_e32 v74, 1.0, v74
	v_rcp_f32_e32 v84, v74
	v_mul_f32_e32 v74, v75, v104
	v_mul_f32_e32 v74, 0xbfb8aa3b, v74
	v_exp_f32_e32 v74, v74
	v_mul_f32_e32 v79, 0xbfb8aa3b, v79
	v_exp_f32_e32 v78, v78
	v_exp_f32_e32 v79, v79
	v_add_f32_e32 v74, 1.0, v74
	v_rcp_f32_e32 v85, v74
	v_mul_f32_e32 v74, v76, v104
	v_mul_f32_e32 v74, 0xbfb8aa3b, v74
	v_exp_f32_e32 v74, v74
	v_mul_f32_e32 v80, v80, v104
	v_mul_f32_e32 v81, v81, v104
	v_add_f32_e32 v78, 1.0, v78
	v_add_f32_e32 v74, 1.0, v74
	v_rcp_f32_e32 v102, v74
	v_mul_f32_e32 v74, v77, v104
	v_mul_f32_e32 v74, 0xbfb8aa3b, v74
	v_exp_f32_e32 v74, v74
	v_add_f32_e32 v79, 1.0, v79
	v_mul_f32_e32 v80, 0xbfb8aa3b, v80
	v_mul_f32_e32 v81, 0xbfb8aa3b, v81
	v_rcp_f32_e32 v78, v78
	v_rcp_f32_e32 v79, v79
	v_exp_f32_e32 v80, v80
	v_exp_f32_e32 v81, v81
	v_add_f32_e32 v74, 1.0, v74
	v_rcp_f32_e32 v103, v74
	v_add_f32_e32 v80, 1.0, v80
	v_add_f32_e32 v81, 1.0, v81
	v_rcp_f32_e32 v80, v80
	v_rcp_f32_e32 v81, v81
	v_mul_f32_e32 v70, v70, v104
	v_mul_f32_e32 v70, 0xbfb8aa3b, v70
	v_exp_f32_e32 v70, v70
	v_mul_f32_e32 v66, v66, v104
	v_mul_f32_e32 v66, 0xbfb8aa3b, v66
	v_exp_f32_e32 v66, v66
	v_add_f32_e32 v70, 1.0, v70
	v_add_f32_e32 v66, 1.0, v66
	s_waitcnt vmcnt(2)
	v_lshlrev_b32_e32 v74, 16, v94
	v_and_b32_e32 v75, 0xffff0000, v94
	s_waitcnt vmcnt(0)
	v_lshlrev_b32_e32 v76, 16, v98
	v_and_b32_e32 v77, 0xffff0000, v98
	v_pk_add_f32 v[74:75], v[74:75], v[76:77]
	v_lshlrev_b32_e32 v76, 16, v106
	v_and_b32_e32 v77, 0xffff0000, v106
	v_pk_fma_f32 v[76:77], v[78:79], v[76:77], v[74:75]
	v_lshlrev_b32_e32 v92, 16, v99
	v_cvt_pk_bf16_f32 v74, v76, v77
	v_lshlrev_b32_e32 v78, 16, v74
	v_and_b32_e32 v79, 0xffff0000, v74
	v_pk_mul_f32 v[90:91], v[76:77], v[76:77]
	v_pk_add_f32 v[78:79], v[76:77], v[78:79] neg_lo:[0,1] neg_hi:[0,1]
	v_lshlrev_b32_e32 v76, 16, v95
	v_and_b32_e32 v77, 0xffff0000, v95
	v_and_b32_e32 v93, 0xffff0000, v99
	v_pk_add_f32 v[76:77], v[76:77], v[92:93]
	v_lshlrev_b32_e32 v92, 16, v107
	v_and_b32_e32 v93, 0xffff0000, v107
	v_pk_fma_f32 v[76:77], v[80:81], v[92:93], v[76:77]
	v_lshlrev_b32_e32 v94, 16, v100
	v_cvt_pk_bf16_f32 v75, v76, v77
	v_lshlrev_b32_e32 v80, 16, v75
	v_and_b32_e32 v81, 0xffff0000, v75
	v_pk_mul_f32 v[92:93], v[76:77], v[76:77]
	v_pk_add_f32 v[80:81], v[76:77], v[80:81] neg_lo:[0,1] neg_hi:[0,1]
	v_lshlrev_b32_e32 v76, 16, v96
	v_and_b32_e32 v77, 0xffff0000, v96
	v_and_b32_e32 v95, 0xffff0000, v100
	v_pk_add_f32 v[76:77], v[76:77], v[94:95]
	v_lshlrev_b32_e32 v94, 16, v108
	v_and_b32_e32 v95, 0xffff0000, v108
	v_pk_fma_f32 v[84:85], v[84:85], v[94:95], v[76:77]
	v_lshlrev_b32_e32 v96, 16, v97
	v_cvt_pk_bf16_f32 v76, v84, v85
	v_lshlrev_b32_e32 v98, 16, v76
	v_and_b32_e32 v99, 0xffff0000, v76
	v_pk_mul_f32 v[94:95], v[84:85], v[84:85]
	v_pk_add_f32 v[84:85], v[84:85], v[98:99] neg_lo:[0,1] neg_hi:[0,1]
	v_and_b32_e32 v97, 0xffff0000, v97
	v_lshlrev_b32_e32 v98, 16, v101
	v_and_b32_e32 v99, 0xffff0000, v101
	v_pk_add_f32 v[96:97], v[96:97], v[98:99]
	v_lshlrev_b32_e32 v98, 16, v109
	v_and_b32_e32 v99, 0xffff0000, v109
	v_pk_fma_f32 v[98:99], v[102:103], v[98:99], v[96:97]
	v_cvt_pk_bf16_f32 v78, v78, v79
	v_cvt_pk_bf16_f32 v77, v98, v99
	v_lshlrev_b32_e32 v100, 16, v77
	v_and_b32_e32 v101, 0xffff0000, v77
	v_pk_mul_f32 v[96:97], v[98:99], v[98:99]
	v_pk_add_f32 v[98:99], v[98:99], v[100:101] neg_lo:[0,1] neg_hi:[0,1]
	v_cvt_pk_bf16_f32 v79, v80, v81
	v_cvt_pk_bf16_f32 v80, v84, v85
	v_lshl_add_u64 v[84:85], s[58:59], 0, v[88:89]
	v_or_b32_e32 v88, 0x100, v88
	v_cvt_pk_bf16_f32 v81, v98, v99
	global_store_dwordx4 v[84:85], v[74:77], off
	global_store_dwordx4 v[82:83], v[78:81], off
	v_lshl_add_u64 v[98:99], s[6:7], 0, v[88:89]
	v_lshl_add_u64 v[74:75], s[10:11], 0, v[88:89]
	global_load_dwordx4 v[74:77], v[74:75], off
	v_lshl_add_u64 v[82:83], s[14:15], 0, v[88:89]
	global_load_dwordx4 v[78:81], v[98:99], off
	v_rcp_f32_e32 v102, v70
	global_load_dwordx4 v[82:85], v[82:83], off
	v_mul_f32_e32 v70, v71, v104
	v_mul_f32_e32 v70, 0xbfb8aa3b, v70
	v_exp_f32_e32 v70, v70
	s_nop 0
	v_add_f32_e32 v70, 1.0, v70
	v_rcp_f32_e32 v103, v70
	v_mul_f32_e32 v70, v72, v104
	v_rcp_f32_e32 v72, v66
	v_mul_f32_e32 v66, v67, v104
	v_mul_f32_e32 v70, 0xbfb8aa3b, v70
	v_mul_f32_e32 v66, 0xbfb8aa3b, v66
	v_exp_f32_e32 v70, v70
	v_exp_f32_e32 v66, v66
	v_add_f32_e32 v70, 1.0, v70
	v_add_f32_e32 v66, 1.0, v66
	v_rcp_f32_e32 v100, v70
	v_mul_f32_e32 v70, v73, v104
	v_rcp_f32_e32 v73, v66
	v_mul_f32_e32 v66, v68, v104
	v_mul_f32_e32 v70, 0xbfb8aa3b, v70
	v_mul_f32_e32 v66, 0xbfb8aa3b, v66
	v_exp_f32_e32 v70, v70
	v_exp_f32_e32 v66, v66
	v_add_f32_e32 v70, 1.0, v70
	v_add_f32_e32 v66, 1.0, v66
	v_rcp_f32_e32 v101, v70
	v_rcp_f32_e32 v70, v66
	v_mul_f32_e32 v66, v69, v104
	v_mul_f32_e32 v66, 0xbfb8aa3b, v66
	v_exp_f32_e32 v66, v66
	s_waitcnt vmcnt(2)
; __device__ __forceinline__ float row_ssq(const float* part, int pitch, int n4, int row, int fq) {
;     f32x4 v = (f32x4){0.f, 0.f, 0.f, 0.f};
;     if (fq < n4) v = *(const f32x4*)(part + (size_t)row * pitch + 4 * fq);
;     float s = (v[0] + v[1]) + (v[2] + v[3]);
;     __device__ __forceinline__ void operator()(const f32x4 (&acc)[2][2][4][2], const Unit& u, int wr, int wc, int fr, int fq) const {
;     ...
;                     const u32x4 hh = *(const u32x4*)(HI + off), ll = *(const u32x4*)(LO + off);
;                     float hv[8] = {bflo(hh.x) + bflo(ll.x), bfhi(hh.x) + bfhi(ll.x), bflo(hh.y) + bflo(ll.y), bfhi(hh.y) + bfhi(ll.y),
;                                    bflo(hh.z) + bflo(ll.z), bfhi(hh.z) + bfhi(ll.z), bflo(hh.w) + bflo(ll.w), bfhi(hh.w) + bfhi(ll.w)};
;                     float av[8] = {acc[ai][bj][m][0][0], acc[ai][bj][m][0][1], acc[ai][bj][m][0][2], acc[ai][bj][m][0][3], acc[ai][bj][m][1][0], acc[ai][bj][m][1][1], acc[ai][bj][m][1][2], acc[ai][bj][m][1][3]};
;                     if (GATED) { const u32x4 pp = *(const u32x4*)(PP + off);
;                         const float pv[8] = {bflo(pp.x), bfhi(pp.x), bflo(pp.y), bfhi(pp.y), bflo(pp.z), bfhi(pp.z), bflo(pp.w), bfhi(pp.w)};
; #pragma unroll
;                         for (int e = 0; e < 8; ++e) av[e] = fast_sigmoid(av[e] * rs) * pv[e]; }
;                     else {
; #pragma unroll
;                         for (int e = 0; e < 8; ++e) av[e] *= alpha; }
;                     float lo[8];
; #pragma unroll
;                     for (int e = 0; e < 8; ++e) { hv[e] += av[e]; sq += hv[e] * hv[e]; }
;                     u32x4 wh; wh.x = pk2(hv[0], hv[1]); wh.y = pk2(hv[2], hv[3]); wh.z = pk2(hv[4], hv[5]); wh.w = pk2(hv[6], hv[7]);
;                     lo[0] = hv[0] - bflo(wh.x); lo[1] = hv[1] - bfhi(wh.x); lo[2] = hv[2] - bflo(wh.y); lo[3] = hv[3] - bfhi(wh.y);
;                     lo[4] = hv[4] - bflo(wh.z); lo[5] = hv[5] - bfhi(wh.z); lo[6] = hv[6] - bflo(wh.w); lo[7] = hv[7] - bfhi(wh.w);
;                     u32x4 wl; wl.x = pk2(lo[0], lo[1]); wl.y = pk2(lo[2], lo[3]); wl.z = pk2(lo[4], lo[5]); wl.w = pk2(lo[6], lo[7]);
;                     *(u32x4*)(HO + off) = wh; *(u32x4*)(LO + off) = wl;
;                 }
;                 sq += __shfl_xor(sq, 16); sq += __shfl_xor(sq, 32);
;                 if (fq == 0) ssq_out[(size_t)row * 16 + 4 * u.pn + wc] = sq;
	v_and_b32_e32 v67, 0xffff0000, v74
	v_add_f32_e32 v66, 1.0, v66
	v_rcp_f32_e32 v71, v66
	v_lshlrev_b32_e32 v66, 16, v74
	s_waitcnt vmcnt(1)
	v_lshlrev_b32_e32 v68, 16, v78
	v_and_b32_e32 v69, 0xffff0000, v78
	v_pk_add_f32 v[66:67], v[66:67], v[68:69]
	s_waitcnt vmcnt(0)
	v_lshlrev_b32_e32 v68, 16, v82
	v_and_b32_e32 v69, 0xffff0000, v82
	v_pk_fma_f32 v[68:69], v[102:103], v[68:69], v[66:67]
	v_lshlrev_b32_e32 v74, 16, v79
	v_cvt_pk_bf16_f32 v66, v68, v69
	v_lshlrev_b32_e32 v102, 16, v66
	v_and_b32_e32 v103, 0xffff0000, v66
	v_pk_mul_f32 v[104:105], v[68:69], v[68:69]
	v_pk_add_f32 v[102:103], v[68:69], v[102:103] neg_lo:[0,1] neg_hi:[0,1]
	v_lshlrev_b32_e32 v68, 16, v75
	v_and_b32_e32 v69, 0xffff0000, v75
	v_and_b32_e32 v75, 0xffff0000, v79
	v_pk_add_f32 v[68:69], v[68:69], v[74:75]
	v_lshlrev_b32_e32 v74, 16, v83
	v_and_b32_e32 v75, 0xffff0000, v83
	v_pk_fma_f32 v[68:69], v[100:101], v[74:75], v[68:69]
	v_lshlrev_b32_e32 v82, 16, v80
	v_cvt_pk_bf16_f32 v67, v68, v69
	v_lshlrev_b32_e32 v78, 16, v67
	v_and_b32_e32 v79, 0xffff0000, v67
	v_pk_mul_f32 v[74:75], v[68:69], v[68:69]
	v_pk_add_f32 v[78:79], v[68:69], v[78:79] neg_lo:[0,1] neg_hi:[0,1]
	v_lshlrev_b32_e32 v68, 16, v76
	v_and_b32_e32 v69, 0xffff0000, v76
	v_and_b32_e32 v83, 0xffff0000, v80
	v_pk_add_f32 v[68:69], v[68:69], v[82:83]
	v_lshlrev_b32_e32 v82, 16, v84
	v_and_b32_e32 v83, 0xffff0000, v84
	v_pk_fma_f32 v[72:73], v[72:73], v[82:83], v[68:69]
	v_add_f32_e32 v69, v90, v91
	v_add_f32_e32 v69, v92, v69
	v_add_f32_e32 v69, v93, v69
	v_add_f32_e32 v69, v94, v69
	v_add_f32_e32 v69, v95, v69
	v_add_f32_e32 v69, v96, v69
	v_add_f32_e32 v69, v97, v69
	v_add_f32_e32 v69, v104, v69
	v_add_f32_e32 v69, v105, v69
	v_lshlrev_b32_e32 v76, 16, v77
	v_and_b32_e32 v77, 0xffff0000, v77
	v_lshlrev_b32_e32 v80, 16, v81
	v_and_b32_e32 v81, 0xffff0000, v81
	v_add_f32_e32 v69, v74, v69
	v_pk_mul_f32 v[82:83], v[72:73], v[72:73]
	v_pk_add_f32 v[76:77], v[76:77], v[80:81]
	v_lshlrev_b32_e32 v80, 16, v85
	v_and_b32_e32 v81, 0xffff0000, v85
	v_add_f32_e32 v69, v75, v69
	v_pk_fma_f32 v[70:71], v[70:71], v[80:81], v[76:77]
	v_add_f32_e32 v69, v82, v69
	v_pk_mul_f32 v[76:77], v[70:71], v[70:71]
	v_add_f32_e32 v69, v83, v69
	v_add_f32_e32 v69, v76, v69
	v_cvt_pk_bf16_f32 v68, v72, v73
	v_add_f32_e32 v76, v77, v69
	v_cvt_pk_bf16_f32 v69, v70, v71
	v_lshlrev_b32_e32 v100, 16, v68
	v_and_b32_e32 v101, 0xffff0000, v68
	v_lshlrev_b32_e32 v74, 16, v69
	v_and_b32_e32 v75, 0xffff0000, v69
	v_pk_add_f32 v[72:73], v[72:73], v[100:101] neg_lo:[0,1] neg_hi:[0,1]
	v_pk_add_f32 v[74:75], v[70:71], v[74:75] neg_lo:[0,1] neg_hi:[0,1]
	v_cvt_pk_bf16_f32 v72, v72, v73
	v_cvt_pk_bf16_f32 v73, v74, v75
	v_lshl_add_u64 v[74:75], s[58:59], 0, v[88:89]
	v_cvt_pk_bf16_f32 v70, v102, v103
	v_cvt_pk_bf16_f32 v71, v78, v79
	global_store_dwordx4 v[74:75], v[66:69], off
	global_store_dwordx4 v[98:99], v[70:73], off
	v_mov_b32_e32 v66, v76
	s_nop 1
	v_permlane16_swap_b32_e32 v76, v66
	s_waitcnt lgkmcnt(0)
	v_add_f32_e32 v66, v76, v66
	ds_bpermute_b32 v67, v145, v66
	s_and_saveexec_b64 s[12:13], s[0:1]
	s_cbranch_execz .LBB0_1346
	v_readlane_b32 s44, v250, 8
	v_readlane_b32 s46, v250, 10
	v_readlane_b32 s47, v250, 11
	s_waitcnt lgkmcnt(0)
	v_add_f32_e32 v68, v66, v67
	s_lshl_b32 s40, s25, 2
	v_lshl_add_u64 v[66:67], s[46:47], 0, v[86:87]
	v_lshl_add_u64 v[66:67], s[54:55], 2, v[66:67]
	v_lshl_add_u64 v[66:67], v[66:67], 0, s[40:41]
	v_readlane_b32 s45, v250, 9
	global_store_dword v[66:67], v68, off
.LBB0_1346:
	s_or_b64 exec, exec, s[12:13]
	v_add_u32_e32 v72, 0x80, v144
	v_ashrrev_i32_e32 v73, 31, v72
	v_lshlrev_b64 v[70:71], 6, v[72:73]
	s_waitcnt lgkmcnt(0)
	v_lshl_add_u64 v[66:67], v[136:137], 0, v[70:71]
	global_load_dwordx4 v[66:69], v[66:67], off
	v_readlane_b32 s10, v253, 35
	v_readlane_b32 s11, v253, 36
	v_readlane_b32 s6, v250, 49
	v_readlane_b32 s7, v250, 50
	s_waitcnt vmcnt(0)
	v_mov_b32_e32 v74, v67
	v_mov_b32_e32 v75, v68
	v_mov_b32_e32 v67, v69
	v_pk_add_f32 v[66:67], v[74:75], v[66:67]
	s_nop 0
	v_add_f32_e32 v66, v66, v67
	v_mov_b32_e32 v67, v66
	s_nop 1
	v_permlane16_swap_b32_e32 v66, v67
	s_waitcnt lgkmcnt(0)
	v_add_f32_e32 v66, v66, v67
	v_mov_b32_e32 v67, v66
	s_nop 1
	v_permlane32_swap_b32_e32 v66, v67
	s_waitcnt lgkmcnt(0)
	v_add_f32_e32 v66, v66, v67
	v_fmamk_f32 v66, v66, 0x3a800000, v239
	v_cmp_gt_f32_e32 vcc, s16, v66
	v_mul_f32_e32 v67, 0x4b800000, v66
	s_nop 0
	v_cndmask_b32_e32 v66, v66, v67, vcc
	v_rsq_f32_e32 v66, v66
	s_nop 0
	v_mul_f32_e32 v67, 0x45800000, v66
	v_cndmask_b32_e32 v88, v66, v67, vcc
	v_lshlrev_b64 v[66:67], 10, v[72:73]
	v_lshl_add_u64 v[66:67], v[66:67], 0, v[142:143]
	v_lshlrev_b64 v[72:73], 1, v[66:67]
	v_lshl_add_u64 v[66:67], s[10:11], 0, v[72:73]
	v_lshl_add_u64 v[68:69], s[14:15], 0, v[72:73]
	global_load_dwordx4 v[78:81], v[66:67], off
	global_load_dwordx4 v[90:93], v[68:69], off
	v_lshl_add_u64 v[66:67], s[6:7], 0, v[72:73]
	global_load_dwordx4 v[82:85], v[66:67], off
	v_mul_f32_e32 v58, v58, v88
	v_mul_f32_e32 v58, 0xbfb8aa3b, v58
	v_exp_f32_e32 v58, v58
	v_mul_f32_e32 v62, v62, v88
	v_mul_f32_e32 v63, v63, v88
	v_mul_f32_e32 v62, 0xbfb8aa3b, v62
	v_add_f32_e32 v58, 1.0, v58
	v_rcp_f32_e32 v68, v58
	v_mul_f32_e32 v58, v59, v88
	v_mul_f32_e32 v58, 0xbfb8aa3b, v58
	v_exp_f32_e32 v58, v58
	v_mul_f32_e32 v63, 0xbfb8aa3b, v63
	v_exp_f32_e32 v62, v62
	v_exp_f32_e32 v63, v63
	v_add_f32_e32 v58, 1.0, v58
	v_rcp_f32_e32 v69, v58
	v_mul_f32_e32 v58, v60, v88
	v_mul_f32_e32 v58, 0xbfb8aa3b, v58
	v_exp_f32_e32 v58, v58
	v_mul_f32_e32 v64, v64, v88
	v_mul_f32_e32 v65, v65, v88
	v_add_f32_e32 v62, 1.0, v62
	v_add_f32_e32 v58, 1.0, v58
	v_rcp_f32_e32 v86, v58
	v_mul_f32_e32 v58, v61, v88
	v_mul_f32_e32 v58, 0xbfb8aa3b, v58
	v_exp_f32_e32 v58, v58
	v_add_f32_e32 v63, 1.0, v63
	v_mul_f32_e32 v64, 0xbfb8aa3b, v64
	v_mul_f32_e32 v65, 0xbfb8aa3b, v65
	v_rcp_f32_e32 v62, v62
	v_rcp_f32_e32 v63, v63
	v_exp_f32_e32 v64, v64
	v_exp_f32_e32 v65, v65
	v_add_f32_e32 v58, 1.0, v58
	v_rcp_f32_e32 v87, v58
	v_add_f32_e32 v64, 1.0, v64
	v_add_f32_e32 v65, 1.0, v65
	v_rcp_f32_e32 v64, v64
	v_rcp_f32_e32 v65, v65
	v_mul_f32_e32 v54, v54, v88
	v_mul_f32_e32 v54, 0xbfb8aa3b, v54
	v_exp_f32_e32 v54, v54
	v_mul_f32_e32 v50, v50, v88
	v_mul_f32_e32 v50, 0xbfb8aa3b, v50
	v_exp_f32_e32 v50, v50
	v_add_f32_e32 v54, 1.0, v54
	v_add_f32_e32 v50, 1.0, v50
	s_waitcnt vmcnt(2)
; __device__ __forceinline__ unsigned pk2(float lo, float hi) { f32x2_t v = {lo, hi}; bf16x2_t b = __builtin_convertvector(v, bf16x2_t); return __builtin_bit_cast(unsigned, b); }
; __device__ __forceinline__ float bflo(unsigned u) { return __uint_as_float(u << 16); }
;     __device__ __forceinline__ void operator()(const f32x4 (&acc)[2][2][4][2], const Unit& u, int wr, int wc, int fr, int fq) const {
;     ...
;                     const u32x4 hh = *(const u32x4*)(HI + off), ll = *(const u32x4*)(LO + off);
;                     float hv[8] = {bflo(hh.x) + bflo(ll.x), bfhi(hh.x) + bfhi(ll.x), bflo(hh.y) + bflo(ll.y), bfhi(hh.y) + bfhi(ll.y),
;                                    bflo(hh.z) + bflo(ll.z), bfhi(hh.z) + bfhi(ll.z), bflo(hh.w) + bflo(ll.w), bfhi(hh.w) + bfhi(ll.w)};
;                     float av[8] = {acc[ai][bj][m][0][0], acc[ai][bj][m][0][1], acc[ai][bj][m][0][2], acc[ai][bj][m][0][3], acc[ai][bj][m][1][0], acc[ai][bj][m][1][1], acc[ai][bj][m][1][2], acc[ai][bj][m][1][3]};
;                     if (GATED) { const u32x4 pp = *(const u32x4*)(PP + off);
;                         const float pv[8] = {bflo(pp.x), bfhi(pp.x), bflo(pp.y), bfhi(pp.y), bflo(pp.z), bfhi(pp.z), bflo(pp.w), bfhi(pp.w)};
; #pragma unroll
;                         for (int e = 0; e < 8; ++e) av[e] = fast_sigmoid(av[e] * rs) * pv[e]; }
;                     else {
; #pragma unroll
;                         for (int e = 0; e < 8; ++e) av[e] *= alpha; }
;                     float lo[8];
; #pragma unroll
;                     for (int e = 0; e < 8; ++e) { hv[e] += av[e]; sq += hv[e] * hv[e]; }
;                     u32x4 wh; wh.x = pk2(hv[0], hv[1]); wh.y = pk2(hv[2], hv[3]); wh.z = pk2(hv[4], hv[5]); wh.w = pk2(hv[6], hv[7]);
;                     lo[0] = hv[0] - bflo(wh.x); lo[1] = hv[1] - bfhi(wh.x); lo[2] = hv[2] - bflo(wh.y); lo[3] = hv[3] - bfhi(wh.y);
;                     lo[4] = hv[4] - bflo(wh.z); lo[5] = hv[5] - bfhi(wh.z); lo[6] = hv[6] - bflo(wh.w); lo[7] = hv[7] - bfhi(wh.w);
;                     u32x4 wl; wl.x = pk2(lo[0], lo[1]); wl.y = pk2(lo[2], lo[3]); wl.z = pk2(lo[4], lo[5]); wl.w = pk2(lo[6], lo[7]);
;                     *(u32x4*)(HO + off) = wh; *(u32x4*)(LO + off) = wl;
;                 }
;                 sq += __shfl_xor(sq, 16); sq += __shfl_xor(sq, 32);
;                 if (fq == 0) ssq_out[(size_t)row * 16 + 4 * u.pn + wc] = sq;
	v_lshlrev_b32_e32 v58, 16, v78
	v_and_b32_e32 v59, 0xffff0000, v78
	s_waitcnt vmcnt(0)
	v_lshlrev_b32_e32 v60, 16, v82
	v_and_b32_e32 v61, 0xffff0000, v82
	v_pk_add_f32 v[58:59], v[58:59], v[60:61]
	v_lshlrev_b32_e32 v60, 16, v90
	v_and_b32_e32 v61, 0xffff0000, v90
	v_pk_fma_f32 v[60:61], v[62:63], v[60:61], v[58:59]
	v_lshlrev_b32_e32 v76, 16, v83
	v_cvt_pk_bf16_f32 v58, v60, v61
	v_lshlrev_b32_e32 v62, 16, v58
	v_and_b32_e32 v63, 0xffff0000, v58
	v_pk_mul_f32 v[74:75], v[60:61], v[60:61]
	v_pk_add_f32 v[62:63], v[60:61], v[62:63] neg_lo:[0,1] neg_hi:[0,1]
	v_lshlrev_b32_e32 v60, 16, v79
	v_and_b32_e32 v61, 0xffff0000, v79
	v_and_b32_e32 v77, 0xffff0000, v83
	v_pk_add_f32 v[60:61], v[60:61], v[76:77]
	v_lshlrev_b32_e32 v76, 16, v91
	v_and_b32_e32 v77, 0xffff0000, v91
	v_pk_fma_f32 v[60:61], v[64:65], v[76:77], v[60:61]
	v_lshlrev_b32_e32 v78, 16, v84
	v_cvt_pk_bf16_f32 v59, v60, v61
	v_lshlrev_b32_e32 v64, 16, v59
	v_and_b32_e32 v65, 0xffff0000, v59
	v_pk_mul_f32 v[76:77], v[60:61], v[60:61]
	v_pk_add_f32 v[64:65], v[60:61], v[64:65] neg_lo:[0,1] neg_hi:[0,1]
	v_lshlrev_b32_e32 v60, 16, v80
	v_and_b32_e32 v61, 0xffff0000, v80
	v_and_b32_e32 v79, 0xffff0000, v84
	v_pk_add_f32 v[60:61], v[60:61], v[78:79]
	v_lshlrev_b32_e32 v78, 16, v92
	v_and_b32_e32 v79, 0xffff0000, v92
	v_pk_fma_f32 v[68:69], v[68:69], v[78:79], v[60:61]
	v_lshlrev_b32_e32 v80, 16, v81
	v_cvt_pk_bf16_f32 v60, v68, v69
	v_lshlrev_b32_e32 v82, 16, v60
	v_and_b32_e32 v83, 0xffff0000, v60
	v_pk_mul_f32 v[78:79], v[68:69], v[68:69]
	v_pk_add_f32 v[68:69], v[68:69], v[82:83] neg_lo:[0,1] neg_hi:[0,1]
	v_and_b32_e32 v81, 0xffff0000, v81
	v_lshlrev_b32_e32 v82, 16, v85
	v_and_b32_e32 v83, 0xffff0000, v85
	v_pk_add_f32 v[80:81], v[80:81], v[82:83]
	v_lshlrev_b32_e32 v82, 16, v93
	v_and_b32_e32 v83, 0xffff0000, v93
	v_pk_fma_f32 v[82:83], v[86:87], v[82:83], v[80:81]
	v_cvt_pk_bf16_f32 v62, v62, v63
	v_cvt_pk_bf16_f32 v61, v82, v83
	v_lshlrev_b32_e32 v84, 16, v61
	v_and_b32_e32 v85, 0xffff0000, v61
	v_pk_mul_f32 v[80:81], v[82:83], v[82:83]
	v_pk_add_f32 v[82:83], v[82:83], v[84:85] neg_lo:[0,1] neg_hi:[0,1]
	v_cvt_pk_bf16_f32 v63, v64, v65
	v_cvt_pk_bf16_f32 v64, v68, v69
	v_lshl_add_u64 v[68:69], s[58:59], 0, v[72:73]
	v_or_b32_e32 v72, 0x100, v72
	v_cvt_pk_bf16_f32 v65, v82, v83
	global_store_dwordx4 v[68:69], v[58:61], off
	global_store_dwordx4 v[66:67], v[62:65], off
	v_lshl_add_u64 v[82:83], s[6:7], 0, v[72:73]
	v_lshl_add_u64 v[58:59], s[10:11], 0, v[72:73]
	global_load_dwordx4 v[58:61], v[58:59], off
	v_lshl_add_u64 v[66:67], s[14:15], 0, v[72:73]
	global_load_dwordx4 v[62:65], v[82:83], off
	v_rcp_f32_e32 v86, v54
	global_load_dwordx4 v[66:69], v[66:67], off
	v_mul_f32_e32 v54, v55, v88
	v_mul_f32_e32 v54, 0xbfb8aa3b, v54
	v_exp_f32_e32 v54, v54
	s_nop 0
	v_add_f32_e32 v54, 1.0, v54
	v_rcp_f32_e32 v87, v54
	v_mul_f32_e32 v54, v56, v88
	v_rcp_f32_e32 v56, v50
	v_mul_f32_e32 v50, v51, v88
	v_mul_f32_e32 v54, 0xbfb8aa3b, v54
	v_mul_f32_e32 v50, 0xbfb8aa3b, v50
	v_exp_f32_e32 v54, v54
	v_exp_f32_e32 v50, v50
	v_add_f32_e32 v54, 1.0, v54
	v_add_f32_e32 v50, 1.0, v50
	v_rcp_f32_e32 v84, v54
	v_mul_f32_e32 v54, v57, v88
	v_rcp_f32_e32 v57, v50
	v_mul_f32_e32 v50, v52, v88
	v_mul_f32_e32 v54, 0xbfb8aa3b, v54
	v_mul_f32_e32 v50, 0xbfb8aa3b, v50
	v_exp_f32_e32 v54, v54
	v_exp_f32_e32 v50, v50
	v_add_f32_e32 v54, 1.0, v54
	v_add_f32_e32 v50, 1.0, v50
	v_rcp_f32_e32 v85, v54
	v_rcp_f32_e32 v54, v50
	v_mul_f32_e32 v50, v53, v88
	v_mul_f32_e32 v50, 0xbfb8aa3b, v50
	v_exp_f32_e32 v50, v50
	s_waitcnt vmcnt(2)
	v_and_b32_e32 v51, 0xffff0000, v58
	v_add_f32_e32 v50, 1.0, v50
	v_rcp_f32_e32 v55, v50
	v_lshlrev_b32_e32 v50, 16, v58
	s_waitcnt vmcnt(1)
	v_lshlrev_b32_e32 v52, 16, v62
	v_and_b32_e32 v53, 0xffff0000, v62
	v_pk_add_f32 v[50:51], v[50:51], v[52:53]
	s_waitcnt vmcnt(0)
	v_lshlrev_b32_e32 v52, 16, v66
	v_and_b32_e32 v53, 0xffff0000, v66
	v_pk_fma_f32 v[52:53], v[86:87], v[52:53], v[50:51]
	v_lshlrev_b32_e32 v58, 16, v63
	v_cvt_pk_bf16_f32 v50, v52, v53
	v_lshlrev_b32_e32 v86, 16, v50
	v_and_b32_e32 v87, 0xffff0000, v50
	v_pk_mul_f32 v[88:89], v[52:53], v[52:53]
	v_pk_add_f32 v[86:87], v[52:53], v[86:87] neg_lo:[0,1] neg_hi:[0,1]
	v_lshlrev_b32_e32 v52, 16, v59
	v_and_b32_e32 v53, 0xffff0000, v59
	v_and_b32_e32 v59, 0xffff0000, v63
	v_pk_add_f32 v[52:53], v[52:53], v[58:59]
	v_lshlrev_b32_e32 v58, 16, v67
	v_and_b32_e32 v59, 0xffff0000, v67
	v_pk_fma_f32 v[52:53], v[84:85], v[58:59], v[52:53]
	v_lshlrev_b32_e32 v66, 16, v64
	v_cvt_pk_bf16_f32 v51, v52, v53
	v_lshlrev_b32_e32 v62, 16, v51
	v_and_b32_e32 v63, 0xffff0000, v51
	v_pk_mul_f32 v[58:59], v[52:53], v[52:53]
	v_pk_add_f32 v[62:63], v[52:53], v[62:63] neg_lo:[0,1] neg_hi:[0,1]
	v_lshlrev_b32_e32 v52, 16, v60
	v_and_b32_e32 v53, 0xffff0000, v60
	v_and_b32_e32 v67, 0xffff0000, v64
	v_pk_add_f32 v[52:53], v[52:53], v[66:67]
	v_lshlrev_b32_e32 v66, 16, v68
	v_and_b32_e32 v67, 0xffff0000, v68
	v_pk_fma_f32 v[56:57], v[56:57], v[66:67], v[52:53]
	v_add_f32_e32 v53, v74, v75
	v_add_f32_e32 v53, v76, v53
	v_add_f32_e32 v53, v77, v53
	v_add_f32_e32 v53, v78, v53
	v_add_f32_e32 v53, v79, v53
	v_add_f32_e32 v53, v80, v53
	v_add_f32_e32 v53, v81, v53
	v_add_f32_e32 v53, v88, v53
	v_add_f32_e32 v53, v89, v53
	v_lshlrev_b32_e32 v60, 16, v61
	v_and_b32_e32 v61, 0xffff0000, v61
	v_lshlrev_b32_e32 v64, 16, v65
	v_and_b32_e32 v65, 0xffff0000, v65
	v_add_f32_e32 v53, v58, v53
	v_pk_mul_f32 v[66:67], v[56:57], v[56:57]
	v_pk_add_f32 v[60:61], v[60:61], v[64:65]
	v_lshlrev_b32_e32 v64, 16, v69
	v_and_b32_e32 v65, 0xffff0000, v69
	v_add_f32_e32 v53, v59, v53
	v_pk_fma_f32 v[54:55], v[54:55], v[64:65], v[60:61]
	v_add_f32_e32 v53, v66, v53
	v_pk_mul_f32 v[60:61], v[54:55], v[54:55]
	v_add_f32_e32 v53, v67, v53
	v_add_f32_e32 v53, v60, v53
	v_cvt_pk_bf16_f32 v52, v56, v57
	v_add_f32_e32 v60, v61, v53
	v_cvt_pk_bf16_f32 v53, v54, v55
	v_lshlrev_b32_e32 v84, 16, v52
	v_and_b32_e32 v85, 0xffff0000, v52
	v_lshlrev_b32_e32 v58, 16, v53
	v_and_b32_e32 v59, 0xffff0000, v53
	v_pk_add_f32 v[56:57], v[56:57], v[84:85] neg_lo:[0,1] neg_hi:[0,1]
	v_pk_add_f32 v[58:59], v[54:55], v[58:59] neg_lo:[0,1] neg_hi:[0,1]
	v_cvt_pk_bf16_f32 v56, v56, v57
	v_cvt_pk_bf16_f32 v57, v58, v59
	v_lshl_add_u64 v[58:59], s[58:59], 0, v[72:73]
	v_cvt_pk_bf16_f32 v54, v86, v87
	v_cvt_pk_bf16_f32 v55, v62, v63
	global_store_dwordx4 v[58:59], v[50:53], off
	global_store_dwordx4 v[82:83], v[54:57], off
	v_mov_b32_e32 v50, v60
	s_nop 1
	v_permlane16_swap_b32_e32 v60, v50
	s_waitcnt lgkmcnt(0)
	v_add_f32_e32 v50, v60, v50
	ds_bpermute_b32 v51, v145, v50
	s_and_saveexec_b64 s[12:13], s[0:1]
	s_cbranch_execz .LBB0_1348
	v_readlane_b32 s44, v250, 8
	v_readlane_b32 s46, v250, 10
	v_readlane_b32 s47, v250, 11
	s_waitcnt lgkmcnt(0)
	v_add_f32_e32 v52, v50, v51
	s_lshl_b32 s40, s25, 2
	v_lshl_add_u64 v[50:51], s[46:47], 0, v[70:71]
	v_lshl_add_u64 v[50:51], s[54:55], 2, v[50:51]
	v_lshl_add_u64 v[50:51], v[50:51], 0, s[40:41]
	v_readlane_b32 s45, v250, 9
	global_store_dword v[50:51], v52, off
; __device__ __forceinline__ float row_ssq(const float* part, int pitch, int n4, int row, int fq) {
;     f32x4 v = (f32x4){0.f, 0.f, 0.f, 0.f};
;     if (fq < n4) v = *(const f32x4*)(part + (size_t)row * pitch + 4 * fq);
;     float s = (v[0] + v[1]) + (v[2] + v[3]);
;     s += __shfl_xor(s, 16); s += __shfl_xor(s, 32);
;     return s;
;     __device__ __forceinline__ void operator()(const f32x4 (&acc)[2][2][4][2], const Unit& u, int wr, int wc, int fr, int fq) const {
;     ...
;                 float rs = 0.f; if (GATED) rs = rsqrtf(row_ssq(ssq_in, 16, 4, row, fq) * (1.f / 1024.f) + EPS);
;                 float sq = 0.f;
; #pragma unroll
;                 for (int bj = 0; bj < 2; ++bj) {
;                     const size_t off = (size_t)row * DM + col0 + bj * HALF;
;                     const u32x4 hh = *(const u32x4*)(HI + off), ll = *(const u32x4*)(LO + off);
;                     float hv[8] = {bflo(hh.x) + bflo(ll.x), bfhi(hh.x) + bfhi(ll.x), bflo(hh.y) + bflo(ll.y), bfhi(hh.y) + bfhi(ll.y),
;                                    bflo(hh.z) + bflo(ll.z), bfhi(hh.z) + bfhi(ll.z), bflo(hh.w) + bflo(ll.w), bfhi(hh.w) + bfhi(ll.w)};
;                     float av[8] = {acc[ai][bj][m][0][0], acc[ai][bj][m][0][1], acc[ai][bj][m][0][2], acc[ai][bj][m][0][3], acc[ai][bj][m][1][0], acc[ai][bj][m][1][1], acc[ai][bj][m][1][2], acc[ai][bj][m][1][3]};
;                     if (GATED) { const u32x4 pp = *(const u32x4*)(PP + off);
;                         const float pv[8] = {bflo(pp.x), bfhi(pp.x), bflo(pp.y), bfhi(pp.y), bflo(pp.z), bfhi(pp.z), bflo(pp.w), bfhi(pp.w)};
; #pragma unroll
;                         for (int e = 0; e < 8; ++e) av[e] = fast_sigmoid(av[e] * rs) * pv[e]; }
;                     else {
; #pragma unroll
;                         for (int e = 0; e < 8; ++e) av[e] *= alpha; }
;                     float lo[8];
; #pragma unroll
;                     for (int e = 0; e < 8; ++e) { hv[e] += av[e]; sq += hv[e] * hv[e]; }
;                     u32x4 wh; wh.x = pk2(hv[0], hv[1]); wh.y = pk2(hv[2], hv[3]); wh.z = pk2(hv[4], hv[5]); wh.w = pk2(hv[6], hv[7]);
;                     lo[0] = hv[0] - bflo(wh.x); lo[1] = hv[1] - bfhi(wh.x); lo[2] = hv[2] - bflo(wh.y); lo[3] = hv[3] - bfhi(wh.y);
;                     lo[4] = hv[4] - bflo(wh.z); lo[5] = hv[5] - bfhi(wh.z); lo[6] = hv[6] - bflo(wh.w); lo[7] = hv[7] - bfhi(wh.w);
.LBB0_1348:
	s_or_b64 exec, exec, s[12:13]
	v_add_u32_e32 v56, 0x90, v144
	v_ashrrev_i32_e32 v57, 31, v56
	v_lshlrev_b64 v[54:55], 6, v[56:57]
	s_waitcnt lgkmcnt(0)
	v_lshl_add_u64 v[50:51], v[136:137], 0, v[54:55]
	global_load_dwordx4 v[50:53], v[50:51], off
	v_readlane_b32 s10, v253, 35
	v_readlane_b32 s11, v253, 36
	v_readlane_b32 s6, v250, 49
	v_readlane_b32 s7, v250, 50
	s_waitcnt vmcnt(0)
	v_mov_b32_e32 v58, v51
	v_mov_b32_e32 v59, v52
	v_mov_b32_e32 v51, v53
	v_pk_add_f32 v[50:51], v[58:59], v[50:51]
	s_nop 0
	v_add_f32_e32 v50, v50, v51
	v_mov_b32_e32 v51, v50
	s_nop 1
	v_permlane16_swap_b32_e32 v50, v51
	s_waitcnt lgkmcnt(0)
	v_add_f32_e32 v50, v50, v51
	v_mov_b32_e32 v51, v50
	s_nop 1
	v_permlane32_swap_b32_e32 v50, v51
	s_waitcnt lgkmcnt(0)
	v_add_f32_e32 v50, v50, v51
	v_fmamk_f32 v50, v50, 0x3a800000, v239
	v_cmp_gt_f32_e32 vcc, s16, v50
	v_mul_f32_e32 v51, 0x4b800000, v50
	s_nop 0
	v_cndmask_b32_e32 v50, v50, v51, vcc
	v_rsq_f32_e32 v50, v50
	s_nop 0
	v_mul_f32_e32 v51, 0x45800000, v50
	v_cndmask_b32_e32 v72, v50, v51, vcc
	v_lshlrev_b64 v[50:51], 10, v[56:57]
	v_lshl_add_u64 v[50:51], v[50:51], 0, v[142:143]
	v_lshlrev_b64 v[56:57], 1, v[50:51]
	v_lshl_add_u64 v[50:51], s[10:11], 0, v[56:57]
	v_lshl_add_u64 v[52:53], s[14:15], 0, v[56:57]
	global_load_dwordx4 v[62:65], v[50:51], off
	global_load_dwordx4 v[74:77], v[52:53], off
	v_lshl_add_u64 v[50:51], s[6:7], 0, v[56:57]
	global_load_dwordx4 v[66:69], v[50:51], off
	v_mul_f32_e32 v42, v42, v72
	v_mul_f32_e32 v42, 0xbfb8aa3b, v42
	v_exp_f32_e32 v42, v42
	v_mul_f32_e32 v46, v46, v72
	v_mul_f32_e32 v47, v47, v72
	v_mul_f32_e32 v46, 0xbfb8aa3b, v46
	v_add_f32_e32 v42, 1.0, v42
	v_rcp_f32_e32 v52, v42
	v_mul_f32_e32 v42, v43, v72
	v_mul_f32_e32 v42, 0xbfb8aa3b, v42
	v_exp_f32_e32 v42, v42
	v_mul_f32_e32 v47, 0xbfb8aa3b, v47
	v_exp_f32_e32 v46, v46
	v_exp_f32_e32 v47, v47
	v_add_f32_e32 v42, 1.0, v42
	v_rcp_f32_e32 v53, v42
	v_mul_f32_e32 v42, v44, v72
	v_mul_f32_e32 v42, 0xbfb8aa3b, v42
	v_exp_f32_e32 v42, v42
	v_mul_f32_e32 v48, v48, v72
	v_mul_f32_e32 v49, v49, v72
	v_add_f32_e32 v46, 1.0, v46
	v_add_f32_e32 v42, 1.0, v42
	v_rcp_f32_e32 v70, v42
	v_mul_f32_e32 v42, v45, v72
	v_mul_f32_e32 v42, 0xbfb8aa3b, v42
	v_exp_f32_e32 v42, v42
	v_add_f32_e32 v47, 1.0, v47
	v_mul_f32_e32 v48, 0xbfb8aa3b, v48
	v_mul_f32_e32 v49, 0xbfb8aa3b, v49
	v_rcp_f32_e32 v46, v46
	v_rcp_f32_e32 v47, v47
	v_exp_f32_e32 v48, v48
	v_exp_f32_e32 v49, v49
	v_add_f32_e32 v42, 1.0, v42
	v_rcp_f32_e32 v71, v42
	v_add_f32_e32 v48, 1.0, v48
	v_add_f32_e32 v49, 1.0, v49
	v_rcp_f32_e32 v48, v48
	v_rcp_f32_e32 v49, v49
	v_mul_f32_e32 v38, v38, v72
	v_mul_f32_e32 v38, 0xbfb8aa3b, v38
	v_exp_f32_e32 v38, v38
	v_mul_f32_e32 v34, v34, v72
	v_mul_f32_e32 v34, 0xbfb8aa3b, v34
	v_exp_f32_e32 v34, v34
	v_add_f32_e32 v38, 1.0, v38
	v_add_f32_e32 v34, 1.0, v34
	s_waitcnt vmcnt(2)
	v_lshlrev_b32_e32 v42, 16, v62
	v_and_b32_e32 v43, 0xffff0000, v62
	s_waitcnt vmcnt(0)
	v_lshlrev_b32_e32 v44, 16, v66
	v_and_b32_e32 v45, 0xffff0000, v66
	v_pk_add_f32 v[42:43], v[42:43], v[44:45]
	v_lshlrev_b32_e32 v44, 16, v74
	v_and_b32_e32 v45, 0xffff0000, v74
	v_pk_fma_f32 v[44:45], v[46:47], v[44:45], v[42:43]
	v_lshlrev_b32_e32 v60, 16, v67
	v_cvt_pk_bf16_f32 v42, v44, v45
	v_lshlrev_b32_e32 v46, 16, v42
	v_and_b32_e32 v47, 0xffff0000, v42
	v_pk_mul_f32 v[58:59], v[44:45], v[44:45]
	v_pk_add_f32 v[46:47], v[44:45], v[46:47] neg_lo:[0,1] neg_hi:[0,1]
	v_lshlrev_b32_e32 v44, 16, v63
	v_and_b32_e32 v45, 0xffff0000, v63
	v_and_b32_e32 v61, 0xffff0000, v67
	v_pk_add_f32 v[44:45], v[44:45], v[60:61]
	v_lshlrev_b32_e32 v60, 16, v75
	v_and_b32_e32 v61, 0xffff0000, v75
	v_pk_fma_f32 v[44:45], v[48:49], v[60:61], v[44:45]
	v_lshlrev_b32_e32 v62, 16, v68
	v_cvt_pk_bf16_f32 v43, v44, v45
	v_lshlrev_b32_e32 v48, 16, v43
	v_and_b32_e32 v49, 0xffff0000, v43
	v_pk_mul_f32 v[60:61], v[44:45], v[44:45]
	v_pk_add_f32 v[48:49], v[44:45], v[48:49] neg_lo:[0,1] neg_hi:[0,1]
	v_lshlrev_b32_e32 v44, 16, v64
	v_and_b32_e32 v45, 0xffff0000, v64
	v_and_b32_e32 v63, 0xffff0000, v68
	v_pk_add_f32 v[44:45], v[44:45], v[62:63]
	v_lshlrev_b32_e32 v62, 16, v76
	v_and_b32_e32 v63, 0xffff0000, v76
	v_pk_fma_f32 v[52:53], v[52:53], v[62:63], v[44:45]
	v_lshlrev_b32_e32 v64, 16, v65
	v_cvt_pk_bf16_f32 v44, v52, v53
	v_lshlrev_b32_e32 v66, 16, v44
	v_and_b32_e32 v67, 0xffff0000, v44
	v_pk_mul_f32 v[62:63], v[52:53], v[52:53]
	v_pk_add_f32 v[52:53], v[52:53], v[66:67] neg_lo:[0,1] neg_hi:[0,1]
	v_and_b32_e32 v65, 0xffff0000, v65
	v_lshlrev_b32_e32 v66, 16, v69
	v_and_b32_e32 v67, 0xffff0000, v69
	v_pk_add_f32 v[64:65], v[64:65], v[66:67]
	v_lshlrev_b32_e32 v66, 16, v77
	v_and_b32_e32 v67, 0xffff0000, v77
	v_pk_fma_f32 v[66:67], v[70:71], v[66:67], v[64:65]
	v_cvt_pk_bf16_f32 v46, v46, v47
	v_cvt_pk_bf16_f32 v45, v66, v67
	v_lshlrev_b32_e32 v68, 16, v45
	v_and_b32_e32 v69, 0xffff0000, v45
	v_pk_mul_f32 v[64:65], v[66:67], v[66:67]
	v_pk_add_f32 v[66:67], v[66:67], v[68:69] neg_lo:[0,1] neg_hi:[0,1]
	v_cvt_pk_bf16_f32 v47, v48, v49
	v_cvt_pk_bf16_f32 v48, v52, v53
	v_lshl_add_u64 v[52:53], s[58:59], 0, v[56:57]
	v_or_b32_e32 v56, 0x100, v56
	v_cvt_pk_bf16_f32 v49, v66, v67
	global_store_dwordx4 v[52:53], v[42:45], off
	global_store_dwordx4 v[50:51], v[46:49], off
	v_lshl_add_u64 v[66:67], s[6:7], 0, v[56:57]
	v_lshl_add_u64 v[42:43], s[10:11], 0, v[56:57]
	global_load_dwordx4 v[42:45], v[42:43], off
	v_lshl_add_u64 v[50:51], s[14:15], 0, v[56:57]
	global_load_dwordx4 v[46:49], v[66:67], off
	v_rcp_f32_e32 v70, v38
	global_load_dwordx4 v[50:53], v[50:51], off
	v_mul_f32_e32 v38, v39, v72
	v_mul_f32_e32 v38, 0xbfb8aa3b, v38
	v_exp_f32_e32 v38, v38
	s_nop 0
	v_add_f32_e32 v38, 1.0, v38
	v_rcp_f32_e32 v71, v38
	v_mul_f32_e32 v38, v40, v72
	v_rcp_f32_e32 v40, v34
	v_mul_f32_e32 v34, v35, v72
	v_mul_f32_e32 v38, 0xbfb8aa3b, v38
	v_mul_f32_e32 v34, 0xbfb8aa3b, v34
	v_exp_f32_e32 v38, v38
	v_exp_f32_e32 v34, v34
	v_add_f32_e32 v38, 1.0, v38
	v_add_f32_e32 v34, 1.0, v34
	v_rcp_f32_e32 v68, v38
	v_mul_f32_e32 v38, v41, v72
	v_rcp_f32_e32 v41, v34
	v_mul_f32_e32 v34, v36, v72
	v_mul_f32_e32 v38, 0xbfb8aa3b, v38
	v_mul_f32_e32 v34, 0xbfb8aa3b, v34
	v_exp_f32_e32 v38, v38
	v_exp_f32_e32 v34, v34
	v_add_f32_e32 v38, 1.0, v38
	v_add_f32_e32 v34, 1.0, v34
	v_rcp_f32_e32 v69, v38
	v_rcp_f32_e32 v38, v34
	v_mul_f32_e32 v34, v37, v72
	v_mul_f32_e32 v34, 0xbfb8aa3b, v34
	v_exp_f32_e32 v34, v34
	s_waitcnt vmcnt(2)
; __device__ __forceinline__ float row_ssq(const float* part, int pitch, int n4, int row, int fq) {
;     f32x4 v = (f32x4){0.f, 0.f, 0.f, 0.f};
;     if (fq < n4) v = *(const f32x4*)(part + (size_t)row * pitch + 4 * fq);
;     float s = (v[0] + v[1]) + (v[2] + v[3]);
;     __device__ __forceinline__ void operator()(const f32x4 (&acc)[2][2][4][2], const Unit& u, int wr, int wc, int fr, int fq) const {
;     ...
;                     const u32x4 hh = *(const u32x4*)(HI + off), ll = *(const u32x4*)(LO + off);
;                     float hv[8] = {bflo(hh.x) + bflo(ll.x), bfhi(hh.x) + bfhi(ll.x), bflo(hh.y) + bflo(ll.y), bfhi(hh.y) + bfhi(ll.y),
;                                    bflo(hh.z) + bflo(ll.z), bfhi(hh.z) + bfhi(ll.z), bflo(hh.w) + bflo(ll.w), bfhi(hh.w) + bfhi(ll.w)};
;                     float av[8] = {acc[ai][bj][m][0][0], acc[ai][bj][m][0][1], acc[ai][bj][m][0][2], acc[ai][bj][m][0][3], acc[ai][bj][m][1][0], acc[ai][bj][m][1][1], acc[ai][bj][m][1][2], acc[ai][bj][m][1][3]};
;                     if (GATED) { const u32x4 pp = *(const u32x4*)(PP + off);
;                         const float pv[8] = {bflo(pp.x), bfhi(pp.x), bflo(pp.y), bfhi(pp.y), bflo(pp.z), bfhi(pp.z), bflo(pp.w), bfhi(pp.w)};
; #pragma unroll
;                         for (int e = 0; e < 8; ++e) av[e] = fast_sigmoid(av[e] * rs) * pv[e]; }
;                     else {
; #pragma unroll
;                         for (int e = 0; e < 8; ++e) av[e] *= alpha; }
;                     float lo[8];
; #pragma unroll
;                     for (int e = 0; e < 8; ++e) { hv[e] += av[e]; sq += hv[e] * hv[e]; }
;                     u32x4 wh; wh.x = pk2(hv[0], hv[1]); wh.y = pk2(hv[2], hv[3]); wh.z = pk2(hv[4], hv[5]); wh.w = pk2(hv[6], hv[7]);
;                     lo[0] = hv[0] - bflo(wh.x); lo[1] = hv[1] - bfhi(wh.x); lo[2] = hv[2] - bflo(wh.y); lo[3] = hv[3] - bfhi(wh.y);
;                     lo[4] = hv[4] - bflo(wh.z); lo[5] = hv[5] - bfhi(wh.z); lo[6] = hv[6] - bflo(wh.w); lo[7] = hv[7] - bfhi(wh.w);
;                     u32x4 wl; wl.x = pk2(lo[0], lo[1]); wl.y = pk2(lo[2], lo[3]); wl.z = pk2(lo[4], lo[5]); wl.w = pk2(lo[6], lo[7]);
;                     *(u32x4*)(HO + off) = wh; *(u32x4*)(LO + off) = wl;
;                 }
;                 sq += __shfl_xor(sq, 16); sq += __shfl_xor(sq, 32);
;                 if (fq == 0) ssq_out[(size_t)row * 16 + 4 * u.pn + wc] = sq;
	v_and_b32_e32 v35, 0xffff0000, v42
	v_add_f32_e32 v34, 1.0, v34
	v_rcp_f32_e32 v39, v34
	v_lshlrev_b32_e32 v34, 16, v42
	s_waitcnt vmcnt(1)
	v_lshlrev_b32_e32 v36, 16, v46
	v_and_b32_e32 v37, 0xffff0000, v46
	v_pk_add_f32 v[34:35], v[34:35], v[36:37]
	s_waitcnt vmcnt(0)
	v_lshlrev_b32_e32 v36, 16, v50
	v_and_b32_e32 v37, 0xffff0000, v50
	v_pk_fma_f32 v[36:37], v[70:71], v[36:37], v[34:35]
	v_lshlrev_b32_e32 v42, 16, v47
	v_cvt_pk_bf16_f32 v34, v36, v37
	v_lshlrev_b32_e32 v70, 16, v34
	v_and_b32_e32 v71, 0xffff0000, v34
	v_pk_mul_f32 v[72:73], v[36:37], v[36:37]
	v_pk_add_f32 v[70:71], v[36:37], v[70:71] neg_lo:[0,1] neg_hi:[0,1]
	v_lshlrev_b32_e32 v36, 16, v43
	v_and_b32_e32 v37, 0xffff0000, v43
	v_and_b32_e32 v43, 0xffff0000, v47
	v_pk_add_f32 v[36:37], v[36:37], v[42:43]
	v_lshlrev_b32_e32 v42, 16, v51
	v_and_b32_e32 v43, 0xffff0000, v51
	v_pk_fma_f32 v[36:37], v[68:69], v[42:43], v[36:37]
	v_lshlrev_b32_e32 v50, 16, v48
	v_cvt_pk_bf16_f32 v35, v36, v37
	v_lshlrev_b32_e32 v46, 16, v35
	v_and_b32_e32 v47, 0xffff0000, v35
	v_pk_mul_f32 v[42:43], v[36:37], v[36:37]
	v_pk_add_f32 v[46:47], v[36:37], v[46:47] neg_lo:[0,1] neg_hi:[0,1]
	v_lshlrev_b32_e32 v36, 16, v44
	v_and_b32_e32 v37, 0xffff0000, v44
	v_and_b32_e32 v51, 0xffff0000, v48
	v_pk_add_f32 v[36:37], v[36:37], v[50:51]
	v_lshlrev_b32_e32 v50, 16, v52
	v_and_b32_e32 v51, 0xffff0000, v52
	v_pk_fma_f32 v[40:41], v[40:41], v[50:51], v[36:37]
	v_add_f32_e32 v37, v58, v59
	v_add_f32_e32 v37, v60, v37
	v_add_f32_e32 v37, v61, v37
	v_add_f32_e32 v37, v62, v37
	v_add_f32_e32 v37, v63, v37
	v_add_f32_e32 v37, v64, v37
	v_add_f32_e32 v37, v65, v37
	v_add_f32_e32 v37, v72, v37
	v_add_f32_e32 v37, v73, v37
	v_lshlrev_b32_e32 v44, 16, v45
	v_and_b32_e32 v45, 0xffff0000, v45
	v_lshlrev_b32_e32 v48, 16, v49
	v_and_b32_e32 v49, 0xffff0000, v49
	v_add_f32_e32 v37, v42, v37
	v_pk_mul_f32 v[50:51], v[40:41], v[40:41]
	v_pk_add_f32 v[44:45], v[44:45], v[48:49]
	v_lshlrev_b32_e32 v48, 16, v53
	v_and_b32_e32 v49, 0xffff0000, v53
	v_add_f32_e32 v37, v43, v37
	v_pk_fma_f32 v[38:39], v[38:39], v[48:49], v[44:45]
	v_add_f32_e32 v37, v50, v37
	v_pk_mul_f32 v[44:45], v[38:39], v[38:39]
	v_add_f32_e32 v37, v51, v37
	v_add_f32_e32 v37, v44, v37
	v_cvt_pk_bf16_f32 v36, v40, v41
	v_add_f32_e32 v44, v45, v37
	v_cvt_pk_bf16_f32 v37, v38, v39
	v_lshlrev_b32_e32 v68, 16, v36
	v_and_b32_e32 v69, 0xffff0000, v36
	v_lshlrev_b32_e32 v42, 16, v37
	v_and_b32_e32 v43, 0xffff0000, v37
	v_pk_add_f32 v[40:41], v[40:41], v[68:69] neg_lo:[0,1] neg_hi:[0,1]
	v_pk_add_f32 v[42:43], v[38:39], v[42:43] neg_lo:[0,1] neg_hi:[0,1]
	v_cvt_pk_bf16_f32 v40, v40, v41
	v_cvt_pk_bf16_f32 v41, v42, v43
	v_lshl_add_u64 v[42:43], s[58:59], 0, v[56:57]
	v_cvt_pk_bf16_f32 v38, v70, v71
	v_cvt_pk_bf16_f32 v39, v46, v47
	global_store_dwordx4 v[42:43], v[34:37], off
	global_store_dwordx4 v[66:67], v[38:41], off
	v_mov_b32_e32 v34, v44
	s_nop 1
	v_permlane16_swap_b32_e32 v44, v34
	s_waitcnt lgkmcnt(0)
	v_add_f32_e32 v34, v44, v34
	ds_bpermute_b32 v35, v145, v34
	s_and_saveexec_b64 s[12:13], s[0:1]
	s_cbranch_execz .LBB0_1350
	v_readlane_b32 s44, v250, 8
	v_readlane_b32 s46, v250, 10
	v_readlane_b32 s47, v250, 11
	s_waitcnt lgkmcnt(0)
	v_add_f32_e32 v36, v34, v35
	s_lshl_b32 s40, s25, 2
	v_lshl_add_u64 v[34:35], s[46:47], 0, v[54:55]
	v_lshl_add_u64 v[34:35], s[54:55], 2, v[34:35]
	v_lshl_add_u64 v[34:35], v[34:35], 0, s[40:41]
	v_readlane_b32 s45, v250, 9
	global_store_dword v[34:35], v36, off
.LBB0_1350:
	s_or_b64 exec, exec, s[12:13]
	v_add_u32_e32 v40, 0xa0, v144
	v_ashrrev_i32_e32 v41, 31, v40
	v_lshlrev_b64 v[38:39], 6, v[40:41]
	s_waitcnt lgkmcnt(0)
	v_lshl_add_u64 v[34:35], v[136:137], 0, v[38:39]
	global_load_dwordx4 v[34:37], v[34:35], off
	v_readlane_b32 s10, v253, 35
	v_readlane_b32 s11, v253, 36
	v_readlane_b32 s6, v250, 49
	v_readlane_b32 s7, v250, 50
	s_waitcnt vmcnt(0)
	v_mov_b32_e32 v42, v35
	v_mov_b32_e32 v43, v36
	v_mov_b32_e32 v35, v37
	v_pk_add_f32 v[34:35], v[42:43], v[34:35]
	s_nop 0
	v_add_f32_e32 v34, v34, v35
	v_mov_b32_e32 v35, v34
	s_nop 1
	v_permlane16_swap_b32_e32 v34, v35
	s_waitcnt lgkmcnt(0)
	v_add_f32_e32 v34, v34, v35
	v_mov_b32_e32 v35, v34
	s_nop 1
	v_permlane32_swap_b32_e32 v34, v35
	s_waitcnt lgkmcnt(0)
	v_add_f32_e32 v34, v34, v35
	v_fmamk_f32 v34, v34, 0x3a800000, v239
	v_cmp_gt_f32_e32 vcc, s16, v34
	v_mul_f32_e32 v35, 0x4b800000, v34
	s_nop 0
	v_cndmask_b32_e32 v34, v34, v35, vcc
	v_rsq_f32_e32 v34, v34
	s_nop 0
	v_mul_f32_e32 v35, 0x45800000, v34
	v_cndmask_b32_e32 v56, v34, v35, vcc
	v_lshlrev_b64 v[34:35], 10, v[40:41]
	v_lshl_add_u64 v[34:35], v[34:35], 0, v[142:143]
	v_lshlrev_b64 v[40:41], 1, v[34:35]
	v_lshl_add_u64 v[34:35], s[10:11], 0, v[40:41]
	v_lshl_add_u64 v[36:37], s[14:15], 0, v[40:41]
	global_load_dwordx4 v[46:49], v[34:35], off
	global_load_dwordx4 v[58:61], v[36:37], off
	v_lshl_add_u64 v[34:35], s[6:7], 0, v[40:41]
	global_load_dwordx4 v[50:53], v[34:35], off
	v_mul_f32_e32 v26, v26, v56
	v_mul_f32_e32 v26, 0xbfb8aa3b, v26
	v_exp_f32_e32 v26, v26
	v_mul_f32_e32 v30, v30, v56
	v_mul_f32_e32 v31, v31, v56
	v_mul_f32_e32 v30, 0xbfb8aa3b, v30
	v_add_f32_e32 v26, 1.0, v26
	v_rcp_f32_e32 v36, v26
	v_mul_f32_e32 v26, v27, v56
	v_mul_f32_e32 v26, 0xbfb8aa3b, v26
	v_exp_f32_e32 v26, v26
	v_mul_f32_e32 v31, 0xbfb8aa3b, v31
	v_exp_f32_e32 v30, v30
	v_exp_f32_e32 v31, v31
	v_add_f32_e32 v26, 1.0, v26
	v_rcp_f32_e32 v37, v26
	v_mul_f32_e32 v26, v28, v56
	v_mul_f32_e32 v26, 0xbfb8aa3b, v26
	v_exp_f32_e32 v26, v26
	v_mul_f32_e32 v32, v32, v56
	v_mul_f32_e32 v33, v33, v56
	v_add_f32_e32 v30, 1.0, v30
	v_add_f32_e32 v26, 1.0, v26
	v_rcp_f32_e32 v54, v26
	v_mul_f32_e32 v26, v29, v56
	v_mul_f32_e32 v26, 0xbfb8aa3b, v26
	v_exp_f32_e32 v26, v26
	v_add_f32_e32 v31, 1.0, v31
	v_mul_f32_e32 v32, 0xbfb8aa3b, v32
	v_mul_f32_e32 v33, 0xbfb8aa3b, v33
	v_rcp_f32_e32 v30, v30
	v_rcp_f32_e32 v31, v31
	v_exp_f32_e32 v32, v32
	v_exp_f32_e32 v33, v33
	v_add_f32_e32 v26, 1.0, v26
	v_rcp_f32_e32 v55, v26
	v_add_f32_e32 v32, 1.0, v32
	v_add_f32_e32 v33, 1.0, v33
	v_rcp_f32_e32 v32, v32
	v_rcp_f32_e32 v33, v33
	v_mul_f32_e32 v22, v22, v56
	v_mul_f32_e32 v22, 0xbfb8aa3b, v22
	v_exp_f32_e32 v22, v22
	v_mul_f32_e32 v18, v18, v56
	v_mul_f32_e32 v18, 0xbfb8aa3b, v18
	v_exp_f32_e32 v18, v18
	v_add_f32_e32 v22, 1.0, v22
	v_add_f32_e32 v18, 1.0, v18
	s_waitcnt vmcnt(2)
; __device__ __forceinline__ unsigned pk2(float lo, float hi) { f32x2_t v = {lo, hi}; bf16x2_t b = __builtin_convertvector(v, bf16x2_t); return __builtin_bit_cast(unsigned, b); }
; __device__ __forceinline__ float bflo(unsigned u) { return __uint_as_float(u << 16); }
;     __device__ __forceinline__ void operator()(const f32x4 (&acc)[2][2][4][2], const Unit& u, int wr, int wc, int fr, int fq) const {
;     ...
;                     const u32x4 hh = *(const u32x4*)(HI + off), ll = *(const u32x4*)(LO + off);
;                     float hv[8] = {bflo(hh.x) + bflo(ll.x), bfhi(hh.x) + bfhi(ll.x), bflo(hh.y) + bflo(ll.y), bfhi(hh.y) + bfhi(ll.y),
;                                    bflo(hh.z) + bflo(ll.z), bfhi(hh.z) + bfhi(ll.z), bflo(hh.w) + bflo(ll.w), bfhi(hh.w) + bfhi(ll.w)};
;                     float av[8] = {acc[ai][bj][m][0][0], acc[ai][bj][m][0][1], acc[ai][bj][m][0][2], acc[ai][bj][m][0][3], acc[ai][bj][m][1][0], acc[ai][bj][m][1][1], acc[ai][bj][m][1][2], acc[ai][bj][m][1][3]};
;                     if (GATED) { const u32x4 pp = *(const u32x4*)(PP + off);
;                         const float pv[8] = {bflo(pp.x), bfhi(pp.x), bflo(pp.y), bfhi(pp.y), bflo(pp.z), bfhi(pp.z), bflo(pp.w), bfhi(pp.w)};
; #pragma unroll
;                         for (int e = 0; e < 8; ++e) av[e] = fast_sigmoid(av[e] * rs) * pv[e]; }
;                     else {
; #pragma unroll
;                         for (int e = 0; e < 8; ++e) av[e] *= alpha; }
;                     float lo[8];
; #pragma unroll
;                     for (int e = 0; e < 8; ++e) { hv[e] += av[e]; sq += hv[e] * hv[e]; }
;                     u32x4 wh; wh.x = pk2(hv[0], hv[1]); wh.y = pk2(hv[2], hv[3]); wh.z = pk2(hv[4], hv[5]); wh.w = pk2(hv[6], hv[7]);
;                     lo[0] = hv[0] - bflo(wh.x); lo[1] = hv[1] - bfhi(wh.x); lo[2] = hv[2] - bflo(wh.y); lo[3] = hv[3] - bfhi(wh.y);
;                     lo[4] = hv[4] - bflo(wh.z); lo[5] = hv[5] - bfhi(wh.z); lo[6] = hv[6] - bflo(wh.w); lo[7] = hv[7] - bfhi(wh.w);
;                     u32x4 wl; wl.x = pk2(lo[0], lo[1]); wl.y = pk2(lo[2], lo[3]); wl.z = pk2(lo[4], lo[5]); wl.w = pk2(lo[6], lo[7]);
;                     *(u32x4*)(HO + off) = wh; *(u32x4*)(LO + off) = wl;
;                 }
;                 sq += __shfl_xor(sq, 16); sq += __shfl_xor(sq, 32);
;                 if (fq == 0) ssq_out[(size_t)row * 16 + 4 * u.pn + wc] = sq;
	v_lshlrev_b32_e32 v26, 16, v46
	v_and_b32_e32 v27, 0xffff0000, v46
	s_waitcnt vmcnt(0)
	v_lshlrev_b32_e32 v28, 16, v50
	v_and_b32_e32 v29, 0xffff0000, v50
	v_pk_add_f32 v[26:27], v[26:27], v[28:29]
	v_lshlrev_b32_e32 v28, 16, v58
	v_and_b32_e32 v29, 0xffff0000, v58
	v_pk_fma_f32 v[28:29], v[30:31], v[28:29], v[26:27]
	v_lshlrev_b32_e32 v44, 16, v51
	v_cvt_pk_bf16_f32 v26, v28, v29
	v_lshlrev_b32_e32 v30, 16, v26
	v_and_b32_e32 v31, 0xffff0000, v26
	v_pk_mul_f32 v[42:43], v[28:29], v[28:29]
	v_pk_add_f32 v[30:31], v[28:29], v[30:31] neg_lo:[0,1] neg_hi:[0,1]
	v_lshlrev_b32_e32 v28, 16, v47
	v_and_b32_e32 v29, 0xffff0000, v47
	v_and_b32_e32 v45, 0xffff0000, v51
	v_pk_add_f32 v[28:29], v[28:29], v[44:45]
	v_lshlrev_b32_e32 v44, 16, v59
	v_and_b32_e32 v45, 0xffff0000, v59
	v_pk_fma_f32 v[28:29], v[32:33], v[44:45], v[28:29]
	v_lshlrev_b32_e32 v46, 16, v52
	v_cvt_pk_bf16_f32 v27, v28, v29
	v_lshlrev_b32_e32 v32, 16, v27
	v_and_b32_e32 v33, 0xffff0000, v27
	v_pk_mul_f32 v[44:45], v[28:29], v[28:29]
	v_pk_add_f32 v[32:33], v[28:29], v[32:33] neg_lo:[0,1] neg_hi:[0,1]
	v_lshlrev_b32_e32 v28, 16, v48
	v_and_b32_e32 v29, 0xffff0000, v48
	v_and_b32_e32 v47, 0xffff0000, v52
	v_pk_add_f32 v[28:29], v[28:29], v[46:47]
	v_lshlrev_b32_e32 v46, 16, v60
	v_and_b32_e32 v47, 0xffff0000, v60
	v_pk_fma_f32 v[36:37], v[36:37], v[46:47], v[28:29]
	v_lshlrev_b32_e32 v48, 16, v49
	v_cvt_pk_bf16_f32 v28, v36, v37
	v_lshlrev_b32_e32 v50, 16, v28
	v_and_b32_e32 v51, 0xffff0000, v28
	v_pk_mul_f32 v[46:47], v[36:37], v[36:37]
	v_pk_add_f32 v[36:37], v[36:37], v[50:51] neg_lo:[0,1] neg_hi:[0,1]
	v_and_b32_e32 v49, 0xffff0000, v49
	v_lshlrev_b32_e32 v50, 16, v53
	v_and_b32_e32 v51, 0xffff0000, v53
	v_pk_add_f32 v[48:49], v[48:49], v[50:51]
	v_lshlrev_b32_e32 v50, 16, v61
	v_and_b32_e32 v51, 0xffff0000, v61
	v_pk_fma_f32 v[50:51], v[54:55], v[50:51], v[48:49]
	v_cvt_pk_bf16_f32 v30, v30, v31
	v_cvt_pk_bf16_f32 v29, v50, v51
	v_lshlrev_b32_e32 v52, 16, v29
	v_and_b32_e32 v53, 0xffff0000, v29
	v_pk_mul_f32 v[48:49], v[50:51], v[50:51]
	v_pk_add_f32 v[50:51], v[50:51], v[52:53] neg_lo:[0,1] neg_hi:[0,1]
	v_cvt_pk_bf16_f32 v31, v32, v33
	v_cvt_pk_bf16_f32 v32, v36, v37
	v_lshl_add_u64 v[36:37], s[58:59], 0, v[40:41]
	v_or_b32_e32 v40, 0x100, v40
	v_cvt_pk_bf16_f32 v33, v50, v51
	global_store_dwordx4 v[36:37], v[26:29], off
	global_store_dwordx4 v[34:35], v[30:33], off
	v_lshl_add_u64 v[50:51], s[6:7], 0, v[40:41]
	v_lshl_add_u64 v[26:27], s[10:11], 0, v[40:41]
	global_load_dwordx4 v[26:29], v[26:27], off
	v_lshl_add_u64 v[34:35], s[14:15], 0, v[40:41]
	global_load_dwordx4 v[30:33], v[50:51], off
	v_rcp_f32_e32 v54, v22
	global_load_dwordx4 v[34:37], v[34:35], off
	v_mul_f32_e32 v22, v23, v56
	v_mul_f32_e32 v22, 0xbfb8aa3b, v22
	v_exp_f32_e32 v22, v22
	s_nop 0
	v_add_f32_e32 v22, 1.0, v22
	v_rcp_f32_e32 v55, v22
	v_mul_f32_e32 v22, v24, v56
	v_rcp_f32_e32 v24, v18
	v_mul_f32_e32 v18, v19, v56
	v_mul_f32_e32 v22, 0xbfb8aa3b, v22
	v_mul_f32_e32 v18, 0xbfb8aa3b, v18
	v_exp_f32_e32 v22, v22
	v_exp_f32_e32 v18, v18
	v_add_f32_e32 v22, 1.0, v22
	v_add_f32_e32 v18, 1.0, v18
	v_rcp_f32_e32 v52, v22
	v_mul_f32_e32 v22, v25, v56
	v_rcp_f32_e32 v25, v18
	v_mul_f32_e32 v18, v20, v56
	v_mul_f32_e32 v22, 0xbfb8aa3b, v22
	v_mul_f32_e32 v18, 0xbfb8aa3b, v18
	v_exp_f32_e32 v22, v22
	v_exp_f32_e32 v18, v18
	v_add_f32_e32 v22, 1.0, v22
	v_add_f32_e32 v18, 1.0, v18
	v_rcp_f32_e32 v53, v22
	v_rcp_f32_e32 v22, v18
	v_mul_f32_e32 v18, v21, v56
	v_mul_f32_e32 v18, 0xbfb8aa3b, v18
	v_exp_f32_e32 v18, v18
	s_waitcnt vmcnt(2)
	v_and_b32_e32 v19, 0xffff0000, v26
	v_add_f32_e32 v18, 1.0, v18
	v_rcp_f32_e32 v23, v18
	v_lshlrev_b32_e32 v18, 16, v26
	s_waitcnt vmcnt(1)
	v_lshlrev_b32_e32 v20, 16, v30
	v_and_b32_e32 v21, 0xffff0000, v30
	v_pk_add_f32 v[18:19], v[18:19], v[20:21]
	s_waitcnt vmcnt(0)
	v_lshlrev_b32_e32 v20, 16, v34
	v_and_b32_e32 v21, 0xffff0000, v34
	v_pk_fma_f32 v[20:21], v[54:55], v[20:21], v[18:19]
	v_lshlrev_b32_e32 v26, 16, v31
	v_cvt_pk_bf16_f32 v18, v20, v21
	v_lshlrev_b32_e32 v54, 16, v18
	v_and_b32_e32 v55, 0xffff0000, v18
	v_pk_mul_f32 v[56:57], v[20:21], v[20:21]
	v_pk_add_f32 v[54:55], v[20:21], v[54:55] neg_lo:[0,1] neg_hi:[0,1]
	v_lshlrev_b32_e32 v20, 16, v27
	v_and_b32_e32 v21, 0xffff0000, v27
	v_and_b32_e32 v27, 0xffff0000, v31
	v_pk_add_f32 v[20:21], v[20:21], v[26:27]
	v_lshlrev_b32_e32 v26, 16, v35
	v_and_b32_e32 v27, 0xffff0000, v35
	v_pk_fma_f32 v[20:21], v[52:53], v[26:27], v[20:21]
	v_lshlrev_b32_e32 v34, 16, v32
	v_cvt_pk_bf16_f32 v19, v20, v21
	v_lshlrev_b32_e32 v30, 16, v19
	v_and_b32_e32 v31, 0xffff0000, v19
	v_pk_mul_f32 v[26:27], v[20:21], v[20:21]
	v_pk_add_f32 v[30:31], v[20:21], v[30:31] neg_lo:[0,1] neg_hi:[0,1]
	v_lshlrev_b32_e32 v20, 16, v28
	v_and_b32_e32 v21, 0xffff0000, v28
	v_and_b32_e32 v35, 0xffff0000, v32
	v_pk_add_f32 v[20:21], v[20:21], v[34:35]
	v_lshlrev_b32_e32 v34, 16, v36
	v_and_b32_e32 v35, 0xffff0000, v36
	v_pk_fma_f32 v[24:25], v[24:25], v[34:35], v[20:21]
	v_add_f32_e32 v21, v42, v43
	v_add_f32_e32 v21, v44, v21
	v_add_f32_e32 v21, v45, v21
	v_add_f32_e32 v21, v46, v21
	v_add_f32_e32 v21, v47, v21
	v_add_f32_e32 v21, v48, v21
	v_add_f32_e32 v21, v49, v21
	v_add_f32_e32 v21, v56, v21
	v_add_f32_e32 v21, v57, v21
	v_lshlrev_b32_e32 v28, 16, v29
	v_and_b32_e32 v29, 0xffff0000, v29
	v_lshlrev_b32_e32 v32, 16, v33
	v_and_b32_e32 v33, 0xffff0000, v33
	v_add_f32_e32 v21, v26, v21
	v_pk_mul_f32 v[34:35], v[24:25], v[24:25]
	v_pk_add_f32 v[28:29], v[28:29], v[32:33]
	v_lshlrev_b32_e32 v32, 16, v37
	v_and_b32_e32 v33, 0xffff0000, v37
	v_add_f32_e32 v21, v27, v21
	v_pk_fma_f32 v[22:23], v[22:23], v[32:33], v[28:29]
	v_add_f32_e32 v21, v34, v21
	v_pk_mul_f32 v[28:29], v[22:23], v[22:23]
	v_add_f32_e32 v21, v35, v21
	v_add_f32_e32 v21, v28, v21
	v_cvt_pk_bf16_f32 v20, v24, v25
	v_add_f32_e32 v28, v29, v21
	v_cvt_pk_bf16_f32 v21, v22, v23
	v_lshlrev_b32_e32 v52, 16, v20
	v_and_b32_e32 v53, 0xffff0000, v20
	v_lshlrev_b32_e32 v26, 16, v21
	v_and_b32_e32 v27, 0xffff0000, v21
	v_pk_add_f32 v[24:25], v[24:25], v[52:53] neg_lo:[0,1] neg_hi:[0,1]
	v_pk_add_f32 v[26:27], v[22:23], v[26:27] neg_lo:[0,1] neg_hi:[0,1]
	v_cvt_pk_bf16_f32 v24, v24, v25
	v_cvt_pk_bf16_f32 v25, v26, v27
	v_lshl_add_u64 v[26:27], s[58:59], 0, v[40:41]
	v_cvt_pk_bf16_f32 v22, v54, v55
	v_cvt_pk_bf16_f32 v23, v30, v31
	global_store_dwordx4 v[26:27], v[18:21], off
	global_store_dwordx4 v[50:51], v[22:25], off
	v_mov_b32_e32 v18, v28
	s_nop 1
	v_permlane16_swap_b32_e32 v28, v18
	s_waitcnt lgkmcnt(0)
	v_add_f32_e32 v18, v28, v18
	ds_bpermute_b32 v19, v145, v18
	s_and_saveexec_b64 s[12:13], s[0:1]
	s_cbranch_execz .LBB0_1352
	v_readlane_b32 s44, v250, 8
	v_readlane_b32 s46, v250, 10
	v_readlane_b32 s47, v250, 11
	s_waitcnt lgkmcnt(0)
	v_add_f32_e32 v20, v18, v19
	s_lshl_b32 s40, s25, 2
	v_lshl_add_u64 v[18:19], s[46:47], 0, v[38:39]
	v_lshl_add_u64 v[18:19], s[54:55], 2, v[18:19]
	v_lshl_add_u64 v[18:19], v[18:19], 0, s[40:41]
	v_readlane_b32 s45, v250, 9
	global_store_dword v[18:19], v20, off
; __device__ __forceinline__ float row_ssq(const float* part, int pitch, int n4, int row, int fq) {
;     f32x4 v = (f32x4){0.f, 0.f, 0.f, 0.f};
;     if (fq < n4) v = *(const f32x4*)(part + (size_t)row * pitch + 4 * fq);
;     float s = (v[0] + v[1]) + (v[2] + v[3]);
;     s += __shfl_xor(s, 16); s += __shfl_xor(s, 32);
;     return s;
;     __device__ __forceinline__ void operator()(const f32x4 (&acc)[2][2][4][2], const Unit& u, int wr, int wc, int fr, int fq) const {
;     ...
;                 float rs = 0.f; if (GATED) rs = rsqrtf(row_ssq(ssq_in, 16, 4, row, fq) * (1.f / 1024.f) + EPS);
;                 float sq = 0.f;
; #pragma unroll
;                 for (int bj = 0; bj < 2; ++bj) {
;                     const size_t off = (size_t)row * DM + col0 + bj * HALF;
;                     const u32x4 hh = *(const u32x4*)(HI + off), ll = *(const u32x4*)(LO + off);
;                     float hv[8] = {bflo(hh.x) + bflo(ll.x), bfhi(hh.x) + bfhi(ll.x), bflo(hh.y) + bflo(ll.y), bfhi(hh.y) + bfhi(ll.y),
;                                    bflo(hh.z) + bflo(ll.z), bfhi(hh.z) + bfhi(ll.z), bflo(hh.w) + bflo(ll.w), bfhi(hh.w) + bfhi(ll.w)};
;                     float av[8] = {acc[ai][bj][m][0][0], acc[ai][bj][m][0][1], acc[ai][bj][m][0][2], acc[ai][bj][m][0][3], acc[ai][bj][m][1][0], acc[ai][bj][m][1][1], acc[ai][bj][m][1][2], acc[ai][bj][m][1][3]};
;                     if (GATED) { const u32x4 pp = *(const u32x4*)(PP + off);
;                         const float pv[8] = {bflo(pp.x), bfhi(pp.x), bflo(pp.y), bfhi(pp.y), bflo(pp.z), bfhi(pp.z), bflo(pp.w), bfhi(pp.w)};
; #pragma unroll
;                         for (int e = 0; e < 8; ++e) av[e] = fast_sigmoid(av[e] * rs) * pv[e]; }
;                     else {
; #pragma unroll
;                         for (int e = 0; e < 8; ++e) av[e] *= alpha; }
;                     float lo[8];
; #pragma unroll
;                     for (int e = 0; e < 8; ++e) { hv[e] += av[e]; sq += hv[e] * hv[e]; }
;                     u32x4 wh; wh.x = pk2(hv[0], hv[1]); wh.y = pk2(hv[2], hv[3]); wh.z = pk2(hv[4], hv[5]); wh.w = pk2(hv[6], hv[7]);
;                     lo[0] = hv[0] - bflo(wh.x); lo[1] = hv[1] - bfhi(wh.x); lo[2] = hv[2] - bflo(wh.y); lo[3] = hv[3] - bfhi(wh.y);
;                     lo[4] = hv[4] - bflo(wh.z); lo[5] = hv[5] - bfhi(wh.z); lo[6] = hv[6] - bflo(wh.w); lo[7] = hv[7] - bfhi(wh.w);
.LBB0_1352:
	s_or_b64 exec, exec, s[12:13]
	v_add_u32_e32 v24, 0xb0, v144
	v_ashrrev_i32_e32 v25, 31, v24
	v_lshlrev_b64 v[22:23], 6, v[24:25]
	s_waitcnt lgkmcnt(0)
	v_lshl_add_u64 v[18:19], v[136:137], 0, v[22:23]
	global_load_dwordx4 v[18:21], v[18:19], off
	v_readlane_b32 s10, v253, 35
	v_readlane_b32 s11, v253, 36
	v_readlane_b32 s6, v250, 49
	v_readlane_b32 s7, v250, 50
	s_waitcnt vmcnt(0)
	v_mov_b32_e32 v26, v19
	v_mov_b32_e32 v27, v20
	v_mov_b32_e32 v19, v21
	v_pk_add_f32 v[18:19], v[26:27], v[18:19]
	s_nop 0
	v_add_f32_e32 v18, v18, v19
	v_mov_b32_e32 v19, v18
	s_nop 1
	v_permlane16_swap_b32_e32 v18, v19
	s_waitcnt lgkmcnt(0)
	v_add_f32_e32 v18, v18, v19
	v_mov_b32_e32 v19, v18
	s_nop 1
	v_permlane32_swap_b32_e32 v18, v19
	s_waitcnt lgkmcnt(0)
	v_add_f32_e32 v18, v18, v19
	v_fmamk_f32 v18, v18, 0x3a800000, v239
	v_cmp_gt_f32_e32 vcc, s16, v18
	v_mul_f32_e32 v19, 0x4b800000, v18
	s_nop 0
	v_cndmask_b32_e32 v18, v18, v19, vcc
	v_rsq_f32_e32 v18, v18
	s_nop 0
	v_mul_f32_e32 v19, 0x45800000, v18
	v_cndmask_b32_e32 v40, v18, v19, vcc
	v_lshlrev_b64 v[18:19], 10, v[24:25]
	v_lshl_add_u64 v[18:19], v[18:19], 0, v[142:143]
	v_lshlrev_b64 v[24:25], 1, v[18:19]
	v_lshl_add_u64 v[18:19], s[10:11], 0, v[24:25]
	v_lshl_add_u64 v[20:21], s[14:15], 0, v[24:25]
	global_load_dwordx4 v[30:33], v[18:19], off
	global_load_dwordx4 v[42:45], v[20:21], off
	v_lshl_add_u64 v[18:19], s[6:7], 0, v[24:25]
	global_load_dwordx4 v[34:37], v[18:19], off
	v_mul_f32_e32 v10, v10, v40
	v_mul_f32_e32 v10, 0xbfb8aa3b, v10
	v_exp_f32_e32 v10, v10
	v_mul_f32_e32 v14, v14, v40
	v_mul_f32_e32 v15, v15, v40
	v_mul_f32_e32 v14, 0xbfb8aa3b, v14
	v_add_f32_e32 v10, 1.0, v10
	v_rcp_f32_e32 v20, v10
	v_mul_f32_e32 v10, v11, v40
	v_mul_f32_e32 v10, 0xbfb8aa3b, v10
	v_exp_f32_e32 v10, v10
	v_mul_f32_e32 v15, 0xbfb8aa3b, v15
	v_exp_f32_e32 v14, v14
	v_exp_f32_e32 v15, v15
	v_add_f32_e32 v10, 1.0, v10
	v_rcp_f32_e32 v21, v10
	v_mul_f32_e32 v10, v12, v40
	v_mul_f32_e32 v10, 0xbfb8aa3b, v10
	v_exp_f32_e32 v10, v10
	v_mul_f32_e32 v16, v16, v40
	v_mul_f32_e32 v17, v17, v40
	v_add_f32_e32 v14, 1.0, v14
	v_add_f32_e32 v10, 1.0, v10
	v_rcp_f32_e32 v38, v10
	v_mul_f32_e32 v10, v13, v40
	v_mul_f32_e32 v10, 0xbfb8aa3b, v10
	v_exp_f32_e32 v10, v10
	v_add_f32_e32 v15, 1.0, v15
	v_mul_f32_e32 v16, 0xbfb8aa3b, v16
	v_mul_f32_e32 v17, 0xbfb8aa3b, v17
	v_rcp_f32_e32 v14, v14
	v_rcp_f32_e32 v15, v15
	v_exp_f32_e32 v16, v16
	v_exp_f32_e32 v17, v17
	v_add_f32_e32 v10, 1.0, v10
	v_rcp_f32_e32 v39, v10
	v_add_f32_e32 v16, 1.0, v16
	v_add_f32_e32 v17, 1.0, v17
	v_rcp_f32_e32 v16, v16
	v_rcp_f32_e32 v17, v17
	v_mul_f32_e32 v6, v6, v40
	v_mul_f32_e32 v6, 0xbfb8aa3b, v6
	v_exp_f32_e32 v6, v6
	v_mul_f32_e32 v2, v2, v40
	v_mul_f32_e32 v2, 0xbfb8aa3b, v2
	v_exp_f32_e32 v2, v2
	v_add_f32_e32 v6, 1.0, v6
	v_add_f32_e32 v2, 1.0, v2
	s_waitcnt vmcnt(2)
	v_lshlrev_b32_e32 v10, 16, v30
	v_and_b32_e32 v11, 0xffff0000, v30
	s_waitcnt vmcnt(0)
	v_lshlrev_b32_e32 v12, 16, v34
	v_and_b32_e32 v13, 0xffff0000, v34
	v_pk_add_f32 v[10:11], v[10:11], v[12:13]
	v_lshlrev_b32_e32 v12, 16, v42
	v_and_b32_e32 v13, 0xffff0000, v42
	v_pk_fma_f32 v[12:13], v[14:15], v[12:13], v[10:11]
	v_lshlrev_b32_e32 v28, 16, v35
	v_cvt_pk_bf16_f32 v10, v12, v13
	v_lshlrev_b32_e32 v14, 16, v10
	v_and_b32_e32 v15, 0xffff0000, v10
	v_pk_mul_f32 v[26:27], v[12:13], v[12:13]
	v_pk_add_f32 v[14:15], v[12:13], v[14:15] neg_lo:[0,1] neg_hi:[0,1]
	v_lshlrev_b32_e32 v12, 16, v31
	v_and_b32_e32 v13, 0xffff0000, v31
	v_and_b32_e32 v29, 0xffff0000, v35
	v_pk_add_f32 v[12:13], v[12:13], v[28:29]
	v_lshlrev_b32_e32 v28, 16, v43
	v_and_b32_e32 v29, 0xffff0000, v43
	v_pk_fma_f32 v[12:13], v[16:17], v[28:29], v[12:13]
	v_lshlrev_b32_e32 v30, 16, v36
	v_cvt_pk_bf16_f32 v11, v12, v13
	v_lshlrev_b32_e32 v16, 16, v11
	v_and_b32_e32 v17, 0xffff0000, v11
	v_pk_mul_f32 v[28:29], v[12:13], v[12:13]
	v_pk_add_f32 v[16:17], v[12:13], v[16:17] neg_lo:[0,1] neg_hi:[0,1]
	v_lshlrev_b32_e32 v12, 16, v32
	v_and_b32_e32 v13, 0xffff0000, v32
	v_and_b32_e32 v31, 0xffff0000, v36
	v_pk_add_f32 v[12:13], v[12:13], v[30:31]
	v_lshlrev_b32_e32 v30, 16, v44
	v_and_b32_e32 v31, 0xffff0000, v44
	v_pk_fma_f32 v[20:21], v[20:21], v[30:31], v[12:13]
	v_lshlrev_b32_e32 v32, 16, v33
	v_cvt_pk_bf16_f32 v12, v20, v21
	v_lshlrev_b32_e32 v34, 16, v12
	v_and_b32_e32 v35, 0xffff0000, v12
	v_pk_mul_f32 v[30:31], v[20:21], v[20:21]
	v_pk_add_f32 v[20:21], v[20:21], v[34:35] neg_lo:[0,1] neg_hi:[0,1]
	v_and_b32_e32 v33, 0xffff0000, v33
	v_lshlrev_b32_e32 v34, 16, v37
	v_and_b32_e32 v35, 0xffff0000, v37
	v_pk_add_f32 v[32:33], v[32:33], v[34:35]
	v_lshlrev_b32_e32 v34, 16, v45
	v_and_b32_e32 v35, 0xffff0000, v45
	v_pk_fma_f32 v[34:35], v[38:39], v[34:35], v[32:33]
	v_cvt_pk_bf16_f32 v14, v14, v15
	v_cvt_pk_bf16_f32 v13, v34, v35
	v_lshlrev_b32_e32 v36, 16, v13
	v_and_b32_e32 v37, 0xffff0000, v13
	v_pk_mul_f32 v[32:33], v[34:35], v[34:35]
	v_pk_add_f32 v[34:35], v[34:35], v[36:37] neg_lo:[0,1] neg_hi:[0,1]
	v_cvt_pk_bf16_f32 v15, v16, v17
	v_cvt_pk_bf16_f32 v16, v20, v21
	v_lshl_add_u64 v[20:21], s[58:59], 0, v[24:25]
	v_or_b32_e32 v24, 0x100, v24
	v_cvt_pk_bf16_f32 v17, v34, v35
	global_store_dwordx4 v[20:21], v[10:13], off
	global_store_dwordx4 v[18:19], v[14:17], off
	v_lshl_add_u64 v[34:35], s[6:7], 0, v[24:25]
	v_lshl_add_u64 v[10:11], s[10:11], 0, v[24:25]
	global_load_dwordx4 v[10:13], v[10:11], off
	v_lshl_add_u64 v[18:19], s[14:15], 0, v[24:25]
	global_load_dwordx4 v[14:17], v[34:35], off
	v_rcp_f32_e32 v38, v6
	global_load_dwordx4 v[18:21], v[18:19], off
	v_mul_f32_e32 v6, v7, v40
	v_mul_f32_e32 v6, 0xbfb8aa3b, v6
	v_exp_f32_e32 v6, v6
	s_nop 0
	v_add_f32_e32 v6, 1.0, v6
	v_rcp_f32_e32 v39, v6
	v_mul_f32_e32 v6, v8, v40
	v_rcp_f32_e32 v8, v2
	v_mul_f32_e32 v2, v3, v40
	v_mul_f32_e32 v6, 0xbfb8aa3b, v6
	v_mul_f32_e32 v2, 0xbfb8aa3b, v2
	v_exp_f32_e32 v6, v6
	v_exp_f32_e32 v2, v2
	v_add_f32_e32 v6, 1.0, v6
	v_add_f32_e32 v2, 1.0, v2
	v_rcp_f32_e32 v36, v6
	v_mul_f32_e32 v6, v9, v40
	v_rcp_f32_e32 v9, v2
	v_mul_f32_e32 v2, v4, v40
	v_mul_f32_e32 v6, 0xbfb8aa3b, v6
	v_mul_f32_e32 v2, 0xbfb8aa3b, v2
	v_exp_f32_e32 v6, v6
	v_exp_f32_e32 v2, v2
	v_add_f32_e32 v6, 1.0, v6
	v_add_f32_e32 v2, 1.0, v2
	v_rcp_f32_e32 v37, v6
	v_rcp_f32_e32 v6, v2
	v_mul_f32_e32 v2, v5, v40
	v_mul_f32_e32 v2, 0xbfb8aa3b, v2
	v_exp_f32_e32 v2, v2
	s_waitcnt vmcnt(2)
; __device__ __forceinline__ unsigned pk2(float lo, float hi) { f32x2_t v = {lo, hi}; bf16x2_t b = __builtin_convertvector(v, bf16x2_t); return __builtin_bit_cast(unsigned, b); }
; __device__ __forceinline__ float bflo(unsigned u) { return __uint_as_float(u << 16); }
;     __device__ __forceinline__ void operator()(const f32x4 (&acc)[2][2][4][2], const Unit& u, int wr, int wc, int fr, int fq) const {
;     ...
;                     const u32x4 hh = *(const u32x4*)(HI + off), ll = *(const u32x4*)(LO + off);
;                     float hv[8] = {bflo(hh.x) + bflo(ll.x), bfhi(hh.x) + bfhi(ll.x), bflo(hh.y) + bflo(ll.y), bfhi(hh.y) + bfhi(ll.y),
;                                    bflo(hh.z) + bflo(ll.z), bfhi(hh.z) + bfhi(ll.z), bflo(hh.w) + bflo(ll.w), bfhi(hh.w) + bfhi(ll.w)};
;                     float av[8] = {acc[ai][bj][m][0][0], acc[ai][bj][m][0][1], acc[ai][bj][m][0][2], acc[ai][bj][m][0][3], acc[ai][bj][m][1][0], acc[ai][bj][m][1][1], acc[ai][bj][m][1][2], acc[ai][bj][m][1][3]};
;                     if (GATED) { const u32x4 pp = *(const u32x4*)(PP + off);
;                         const float pv[8] = {bflo(pp.x), bfhi(pp.x), bflo(pp.y), bfhi(pp.y), bflo(pp.z), bfhi(pp.z), bflo(pp.w), bfhi(pp.w)};
; #pragma unroll
;                         for (int e = 0; e < 8; ++e) av[e] = fast_sigmoid(av[e] * rs) * pv[e]; }
;                     else {
; #pragma unroll
;                         for (int e = 0; e < 8; ++e) av[e] *= alpha; }
;                     float lo[8];
; #pragma unroll
;                     for (int e = 0; e < 8; ++e) { hv[e] += av[e]; sq += hv[e] * hv[e]; }
;                     u32x4 wh; wh.x = pk2(hv[0], hv[1]); wh.y = pk2(hv[2], hv[3]); wh.z = pk2(hv[4], hv[5]); wh.w = pk2(hv[6], hv[7]);
;                     lo[0] = hv[0] - bflo(wh.x); lo[1] = hv[1] - bfhi(wh.x); lo[2] = hv[2] - bflo(wh.y); lo[3] = hv[3] - bfhi(wh.y);
;                     lo[4] = hv[4] - bflo(wh.z); lo[5] = hv[5] - bfhi(wh.z); lo[6] = hv[6] - bflo(wh.w); lo[7] = hv[7] - bfhi(wh.w);
;                     u32x4 wl; wl.x = pk2(lo[0], lo[1]); wl.y = pk2(lo[2], lo[3]); wl.z = pk2(lo[4], lo[5]); wl.w = pk2(lo[6], lo[7]);
;                     *(u32x4*)(HO + off) = wh; *(u32x4*)(LO + off) = wl;
;                 }
;                 sq += __shfl_xor(sq, 16); sq += __shfl_xor(sq, 32);
;                 if (fq == 0) ssq_out[(size_t)row * 16 + 4 * u.pn + wc] = sq;
	v_and_b32_e32 v3, 0xffff0000, v10
	v_add_f32_e32 v2, 1.0, v2
	v_rcp_f32_e32 v7, v2
	v_lshlrev_b32_e32 v2, 16, v10
	s_waitcnt vmcnt(1)
	v_lshlrev_b32_e32 v4, 16, v14
	v_and_b32_e32 v5, 0xffff0000, v14
	v_pk_add_f32 v[2:3], v[2:3], v[4:5]
	s_waitcnt vmcnt(0)
	v_lshlrev_b32_e32 v4, 16, v18
	v_and_b32_e32 v5, 0xffff0000, v18
	v_pk_fma_f32 v[4:5], v[38:39], v[4:5], v[2:3]
	v_lshlrev_b32_e32 v10, 16, v15
	v_cvt_pk_bf16_f32 v2, v4, v5
	v_lshlrev_b32_e32 v38, 16, v2
	v_and_b32_e32 v39, 0xffff0000, v2
	v_pk_mul_f32 v[40:41], v[4:5], v[4:5]
	v_pk_add_f32 v[38:39], v[4:5], v[38:39] neg_lo:[0,1] neg_hi:[0,1]
	v_lshlrev_b32_e32 v4, 16, v11
	v_and_b32_e32 v5, 0xffff0000, v11
	v_and_b32_e32 v11, 0xffff0000, v15
	v_pk_add_f32 v[4:5], v[4:5], v[10:11]
	v_lshlrev_b32_e32 v10, 16, v19
	v_and_b32_e32 v11, 0xffff0000, v19
	v_pk_fma_f32 v[4:5], v[36:37], v[10:11], v[4:5]
	v_lshlrev_b32_e32 v18, 16, v16
	v_cvt_pk_bf16_f32 v3, v4, v5
	v_lshlrev_b32_e32 v14, 16, v3
	v_and_b32_e32 v15, 0xffff0000, v3
	v_pk_mul_f32 v[10:11], v[4:5], v[4:5]
	v_pk_add_f32 v[14:15], v[4:5], v[14:15] neg_lo:[0,1] neg_hi:[0,1]
	v_lshlrev_b32_e32 v4, 16, v12
	v_and_b32_e32 v5, 0xffff0000, v12
	v_and_b32_e32 v19, 0xffff0000, v16
	v_pk_add_f32 v[4:5], v[4:5], v[18:19]
	v_lshlrev_b32_e32 v18, 16, v20
	v_and_b32_e32 v19, 0xffff0000, v20
	v_pk_fma_f32 v[8:9], v[8:9], v[18:19], v[4:5]
	v_add_f32_e32 v5, v26, v27
	v_add_f32_e32 v5, v28, v5
	v_add_f32_e32 v5, v29, v5
	v_add_f32_e32 v5, v30, v5
	v_add_f32_e32 v5, v31, v5
	v_add_f32_e32 v5, v32, v5
	v_add_f32_e32 v5, v33, v5
	v_add_f32_e32 v5, v40, v5
	v_add_f32_e32 v5, v41, v5
	v_lshlrev_b32_e32 v12, 16, v13
	v_and_b32_e32 v13, 0xffff0000, v13
	v_lshlrev_b32_e32 v16, 16, v17
	v_and_b32_e32 v17, 0xffff0000, v17
	v_add_f32_e32 v5, v10, v5
	v_pk_mul_f32 v[18:19], v[8:9], v[8:9]
	v_pk_add_f32 v[12:13], v[12:13], v[16:17]
	v_lshlrev_b32_e32 v16, 16, v21
	v_and_b32_e32 v17, 0xffff0000, v21
	v_add_f32_e32 v5, v11, v5
	v_pk_fma_f32 v[6:7], v[6:7], v[16:17], v[12:13]
	v_add_f32_e32 v5, v18, v5
	v_pk_mul_f32 v[12:13], v[6:7], v[6:7]
	v_add_f32_e32 v5, v19, v5
	v_add_f32_e32 v5, v12, v5
	v_cvt_pk_bf16_f32 v4, v8, v9
	v_add_f32_e32 v12, v13, v5
	v_cvt_pk_bf16_f32 v5, v6, v7
	v_lshlrev_b32_e32 v36, 16, v4
	v_and_b32_e32 v37, 0xffff0000, v4
	v_lshlrev_b32_e32 v10, 16, v5
	v_and_b32_e32 v11, 0xffff0000, v5
	v_pk_add_f32 v[8:9], v[8:9], v[36:37] neg_lo:[0,1] neg_hi:[0,1]
	v_pk_add_f32 v[10:11], v[6:7], v[10:11] neg_lo:[0,1] neg_hi:[0,1]
	v_cvt_pk_bf16_f32 v8, v8, v9
	v_cvt_pk_bf16_f32 v9, v10, v11
	v_lshl_add_u64 v[10:11], s[58:59], 0, v[24:25]
	v_cvt_pk_bf16_f32 v6, v38, v39
	v_cvt_pk_bf16_f32 v7, v14, v15
	global_store_dwordx4 v[10:11], v[2:5], off
	global_store_dwordx4 v[34:35], v[6:9], off
	v_mov_b32_e32 v2, v12
	s_nop 1
	v_permlane16_swap_b32_e32 v12, v2
	s_waitcnt lgkmcnt(0)
	v_add_f32_e32 v2, v12, v2
	ds_bpermute_b32 v3, v145, v2
	s_and_saveexec_b64 s[12:13], s[0:1]
	s_cbranch_execz .LBB0_1354
	v_readlane_b32 s44, v250, 8
	v_readlane_b32 s46, v250, 10
	v_readlane_b32 s47, v250, 11
	s_waitcnt lgkmcnt(0)
	v_add_f32_e32 v4, v2, v3
	s_lshl_b32 s40, s25, 2
	v_lshl_add_u64 v[2:3], s[46:47], 0, v[22:23]
	v_lshl_add_u64 v[2:3], s[54:55], 2, v[2:3]
	v_lshl_add_u64 v[2:3], v[2:3], 0, s[40:41]
	v_readlane_b32 s45, v250, 9
	global_store_dword v[2:3], v4, off
